# static-priority A/B (strategy 4): all per-segment s_setprio flips deleted from the 7 merged GEMM K-loops (every wave stays at priority 0)
# baseline (speedup 1.0000x reference)
; #define PG8_STAGE(bufoff, gbase, voff) do { _Pragma("unroll") for (int _i = 0; _i < 2; ++_i) \
;         __builtin_amdgcn_global_load_lds((const unsigned*)((const char*)(gbase) + (voff)[_i]), (LAS unsigned*)(lds + (bufoff) + ldsw + _i * 8192), 16, 0, 0); } while (0)
; #define PG8_LDA(dst, b, h) do { _Pragma("unroll") for (int m = 0; m < 4; ++m) _Pragma("unroll") for (int k = 0; k < 2; ++k) dst[m][k] = *(const LAS bf16x8*)(lds + PG8_SA(b, h) + aoff + m * 2048 + k * 1024); } while (0)
; #define PG8_LDB(dst, b, h) do { _Pragma("unroll") for (int n = 0; n < 2; ++n) _Pragma("unroll") for (int k = 0; k < 2; ++k) dst[n][k] = *(const LAS bf16x8*)(lds + PG8_SB(b, h) + boff + n * 2048 + k * 1024); } while (0)
; #define PG8_WAIT_V(n) asm volatile("s_waitcnt vmcnt(" #n ")" ::: "memory")
; #define PG8_WAIT_L(n) asm volatile("s_waitcnt lgkmcnt(" #n ")" ::: "memory")
; #define PG8_BAR __builtin_amdgcn_s_barrier()
; #define PG8_SCHED __builtin_amdgcn_sched_barrier(0)
; template <class Epi, class Sched>
; __device__ __forceinline__ void gemm_phase(LAS unsigned char* lds, const Gemm g, const Sched& S, const Epi& E) {
;     ...
;         const bool has_next = S.next(ui + 1, nxt);
;         const char* nA = has_next ? (const char*)g.A + (size_t)nxt.pm * tstepA : cA; const char* nB = has_next ? (const char*)g.Bt + (size_t)nxt.pn * tstepB : cB;
;         for (int t = 0; t < nt; t += 2) {
;             const bool last = (t == nt - 2);
;             const char* a1 = cA + (size_t)(t + 1) * kstep;
;             const char* a2 = last ? nA : cA + (size_t)(t + 2) * kstep; const char* b2 = last ? nB : cB + (size_t)(t + 2) * kstep;
;             const char* a3 = a2 + kstep; const char* b3 = b2 + kstep;
;             if (last && has_next) S.a_ready(nxt);
;             PG8_LDB(B0, 0, 0); PG8_SCHED; PG8_LDA(At, 0, 0); PG8_STAGE(PG8_SA(1, 1), a1 + hstepA, voffA);
;             PG8_WAIT_L(8); PG8_BAR; PG8_WAIT_L(0); PG8_MMA(0, 0, At, B0); PG8_BAR; PG8_SCHED;
;             PG8_LDB(B1, 0, 1); PG8_STAGE(PG8_SB(0, 0), b2, voffB);
;             PG8_BAR; PG8_WAIT_L(0); PG8_MMA(0, 1, At, B1); PG8_BAR;
;             PG8_LDA(At, 0, 1); PG8_STAGE(PG8_SA(0, 0), a2, voffA);
;             PG8_BAR; PG8_WAIT_L(0); PG8_MMA(1, 0, At, B0); PG8_BAR; PG8_SCHED;
;             PG8_STAGE(PG8_SB(0, 1), b2 + hstepB, voffB);
;             PG8_WAIT_V(6); PG8_BAR; PG8_MMA(1, 1, At, B1); PG8_BAR;
.LBB0_351:
	v_mov_b64_e32 v[4:5], 0xd80
	s_ashr_i32 s15, s14, 31
	v_cmp_lt_i64_e32 vcc, s[4:5], v[4:5]
	s_lshl_b64 s[4:5], s[14:15], 20
	s_add_u32 s18, s88, s4
	s_addc_u32 s19, s89, s5
	s_and_b64 s[4:5], vcc, exec
	s_cselect_b32 s15, s19, s7
	s_cselect_b32 s51, s18, s6
	s_ashr_i32 s1, s0, 31
	s_lshl_b64 s[4:5], s[0:1], 20
	s_add_u32 s4, s28, s4
	s_addc_u32 s5, s29, s5
	s_and_b64 s[24:25], vcc, exec
	s_cselect_b32 s1, s5, s21
	s_cselect_b32 s52, s4, s20
	s_add_u32 s6, s6, 0x80080
	s_addc_u32 s7, s7, 0
	s_add_u32 s53, s20, 0x100
	s_addc_u32 s54, s21, 0
	s_mov_b32 s55, -2
	s_waitcnt lgkmcnt(0)
	s_setprio 0
	s_add_u32 s20, s6, 0xfff80080
	s_addc_u32 s21, s7, -1
	s_add_i32 s56, 0, 0x10000
	v_add_u32_e32 v2, s56, v1
	ds_read_b128 v[144:147], v2
	ds_read_b128 v[150:153], v2 offset:1024
	ds_read_b128 v[154:157], v2 offset:2048
	ds_read_b128 v[158:161], v2 offset:3072
	s_cmp_eq_u32 s55, 28
	s_cselect_b32 s25, s15, s21
	s_cselect_b32 s24, s51, s20
	s_cselect_b32 s21, s1, s54
	s_cselect_b32 s20, s52, s53
	ds_read_b128 v[162:165], v149
	ds_read_b128 v[166:169], v149 offset:1024
	ds_read_b128 v[170:173], v149 offset:2048
	ds_read_b128 v[174:177], v149 offset:3072
	ds_read_b128 v[178:181], v149 offset:4096
	ds_read_b128 v[182:185], v149 offset:5120
	ds_read_b128 v[186:189], v149 offset:6144
	ds_read_b128 v[190:193], v149 offset:7168
	s_add_i32 s58, 0, 0x14000
	v_add_u32_e32 v2, s58, v1
	ds_read_b128 v[194:197], v2
	ds_read_b128 v[198:201], v2 offset:1024
	ds_read_b128 v[202:205], v2 offset:2048
	ds_read_b128 v[206:209], v2 offset:3072
	s_add_i32 m0, s31, 0xc000
	s_nop 0
	global_load_lds_dwordx4 v140, s[6:7]
	s_add_i32 m0, s31, 0xe000
	s_nop 0
	global_load_lds_dwordx4 v142, s[6:7]
	s_waitcnt lgkmcnt(0)
	s_barrier
	v_mfma_f32_16x16x32_bf16 v[128:131], v[144:147], v[162:165], 0
	v_mfma_f32_16x16x32_bf16 v[124:127], v[154:157], v[162:165], 0
	v_mfma_f32_16x16x32_bf16 v[112:115], v[144:147], v[170:173], 0
	v_mfma_f32_16x16x32_bf16 v[108:111], v[154:157], v[170:173], 0
	v_mfma_f32_16x16x32_bf16 v[96:99], v[144:147], v[178:181], 0
	v_mfma_f32_16x16x32_bf16 v[92:95], v[154:157], v[178:181], 0
	v_mfma_f32_16x16x32_bf16 v[80:83], v[144:147], v[186:189], 0
	v_mfma_f32_16x16x32_bf16 v[76:79], v[154:157], v[186:189], 0
	v_mfma_f32_16x16x32_bf16 v[128:131], v[150:153], v[166:169], v[128:131]
	v_mfma_f32_16x16x32_bf16 v[124:127], v[158:161], v[166:169], v[124:127]
	v_mfma_f32_16x16x32_bf16 v[112:115], v[150:153], v[174:177], v[112:115]
	v_mfma_f32_16x16x32_bf16 v[108:111], v[158:161], v[174:177], v[108:111]
	v_mfma_f32_16x16x32_bf16 v[96:99], v[150:153], v[182:185], v[96:99]
	v_mfma_f32_16x16x32_bf16 v[92:95], v[158:161], v[182:185], v[92:95]
	v_mfma_f32_16x16x32_bf16 v[80:83], v[150:153], v[190:193], v[80:83]
	v_mfma_f32_16x16x32_bf16 v[76:79], v[158:161], v[190:193], v[76:79]
	v_mfma_f32_16x16x32_bf16 v[120:123], v[194:197], v[162:165], 0
	v_mfma_f32_16x16x32_bf16 v[116:119], v[202:205], v[162:165], 0
	v_mfma_f32_16x16x32_bf16 v[104:107], v[194:197], v[170:173], 0
	v_mfma_f32_16x16x32_bf16 v[100:103], v[202:205], v[170:173], 0
	v_mfma_f32_16x16x32_bf16 v[88:91], v[194:197], v[178:181], 0
	v_mfma_f32_16x16x32_bf16 v[84:87], v[202:205], v[178:181], 0
	v_mfma_f32_16x16x32_bf16 v[72:75], v[194:197], v[186:189], 0
	v_mfma_f32_16x16x32_bf16 v[68:71], v[202:205], v[186:189], 0
	v_mfma_f32_16x16x32_bf16 v[120:123], v[198:201], v[166:169], v[120:123]
	v_mfma_f32_16x16x32_bf16 v[116:119], v[206:209], v[166:169], v[116:119]
	v_mfma_f32_16x16x32_bf16 v[104:107], v[198:201], v[174:177], v[104:107]
	v_mfma_f32_16x16x32_bf16 v[100:103], v[206:209], v[174:177], v[100:103]
	v_mfma_f32_16x16x32_bf16 v[88:91], v[198:201], v[182:185], v[88:91]
	v_mfma_f32_16x16x32_bf16 v[84:87], v[206:209], v[182:185], v[84:87]
	v_mfma_f32_16x16x32_bf16 v[72:75], v[198:201], v[190:193], v[72:75]
	v_mfma_f32_16x16x32_bf16 v[68:71], v[206:209], v[190:193], v[68:71]
	s_barrier
	ds_read_b128 v[162:165], v149 offset:16384
	ds_read_b128 v[166:169], v149 offset:17408
	ds_read_b128 v[170:173], v149 offset:18432
	ds_read_b128 v[174:177], v149 offset:19456
	ds_read_b128 v[178:181], v149 offset:20480
	ds_read_b128 v[182:185], v149 offset:21504
	ds_read_b128 v[186:189], v149 offset:22528
	ds_read_b128 v[190:193], v149 offset:23552
	s_add_i32 s56, s56, s30
	v_lshl_add_u64 v[210:211], s[20:21], 0, v[136:137]
	s_mov_b32 m0, s56
	s_nop 0
	global_load_lds_dwordx4 v[210:211], off
	v_lshl_add_u64 v[212:213], s[20:21], 0, v[132:133]
	s_add_i32 m0, s56, 0x2000
	s_nop 0
	global_load_lds_dwordx4 v[212:213], off
	s_mov_b32 m0, s31
	v_lshl_add_u64 v[216:217], s[24:25], 0, v[138:139]
	global_load_lds_dwordx4 v[216:217], off
	v_lshl_add_u64 v[218:219], s[24:25], 0, v[134:135]
	s_mov_b32 m0, s35
	s_nop 0
	global_load_lds_dwordx4 v[218:219], off
	s_add_u32 s56, s20, 0x80000
	s_addc_u32 s57, s21, 0
	s_add_i32 s58, s58, s30
	s_mov_b32 m0, s58
	s_nop 0
	global_load_lds_dwordx4 v136, s[56:57]
	s_add_i32 m0, s58, 0x2000
	s_nop 0
	global_load_lds_dwordx4 v132, s[56:57]
	s_waitcnt lgkmcnt(0)
	s_waitcnt vmcnt(6)
	s_barrier
; #define PG8_STAGE(bufoff, gbase, voff) do { _Pragma("unroll") for (int _i = 0; _i < 2; ++_i) \
;         __builtin_amdgcn_global_load_lds((const unsigned*)((const char*)(gbase) + (voff)[_i]), (LAS unsigned*)(lds + (bufoff) + ldsw + _i * 8192), 16, 0, 0); } while (0)
; #define PG8_LDA(dst, b, h) do { _Pragma("unroll") for (int m = 0; m < 4; ++m) _Pragma("unroll") for (int k = 0; k < 2; ++k) dst[m][k] = *(const LAS bf16x8*)(lds + PG8_SA(b, h) + aoff + m * 2048 + k * 1024); } while (0)
; #define PG8_LDB(dst, b, h) do { _Pragma("unroll") for (int n = 0; n < 2; ++n) _Pragma("unroll") for (int k = 0; k < 2; ++k) dst[n][k] = *(const LAS bf16x8*)(lds + PG8_SB(b, h) + boff + n * 2048 + k * 1024); } while (0)
; #define PG8_MMA(ai, bj, At, Bt) do { __builtin_amdgcn_s_setprio(1); _Pragma("unroll") for (int m = 0; m < 4; ++m) _Pragma("unroll") for (int n = 0; n < 2; ++n) _Pragma("unroll") for (int k = 0; k < 2; ++k) \
;         acc[ai][bj][m][n] = __builtin_amdgcn_mfma_f32_16x16x32_bf16(Bt[n][k], At[m][k], acc[ai][bj][m][n], 0, 0, 0); __builtin_amdgcn_s_setprio(0); } while (0)
; #define PG8_WAIT_V(n) asm volatile("s_waitcnt vmcnt(" #n ")" ::: "memory")
; #define PG8_WAIT_L(n) asm volatile("s_waitcnt lgkmcnt(" #n ")" ::: "memory")
; #define PG8_BAR __builtin_amdgcn_s_barrier()
; #define PG8_SCHED __builtin_amdgcn_sched_barrier(0)
; template <class Epi, class Sched>
; __device__ __forceinline__ void gemm_phase(LAS unsigned char* lds, const Gemm g, const Sched& S, const Epi& E) {
;     ...
;             PG8_WAIT_V(6); PG8_BAR; PG8_MMA(1, 1, At, B1); PG8_BAR;
;             PG8_LDB(B0, 1, 0); PG8_SCHED; PG8_LDA(At, 1, 0); PG8_STAGE(PG8_SA(0, 1), a2 + hstepA, voffA);
;             PG8_WAIT_L(8); PG8_BAR; PG8_WAIT_L(0); PG8_MMA(0, 0, At, B0); PG8_BAR; PG8_SCHED;
;             PG8_LDB(B1, 1, 1); PG8_STAGE(PG8_SB(1, 0), b3, voffB);
;             PG8_BAR; PG8_WAIT_L(0); PG8_MMA(0, 1, At, B1); PG8_BAR;
;             PG8_LDA(At, 1, 1); PG8_STAGE(PG8_SA(1, 0), a3, voffA);
;             PG8_BAR; PG8_WAIT_L(0); PG8_MMA(1, 0, At, B0); PG8_BAR; PG8_SCHED;
	v_mfma_f32_16x16x32_bf16 v[64:67], v[144:147], v[162:165], 0
	v_mfma_f32_16x16x32_bf16 v[60:63], v[154:157], v[162:165], 0
	v_mfma_f32_16x16x32_bf16 v[48:51], v[144:147], v[170:173], 0
	v_mfma_f32_16x16x32_bf16 v[44:47], v[154:157], v[170:173], 0
	v_mfma_f32_16x16x32_bf16 v[32:35], v[144:147], v[178:181], 0
	v_mfma_f32_16x16x32_bf16 v[28:31], v[154:157], v[178:181], 0
	v_mfma_f32_16x16x32_bf16 v[16:19], v[144:147], v[186:189], 0
	v_mfma_f32_16x16x32_bf16 v[12:15], v[154:157], v[186:189], 0
	v_mfma_f32_16x16x32_bf16 v[64:67], v[150:153], v[166:169], v[64:67]
	v_mfma_f32_16x16x32_bf16 v[60:63], v[158:161], v[166:169], v[60:63]
	v_mfma_f32_16x16x32_bf16 v[48:51], v[150:153], v[174:177], v[48:51]
	v_mfma_f32_16x16x32_bf16 v[44:47], v[158:161], v[174:177], v[44:47]
	v_mfma_f32_16x16x32_bf16 v[32:35], v[150:153], v[182:185], v[32:35]
	v_mfma_f32_16x16x32_bf16 v[28:31], v[158:161], v[182:185], v[28:31]
	v_mfma_f32_16x16x32_bf16 v[16:19], v[150:153], v[190:193], v[16:19]
	v_mfma_f32_16x16x32_bf16 v[12:15], v[158:161], v[190:193], v[12:15]
	v_mfma_f32_16x16x32_bf16 v[56:59], v[194:197], v[162:165], 0
	v_mfma_f32_16x16x32_bf16 v[52:55], v[202:205], v[162:165], 0
	v_mfma_f32_16x16x32_bf16 v[40:43], v[194:197], v[170:173], 0
	v_mfma_f32_16x16x32_bf16 v[36:39], v[202:205], v[170:173], 0
	v_mfma_f32_16x16x32_bf16 v[24:27], v[194:197], v[178:181], 0
	v_mfma_f32_16x16x32_bf16 v[20:23], v[202:205], v[178:181], 0
	v_mfma_f32_16x16x32_bf16 v[8:11], v[194:197], v[186:189], 0
	v_mfma_f32_16x16x32_bf16 v[4:7], v[202:205], v[186:189], 0
	v_mfma_f32_16x16x32_bf16 v[56:59], v[198:201], v[166:169], v[56:59]
	v_mfma_f32_16x16x32_bf16 v[52:55], v[206:209], v[166:169], v[52:55]
	v_mfma_f32_16x16x32_bf16 v[40:43], v[198:201], v[174:177], v[40:43]
	v_mfma_f32_16x16x32_bf16 v[36:39], v[206:209], v[174:177], v[36:39]
	v_mfma_f32_16x16x32_bf16 v[24:27], v[198:201], v[182:185], v[24:27]
	v_mfma_f32_16x16x32_bf16 v[20:23], v[206:209], v[182:185], v[20:23]
	v_mfma_f32_16x16x32_bf16 v[8:11], v[198:201], v[190:193], v[8:11]
	v_mfma_f32_16x16x32_bf16 v[4:7], v[206:209], v[190:193], v[4:7]
	s_barrier
	s_add_i32 s56, 0, 0x18000
	v_add_u32_e32 v2, s56, v1
	ds_read_b128 v[144:147], v2
	ds_read_b128 v[150:153], v2 offset:1024
	ds_read_b128 v[154:157], v2 offset:2048
	ds_read_b128 v[158:161], v2 offset:3072
	s_add_u32 s24, s24, 0x80000
	s_addc_u32 s25, s25, 0
	ds_read_b128 v[162:165], v149 offset:32768
	ds_read_b128 v[166:169], v149 offset:33792
	ds_read_b128 v[170:173], v149 offset:34816
	ds_read_b128 v[174:177], v149 offset:35840
	ds_read_b128 v[178:181], v149 offset:36864
	ds_read_b128 v[182:185], v149 offset:37888
	ds_read_b128 v[186:189], v149 offset:38912
	ds_read_b128 v[190:193], v149 offset:39936
	s_mov_b32 m0, s36
	s_nop 0
	global_load_lds_dwordx4 v138, s[24:25]
	s_mov_b32 m0, s37
	s_nop 0
	global_load_lds_dwordx4 v134, s[24:25]
	s_add_i32 s24, 0, 0x1c000
	v_add_u32_e32 v2, s24, v1
	ds_read_b128 v[194:197], v2
	ds_read_b128 v[198:201], v2 offset:1024
	ds_read_b128 v[202:205], v2 offset:2048
	ds_read_b128 v[206:209], v2 offset:3072
	s_waitcnt lgkmcnt(0)
	s_barrier
	v_mfma_f32_16x16x32_bf16 v[128:131], v[144:147], v[162:165], v[128:131]
	v_mfma_f32_16x16x32_bf16 v[124:127], v[154:157], v[162:165], v[124:127]
	v_mfma_f32_16x16x32_bf16 v[112:115], v[144:147], v[170:173], v[112:115]
	v_mfma_f32_16x16x32_bf16 v[108:111], v[154:157], v[170:173], v[108:111]
	v_mfma_f32_16x16x32_bf16 v[96:99], v[144:147], v[178:181], v[96:99]
	v_mfma_f32_16x16x32_bf16 v[92:95], v[154:157], v[178:181], v[92:95]
	v_mfma_f32_16x16x32_bf16 v[80:83], v[144:147], v[186:189], v[80:83]
	v_mfma_f32_16x16x32_bf16 v[76:79], v[154:157], v[186:189], v[76:79]
	v_mfma_f32_16x16x32_bf16 v[128:131], v[150:153], v[166:169], v[128:131]
	v_mfma_f32_16x16x32_bf16 v[124:127], v[158:161], v[166:169], v[124:127]
	v_mfma_f32_16x16x32_bf16 v[112:115], v[150:153], v[174:177], v[112:115]
	v_mfma_f32_16x16x32_bf16 v[108:111], v[158:161], v[174:177], v[108:111]
	v_mfma_f32_16x16x32_bf16 v[96:99], v[150:153], v[182:185], v[96:99]
	v_mfma_f32_16x16x32_bf16 v[92:95], v[158:161], v[182:185], v[92:95]
	v_mfma_f32_16x16x32_bf16 v[80:83], v[150:153], v[190:193], v[80:83]
	v_mfma_f32_16x16x32_bf16 v[76:79], v[158:161], v[190:193], v[76:79]
	v_mfma_f32_16x16x32_bf16 v[120:123], v[194:197], v[162:165], v[120:123]
	v_mfma_f32_16x16x32_bf16 v[116:119], v[202:205], v[162:165], v[116:119]
	v_mfma_f32_16x16x32_bf16 v[104:107], v[194:197], v[170:173], v[104:107]
	v_mfma_f32_16x16x32_bf16 v[100:103], v[202:205], v[170:173], v[100:103]
	v_mfma_f32_16x16x32_bf16 v[88:91], v[194:197], v[178:181], v[88:91]
	v_mfma_f32_16x16x32_bf16 v[84:87], v[202:205], v[178:181], v[84:87]
	v_mfma_f32_16x16x32_bf16 v[72:75], v[194:197], v[186:189], v[72:75]
	v_mfma_f32_16x16x32_bf16 v[68:71], v[202:205], v[186:189], v[68:71]
	v_mfma_f32_16x16x32_bf16 v[120:123], v[198:201], v[166:169], v[120:123]
	v_mfma_f32_16x16x32_bf16 v[116:119], v[206:209], v[166:169], v[116:119]
	v_mfma_f32_16x16x32_bf16 v[104:107], v[198:201], v[174:177], v[104:107]
	v_mfma_f32_16x16x32_bf16 v[100:103], v[206:209], v[174:177], v[100:103]
	v_mfma_f32_16x16x32_bf16 v[88:91], v[198:201], v[182:185], v[88:91]
	v_mfma_f32_16x16x32_bf16 v[84:87], v[206:209], v[182:185], v[84:87]
	v_mfma_f32_16x16x32_bf16 v[72:75], v[198:201], v[190:193], v[72:75]
	v_mfma_f32_16x16x32_bf16 v[68:71], v[206:209], v[190:193], v[68:71]
	s_barrier
; #define PG8_STAGE(bufoff, gbase, voff) do { _Pragma("unroll") for (int _i = 0; _i < 2; ++_i) \
;         __builtin_amdgcn_global_load_lds((const unsigned*)((const char*)(gbase) + (voff)[_i]), (LAS unsigned*)(lds + (bufoff) + ldsw + _i * 8192), 16, 0, 0); } while (0)
; #define PG8_LDA(dst, b, h) do { _Pragma("unroll") for (int m = 0; m < 4; ++m) _Pragma("unroll") for (int k = 0; k < 2; ++k) dst[m][k] = *(const LAS bf16x8*)(lds + PG8_SA(b, h) + aoff + m * 2048 + k * 1024); } while (0)
; #define PG8_LDB(dst, b, h) do { _Pragma("unroll") for (int n = 0; n < 2; ++n) _Pragma("unroll") for (int k = 0; k < 2; ++k) dst[n][k] = *(const LAS bf16x8*)(lds + PG8_SB(b, h) + boff + n * 2048 + k * 1024); } while (0)
; #define PG8_WAIT_V(n) asm volatile("s_waitcnt vmcnt(" #n ")" ::: "memory")
; #define PG8_WAIT_L(n) asm volatile("s_waitcnt lgkmcnt(" #n ")" ::: "memory")
; #define PG8_BAR __builtin_amdgcn_s_barrier()
; #define PG8_SCHED __builtin_amdgcn_sched_barrier(0)
; template <class Epi, class Sched>
; __device__ __forceinline__ void gemm_phase(LAS unsigned char* lds, const Gemm g, const Sched& S, const Epi& E) {
;     ...
;             PG8_LDB(B0, 0, 0); PG8_SCHED; PG8_LDA(At, 0, 0); PG8_STAGE(PG8_SA(1, 1), a1 + hstepA, voffA);
;             PG8_WAIT_L(8); PG8_BAR; PG8_WAIT_L(0); PG8_MMA(0, 0, At, B0); PG8_BAR; PG8_SCHED;
;             PG8_LDB(B1, 0, 1); PG8_STAGE(PG8_SB(0, 0), b2, voffB);
;             PG8_BAR; PG8_WAIT_L(0); PG8_MMA(0, 1, At, B1); PG8_BAR;
;             PG8_LDA(At, 0, 1); PG8_STAGE(PG8_SA(0, 0), a2, voffA);
;             PG8_BAR; PG8_WAIT_L(0); PG8_MMA(1, 0, At, B0); PG8_BAR; PG8_SCHED;
;             PG8_STAGE(PG8_SB(0, 1), b2 + hstepB, voffB);
;             PG8_WAIT_V(6); PG8_BAR; PG8_MMA(1, 1, At, B1); PG8_BAR;
;             PG8_LDB(B0, 1, 0); PG8_SCHED; PG8_LDA(At, 1, 0); PG8_STAGE(PG8_SA(0, 1), a2 + hstepA, voffA);
;             PG8_WAIT_L(8); PG8_BAR; PG8_WAIT_L(0); PG8_MMA(0, 0, At, B0); PG8_BAR; PG8_SCHED;
;             PG8_LDB(B1, 1, 1); PG8_STAGE(PG8_SB(1, 0), b3, voffB);
;             PG8_BAR; PG8_WAIT_L(0); PG8_MMA(0, 1, At, B1); PG8_BAR;
;             PG8_LDA(At, 1, 1); PG8_STAGE(PG8_SA(1, 0), a3, voffA);
;             PG8_BAR; PG8_WAIT_L(0); PG8_MMA(1, 0, At, B0); PG8_BAR; PG8_SCHED;
;             PG8_STAGE(PG8_SB(1, 1), b3 + hstepB, voffB);
;             PG8_WAIT_V(6); PG8_BAR; PG8_MMA(1, 1, At, B1); PG8_BAR;
	ds_read_b128 v[162:165], v149 offset:49152
	ds_read_b128 v[166:169], v149 offset:50176
	ds_read_b128 v[170:173], v149 offset:51200
	ds_read_b128 v[174:177], v149 offset:52224
	ds_read_b128 v[178:181], v149 offset:53248
	ds_read_b128 v[182:185], v149 offset:54272
	ds_read_b128 v[186:189], v149 offset:55296
	ds_read_b128 v[190:193], v149 offset:56320
	s_add_i32 s25, s56, s30
	v_lshl_add_u64 v[210:211], v[210:211], 0, s[8:9]
	s_mov_b32 m0, s25
	s_nop 0
	global_load_lds_dwordx4 v[210:211], off
	v_lshl_add_u64 v[210:211], v[212:213], 0, s[8:9]
	s_add_i32 m0, s25, 0x2000
	s_nop 0
	global_load_lds_dwordx4 v[210:211], off
	s_mov_b32 m0, s40
	v_lshl_add_u64 v[210:211], v[216:217], 0, s[8:9]
	global_load_lds_dwordx4 v[210:211], off
	v_lshl_add_u64 v[210:211], v[218:219], 0, s[8:9]
	s_mov_b32 m0, s41
	s_nop 0
	global_load_lds_dwordx4 v[210:211], off
	s_add_u32 s20, s20, 0x80080
	s_addc_u32 s21, s21, 0
	s_add_i32 s24, s24, s30
	s_mov_b32 m0, s24
	s_nop 0
	global_load_lds_dwordx4 v136, s[20:21]
	s_add_i32 m0, s24, 0x2000
	s_nop 0
	global_load_lds_dwordx4 v132, s[20:21]
	s_add_i32 s55, s55, 2
	s_add_u32 s6, s6, 0x100
	s_addc_u32 s7, s7, 0
	s_add_u32 s53, s53, 0x100
	s_addc_u32 s54, s54, 0
	s_cmp_gt_u32 s55, 29
	s_waitcnt lgkmcnt(0)
	s_waitcnt vmcnt(6)
	s_barrier
	v_mfma_f32_16x16x32_bf16 v[64:67], v[144:147], v[162:165], v[64:67]
	v_mfma_f32_16x16x32_bf16 v[60:63], v[154:157], v[162:165], v[60:63]
	v_mfma_f32_16x16x32_bf16 v[48:51], v[144:147], v[170:173], v[48:51]
	v_mfma_f32_16x16x32_bf16 v[44:47], v[154:157], v[170:173], v[44:47]
	v_mfma_f32_16x16x32_bf16 v[32:35], v[144:147], v[178:181], v[32:35]
	v_mfma_f32_16x16x32_bf16 v[28:31], v[154:157], v[178:181], v[28:31]
	v_mfma_f32_16x16x32_bf16 v[16:19], v[144:147], v[186:189], v[16:19]
	v_mfma_f32_16x16x32_bf16 v[12:15], v[154:157], v[186:189], v[12:15]
	v_mfma_f32_16x16x32_bf16 v[64:67], v[150:153], v[166:169], v[64:67]
	v_mfma_f32_16x16x32_bf16 v[60:63], v[158:161], v[166:169], v[60:63]
	v_mfma_f32_16x16x32_bf16 v[48:51], v[150:153], v[174:177], v[48:51]
	v_mfma_f32_16x16x32_bf16 v[44:47], v[158:161], v[174:177], v[44:47]
	v_mfma_f32_16x16x32_bf16 v[32:35], v[150:153], v[182:185], v[32:35]
	v_mfma_f32_16x16x32_bf16 v[28:31], v[158:161], v[182:185], v[28:31]
	v_mfma_f32_16x16x32_bf16 v[16:19], v[150:153], v[190:193], v[16:19]
	v_mfma_f32_16x16x32_bf16 v[12:15], v[158:161], v[190:193], v[12:15]
	v_mfma_f32_16x16x32_bf16 v[56:59], v[194:197], v[162:165], v[56:59]
	v_mfma_f32_16x16x32_bf16 v[52:55], v[202:205], v[162:165], v[52:55]
	v_mfma_f32_16x16x32_bf16 v[40:43], v[194:197], v[170:173], v[40:43]
	v_mfma_f32_16x16x32_bf16 v[36:39], v[202:205], v[170:173], v[36:39]
	v_mfma_f32_16x16x32_bf16 v[24:27], v[194:197], v[178:181], v[24:27]
	v_mfma_f32_16x16x32_bf16 v[20:23], v[202:205], v[178:181], v[20:23]
	v_mfma_f32_16x16x32_bf16 v[8:11], v[194:197], v[186:189], v[8:11]
	v_mfma_f32_16x16x32_bf16 v[4:7], v[202:205], v[186:189], v[4:7]
	v_mfma_f32_16x16x32_bf16 v[56:59], v[198:201], v[166:169], v[56:59]
	v_mfma_f32_16x16x32_bf16 v[52:55], v[206:209], v[166:169], v[52:55]
	v_mfma_f32_16x16x32_bf16 v[40:43], v[198:201], v[174:177], v[40:43]
	v_mfma_f32_16x16x32_bf16 v[36:39], v[206:209], v[174:177], v[36:39]
	v_mfma_f32_16x16x32_bf16 v[24:27], v[198:201], v[182:185], v[24:27]
	v_mfma_f32_16x16x32_bf16 v[20:23], v[206:209], v[182:185], v[20:23]
	v_mfma_f32_16x16x32_bf16 v[8:11], v[198:201], v[190:193], v[8:11]
	v_mfma_f32_16x16x32_bf16 v[4:7], v[206:209], v[190:193], v[4:7]
	s_barrier
	s_setprio 0
.LBB0_352:
	s_setprio 0
	s_add_u32 s20, s6, 0xfff80080
	s_addc_u32 s21, s7, -1
	s_add_i32 s56, 0, 0x10000
	v_add_u32_e32 v2, s56, v1
	ds_read_b128 v[144:147], v2
	ds_read_b128 v[150:153], v2 offset:1024
	ds_read_b128 v[154:157], v2 offset:2048
	ds_read_b128 v[158:161], v2 offset:3072
	s_cmp_eq_u32 s55, 28
	s_cselect_b32 s25, s15, s21
	s_cselect_b32 s24, s51, s20
	s_cselect_b32 s21, s1, s54
	s_cselect_b32 s20, s52, s53
	ds_read_b128 v[162:165], v149
	ds_read_b128 v[166:169], v149 offset:1024
	ds_read_b128 v[170:173], v149 offset:2048
	ds_read_b128 v[174:177], v149 offset:3072
	ds_read_b128 v[178:181], v149 offset:4096
	ds_read_b128 v[182:185], v149 offset:5120
	ds_read_b128 v[186:189], v149 offset:6144
	ds_read_b128 v[190:193], v149 offset:7168
	s_add_i32 s58, 0, 0x14000
	v_add_u32_e32 v2, s58, v1
	ds_read_b128 v[194:197], v2
	ds_read_b128 v[198:201], v2 offset:1024
	ds_read_b128 v[202:205], v2 offset:2048
	ds_read_b128 v[206:209], v2 offset:3072
	s_add_i32 m0, s31, 0xc000
	s_nop 0
	global_load_lds_dwordx4 v140, s[6:7]
	s_add_i32 m0, s31, 0xe000
	s_nop 0
	global_load_lds_dwordx4 v142, s[6:7]
	s_waitcnt lgkmcnt(0)
	s_barrier
; #define PG8_STAGE(bufoff, gbase, voff) do { _Pragma("unroll") for (int _i = 0; _i < 2; ++_i) \
;         __builtin_amdgcn_global_load_lds((const unsigned*)((const char*)(gbase) + (voff)[_i]), (LAS unsigned*)(lds + (bufoff) + ldsw + _i * 8192), 16, 0, 0); } while (0)
; #define PG8_LDA(dst, b, h) do { _Pragma("unroll") for (int m = 0; m < 4; ++m) _Pragma("unroll") for (int k = 0; k < 2; ++k) dst[m][k] = *(const LAS bf16x8*)(lds + PG8_SA(b, h) + aoff + m * 2048 + k * 1024); } while (0)
; #define PG8_LDB(dst, b, h) do { _Pragma("unroll") for (int n = 0; n < 2; ++n) _Pragma("unroll") for (int k = 0; k < 2; ++k) dst[n][k] = *(const LAS bf16x8*)(lds + PG8_SB(b, h) + boff + n * 2048 + k * 1024); } while (0)
; #define PG8_MMA(ai, bj, At, Bt) do { __builtin_amdgcn_s_setprio(1); _Pragma("unroll") for (int m = 0; m < 4; ++m) _Pragma("unroll") for (int n = 0; n < 2; ++n) _Pragma("unroll") for (int k = 0; k < 2; ++k) \
;         acc[ai][bj][m][n] = __builtin_amdgcn_mfma_f32_16x16x32_bf16(Bt[n][k], At[m][k], acc[ai][bj][m][n], 0, 0, 0); __builtin_amdgcn_s_setprio(0); } while (0)
; #define PG8_WAIT_V(n) asm volatile("s_waitcnt vmcnt(" #n ")" ::: "memory")
; #define PG8_WAIT_L(n) asm volatile("s_waitcnt lgkmcnt(" #n ")" ::: "memory")
; #define PG8_BAR __builtin_amdgcn_s_barrier()
; #define PG8_SCHED __builtin_amdgcn_sched_barrier(0)
; template <class Epi, class Sched>
; __device__ __forceinline__ void gemm_phase(LAS unsigned char* lds, const Gemm g, const Sched& S, const Epi& E) {
;     ...
;             PG8_WAIT_L(8); PG8_BAR; PG8_WAIT_L(0); PG8_MMA(0, 0, At, B0); PG8_BAR; PG8_SCHED;
;             PG8_LDB(B1, 0, 1); PG8_STAGE(PG8_SB(0, 0), b2, voffB);
;             PG8_BAR; PG8_WAIT_L(0); PG8_MMA(0, 1, At, B1); PG8_BAR;
;             PG8_LDA(At, 0, 1); PG8_STAGE(PG8_SA(0, 0), a2, voffA);
;             PG8_BAR; PG8_WAIT_L(0); PG8_MMA(1, 0, At, B0); PG8_BAR; PG8_SCHED;
;             PG8_STAGE(PG8_SB(0, 1), b2 + hstepB, voffB);
;             PG8_WAIT_V(6); PG8_BAR; PG8_MMA(1, 1, At, B1); PG8_BAR;
;             PG8_LDB(B0, 1, 0); PG8_SCHED; PG8_LDA(At, 1, 0); PG8_STAGE(PG8_SA(0, 1), a2 + hstepA, voffA);
;             PG8_WAIT_L(8); PG8_BAR; PG8_WAIT_L(0); PG8_MMA(0, 0, At, B0); PG8_BAR; PG8_SCHED;
	v_mfma_f32_16x16x32_bf16 v[128:131], v[144:147], v[162:165], v[128:131]
	v_mfma_f32_16x16x32_bf16 v[124:127], v[154:157], v[162:165], v[124:127]
	v_mfma_f32_16x16x32_bf16 v[112:115], v[144:147], v[170:173], v[112:115]
	v_mfma_f32_16x16x32_bf16 v[108:111], v[154:157], v[170:173], v[108:111]
	v_mfma_f32_16x16x32_bf16 v[96:99], v[144:147], v[178:181], v[96:99]
	v_mfma_f32_16x16x32_bf16 v[92:95], v[154:157], v[178:181], v[92:95]
	v_mfma_f32_16x16x32_bf16 v[80:83], v[144:147], v[186:189], v[80:83]
	v_mfma_f32_16x16x32_bf16 v[76:79], v[154:157], v[186:189], v[76:79]
	v_mfma_f32_16x16x32_bf16 v[128:131], v[150:153], v[166:169], v[128:131]
	v_mfma_f32_16x16x32_bf16 v[124:127], v[158:161], v[166:169], v[124:127]
	v_mfma_f32_16x16x32_bf16 v[112:115], v[150:153], v[174:177], v[112:115]
	v_mfma_f32_16x16x32_bf16 v[108:111], v[158:161], v[174:177], v[108:111]
	v_mfma_f32_16x16x32_bf16 v[96:99], v[150:153], v[182:185], v[96:99]
	v_mfma_f32_16x16x32_bf16 v[92:95], v[158:161], v[182:185], v[92:95]
	v_mfma_f32_16x16x32_bf16 v[80:83], v[150:153], v[190:193], v[80:83]
	v_mfma_f32_16x16x32_bf16 v[76:79], v[158:161], v[190:193], v[76:79]
	v_mfma_f32_16x16x32_bf16 v[120:123], v[194:197], v[162:165], v[120:123]
	v_mfma_f32_16x16x32_bf16 v[116:119], v[202:205], v[162:165], v[116:119]
	v_mfma_f32_16x16x32_bf16 v[104:107], v[194:197], v[170:173], v[104:107]
	v_mfma_f32_16x16x32_bf16 v[100:103], v[202:205], v[170:173], v[100:103]
	v_mfma_f32_16x16x32_bf16 v[88:91], v[194:197], v[178:181], v[88:91]
	v_mfma_f32_16x16x32_bf16 v[84:87], v[202:205], v[178:181], v[84:87]
	v_mfma_f32_16x16x32_bf16 v[72:75], v[194:197], v[186:189], v[72:75]
	v_mfma_f32_16x16x32_bf16 v[68:71], v[202:205], v[186:189], v[68:71]
	v_mfma_f32_16x16x32_bf16 v[120:123], v[198:201], v[166:169], v[120:123]
	v_mfma_f32_16x16x32_bf16 v[116:119], v[206:209], v[166:169], v[116:119]
	v_mfma_f32_16x16x32_bf16 v[104:107], v[198:201], v[174:177], v[104:107]
	v_mfma_f32_16x16x32_bf16 v[100:103], v[206:209], v[174:177], v[100:103]
	v_mfma_f32_16x16x32_bf16 v[88:91], v[198:201], v[182:185], v[88:91]
	v_mfma_f32_16x16x32_bf16 v[84:87], v[206:209], v[182:185], v[84:87]
	v_mfma_f32_16x16x32_bf16 v[72:75], v[198:201], v[190:193], v[72:75]
	v_mfma_f32_16x16x32_bf16 v[68:71], v[206:209], v[190:193], v[68:71]
	s_barrier
	ds_read_b128 v[162:165], v149 offset:16384
	ds_read_b128 v[166:169], v149 offset:17408
	ds_read_b128 v[170:173], v149 offset:18432
	ds_read_b128 v[174:177], v149 offset:19456
	ds_read_b128 v[178:181], v149 offset:20480
	ds_read_b128 v[182:185], v149 offset:21504
	ds_read_b128 v[186:189], v149 offset:22528
	ds_read_b128 v[190:193], v149 offset:23552
	s_add_i32 s56, s56, s30
	v_lshl_add_u64 v[210:211], s[20:21], 0, v[136:137]
	s_mov_b32 m0, s56
	s_nop 0
	global_load_lds_dwordx4 v[210:211], off
	v_lshl_add_u64 v[212:213], s[20:21], 0, v[132:133]
	s_add_i32 m0, s56, 0x2000
	s_nop 0
	global_load_lds_dwordx4 v[212:213], off
	s_mov_b32 m0, s31
	v_lshl_add_u64 v[216:217], s[24:25], 0, v[138:139]
	global_load_lds_dwordx4 v[216:217], off
	v_lshl_add_u64 v[218:219], s[24:25], 0, v[134:135]
	s_mov_b32 m0, s35
	s_nop 0
	global_load_lds_dwordx4 v[218:219], off
	s_add_u32 s56, s20, 0x80000
	s_addc_u32 s57, s21, 0
	s_add_i32 s58, s58, s30
	s_mov_b32 m0, s58
	s_nop 0
	global_load_lds_dwordx4 v136, s[56:57]
	s_add_i32 m0, s58, 0x2000
	s_nop 0
	global_load_lds_dwordx4 v132, s[56:57]
	s_waitcnt lgkmcnt(0)
	s_waitcnt vmcnt(6)
	s_barrier
	v_mfma_f32_16x16x32_bf16 v[64:67], v[144:147], v[162:165], v[64:67]
	v_mfma_f32_16x16x32_bf16 v[60:63], v[154:157], v[162:165], v[60:63]
	v_mfma_f32_16x16x32_bf16 v[48:51], v[144:147], v[170:173], v[48:51]
	v_mfma_f32_16x16x32_bf16 v[44:47], v[154:157], v[170:173], v[44:47]
	v_mfma_f32_16x16x32_bf16 v[32:35], v[144:147], v[178:181], v[32:35]
	v_mfma_f32_16x16x32_bf16 v[28:31], v[154:157], v[178:181], v[28:31]
	v_mfma_f32_16x16x32_bf16 v[16:19], v[144:147], v[186:189], v[16:19]
	v_mfma_f32_16x16x32_bf16 v[12:15], v[154:157], v[186:189], v[12:15]
	v_mfma_f32_16x16x32_bf16 v[64:67], v[150:153], v[166:169], v[64:67]
	v_mfma_f32_16x16x32_bf16 v[60:63], v[158:161], v[166:169], v[60:63]
	v_mfma_f32_16x16x32_bf16 v[48:51], v[150:153], v[174:177], v[48:51]
	v_mfma_f32_16x16x32_bf16 v[44:47], v[158:161], v[174:177], v[44:47]
	v_mfma_f32_16x16x32_bf16 v[32:35], v[150:153], v[182:185], v[32:35]
	v_mfma_f32_16x16x32_bf16 v[28:31], v[158:161], v[182:185], v[28:31]
	v_mfma_f32_16x16x32_bf16 v[16:19], v[150:153], v[190:193], v[16:19]
	v_mfma_f32_16x16x32_bf16 v[12:15], v[158:161], v[190:193], v[12:15]
	v_mfma_f32_16x16x32_bf16 v[56:59], v[194:197], v[162:165], v[56:59]
	v_mfma_f32_16x16x32_bf16 v[52:55], v[202:205], v[162:165], v[52:55]
	v_mfma_f32_16x16x32_bf16 v[40:43], v[194:197], v[170:173], v[40:43]
	v_mfma_f32_16x16x32_bf16 v[36:39], v[202:205], v[170:173], v[36:39]
	v_mfma_f32_16x16x32_bf16 v[24:27], v[194:197], v[178:181], v[24:27]
	v_mfma_f32_16x16x32_bf16 v[20:23], v[202:205], v[178:181], v[20:23]
	v_mfma_f32_16x16x32_bf16 v[8:11], v[194:197], v[186:189], v[8:11]
	v_mfma_f32_16x16x32_bf16 v[4:7], v[202:205], v[186:189], v[4:7]
	v_mfma_f32_16x16x32_bf16 v[56:59], v[198:201], v[166:169], v[56:59]
	v_mfma_f32_16x16x32_bf16 v[52:55], v[206:209], v[166:169], v[52:55]
	v_mfma_f32_16x16x32_bf16 v[40:43], v[198:201], v[174:177], v[40:43]
	v_mfma_f32_16x16x32_bf16 v[36:39], v[206:209], v[174:177], v[36:39]
	v_mfma_f32_16x16x32_bf16 v[24:27], v[198:201], v[182:185], v[24:27]
	v_mfma_f32_16x16x32_bf16 v[20:23], v[206:209], v[182:185], v[20:23]
	v_mfma_f32_16x16x32_bf16 v[8:11], v[198:201], v[190:193], v[8:11]
	v_mfma_f32_16x16x32_bf16 v[4:7], v[206:209], v[190:193], v[4:7]
	s_barrier
; #define PG8_STAGE(bufoff, gbase, voff) do { _Pragma("unroll") for (int _i = 0; _i < 2; ++_i) \
;         __builtin_amdgcn_global_load_lds((const unsigned*)((const char*)(gbase) + (voff)[_i]), (LAS unsigned*)(lds + (bufoff) + ldsw + _i * 8192), 16, 0, 0); } while (0)
; #define PG8_LDA(dst, b, h) do { _Pragma("unroll") for (int m = 0; m < 4; ++m) _Pragma("unroll") for (int k = 0; k < 2; ++k) dst[m][k] = *(const LAS bf16x8*)(lds + PG8_SA(b, h) + aoff + m * 2048 + k * 1024); } while (0)
; #define PG8_LDB(dst, b, h) do { _Pragma("unroll") for (int n = 0; n < 2; ++n) _Pragma("unroll") for (int k = 0; k < 2; ++k) dst[n][k] = *(const LAS bf16x8*)(lds + PG8_SB(b, h) + boff + n * 2048 + k * 1024); } while (0)
; #define PG8_MMA(ai, bj, At, Bt) do { __builtin_amdgcn_s_setprio(1); _Pragma("unroll") for (int m = 0; m < 4; ++m) _Pragma("unroll") for (int n = 0; n < 2; ++n) _Pragma("unroll") for (int k = 0; k < 2; ++k) \
;         acc[ai][bj][m][n] = __builtin_amdgcn_mfma_f32_16x16x32_bf16(Bt[n][k], At[m][k], acc[ai][bj][m][n], 0, 0, 0); __builtin_amdgcn_s_setprio(0); } while (0)
; #define PG8_WAIT_V(n) asm volatile("s_waitcnt vmcnt(" #n ")" ::: "memory")
; #define PG8_WAIT_L(n) asm volatile("s_waitcnt lgkmcnt(" #n ")" ::: "memory")
; #define PG8_BAR __builtin_amdgcn_s_barrier()
; #define PG8_SCHED __builtin_amdgcn_sched_barrier(0)
; template <class Epi, class Sched>
; __device__ __forceinline__ void gemm_phase(LAS unsigned char* lds, const Gemm g, const Sched& S, const Epi& E) {
;     ...
;             PG8_LDB(B1, 1, 1); PG8_STAGE(PG8_SB(1, 0), b3, voffB);
;             PG8_BAR; PG8_WAIT_L(0); PG8_MMA(0, 1, At, B1); PG8_BAR;
;             PG8_LDA(At, 1, 1); PG8_STAGE(PG8_SA(1, 0), a3, voffA);
;             PG8_BAR; PG8_WAIT_L(0); PG8_MMA(1, 0, At, B0); PG8_BAR; PG8_SCHED;
;             PG8_STAGE(PG8_SB(1, 1), b3 + hstepB, voffB);
;             PG8_WAIT_V(6); PG8_BAR; PG8_MMA(1, 1, At, B1); PG8_BAR;
;         }
	s_add_i32 s56, 0, 0x18000
	v_add_u32_e32 v2, s56, v1
	ds_read_b128 v[144:147], v2
	ds_read_b128 v[150:153], v2 offset:1024
	ds_read_b128 v[154:157], v2 offset:2048
	ds_read_b128 v[158:161], v2 offset:3072
	s_add_u32 s24, s24, 0x80000
	s_addc_u32 s25, s25, 0
	ds_read_b128 v[162:165], v149 offset:32768
	ds_read_b128 v[166:169], v149 offset:33792
	ds_read_b128 v[170:173], v149 offset:34816
	ds_read_b128 v[174:177], v149 offset:35840
	ds_read_b128 v[178:181], v149 offset:36864
	ds_read_b128 v[182:185], v149 offset:37888
	ds_read_b128 v[186:189], v149 offset:38912
	ds_read_b128 v[190:193], v149 offset:39936
	s_mov_b32 m0, s36
	s_nop 0
	global_load_lds_dwordx4 v138, s[24:25]
	s_mov_b32 m0, s37
	s_nop 0
	global_load_lds_dwordx4 v134, s[24:25]
	s_add_i32 s24, 0, 0x1c000
	v_add_u32_e32 v2, s24, v1
	ds_read_b128 v[194:197], v2
	ds_read_b128 v[198:201], v2 offset:1024
	ds_read_b128 v[202:205], v2 offset:2048
	ds_read_b128 v[206:209], v2 offset:3072
	s_waitcnt lgkmcnt(0)
	s_barrier
	v_mfma_f32_16x16x32_bf16 v[128:131], v[144:147], v[162:165], v[128:131]
	v_mfma_f32_16x16x32_bf16 v[124:127], v[154:157], v[162:165], v[124:127]
	v_mfma_f32_16x16x32_bf16 v[112:115], v[144:147], v[170:173], v[112:115]
	v_mfma_f32_16x16x32_bf16 v[108:111], v[154:157], v[170:173], v[108:111]
	v_mfma_f32_16x16x32_bf16 v[96:99], v[144:147], v[178:181], v[96:99]
	v_mfma_f32_16x16x32_bf16 v[92:95], v[154:157], v[178:181], v[92:95]
	v_mfma_f32_16x16x32_bf16 v[80:83], v[144:147], v[186:189], v[80:83]
	v_mfma_f32_16x16x32_bf16 v[76:79], v[154:157], v[186:189], v[76:79]
	v_mfma_f32_16x16x32_bf16 v[128:131], v[150:153], v[166:169], v[128:131]
	v_mfma_f32_16x16x32_bf16 v[124:127], v[158:161], v[166:169], v[124:127]
	v_mfma_f32_16x16x32_bf16 v[112:115], v[150:153], v[174:177], v[112:115]
	v_mfma_f32_16x16x32_bf16 v[108:111], v[158:161], v[174:177], v[108:111]
	v_mfma_f32_16x16x32_bf16 v[96:99], v[150:153], v[182:185], v[96:99]
	v_mfma_f32_16x16x32_bf16 v[92:95], v[158:161], v[182:185], v[92:95]
	v_mfma_f32_16x16x32_bf16 v[80:83], v[150:153], v[190:193], v[80:83]
	v_mfma_f32_16x16x32_bf16 v[76:79], v[158:161], v[190:193], v[76:79]
	v_mfma_f32_16x16x32_bf16 v[120:123], v[194:197], v[162:165], v[120:123]
	v_mfma_f32_16x16x32_bf16 v[116:119], v[202:205], v[162:165], v[116:119]
	v_mfma_f32_16x16x32_bf16 v[104:107], v[194:197], v[170:173], v[104:107]
	v_mfma_f32_16x16x32_bf16 v[100:103], v[202:205], v[170:173], v[100:103]
	v_mfma_f32_16x16x32_bf16 v[88:91], v[194:197], v[178:181], v[88:91]
	v_mfma_f32_16x16x32_bf16 v[84:87], v[202:205], v[178:181], v[84:87]
	v_mfma_f32_16x16x32_bf16 v[72:75], v[194:197], v[186:189], v[72:75]
	v_mfma_f32_16x16x32_bf16 v[68:71], v[202:205], v[186:189], v[68:71]
	v_mfma_f32_16x16x32_bf16 v[120:123], v[198:201], v[166:169], v[120:123]
	v_mfma_f32_16x16x32_bf16 v[116:119], v[206:209], v[166:169], v[116:119]
	v_mfma_f32_16x16x32_bf16 v[104:107], v[198:201], v[174:177], v[104:107]
	v_mfma_f32_16x16x32_bf16 v[100:103], v[206:209], v[174:177], v[100:103]
	v_mfma_f32_16x16x32_bf16 v[88:91], v[198:201], v[182:185], v[88:91]
	v_mfma_f32_16x16x32_bf16 v[84:87], v[206:209], v[182:185], v[84:87]
	v_mfma_f32_16x16x32_bf16 v[72:75], v[198:201], v[190:193], v[72:75]
	v_mfma_f32_16x16x32_bf16 v[68:71], v[206:209], v[190:193], v[68:71]
	s_barrier
	ds_read_b128 v[162:165], v149 offset:49152
	ds_read_b128 v[166:169], v149 offset:50176
	ds_read_b128 v[170:173], v149 offset:51200
	ds_read_b128 v[174:177], v149 offset:52224
	ds_read_b128 v[178:181], v149 offset:53248
	ds_read_b128 v[182:185], v149 offset:54272
	ds_read_b128 v[186:189], v149 offset:55296
	ds_read_b128 v[190:193], v149 offset:56320
	s_add_i32 s25, s56, s30
	v_lshl_add_u64 v[210:211], v[210:211], 0, s[8:9]
	s_mov_b32 m0, s25
	s_nop 0
	global_load_lds_dwordx4 v[210:211], off
	v_lshl_add_u64 v[210:211], v[212:213], 0, s[8:9]
	s_add_i32 m0, s25, 0x2000
	s_nop 0
	global_load_lds_dwordx4 v[210:211], off
	s_mov_b32 m0, s40
	v_lshl_add_u64 v[210:211], v[216:217], 0, s[8:9]
	global_load_lds_dwordx4 v[210:211], off
	v_lshl_add_u64 v[210:211], v[218:219], 0, s[8:9]
	s_mov_b32 m0, s41
	s_nop 0
	global_load_lds_dwordx4 v[210:211], off
	s_add_u32 s20, s20, 0x80080
	s_addc_u32 s21, s21, 0
	s_add_i32 s24, s24, s30
	s_mov_b32 m0, s24
	s_nop 0
	global_load_lds_dwordx4 v136, s[20:21]
	s_add_i32 m0, s24, 0x2000
	s_nop 0
	global_load_lds_dwordx4 v132, s[20:21]
	s_add_i32 s55, s55, 2
	s_add_u32 s6, s6, 0x100
	s_addc_u32 s7, s7, 0
	s_add_u32 s53, s53, 0x100
	s_addc_u32 s54, s54, 0
	s_cmp_gt_u32 s55, 29
	s_waitcnt lgkmcnt(0)
	s_waitcnt vmcnt(6)
	s_barrier
	v_mfma_f32_16x16x32_bf16 v[64:67], v[144:147], v[162:165], v[64:67]
	v_mfma_f32_16x16x32_bf16 v[60:63], v[154:157], v[162:165], v[60:63]
	v_mfma_f32_16x16x32_bf16 v[48:51], v[144:147], v[170:173], v[48:51]
	v_mfma_f32_16x16x32_bf16 v[44:47], v[154:157], v[170:173], v[44:47]
	v_mfma_f32_16x16x32_bf16 v[32:35], v[144:147], v[178:181], v[32:35]
	v_mfma_f32_16x16x32_bf16 v[28:31], v[154:157], v[178:181], v[28:31]
	v_mfma_f32_16x16x32_bf16 v[16:19], v[144:147], v[186:189], v[16:19]
	v_mfma_f32_16x16x32_bf16 v[12:15], v[154:157], v[186:189], v[12:15]
	v_mfma_f32_16x16x32_bf16 v[64:67], v[150:153], v[166:169], v[64:67]
	v_mfma_f32_16x16x32_bf16 v[60:63], v[158:161], v[166:169], v[60:63]
	v_mfma_f32_16x16x32_bf16 v[48:51], v[150:153], v[174:177], v[48:51]
	v_mfma_f32_16x16x32_bf16 v[44:47], v[158:161], v[174:177], v[44:47]
	v_mfma_f32_16x16x32_bf16 v[32:35], v[150:153], v[182:185], v[32:35]
	v_mfma_f32_16x16x32_bf16 v[28:31], v[158:161], v[182:185], v[28:31]
	v_mfma_f32_16x16x32_bf16 v[16:19], v[150:153], v[190:193], v[16:19]
	v_mfma_f32_16x16x32_bf16 v[12:15], v[158:161], v[190:193], v[12:15]
	v_mfma_f32_16x16x32_bf16 v[56:59], v[194:197], v[162:165], v[56:59]
	v_mfma_f32_16x16x32_bf16 v[52:55], v[202:205], v[162:165], v[52:55]
	v_mfma_f32_16x16x32_bf16 v[40:43], v[194:197], v[170:173], v[40:43]
	v_mfma_f32_16x16x32_bf16 v[36:39], v[202:205], v[170:173], v[36:39]
	v_mfma_f32_16x16x32_bf16 v[24:27], v[194:197], v[178:181], v[24:27]
	v_mfma_f32_16x16x32_bf16 v[20:23], v[202:205], v[178:181], v[20:23]
	v_mfma_f32_16x16x32_bf16 v[8:11], v[194:197], v[186:189], v[8:11]
	v_mfma_f32_16x16x32_bf16 v[4:7], v[202:205], v[186:189], v[4:7]
	v_mfma_f32_16x16x32_bf16 v[56:59], v[198:201], v[166:169], v[56:59]
	v_mfma_f32_16x16x32_bf16 v[52:55], v[206:209], v[166:169], v[52:55]
	v_mfma_f32_16x16x32_bf16 v[40:43], v[198:201], v[174:177], v[40:43]
	v_mfma_f32_16x16x32_bf16 v[36:39], v[206:209], v[174:177], v[36:39]
	v_mfma_f32_16x16x32_bf16 v[24:27], v[198:201], v[182:185], v[24:27]
	v_mfma_f32_16x16x32_bf16 v[20:23], v[206:209], v[182:185], v[20:23]
	v_mfma_f32_16x16x32_bf16 v[8:11], v[198:201], v[190:193], v[8:11]
	v_mfma_f32_16x16x32_bf16 v[4:7], v[206:209], v[190:193], v[4:7]
	s_barrier
	s_cbranch_scc0 .LBB0_352
	s_setprio 0
	s_cmpk_gt_u32 s2, 0xff
	s_cbranch_scc1 .Lalign_a_352
	s_barrier

; #define PG8_STAGE(bufoff, gbase, voff) do { _Pragma("unroll") for (int _i = 0; _i < 2; ++_i) \
;         __builtin_amdgcn_global_load_lds((const unsigned*)((const char*)(gbase) + (voff)[_i]), (LAS unsigned*)(lds + (bufoff) + ldsw + _i * 8192), 16, 0, 0); } while (0)
; #define PG8_LDA(dst, b, h) do { _Pragma("unroll") for (int m = 0; m < 4; ++m) _Pragma("unroll") for (int k = 0; k < 2; ++k) dst[m][k] = *(const LAS bf16x8*)(lds + PG8_SA(b, h) + aoff + m * 2048 + k * 1024); } while (0)
; #define PG8_LDB(dst, b, h) do { _Pragma("unroll") for (int n = 0; n < 2; ++n) _Pragma("unroll") for (int k = 0; k < 2; ++k) dst[n][k] = *(const LAS bf16x8*)(lds + PG8_SB(b, h) + boff + n * 2048 + k * 1024); } while (0)
; #define PG8_WAIT_V(n) asm volatile("s_waitcnt vmcnt(" #n ")" ::: "memory")
; #define PG8_WAIT_L(n) asm volatile("s_waitcnt lgkmcnt(" #n ")" ::: "memory")
; #define PG8_BAR __builtin_amdgcn_s_barrier()
; #define PG8_SCHED __builtin_amdgcn_sched_barrier(0)
; template <class Epi, class Sched>
; __device__ __forceinline__ void gemm_phase(LAS unsigned char* lds, const Gemm g, const Sched& S, const Epi& E) {
;     ...
;         const bool has_next = S.next(ui + 1, nxt);
;         const char* nA = has_next ? (const char*)g.A + (size_t)nxt.pm * tstepA : cA; const char* nB = has_next ? (const char*)g.Bt + (size_t)nxt.pn * tstepB : cB;
;         for (int t = 0; t < nt; t += 2) {
;             const bool last = (t == nt - 2);
;             const char* a1 = cA + (size_t)(t + 1) * kstep;
;             const char* a2 = last ? nA : cA + (size_t)(t + 2) * kstep; const char* b2 = last ? nB : cB + (size_t)(t + 2) * kstep;
;             const char* a3 = a2 + kstep; const char* b3 = b2 + kstep;
;             if (last && has_next) S.a_ready(nxt);
;             PG8_LDB(B0, 0, 0); PG8_SCHED; PG8_LDA(At, 0, 0); PG8_STAGE(PG8_SA(1, 1), a1 + hstepA, voffA);
;             PG8_WAIT_L(8); PG8_BAR; PG8_WAIT_L(0); PG8_MMA(0, 0, At, B0); PG8_BAR; PG8_SCHED;
;             PG8_LDB(B1, 0, 1); PG8_STAGE(PG8_SB(0, 0), b2, voffB);
;             PG8_BAR; PG8_WAIT_L(0); PG8_MMA(0, 1, At, B1); PG8_BAR;
;             PG8_LDA(At, 0, 1); PG8_STAGE(PG8_SA(0, 0), a2, voffA);
;             PG8_BAR; PG8_WAIT_L(0); PG8_MMA(1, 0, At, B0); PG8_BAR; PG8_SCHED;
;             PG8_STAGE(PG8_SB(0, 1), b2 + hstepB, voffB);
;             PG8_WAIT_V(6); PG8_BAR; PG8_MMA(1, 1, At, B1); PG8_BAR;
.LBB0_490:
	s_ashr_i32 s53, s52, 31
	s_lshl_b64 s[18:19], s[52:53], 20
	s_add_u32 s54, s25, s18
	v_cmp_lt_i64_e64 s[14:15], s[14:15], 16
	s_addc_u32 s55, s28, s19
	s_and_b64 s[18:19], s[14:15], exec
	s_cselect_b32 s18, s55, s5
	s_cselect_b32 s19, s54, s4
	s_ashr_i32 s51, s50, 31
	s_lshl_b64 s[56:57], s[50:51], 21
	s_add_u32 s56, s44, s56
	s_addc_u32 s57, s45, s57
	s_and_b64 s[14:15], s[14:15], exec
	s_cselect_b32 s51, s57, s7
	s_cselect_b32 s53, s56, s6
	s_add_u32 s4, s4, 0x80080
	s_addc_u32 s5, s5, 0
	s_add_u32 s65, s6, 0x100
	s_addc_u32 s66, s7, 0
	s_mov_b32 s67, -2
	s_waitcnt lgkmcnt(0)
	s_setprio 0
	s_add_u32 s6, s4, 0xfff80080
	s_addc_u32 s7, s5, -1
	s_add_i32 s68, 0, 0x10000
	v_add_u32_e32 v154, s68, v1
	ds_read_b128 v[142:145], v154
	ds_read_b128 v[146:149], v154 offset:1024
	ds_read_b128 v[150:153], v154 offset:2048
	ds_read_b128 v[158:161], v154 offset:3072
	s_cmp_eq_u32 s67, 60
	s_cselect_b32 s15, s18, s7
	s_cselect_b32 s14, s19, s6
	s_cselect_b32 s7, s51, s66
	s_cselect_b32 s6, s53, s65
	ds_read_b128 v[162:165], v156
	ds_read_b128 v[166:169], v156 offset:1024
	ds_read_b128 v[170:173], v156 offset:2048
	ds_read_b128 v[174:177], v156 offset:3072
	ds_read_b128 v[178:181], v156 offset:4096
	ds_read_b128 v[182:185], v156 offset:5120
	ds_read_b128 v[186:189], v156 offset:6144
	ds_read_b128 v[190:193], v156 offset:7168
	s_add_i32 s70, 0, 0x14000
	v_add_u32_e32 v154, s70, v1
	ds_read_b128 v[194:197], v154
	ds_read_b128 v[198:201], v154 offset:1024
	ds_read_b128 v[202:205], v154 offset:2048
	ds_read_b128 v[206:209], v154 offset:3072
	s_add_i32 m0, s30, 0xc000
	s_nop 0
	global_load_lds_dwordx4 v138, s[4:5]
	s_add_i32 m0, s30, 0xe000
	s_nop 0
	global_load_lds_dwordx4 v140, s[4:5]
	s_waitcnt lgkmcnt(0)
	s_barrier
	v_mfma_f32_16x16x32_bf16 v[128:131], v[142:145], v[162:165], 0
	v_mfma_f32_16x16x32_bf16 v[124:127], v[150:153], v[162:165], 0
	v_mfma_f32_16x16x32_bf16 v[120:123], v[142:145], v[170:173], 0
	v_mfma_f32_16x16x32_bf16 v[116:119], v[150:153], v[170:173], 0
	v_mfma_f32_16x16x32_bf16 v[112:115], v[142:145], v[178:181], 0
	v_mfma_f32_16x16x32_bf16 v[108:111], v[150:153], v[178:181], 0
	v_mfma_f32_16x16x32_bf16 v[104:107], v[142:145], v[186:189], 0
	v_mfma_f32_16x16x32_bf16 v[100:103], v[150:153], v[186:189], 0
	v_mfma_f32_16x16x32_bf16 v[128:131], v[146:149], v[166:169], v[128:131]
	v_mfma_f32_16x16x32_bf16 v[124:127], v[158:161], v[166:169], v[124:127]
	v_mfma_f32_16x16x32_bf16 v[120:123], v[146:149], v[174:177], v[120:123]
	v_mfma_f32_16x16x32_bf16 v[116:119], v[158:161], v[174:177], v[116:119]
	v_mfma_f32_16x16x32_bf16 v[112:115], v[146:149], v[182:185], v[112:115]
	v_mfma_f32_16x16x32_bf16 v[108:111], v[158:161], v[182:185], v[108:111]
	v_mfma_f32_16x16x32_bf16 v[104:107], v[146:149], v[190:193], v[104:107]
	v_mfma_f32_16x16x32_bf16 v[100:103], v[158:161], v[190:193], v[100:103]
	v_mfma_f32_16x16x32_bf16 v[64:67], v[194:197], v[162:165], 0
	v_mfma_f32_16x16x32_bf16 v[60:63], v[202:205], v[162:165], 0
	v_mfma_f32_16x16x32_bf16 v[56:59], v[194:197], v[170:173], 0
	v_mfma_f32_16x16x32_bf16 v[52:55], v[202:205], v[170:173], 0
	v_mfma_f32_16x16x32_bf16 v[48:51], v[194:197], v[178:181], 0
	v_mfma_f32_16x16x32_bf16 v[44:47], v[202:205], v[178:181], 0
	v_mfma_f32_16x16x32_bf16 v[40:43], v[194:197], v[186:189], 0
	v_mfma_f32_16x16x32_bf16 v[36:39], v[202:205], v[186:189], 0
	v_mfma_f32_16x16x32_bf16 v[64:67], v[198:201], v[166:169], v[64:67]
	v_mfma_f32_16x16x32_bf16 v[60:63], v[206:209], v[166:169], v[60:63]
	v_mfma_f32_16x16x32_bf16 v[56:59], v[198:201], v[174:177], v[56:59]
	v_mfma_f32_16x16x32_bf16 v[52:55], v[206:209], v[174:177], v[52:55]
	v_mfma_f32_16x16x32_bf16 v[48:51], v[198:201], v[182:185], v[48:51]
	v_mfma_f32_16x16x32_bf16 v[44:47], v[206:209], v[182:185], v[44:47]
	v_mfma_f32_16x16x32_bf16 v[40:43], v[198:201], v[190:193], v[40:43]
	v_mfma_f32_16x16x32_bf16 v[36:39], v[206:209], v[190:193], v[36:39]
	s_barrier
	ds_read_b128 v[162:165], v156 offset:16384
	ds_read_b128 v[166:169], v156 offset:17408
	ds_read_b128 v[170:173], v156 offset:18432
	ds_read_b128 v[174:177], v156 offset:19456
	ds_read_b128 v[178:181], v156 offset:20480
	ds_read_b128 v[182:185], v156 offset:21504
	ds_read_b128 v[186:189], v156 offset:22528
	ds_read_b128 v[190:193], v156 offset:23552
	s_add_i32 s68, s68, s29
	v_lshl_add_u64 v[154:155], s[6:7], 0, v[2:3]
	s_mov_b32 m0, s68
	v_lshl_add_u64 v[210:211], s[6:7], 0, v[136:137]
	global_load_lds_dwordx4 v[154:155], off
	s_add_i32 m0, s68, 0x2000
	s_nop 0
	global_load_lds_dwordx4 v[210:211], off
	s_mov_b32 m0, s30
	v_lshl_add_u64 v[212:213], s[14:15], 0, v[132:133]
	global_load_lds_dwordx4 v[212:213], off
	v_lshl_add_u64 v[216:217], s[14:15], 0, v[134:135]
	s_mov_b32 m0, s31
	s_nop 0
	global_load_lds_dwordx4 v[216:217], off
	s_add_u32 s68, s6, 0x100000
	s_addc_u32 s69, s7, 0
	s_add_i32 s70, s70, s29
	s_mov_b32 m0, s70
	s_nop 0
	global_load_lds_dwordx4 v2, s[68:69]
	s_add_i32 m0, s70, 0x2000
	s_nop 0
	global_load_lds_dwordx4 v136, s[68:69]
	s_waitcnt lgkmcnt(0)
	s_waitcnt vmcnt(6)
	s_barrier
; #define PG8_STAGE(bufoff, gbase, voff) do { _Pragma("unroll") for (int _i = 0; _i < 2; ++_i) \
;         __builtin_amdgcn_global_load_lds((const unsigned*)((const char*)(gbase) + (voff)[_i]), (LAS unsigned*)(lds + (bufoff) + ldsw + _i * 8192), 16, 0, 0); } while (0)
; #define PG8_LDA(dst, b, h) do { _Pragma("unroll") for (int m = 0; m < 4; ++m) _Pragma("unroll") for (int k = 0; k < 2; ++k) dst[m][k] = *(const LAS bf16x8*)(lds + PG8_SA(b, h) + aoff + m * 2048 + k * 1024); } while (0)
; #define PG8_LDB(dst, b, h) do { _Pragma("unroll") for (int n = 0; n < 2; ++n) _Pragma("unroll") for (int k = 0; k < 2; ++k) dst[n][k] = *(const LAS bf16x8*)(lds + PG8_SB(b, h) + boff + n * 2048 + k * 1024); } while (0)
; #define PG8_MMA(ai, bj, At, Bt) do { __builtin_amdgcn_s_setprio(1); _Pragma("unroll") for (int m = 0; m < 4; ++m) _Pragma("unroll") for (int n = 0; n < 2; ++n) _Pragma("unroll") for (int k = 0; k < 2; ++k) \
;         acc[ai][bj][m][n] = __builtin_amdgcn_mfma_f32_16x16x32_bf16(Bt[n][k], At[m][k], acc[ai][bj][m][n], 0, 0, 0); __builtin_amdgcn_s_setprio(0); } while (0)
; #define PG8_WAIT_V(n) asm volatile("s_waitcnt vmcnt(" #n ")" ::: "memory")
; #define PG8_WAIT_L(n) asm volatile("s_waitcnt lgkmcnt(" #n ")" ::: "memory")
; #define PG8_BAR __builtin_amdgcn_s_barrier()
; #define PG8_SCHED __builtin_amdgcn_sched_barrier(0)
; template <class Epi, class Sched>
; __device__ __forceinline__ void gemm_phase(LAS unsigned char* lds, const Gemm g, const Sched& S, const Epi& E) {
;     ...
;             PG8_WAIT_V(6); PG8_BAR; PG8_MMA(1, 1, At, B1); PG8_BAR;
;             PG8_LDB(B0, 1, 0); PG8_SCHED; PG8_LDA(At, 1, 0); PG8_STAGE(PG8_SA(0, 1), a2 + hstepA, voffA);
;             PG8_WAIT_L(8); PG8_BAR; PG8_WAIT_L(0); PG8_MMA(0, 0, At, B0); PG8_BAR; PG8_SCHED;
;             PG8_LDB(B1, 1, 1); PG8_STAGE(PG8_SB(1, 0), b3, voffB);
;             PG8_BAR; PG8_WAIT_L(0); PG8_MMA(0, 1, At, B1); PG8_BAR;
;             PG8_LDA(At, 1, 1); PG8_STAGE(PG8_SA(1, 0), a3, voffA);
;             PG8_BAR; PG8_WAIT_L(0); PG8_MMA(1, 0, At, B0); PG8_BAR; PG8_SCHED;
	v_mfma_f32_16x16x32_bf16 v[96:99], v[142:145], v[162:165], 0
	v_mfma_f32_16x16x32_bf16 v[92:95], v[150:153], v[162:165], 0
	v_mfma_f32_16x16x32_bf16 v[88:91], v[142:145], v[170:173], 0
	v_mfma_f32_16x16x32_bf16 v[84:87], v[150:153], v[170:173], 0
	v_mfma_f32_16x16x32_bf16 v[80:83], v[142:145], v[178:181], 0
	v_mfma_f32_16x16x32_bf16 v[76:79], v[150:153], v[178:181], 0
	v_mfma_f32_16x16x32_bf16 v[72:75], v[142:145], v[186:189], 0
	v_mfma_f32_16x16x32_bf16 v[68:71], v[150:153], v[186:189], 0
	v_mfma_f32_16x16x32_bf16 v[96:99], v[146:149], v[166:169], v[96:99]
	v_mfma_f32_16x16x32_bf16 v[92:95], v[158:161], v[166:169], v[92:95]
	v_mfma_f32_16x16x32_bf16 v[88:91], v[146:149], v[174:177], v[88:91]
	v_mfma_f32_16x16x32_bf16 v[84:87], v[158:161], v[174:177], v[84:87]
	v_mfma_f32_16x16x32_bf16 v[80:83], v[146:149], v[182:185], v[80:83]
	v_mfma_f32_16x16x32_bf16 v[76:79], v[158:161], v[182:185], v[76:79]
	v_mfma_f32_16x16x32_bf16 v[72:75], v[146:149], v[190:193], v[72:75]
	v_mfma_f32_16x16x32_bf16 v[68:71], v[158:161], v[190:193], v[68:71]
	v_mfma_f32_16x16x32_bf16 v[32:35], v[194:197], v[162:165], 0
	v_mfma_f32_16x16x32_bf16 v[28:31], v[202:205], v[162:165], 0
	v_mfma_f32_16x16x32_bf16 v[24:27], v[194:197], v[170:173], 0
	v_mfma_f32_16x16x32_bf16 v[20:23], v[202:205], v[170:173], 0
	v_mfma_f32_16x16x32_bf16 v[16:19], v[194:197], v[178:181], 0
	v_mfma_f32_16x16x32_bf16 v[12:15], v[202:205], v[178:181], 0
	v_mfma_f32_16x16x32_bf16 v[8:11], v[194:197], v[186:189], 0
	v_mfma_f32_16x16x32_bf16 v[4:7], v[202:205], v[186:189], 0
	v_mfma_f32_16x16x32_bf16 v[32:35], v[198:201], v[166:169], v[32:35]
	v_mfma_f32_16x16x32_bf16 v[28:31], v[206:209], v[166:169], v[28:31]
	v_mfma_f32_16x16x32_bf16 v[24:27], v[198:201], v[174:177], v[24:27]
	v_mfma_f32_16x16x32_bf16 v[20:23], v[206:209], v[174:177], v[20:23]
	v_mfma_f32_16x16x32_bf16 v[16:19], v[198:201], v[182:185], v[16:19]
	v_mfma_f32_16x16x32_bf16 v[12:15], v[206:209], v[182:185], v[12:15]
	v_mfma_f32_16x16x32_bf16 v[8:11], v[198:201], v[190:193], v[8:11]
	v_mfma_f32_16x16x32_bf16 v[4:7], v[206:209], v[190:193], v[4:7]
	s_barrier
	s_add_i32 s68, 0, 0x18000
	v_add_u32_e32 v157, s68, v1
	ds_read_b128 v[142:145], v157
	ds_read_b128 v[146:149], v157 offset:1024
	ds_read_b128 v[150:153], v157 offset:2048
	ds_read_b128 v[158:161], v157 offset:3072
	s_add_u32 s14, s14, 0x80000
	s_addc_u32 s15, s15, 0
	ds_read_b128 v[162:165], v156 offset:32768
	ds_read_b128 v[166:169], v156 offset:33792
	ds_read_b128 v[170:173], v156 offset:34816
	ds_read_b128 v[174:177], v156 offset:35840
	ds_read_b128 v[178:181], v156 offset:36864
	ds_read_b128 v[182:185], v156 offset:37888
	ds_read_b128 v[186:189], v156 offset:38912
	ds_read_b128 v[190:193], v156 offset:39936
	s_mov_b32 m0, s38
	s_nop 0
	global_load_lds_dwordx4 v132, s[14:15]
	s_mov_b32 m0, s39
	s_nop 0
	global_load_lds_dwordx4 v134, s[14:15]
	s_add_i32 s14, 0, 0x1c000
	v_add_u32_e32 v157, s14, v1
	ds_read_b128 v[194:197], v157
	ds_read_b128 v[198:201], v157 offset:1024
	ds_read_b128 v[202:205], v157 offset:2048
	ds_read_b128 v[206:209], v157 offset:3072
	s_waitcnt lgkmcnt(0)
	s_barrier
	v_mfma_f32_16x16x32_bf16 v[128:131], v[142:145], v[162:165], v[128:131]
	v_mfma_f32_16x16x32_bf16 v[124:127], v[150:153], v[162:165], v[124:127]
	v_mfma_f32_16x16x32_bf16 v[120:123], v[142:145], v[170:173], v[120:123]
	v_mfma_f32_16x16x32_bf16 v[116:119], v[150:153], v[170:173], v[116:119]
	v_mfma_f32_16x16x32_bf16 v[112:115], v[142:145], v[178:181], v[112:115]
	v_mfma_f32_16x16x32_bf16 v[108:111], v[150:153], v[178:181], v[108:111]
	v_mfma_f32_16x16x32_bf16 v[104:107], v[142:145], v[186:189], v[104:107]
	v_mfma_f32_16x16x32_bf16 v[100:103], v[150:153], v[186:189], v[100:103]
	v_mfma_f32_16x16x32_bf16 v[128:131], v[146:149], v[166:169], v[128:131]
	v_mfma_f32_16x16x32_bf16 v[124:127], v[158:161], v[166:169], v[124:127]
	v_mfma_f32_16x16x32_bf16 v[120:123], v[146:149], v[174:177], v[120:123]
	v_mfma_f32_16x16x32_bf16 v[116:119], v[158:161], v[174:177], v[116:119]
	v_mfma_f32_16x16x32_bf16 v[112:115], v[146:149], v[182:185], v[112:115]
	v_mfma_f32_16x16x32_bf16 v[108:111], v[158:161], v[182:185], v[108:111]
	v_mfma_f32_16x16x32_bf16 v[104:107], v[146:149], v[190:193], v[104:107]
	v_mfma_f32_16x16x32_bf16 v[100:103], v[158:161], v[190:193], v[100:103]
	v_mfma_f32_16x16x32_bf16 v[64:67], v[194:197], v[162:165], v[64:67]
	v_mfma_f32_16x16x32_bf16 v[60:63], v[202:205], v[162:165], v[60:63]
	v_mfma_f32_16x16x32_bf16 v[56:59], v[194:197], v[170:173], v[56:59]
	v_mfma_f32_16x16x32_bf16 v[52:55], v[202:205], v[170:173], v[52:55]
	v_mfma_f32_16x16x32_bf16 v[48:51], v[194:197], v[178:181], v[48:51]
	v_mfma_f32_16x16x32_bf16 v[44:47], v[202:205], v[178:181], v[44:47]
	v_mfma_f32_16x16x32_bf16 v[40:43], v[194:197], v[186:189], v[40:43]
	v_mfma_f32_16x16x32_bf16 v[36:39], v[202:205], v[186:189], v[36:39]
	v_mfma_f32_16x16x32_bf16 v[64:67], v[198:201], v[166:169], v[64:67]
	v_mfma_f32_16x16x32_bf16 v[60:63], v[206:209], v[166:169], v[60:63]
	v_mfma_f32_16x16x32_bf16 v[56:59], v[198:201], v[174:177], v[56:59]
	v_mfma_f32_16x16x32_bf16 v[52:55], v[206:209], v[174:177], v[52:55]
	v_mfma_f32_16x16x32_bf16 v[48:51], v[198:201], v[182:185], v[48:51]
	v_mfma_f32_16x16x32_bf16 v[44:47], v[206:209], v[182:185], v[44:47]
	v_mfma_f32_16x16x32_bf16 v[40:43], v[198:201], v[190:193], v[40:43]
	v_mfma_f32_16x16x32_bf16 v[36:39], v[206:209], v[190:193], v[36:39]
	s_barrier
; #define PG8_STAGE(bufoff, gbase, voff) do { _Pragma("unroll") for (int _i = 0; _i < 2; ++_i) \
;         __builtin_amdgcn_global_load_lds((const unsigned*)((const char*)(gbase) + (voff)[_i]), (LAS unsigned*)(lds + (bufoff) + ldsw + _i * 8192), 16, 0, 0); } while (0)
; #define PG8_LDA(dst, b, h) do { _Pragma("unroll") for (int m = 0; m < 4; ++m) _Pragma("unroll") for (int k = 0; k < 2; ++k) dst[m][k] = *(const LAS bf16x8*)(lds + PG8_SA(b, h) + aoff + m * 2048 + k * 1024); } while (0)
; #define PG8_LDB(dst, b, h) do { _Pragma("unroll") for (int n = 0; n < 2; ++n) _Pragma("unroll") for (int k = 0; k < 2; ++k) dst[n][k] = *(const LAS bf16x8*)(lds + PG8_SB(b, h) + boff + n * 2048 + k * 1024); } while (0)
; #define PG8_WAIT_V(n) asm volatile("s_waitcnt vmcnt(" #n ")" ::: "memory")
; #define PG8_WAIT_L(n) asm volatile("s_waitcnt lgkmcnt(" #n ")" ::: "memory")
; #define PG8_BAR __builtin_amdgcn_s_barrier()
; #define PG8_SCHED __builtin_amdgcn_sched_barrier(0)
; template <class Epi, class Sched>
; __device__ __forceinline__ void gemm_phase(LAS unsigned char* lds, const Gemm g, const Sched& S, const Epi& E) {
;     ...
;             PG8_LDB(B0, 0, 0); PG8_SCHED; PG8_LDA(At, 0, 0); PG8_STAGE(PG8_SA(1, 1), a1 + hstepA, voffA);
;             PG8_WAIT_L(8); PG8_BAR; PG8_WAIT_L(0); PG8_MMA(0, 0, At, B0); PG8_BAR; PG8_SCHED;
;             PG8_LDB(B1, 0, 1); PG8_STAGE(PG8_SB(0, 0), b2, voffB);
;             PG8_BAR; PG8_WAIT_L(0); PG8_MMA(0, 1, At, B1); PG8_BAR;
;             PG8_LDA(At, 0, 1); PG8_STAGE(PG8_SA(0, 0), a2, voffA);
;             PG8_BAR; PG8_WAIT_L(0); PG8_MMA(1, 0, At, B0); PG8_BAR; PG8_SCHED;
;             PG8_STAGE(PG8_SB(0, 1), b2 + hstepB, voffB);
;             PG8_WAIT_V(6); PG8_BAR; PG8_MMA(1, 1, At, B1); PG8_BAR;
;             PG8_LDB(B0, 1, 0); PG8_SCHED; PG8_LDA(At, 1, 0); PG8_STAGE(PG8_SA(0, 1), a2 + hstepA, voffA);
;             PG8_WAIT_L(8); PG8_BAR; PG8_WAIT_L(0); PG8_MMA(0, 0, At, B0); PG8_BAR; PG8_SCHED;
;             PG8_LDB(B1, 1, 1); PG8_STAGE(PG8_SB(1, 0), b3, voffB);
;             PG8_BAR; PG8_WAIT_L(0); PG8_MMA(0, 1, At, B1); PG8_BAR;
;             PG8_LDA(At, 1, 1); PG8_STAGE(PG8_SA(1, 0), a3, voffA);
;             PG8_BAR; PG8_WAIT_L(0); PG8_MMA(1, 0, At, B0); PG8_BAR; PG8_SCHED;
;             PG8_STAGE(PG8_SB(1, 1), b3 + hstepB, voffB);
;             PG8_WAIT_V(6); PG8_BAR; PG8_MMA(1, 1, At, B1); PG8_BAR;
	ds_read_b128 v[162:165], v156 offset:49152
	ds_read_b128 v[166:169], v156 offset:50176
	ds_read_b128 v[170:173], v156 offset:51200
	ds_read_b128 v[174:177], v156 offset:52224
	ds_read_b128 v[178:181], v156 offset:53248
	ds_read_b128 v[182:185], v156 offset:54272
	ds_read_b128 v[186:189], v156 offset:55296
	ds_read_b128 v[190:193], v156 offset:56320
	s_add_i32 s15, s68, s29
	v_lshl_add_u64 v[154:155], v[154:155], 0, s[8:9]
	s_mov_b32 m0, s15
	s_nop 0
	global_load_lds_dwordx4 v[154:155], off
	v_lshl_add_u64 v[154:155], v[210:211], 0, s[8:9]
	s_add_i32 m0, s15, 0x2000
	s_nop 0
	global_load_lds_dwordx4 v[154:155], off
	s_mov_b32 m0, s62
	v_lshl_add_u64 v[154:155], v[212:213], 0, s[8:9]
	global_load_lds_dwordx4 v[154:155], off
	v_lshl_add_u64 v[154:155], v[216:217], 0, s[8:9]
	s_mov_b32 m0, s63
	s_nop 0
	global_load_lds_dwordx4 v[154:155], off
	s_add_u32 s6, s6, 0x100080
	s_addc_u32 s7, s7, 0
	s_add_i32 s14, s14, s29
	s_mov_b32 m0, s14
	s_nop 0
	global_load_lds_dwordx4 v2, s[6:7]
	s_add_i32 m0, s14, 0x2000
	s_nop 0
	global_load_lds_dwordx4 v136, s[6:7]
	s_add_i32 s67, s67, 2
	s_add_u32 s4, s4, 0x100
	s_addc_u32 s5, s5, 0
	s_add_u32 s65, s65, 0x100
	s_addc_u32 s66, s66, 0
	s_cmp_gt_u32 s67, 61
	s_waitcnt lgkmcnt(0)
	s_waitcnt vmcnt(6)
	s_barrier
	v_mfma_f32_16x16x32_bf16 v[96:99], v[142:145], v[162:165], v[96:99]
	v_mfma_f32_16x16x32_bf16 v[92:95], v[150:153], v[162:165], v[92:95]
	v_mfma_f32_16x16x32_bf16 v[88:91], v[142:145], v[170:173], v[88:91]
	v_mfma_f32_16x16x32_bf16 v[84:87], v[150:153], v[170:173], v[84:87]
	v_mfma_f32_16x16x32_bf16 v[80:83], v[142:145], v[178:181], v[80:83]
	v_mfma_f32_16x16x32_bf16 v[76:79], v[150:153], v[178:181], v[76:79]
	v_mfma_f32_16x16x32_bf16 v[72:75], v[142:145], v[186:189], v[72:75]
	v_mfma_f32_16x16x32_bf16 v[68:71], v[150:153], v[186:189], v[68:71]
	v_mfma_f32_16x16x32_bf16 v[96:99], v[146:149], v[166:169], v[96:99]
	v_mfma_f32_16x16x32_bf16 v[92:95], v[158:161], v[166:169], v[92:95]
	v_mfma_f32_16x16x32_bf16 v[88:91], v[146:149], v[174:177], v[88:91]
	v_mfma_f32_16x16x32_bf16 v[84:87], v[158:161], v[174:177], v[84:87]
	v_mfma_f32_16x16x32_bf16 v[80:83], v[146:149], v[182:185], v[80:83]
	v_mfma_f32_16x16x32_bf16 v[76:79], v[158:161], v[182:185], v[76:79]
	v_mfma_f32_16x16x32_bf16 v[72:75], v[146:149], v[190:193], v[72:75]
	v_mfma_f32_16x16x32_bf16 v[68:71], v[158:161], v[190:193], v[68:71]
	v_mfma_f32_16x16x32_bf16 v[32:35], v[194:197], v[162:165], v[32:35]
	v_mfma_f32_16x16x32_bf16 v[28:31], v[202:205], v[162:165], v[28:31]
	v_mfma_f32_16x16x32_bf16 v[24:27], v[194:197], v[170:173], v[24:27]
	v_mfma_f32_16x16x32_bf16 v[20:23], v[202:205], v[170:173], v[20:23]
	v_mfma_f32_16x16x32_bf16 v[16:19], v[194:197], v[178:181], v[16:19]
	v_mfma_f32_16x16x32_bf16 v[12:15], v[202:205], v[178:181], v[12:15]
	v_mfma_f32_16x16x32_bf16 v[8:11], v[194:197], v[186:189], v[8:11]
	v_mfma_f32_16x16x32_bf16 v[4:7], v[202:205], v[186:189], v[4:7]
	v_mfma_f32_16x16x32_bf16 v[32:35], v[198:201], v[166:169], v[32:35]
	v_mfma_f32_16x16x32_bf16 v[28:31], v[206:209], v[166:169], v[28:31]
	v_mfma_f32_16x16x32_bf16 v[24:27], v[198:201], v[174:177], v[24:27]
	v_mfma_f32_16x16x32_bf16 v[20:23], v[206:209], v[174:177], v[20:23]
	v_mfma_f32_16x16x32_bf16 v[16:19], v[198:201], v[182:185], v[16:19]
	v_mfma_f32_16x16x32_bf16 v[12:15], v[206:209], v[182:185], v[12:15]
	v_mfma_f32_16x16x32_bf16 v[8:11], v[198:201], v[190:193], v[8:11]
	v_mfma_f32_16x16x32_bf16 v[4:7], v[206:209], v[190:193], v[4:7]
	s_barrier
	s_setprio 0
.LBB0_491:
	s_setprio 0
	s_add_u32 s6, s4, 0xfff80080
	s_addc_u32 s7, s5, -1
	s_add_i32 s68, 0, 0x10000
	v_add_u32_e32 v154, s68, v1
	ds_read_b128 v[142:145], v154
	ds_read_b128 v[146:149], v154 offset:1024
	ds_read_b128 v[150:153], v154 offset:2048
	ds_read_b128 v[158:161], v154 offset:3072
	s_cmp_eq_u32 s67, 60
	s_cselect_b32 s15, s18, s7
	s_cselect_b32 s14, s19, s6
	s_cselect_b32 s7, s51, s66
	s_cselect_b32 s6, s53, s65
	ds_read_b128 v[162:165], v156
	ds_read_b128 v[166:169], v156 offset:1024
	ds_read_b128 v[170:173], v156 offset:2048
	ds_read_b128 v[174:177], v156 offset:3072
	ds_read_b128 v[178:181], v156 offset:4096
	ds_read_b128 v[182:185], v156 offset:5120
	ds_read_b128 v[186:189], v156 offset:6144
	ds_read_b128 v[190:193], v156 offset:7168
	s_add_i32 s70, 0, 0x14000
	v_add_u32_e32 v154, s70, v1
	ds_read_b128 v[194:197], v154
	ds_read_b128 v[198:201], v154 offset:1024
	ds_read_b128 v[202:205], v154 offset:2048
	ds_read_b128 v[206:209], v154 offset:3072
	s_add_i32 m0, s30, 0xc000
	s_nop 0
	global_load_lds_dwordx4 v138, s[4:5]
	s_add_i32 m0, s30, 0xe000
	s_nop 0
	global_load_lds_dwordx4 v140, s[4:5]
	s_waitcnt lgkmcnt(0)
	s_barrier
; #define PG8_STAGE(bufoff, gbase, voff) do { _Pragma("unroll") for (int _i = 0; _i < 2; ++_i) \
;         __builtin_amdgcn_global_load_lds((const unsigned*)((const char*)(gbase) + (voff)[_i]), (LAS unsigned*)(lds + (bufoff) + ldsw + _i * 8192), 16, 0, 0); } while (0)
; #define PG8_LDA(dst, b, h) do { _Pragma("unroll") for (int m = 0; m < 4; ++m) _Pragma("unroll") for (int k = 0; k < 2; ++k) dst[m][k] = *(const LAS bf16x8*)(lds + PG8_SA(b, h) + aoff + m * 2048 + k * 1024); } while (0)
; #define PG8_LDB(dst, b, h) do { _Pragma("unroll") for (int n = 0; n < 2; ++n) _Pragma("unroll") for (int k = 0; k < 2; ++k) dst[n][k] = *(const LAS bf16x8*)(lds + PG8_SB(b, h) + boff + n * 2048 + k * 1024); } while (0)
; #define PG8_MMA(ai, bj, At, Bt) do { __builtin_amdgcn_s_setprio(1); _Pragma("unroll") for (int m = 0; m < 4; ++m) _Pragma("unroll") for (int n = 0; n < 2; ++n) _Pragma("unroll") for (int k = 0; k < 2; ++k) \
;         acc[ai][bj][m][n] = __builtin_amdgcn_mfma_f32_16x16x32_bf16(Bt[n][k], At[m][k], acc[ai][bj][m][n], 0, 0, 0); __builtin_amdgcn_s_setprio(0); } while (0)
; #define PG8_WAIT_V(n) asm volatile("s_waitcnt vmcnt(" #n ")" ::: "memory")
; #define PG8_WAIT_L(n) asm volatile("s_waitcnt lgkmcnt(" #n ")" ::: "memory")
; #define PG8_BAR __builtin_amdgcn_s_barrier()
; #define PG8_SCHED __builtin_amdgcn_sched_barrier(0)
; template <class Epi, class Sched>
; __device__ __forceinline__ void gemm_phase(LAS unsigned char* lds, const Gemm g, const Sched& S, const Epi& E) {
;     ...
;             PG8_LDB(B0, 0, 0); PG8_SCHED; PG8_LDA(At, 0, 0); PG8_STAGE(PG8_SA(1, 1), a1 + hstepA, voffA);
;             PG8_WAIT_L(8); PG8_BAR; PG8_WAIT_L(0); PG8_MMA(0, 0, At, B0); PG8_BAR; PG8_SCHED;
;             PG8_LDB(B1, 0, 1); PG8_STAGE(PG8_SB(0, 0), b2, voffB);
;             PG8_BAR; PG8_WAIT_L(0); PG8_MMA(0, 1, At, B1); PG8_BAR;
;             PG8_LDA(At, 0, 1); PG8_STAGE(PG8_SA(0, 0), a2, voffA);
;             PG8_BAR; PG8_WAIT_L(0); PG8_MMA(1, 0, At, B0); PG8_BAR; PG8_SCHED;
;             PG8_STAGE(PG8_SB(0, 1), b2 + hstepB, voffB);
;             PG8_WAIT_V(6); PG8_BAR; PG8_MMA(1, 1, At, B1); PG8_BAR;
	v_mfma_f32_16x16x32_bf16 v[128:131], v[142:145], v[162:165], v[128:131]
	v_mfma_f32_16x16x32_bf16 v[124:127], v[150:153], v[162:165], v[124:127]
	v_mfma_f32_16x16x32_bf16 v[120:123], v[142:145], v[170:173], v[120:123]
	v_mfma_f32_16x16x32_bf16 v[116:119], v[150:153], v[170:173], v[116:119]
	v_mfma_f32_16x16x32_bf16 v[112:115], v[142:145], v[178:181], v[112:115]
	v_mfma_f32_16x16x32_bf16 v[108:111], v[150:153], v[178:181], v[108:111]
	v_mfma_f32_16x16x32_bf16 v[104:107], v[142:145], v[186:189], v[104:107]
	v_mfma_f32_16x16x32_bf16 v[100:103], v[150:153], v[186:189], v[100:103]
	v_mfma_f32_16x16x32_bf16 v[128:131], v[146:149], v[166:169], v[128:131]
	v_mfma_f32_16x16x32_bf16 v[124:127], v[158:161], v[166:169], v[124:127]
	v_mfma_f32_16x16x32_bf16 v[120:123], v[146:149], v[174:177], v[120:123]
	v_mfma_f32_16x16x32_bf16 v[116:119], v[158:161], v[174:177], v[116:119]
	v_mfma_f32_16x16x32_bf16 v[112:115], v[146:149], v[182:185], v[112:115]
	v_mfma_f32_16x16x32_bf16 v[108:111], v[158:161], v[182:185], v[108:111]
	v_mfma_f32_16x16x32_bf16 v[104:107], v[146:149], v[190:193], v[104:107]
	v_mfma_f32_16x16x32_bf16 v[100:103], v[158:161], v[190:193], v[100:103]
	v_mfma_f32_16x16x32_bf16 v[64:67], v[194:197], v[162:165], v[64:67]
	v_mfma_f32_16x16x32_bf16 v[60:63], v[202:205], v[162:165], v[60:63]
	v_mfma_f32_16x16x32_bf16 v[56:59], v[194:197], v[170:173], v[56:59]
	v_mfma_f32_16x16x32_bf16 v[52:55], v[202:205], v[170:173], v[52:55]
	v_mfma_f32_16x16x32_bf16 v[48:51], v[194:197], v[178:181], v[48:51]
	v_mfma_f32_16x16x32_bf16 v[44:47], v[202:205], v[178:181], v[44:47]
	v_mfma_f32_16x16x32_bf16 v[40:43], v[194:197], v[186:189], v[40:43]
	v_mfma_f32_16x16x32_bf16 v[36:39], v[202:205], v[186:189], v[36:39]
	v_mfma_f32_16x16x32_bf16 v[64:67], v[198:201], v[166:169], v[64:67]
	v_mfma_f32_16x16x32_bf16 v[60:63], v[206:209], v[166:169], v[60:63]
	v_mfma_f32_16x16x32_bf16 v[56:59], v[198:201], v[174:177], v[56:59]
	v_mfma_f32_16x16x32_bf16 v[52:55], v[206:209], v[174:177], v[52:55]
	v_mfma_f32_16x16x32_bf16 v[48:51], v[198:201], v[182:185], v[48:51]
	v_mfma_f32_16x16x32_bf16 v[44:47], v[206:209], v[182:185], v[44:47]
	v_mfma_f32_16x16x32_bf16 v[40:43], v[198:201], v[190:193], v[40:43]
	v_mfma_f32_16x16x32_bf16 v[36:39], v[206:209], v[190:193], v[36:39]
	s_barrier
	ds_read_b128 v[162:165], v156 offset:16384
	ds_read_b128 v[166:169], v156 offset:17408
	ds_read_b128 v[170:173], v156 offset:18432
	ds_read_b128 v[174:177], v156 offset:19456
	ds_read_b128 v[178:181], v156 offset:20480
	ds_read_b128 v[182:185], v156 offset:21504
	ds_read_b128 v[186:189], v156 offset:22528
	ds_read_b128 v[190:193], v156 offset:23552
	s_add_i32 s68, s68, s29
	v_lshl_add_u64 v[154:155], s[6:7], 0, v[2:3]
	s_mov_b32 m0, s68
	v_lshl_add_u64 v[210:211], s[6:7], 0, v[136:137]
	global_load_lds_dwordx4 v[154:155], off
	s_add_i32 m0, s68, 0x2000
	s_nop 0
	global_load_lds_dwordx4 v[210:211], off
	s_mov_b32 m0, s30
	v_lshl_add_u64 v[212:213], s[14:15], 0, v[132:133]
	global_load_lds_dwordx4 v[212:213], off
	v_lshl_add_u64 v[216:217], s[14:15], 0, v[134:135]
	s_mov_b32 m0, s31
	s_nop 0
	global_load_lds_dwordx4 v[216:217], off
	s_add_u32 s68, s6, 0x100000
	s_addc_u32 s69, s7, 0
	s_add_i32 s70, s70, s29
	s_mov_b32 m0, s70
	s_nop 0
	global_load_lds_dwordx4 v2, s[68:69]
	s_add_i32 m0, s70, 0x2000
	s_nop 0
	global_load_lds_dwordx4 v136, s[68:69]
	s_waitcnt lgkmcnt(0)
	s_waitcnt vmcnt(6)
	s_barrier
	v_mfma_f32_16x16x32_bf16 v[96:99], v[142:145], v[162:165], v[96:99]
	v_mfma_f32_16x16x32_bf16 v[92:95], v[150:153], v[162:165], v[92:95]
	v_mfma_f32_16x16x32_bf16 v[88:91], v[142:145], v[170:173], v[88:91]
	v_mfma_f32_16x16x32_bf16 v[84:87], v[150:153], v[170:173], v[84:87]
	v_mfma_f32_16x16x32_bf16 v[80:83], v[142:145], v[178:181], v[80:83]
	v_mfma_f32_16x16x32_bf16 v[76:79], v[150:153], v[178:181], v[76:79]
	v_mfma_f32_16x16x32_bf16 v[72:75], v[142:145], v[186:189], v[72:75]
	v_mfma_f32_16x16x32_bf16 v[68:71], v[150:153], v[186:189], v[68:71]
	v_mfma_f32_16x16x32_bf16 v[96:99], v[146:149], v[166:169], v[96:99]
	v_mfma_f32_16x16x32_bf16 v[92:95], v[158:161], v[166:169], v[92:95]
	v_mfma_f32_16x16x32_bf16 v[88:91], v[146:149], v[174:177], v[88:91]
	v_mfma_f32_16x16x32_bf16 v[84:87], v[158:161], v[174:177], v[84:87]
	v_mfma_f32_16x16x32_bf16 v[80:83], v[146:149], v[182:185], v[80:83]
	v_mfma_f32_16x16x32_bf16 v[76:79], v[158:161], v[182:185], v[76:79]
	v_mfma_f32_16x16x32_bf16 v[72:75], v[146:149], v[190:193], v[72:75]
	v_mfma_f32_16x16x32_bf16 v[68:71], v[158:161], v[190:193], v[68:71]
	v_mfma_f32_16x16x32_bf16 v[32:35], v[194:197], v[162:165], v[32:35]
	v_mfma_f32_16x16x32_bf16 v[28:31], v[202:205], v[162:165], v[28:31]
	v_mfma_f32_16x16x32_bf16 v[24:27], v[194:197], v[170:173], v[24:27]
	v_mfma_f32_16x16x32_bf16 v[20:23], v[202:205], v[170:173], v[20:23]
	v_mfma_f32_16x16x32_bf16 v[16:19], v[194:197], v[178:181], v[16:19]
	v_mfma_f32_16x16x32_bf16 v[12:15], v[202:205], v[178:181], v[12:15]
	v_mfma_f32_16x16x32_bf16 v[8:11], v[194:197], v[186:189], v[8:11]
	v_mfma_f32_16x16x32_bf16 v[4:7], v[202:205], v[186:189], v[4:7]
	v_mfma_f32_16x16x32_bf16 v[32:35], v[198:201], v[166:169], v[32:35]
	v_mfma_f32_16x16x32_bf16 v[28:31], v[206:209], v[166:169], v[28:31]
	v_mfma_f32_16x16x32_bf16 v[24:27], v[198:201], v[174:177], v[24:27]
	v_mfma_f32_16x16x32_bf16 v[20:23], v[206:209], v[174:177], v[20:23]
	v_mfma_f32_16x16x32_bf16 v[16:19], v[198:201], v[182:185], v[16:19]
	v_mfma_f32_16x16x32_bf16 v[12:15], v[206:209], v[182:185], v[12:15]
	v_mfma_f32_16x16x32_bf16 v[8:11], v[198:201], v[190:193], v[8:11]
	v_mfma_f32_16x16x32_bf16 v[4:7], v[206:209], v[190:193], v[4:7]
	s_barrier
; #define PG8_STAGE(bufoff, gbase, voff) do { _Pragma("unroll") for (int _i = 0; _i < 2; ++_i) \
;         __builtin_amdgcn_global_load_lds((const unsigned*)((const char*)(gbase) + (voff)[_i]), (LAS unsigned*)(lds + (bufoff) + ldsw + _i * 8192), 16, 0, 0); } while (0)
; #define PG8_LDA(dst, b, h) do { _Pragma("unroll") for (int m = 0; m < 4; ++m) _Pragma("unroll") for (int k = 0; k < 2; ++k) dst[m][k] = *(const LAS bf16x8*)(lds + PG8_SA(b, h) + aoff + m * 2048 + k * 1024); } while (0)
; #define PG8_LDB(dst, b, h) do { _Pragma("unroll") for (int n = 0; n < 2; ++n) _Pragma("unroll") for (int k = 0; k < 2; ++k) dst[n][k] = *(const LAS bf16x8*)(lds + PG8_SB(b, h) + boff + n * 2048 + k * 1024); } while (0)
; #define PG8_MMA(ai, bj, At, Bt) do { __builtin_amdgcn_s_setprio(1); _Pragma("unroll") for (int m = 0; m < 4; ++m) _Pragma("unroll") for (int n = 0; n < 2; ++n) _Pragma("unroll") for (int k = 0; k < 2; ++k) \
;         acc[ai][bj][m][n] = __builtin_amdgcn_mfma_f32_16x16x32_bf16(Bt[n][k], At[m][k], acc[ai][bj][m][n], 0, 0, 0); __builtin_amdgcn_s_setprio(0); } while (0)
; #define PG8_WAIT_L(n) asm volatile("s_waitcnt lgkmcnt(" #n ")" ::: "memory")
; #define PG8_BAR __builtin_amdgcn_s_barrier()
; #define PG8_SCHED __builtin_amdgcn_sched_barrier(0)
; template <class Epi, class Sched>
; __device__ __forceinline__ void gemm_phase(LAS unsigned char* lds, const Gemm g, const Sched& S, const Epi& E) {
;     ...
;             PG8_LDB(B0, 1, 0); PG8_SCHED; PG8_LDA(At, 1, 0); PG8_STAGE(PG8_SA(0, 1), a2 + hstepA, voffA);
;             PG8_WAIT_L(8); PG8_BAR; PG8_WAIT_L(0); PG8_MMA(0, 0, At, B0); PG8_BAR; PG8_SCHED;
;             PG8_LDB(B1, 1, 1); PG8_STAGE(PG8_SB(1, 0), b3, voffB);
;             PG8_BAR; PG8_WAIT_L(0); PG8_MMA(0, 1, At, B1); PG8_BAR;
	s_add_i32 s68, 0, 0x18000
	v_add_u32_e32 v157, s68, v1
	ds_read_b128 v[142:145], v157
	ds_read_b128 v[146:149], v157 offset:1024
	ds_read_b128 v[150:153], v157 offset:2048
	ds_read_b128 v[158:161], v157 offset:3072
	s_add_u32 s14, s14, 0x80000
	s_addc_u32 s15, s15, 0
	ds_read_b128 v[162:165], v156 offset:32768
	ds_read_b128 v[166:169], v156 offset:33792
	ds_read_b128 v[170:173], v156 offset:34816
	ds_read_b128 v[174:177], v156 offset:35840
	ds_read_b128 v[178:181], v156 offset:36864
	ds_read_b128 v[182:185], v156 offset:37888
	ds_read_b128 v[186:189], v156 offset:38912
	ds_read_b128 v[190:193], v156 offset:39936
	s_mov_b32 m0, s38
	s_nop 0
	global_load_lds_dwordx4 v132, s[14:15]
	s_mov_b32 m0, s39
	s_nop 0
	global_load_lds_dwordx4 v134, s[14:15]
	s_add_i32 s14, 0, 0x1c000
	v_add_u32_e32 v157, s14, v1
	ds_read_b128 v[194:197], v157
	ds_read_b128 v[198:201], v157 offset:1024
	ds_read_b128 v[202:205], v157 offset:2048
	ds_read_b128 v[206:209], v157 offset:3072
	s_waitcnt lgkmcnt(0)
	s_barrier
	v_mfma_f32_16x16x32_bf16 v[128:131], v[142:145], v[162:165], v[128:131]
	v_mfma_f32_16x16x32_bf16 v[124:127], v[150:153], v[162:165], v[124:127]
	v_mfma_f32_16x16x32_bf16 v[120:123], v[142:145], v[170:173], v[120:123]
	v_mfma_f32_16x16x32_bf16 v[116:119], v[150:153], v[170:173], v[116:119]
	v_mfma_f32_16x16x32_bf16 v[112:115], v[142:145], v[178:181], v[112:115]
	v_mfma_f32_16x16x32_bf16 v[108:111], v[150:153], v[178:181], v[108:111]
	v_mfma_f32_16x16x32_bf16 v[104:107], v[142:145], v[186:189], v[104:107]
	v_mfma_f32_16x16x32_bf16 v[100:103], v[150:153], v[186:189], v[100:103]
	v_mfma_f32_16x16x32_bf16 v[128:131], v[146:149], v[166:169], v[128:131]
	v_mfma_f32_16x16x32_bf16 v[124:127], v[158:161], v[166:169], v[124:127]
	v_mfma_f32_16x16x32_bf16 v[120:123], v[146:149], v[174:177], v[120:123]
	v_mfma_f32_16x16x32_bf16 v[116:119], v[158:161], v[174:177], v[116:119]
	v_mfma_f32_16x16x32_bf16 v[112:115], v[146:149], v[182:185], v[112:115]
	v_mfma_f32_16x16x32_bf16 v[108:111], v[158:161], v[182:185], v[108:111]
	v_mfma_f32_16x16x32_bf16 v[104:107], v[146:149], v[190:193], v[104:107]
	v_mfma_f32_16x16x32_bf16 v[100:103], v[158:161], v[190:193], v[100:103]
	v_mfma_f32_16x16x32_bf16 v[64:67], v[194:197], v[162:165], v[64:67]
	v_mfma_f32_16x16x32_bf16 v[60:63], v[202:205], v[162:165], v[60:63]
	v_mfma_f32_16x16x32_bf16 v[56:59], v[194:197], v[170:173], v[56:59]
	v_mfma_f32_16x16x32_bf16 v[52:55], v[202:205], v[170:173], v[52:55]
	v_mfma_f32_16x16x32_bf16 v[48:51], v[194:197], v[178:181], v[48:51]
	v_mfma_f32_16x16x32_bf16 v[44:47], v[202:205], v[178:181], v[44:47]
	v_mfma_f32_16x16x32_bf16 v[40:43], v[194:197], v[186:189], v[40:43]
	v_mfma_f32_16x16x32_bf16 v[36:39], v[202:205], v[186:189], v[36:39]
	v_mfma_f32_16x16x32_bf16 v[64:67], v[198:201], v[166:169], v[64:67]
	v_mfma_f32_16x16x32_bf16 v[60:63], v[206:209], v[166:169], v[60:63]
	v_mfma_f32_16x16x32_bf16 v[56:59], v[198:201], v[174:177], v[56:59]
	v_mfma_f32_16x16x32_bf16 v[52:55], v[206:209], v[174:177], v[52:55]
	v_mfma_f32_16x16x32_bf16 v[48:51], v[198:201], v[182:185], v[48:51]
	v_mfma_f32_16x16x32_bf16 v[44:47], v[206:209], v[182:185], v[44:47]
	v_mfma_f32_16x16x32_bf16 v[40:43], v[198:201], v[190:193], v[40:43]
	v_mfma_f32_16x16x32_bf16 v[36:39], v[206:209], v[190:193], v[36:39]
	s_barrier
; #define PG8_STAGE(bufoff, gbase, voff) do { _Pragma("unroll") for (int _i = 0; _i < 2; ++_i) \
;         __builtin_amdgcn_global_load_lds((const unsigned*)((const char*)(gbase) + (voff)[_i]), (LAS unsigned*)(lds + (bufoff) + ldsw + _i * 8192), 16, 0, 0); } while (0)
; #define PG8_LDA(dst, b, h) do { _Pragma("unroll") for (int m = 0; m < 4; ++m) _Pragma("unroll") for (int k = 0; k < 2; ++k) dst[m][k] = *(const LAS bf16x8*)(lds + PG8_SA(b, h) + aoff + m * 2048 + k * 1024); } while (0)
; #define PG8_MMA(ai, bj, At, Bt) do { __builtin_amdgcn_s_setprio(1); _Pragma("unroll") for (int m = 0; m < 4; ++m) _Pragma("unroll") for (int n = 0; n < 2; ++n) _Pragma("unroll") for (int k = 0; k < 2; ++k) \
;         acc[ai][bj][m][n] = __builtin_amdgcn_mfma_f32_16x16x32_bf16(Bt[n][k], At[m][k], acc[ai][bj][m][n], 0, 0, 0); __builtin_amdgcn_s_setprio(0); } while (0)
; #define PG8_WAIT_V(n) asm volatile("s_waitcnt vmcnt(" #n ")" ::: "memory")
; #define PG8_WAIT_L(n) asm volatile("s_waitcnt lgkmcnt(" #n ")" ::: "memory")
; #define PG8_BAR __builtin_amdgcn_s_barrier()
; #define PG8_SCHED __builtin_amdgcn_sched_barrier(0)
; template <class Epi, class Sched>
; __device__ __forceinline__ void gemm_phase(LAS unsigned char* lds, const Gemm g, const Sched& S, const Epi& E) {
;     ...
;             PG8_LDA(At, 1, 1); PG8_STAGE(PG8_SA(1, 0), a3, voffA);
;             PG8_BAR; PG8_WAIT_L(0); PG8_MMA(1, 0, At, B0); PG8_BAR; PG8_SCHED;
;             PG8_STAGE(PG8_SB(1, 1), b3 + hstepB, voffB);
;             PG8_WAIT_V(6); PG8_BAR; PG8_MMA(1, 1, At, B1); PG8_BAR;
;     __device__ __forceinline__ void operator()(const f32x4 (&acc)[2][2][4][2], const Unit& u, int wr, int wc, int, int) const {
;     ...
; #pragma unroll
;         for (int bj = 0; bj < 2; ++bj) { f32x4 b0 = (f32x4){0.f, 0.f, 0.f, 0.f}, b1 = b0;
; #pragma unroll 8
;             for (int pp = 0; pp < 32; ++pp) { b0 += *(const f32x4*)(bias + pp * 256 + col0 + bj * HALF); b1 += *(const f32x4*)(bias + pp * 256 + col0 + bj * HALF + 4); }
	ds_read_b128 v[162:165], v156 offset:49152
	ds_read_b128 v[166:169], v156 offset:50176
	ds_read_b128 v[170:173], v156 offset:51200
	ds_read_b128 v[174:177], v156 offset:52224
	ds_read_b128 v[178:181], v156 offset:53248
	ds_read_b128 v[182:185], v156 offset:54272
	ds_read_b128 v[186:189], v156 offset:55296
	ds_read_b128 v[190:193], v156 offset:56320
	s_add_i32 s15, s68, s29
	v_lshl_add_u64 v[154:155], v[154:155], 0, s[8:9]
	s_mov_b32 m0, s15
	s_nop 0
	global_load_lds_dwordx4 v[154:155], off
	v_lshl_add_u64 v[154:155], v[210:211], 0, s[8:9]
	s_add_i32 m0, s15, 0x2000
	s_nop 0
	global_load_lds_dwordx4 v[154:155], off
	s_mov_b32 m0, s62
	v_lshl_add_u64 v[154:155], v[212:213], 0, s[8:9]
	global_load_lds_dwordx4 v[154:155], off
	v_lshl_add_u64 v[154:155], v[216:217], 0, s[8:9]
	s_mov_b32 m0, s63
	s_nop 0
	global_load_lds_dwordx4 v[154:155], off
	s_add_u32 s6, s6, 0x100080
	s_addc_u32 s7, s7, 0
	s_add_i32 s14, s14, s29
	s_mov_b32 m0, s14
	s_nop 0
	global_load_lds_dwordx4 v2, s[6:7]
	s_add_i32 m0, s14, 0x2000
	s_nop 0
	global_load_lds_dwordx4 v136, s[6:7]
	s_add_i32 s67, s67, 2
	s_add_u32 s4, s4, 0x100
	s_addc_u32 s5, s5, 0
	s_add_u32 s65, s65, 0x100
	s_addc_u32 s66, s66, 0
	s_cmp_gt_u32 s67, 61
	s_waitcnt lgkmcnt(0)
	s_waitcnt vmcnt(6)
	s_barrier
	v_mfma_f32_16x16x32_bf16 v[96:99], v[142:145], v[162:165], v[96:99]
	v_mfma_f32_16x16x32_bf16 v[92:95], v[150:153], v[162:165], v[92:95]
	v_mfma_f32_16x16x32_bf16 v[88:91], v[142:145], v[170:173], v[88:91]
	v_mfma_f32_16x16x32_bf16 v[84:87], v[150:153], v[170:173], v[84:87]
	v_mfma_f32_16x16x32_bf16 v[80:83], v[142:145], v[178:181], v[80:83]
	v_mfma_f32_16x16x32_bf16 v[76:79], v[150:153], v[178:181], v[76:79]
	v_mfma_f32_16x16x32_bf16 v[72:75], v[142:145], v[186:189], v[72:75]
	v_mfma_f32_16x16x32_bf16 v[68:71], v[150:153], v[186:189], v[68:71]
	v_mfma_f32_16x16x32_bf16 v[96:99], v[146:149], v[166:169], v[96:99]
	v_mfma_f32_16x16x32_bf16 v[92:95], v[158:161], v[166:169], v[92:95]
	v_mfma_f32_16x16x32_bf16 v[88:91], v[146:149], v[174:177], v[88:91]
	v_mfma_f32_16x16x32_bf16 v[84:87], v[158:161], v[174:177], v[84:87]
	v_mfma_f32_16x16x32_bf16 v[80:83], v[146:149], v[182:185], v[80:83]
	v_mfma_f32_16x16x32_bf16 v[76:79], v[158:161], v[182:185], v[76:79]
	v_mfma_f32_16x16x32_bf16 v[72:75], v[146:149], v[190:193], v[72:75]
	v_mfma_f32_16x16x32_bf16 v[68:71], v[158:161], v[190:193], v[68:71]
	v_mfma_f32_16x16x32_bf16 v[32:35], v[194:197], v[162:165], v[32:35]
	v_mfma_f32_16x16x32_bf16 v[28:31], v[202:205], v[162:165], v[28:31]
	v_mfma_f32_16x16x32_bf16 v[24:27], v[194:197], v[170:173], v[24:27]
	v_mfma_f32_16x16x32_bf16 v[20:23], v[202:205], v[170:173], v[20:23]
	v_mfma_f32_16x16x32_bf16 v[16:19], v[194:197], v[178:181], v[16:19]
	v_mfma_f32_16x16x32_bf16 v[12:15], v[202:205], v[178:181], v[12:15]
	v_mfma_f32_16x16x32_bf16 v[8:11], v[194:197], v[186:189], v[8:11]
	v_mfma_f32_16x16x32_bf16 v[4:7], v[202:205], v[186:189], v[4:7]
	v_mfma_f32_16x16x32_bf16 v[32:35], v[198:201], v[166:169], v[32:35]
	v_mfma_f32_16x16x32_bf16 v[28:31], v[206:209], v[166:169], v[28:31]
	v_mfma_f32_16x16x32_bf16 v[24:27], v[198:201], v[174:177], v[24:27]
	v_mfma_f32_16x16x32_bf16 v[20:23], v[206:209], v[174:177], v[20:23]
	v_mfma_f32_16x16x32_bf16 v[16:19], v[198:201], v[182:185], v[16:19]
	v_mfma_f32_16x16x32_bf16 v[12:15], v[206:209], v[182:185], v[12:15]
	v_mfma_f32_16x16x32_bf16 v[8:11], v[198:201], v[190:193], v[8:11]
	v_mfma_f32_16x16x32_bf16 v[4:7], v[206:209], v[190:193], v[4:7]
	s_barrier
	s_cbranch_scc0 .LBB0_491
	s_setprio 0
	v_mov_b32_e32 v157, v0
	s_lshl_b32 s1, s1, 8
	v_lshrrev_b32_e32 v142, 1, v157
	v_and_or_b32 v142, v142, 24, s1
	v_or_b32_e32 v154, s61, v142
	v_ashrrev_i32_e32 v155, 31, v154
	v_mov_b32_e32 v144, 0
	v_lshl_add_u64 v[142:143], v[154:155], 2, s[46:47]
	s_mov_b64 s[4:5], 0
	v_mov_b32_e32 v145, v144
	v_mov_b32_e32 v146, v144
	v_mov_b32_e32 v147, v144
	v_mov_b32_e32 v148, v144
	v_mov_b32_e32 v149, v144
	v_mov_b32_e32 v150, v144
	v_mov_b32_e32 v151, v144

; #define PG8_STAGE(bufoff, gbase, voff) do { _Pragma("unroll") for (int _i = 0; _i < 2; ++_i) \
;         __builtin_amdgcn_global_load_lds((const unsigned*)((const char*)(gbase) + (voff)[_i]), (LAS unsigned*)(lds + (bufoff) + ldsw + _i * 8192), 16, 0, 0); } while (0)
; #define PG8_LDA(dst, b, h) do { _Pragma("unroll") for (int m = 0; m < 4; ++m) _Pragma("unroll") for (int k = 0; k < 2; ++k) dst[m][k] = *(const LAS bf16x8*)(lds + PG8_SA(b, h) + aoff + m * 2048 + k * 1024); } while (0)
; #define PG8_LDB(dst, b, h) do { _Pragma("unroll") for (int n = 0; n < 2; ++n) _Pragma("unroll") for (int k = 0; k < 2; ++k) dst[n][k] = *(const LAS bf16x8*)(lds + PG8_SB(b, h) + boff + n * 2048 + k * 1024); } while (0)
; #define PG8_MMA(ai, bj, At, Bt) do { __builtin_amdgcn_s_setprio(1); _Pragma("unroll") for (int m = 0; m < 4; ++m) _Pragma("unroll") for (int n = 0; n < 2; ++n) _Pragma("unroll") for (int k = 0; k < 2; ++k) \
;         acc[ai][bj][m][n] = __builtin_amdgcn_mfma_f32_16x16x32_bf16(Bt[n][k], At[m][k], acc[ai][bj][m][n], 0, 0, 0); __builtin_amdgcn_s_setprio(0); } while (0)
; #define PG8_BAR __builtin_amdgcn_s_barrier()
; template <class Epi, class Sched>
; __device__ __forceinline__ void gemm_phase(LAS unsigned char* lds, const Gemm g, const Sched& S, const Epi& E) {
;     ...
;         const bool has_next = S.next(ui + 1, nxt);
;         const char* nA = has_next ? (const char*)g.A + (size_t)nxt.pm * tstepA : cA; const char* nB = has_next ? (const char*)g.Bt + (size_t)nxt.pn * tstepB : cB;
;         for (int t = 0; t < nt; t += 2) {
;             const bool last = (t == nt - 2);
;             const char* a1 = cA + (size_t)(t + 1) * kstep;
;             const char* a2 = last ? nA : cA + (size_t)(t + 2) * kstep; const char* b2 = last ? nB : cB + (size_t)(t + 2) * kstep;
;             const char* a3 = a2 + kstep; const char* b3 = b2 + kstep;
;             if (last && has_next) S.a_ready(nxt);
;             PG8_LDB(B0, 0, 0); PG8_SCHED; PG8_LDA(At, 0, 0); PG8_STAGE(PG8_SA(1, 1), a1 + hstepA, voffA);
;             PG8_WAIT_L(8); PG8_BAR; PG8_WAIT_L(0); PG8_MMA(0, 0, At, B0); PG8_BAR; PG8_SCHED;
;             PG8_LDB(B1, 0, 1); PG8_STAGE(PG8_SB(0, 0), b2, voffB);
;             PG8_BAR; PG8_WAIT_L(0); PG8_MMA(0, 1, At, B1); PG8_BAR;
;             PG8_LDA(At, 0, 1); PG8_STAGE(PG8_SA(0, 0), a2, voffA);
;             PG8_BAR; PG8_WAIT_L(0); PG8_MMA(1, 0, At, B0); PG8_BAR; PG8_SCHED;
.LBB0_965:
	v_mov_b64_e32 v[4:5], 0x400
	s_ashr_i32 s15, s14, 31
	v_cmp_lt_i64_e32 vcc, s[4:5], v[4:5]
	s_lshl_b64 s[4:5], s[14:15], 20
	v_readlane_b32 s48, v252, 0
	v_readlane_b32 s49, v252, 1
	s_add_u32 s4, s48, s4
	s_addc_u32 s5, s49, s5
	s_and_b64 s[18:19], vcc, exec
	s_cselect_b32 s15, s5, s7
	s_cselect_b32 s47, s4, s6
	s_ashr_i32 s1, s0, 31
	s_lshl_b64 s[18:19], s[0:1], 20
	s_add_u32 s18, s28, s18
	s_addc_u32 s19, s29, s19
	s_and_b64 s[24:25], vcc, exec
	s_cselect_b32 s1, s19, s21
	s_cselect_b32 s48, s18, s20
	s_add_u32 s6, s6, 0x80080
	s_addc_u32 s7, s7, 0
	v_readlane_b32 s50, v252, 2
	v_readlane_b32 s51, v252, 3
	s_add_u32 s49, s20, 0x100
	s_addc_u32 s50, s21, 0
	s_mov_b32 s51, -2
	s_waitcnt lgkmcnt(0)
	s_setprio 0
	s_add_u32 s20, s6, 0xfff80080
	s_addc_u32 s21, s7, -1
	s_add_i32 s52, 0, 0x10000
	v_add_u32_e32 v144, s52, v1
	ds_read_b128 v[132:135], v144
	ds_read_b128 v[136:139], v144 offset:1024
	ds_read_b128 v[140:143], v144 offset:2048
	ds_read_b128 v[144:147], v144 offset:3072
	s_cmp_eq_u32 s51, 28
	s_cselect_b32 s25, s15, s21
	s_cselect_b32 s24, s47, s20
	s_cselect_b32 s21, s1, s50
	s_cselect_b32 s20, s48, s49
	ds_read_b128 v[148:151], v224
	ds_read_b128 v[152:155], v224 offset:1024
	ds_read_b128 v[156:159], v224 offset:2048
	ds_read_b128 v[160:163], v224 offset:3072
	ds_read_b128 v[164:167], v224 offset:4096
	ds_read_b128 v[168:171], v224 offset:5120
	ds_read_b128 v[172:175], v224 offset:6144
	ds_read_b128 v[176:179], v224 offset:7168
	s_add_i32 s54, 0, 0x14000
	v_add_u32_e32 v202, s54, v1
	ds_read_b128 v[180:183], v202
	ds_read_b128 v[184:187], v202 offset:1024
	ds_read_b128 v[188:191], v202 offset:2048
	ds_read_b128 v[202:205], v202 offset:3072
	s_add_i32 m0, s31, 0xc000
	s_nop 0
	global_load_lds_dwordx4 v198, s[6:7]
	s_add_i32 m0, s31, 0xe000
	s_nop 0
	global_load_lds_dwordx4 v200, s[6:7]
	s_waitcnt lgkmcnt(0)
	s_barrier
	v_mfma_f32_16x16x32_bf16 v[128:131], v[132:135], v[148:151], 0
	v_mfma_f32_16x16x32_bf16 v[124:127], v[140:143], v[148:151], 0
	v_mfma_f32_16x16x32_bf16 v[112:115], v[132:135], v[156:159], 0
	v_mfma_f32_16x16x32_bf16 v[108:111], v[140:143], v[156:159], 0
	v_mfma_f32_16x16x32_bf16 v[100:103], v[132:135], v[164:167], 0
	v_mfma_f32_16x16x32_bf16 v[92:95], v[140:143], v[164:167], 0
	v_mfma_f32_16x16x32_bf16 v[84:87], v[132:135], v[172:175], 0
	v_mfma_f32_16x16x32_bf16 v[76:79], v[140:143], v[172:175], 0
	v_mfma_f32_16x16x32_bf16 v[128:131], v[136:139], v[152:155], v[128:131]
	v_mfma_f32_16x16x32_bf16 v[124:127], v[144:147], v[152:155], v[124:127]
	v_mfma_f32_16x16x32_bf16 v[112:115], v[136:139], v[160:163], v[112:115]
	v_mfma_f32_16x16x32_bf16 v[108:111], v[144:147], v[160:163], v[108:111]
	v_mfma_f32_16x16x32_bf16 v[100:103], v[136:139], v[168:171], v[100:103]
	v_mfma_f32_16x16x32_bf16 v[92:95], v[144:147], v[168:171], v[92:95]
	v_mfma_f32_16x16x32_bf16 v[84:87], v[136:139], v[176:179], v[84:87]
	v_mfma_f32_16x16x32_bf16 v[76:79], v[144:147], v[176:179], v[76:79]
	v_mfma_f32_16x16x32_bf16 v[120:123], v[180:183], v[148:151], 0
	v_mfma_f32_16x16x32_bf16 v[116:119], v[188:191], v[148:151], 0
	v_mfma_f32_16x16x32_bf16 v[104:107], v[180:183], v[156:159], 0
	v_mfma_f32_16x16x32_bf16 v[96:99], v[188:191], v[156:159], 0
	v_mfma_f32_16x16x32_bf16 v[88:91], v[180:183], v[164:167], 0
	v_mfma_f32_16x16x32_bf16 v[80:83], v[188:191], v[164:167], 0
	v_mfma_f32_16x16x32_bf16 v[72:75], v[180:183], v[172:175], 0
	v_mfma_f32_16x16x32_bf16 v[68:71], v[188:191], v[172:175], 0
	v_mfma_f32_16x16x32_bf16 v[120:123], v[184:187], v[152:155], v[120:123]
	v_mfma_f32_16x16x32_bf16 v[116:119], v[202:205], v[152:155], v[116:119]
	v_mfma_f32_16x16x32_bf16 v[104:107], v[184:187], v[160:163], v[104:107]
	v_mfma_f32_16x16x32_bf16 v[96:99], v[202:205], v[160:163], v[96:99]
	v_mfma_f32_16x16x32_bf16 v[88:91], v[184:187], v[168:171], v[88:91]
	v_mfma_f32_16x16x32_bf16 v[80:83], v[202:205], v[168:171], v[80:83]
	v_mfma_f32_16x16x32_bf16 v[72:75], v[184:187], v[176:179], v[72:75]
	v_mfma_f32_16x16x32_bf16 v[68:71], v[202:205], v[176:179], v[68:71]
	s_barrier
	ds_read_b128 v[148:151], v224 offset:16384
	ds_read_b128 v[152:155], v224 offset:17408
	ds_read_b128 v[156:159], v224 offset:18432
	ds_read_b128 v[160:163], v224 offset:19456
	ds_read_b128 v[164:167], v224 offset:20480
	ds_read_b128 v[168:171], v224 offset:21504
	ds_read_b128 v[172:175], v224 offset:22528
	ds_read_b128 v[176:179], v224 offset:23552
	s_add_i32 s52, s52, s30
	v_lshl_add_u64 v[206:207], s[20:21], 0, v[2:3]
	s_mov_b32 m0, s52
	s_nop 0
	global_load_lds_dwordx4 v[206:207], off
	v_lshl_add_u64 v[208:209], s[20:21], 0, v[192:193]
	s_add_i32 m0, s52, 0x2000
	s_nop 0
	global_load_lds_dwordx4 v[208:209], off
	s_mov_b32 m0, s31
	v_lshl_add_u64 v[210:211], s[24:25], 0, v[196:197]
	global_load_lds_dwordx4 v[210:211], off
	v_lshl_add_u64 v[212:213], s[24:25], 0, v[194:195]
	s_mov_b32 m0, s35
	s_nop 0
	global_load_lds_dwordx4 v[212:213], off
	s_add_u32 s52, s20, 0x80000
	s_addc_u32 s53, s21, 0
	s_add_i32 s54, s54, s30
	s_mov_b32 m0, s54
	s_nop 0
	global_load_lds_dwordx4 v2, s[52:53]
	s_add_i32 m0, s54, 0x2000
	s_nop 0
	global_load_lds_dwordx4 v192, s[52:53]
	s_waitcnt lgkmcnt(0)
	s_waitcnt vmcnt(6)
	s_barrier
; #define PG8_STAGE(bufoff, gbase, voff) do { _Pragma("unroll") for (int _i = 0; _i < 2; ++_i) \
;         __builtin_amdgcn_global_load_lds((const unsigned*)((const char*)(gbase) + (voff)[_i]), (LAS unsigned*)(lds + (bufoff) + ldsw + _i * 8192), 16, 0, 0); } while (0)
; #define PG8_LDA(dst, b, h) do { _Pragma("unroll") for (int m = 0; m < 4; ++m) _Pragma("unroll") for (int k = 0; k < 2; ++k) dst[m][k] = *(const LAS bf16x8*)(lds + PG8_SA(b, h) + aoff + m * 2048 + k * 1024); } while (0)
; #define PG8_LDB(dst, b, h) do { _Pragma("unroll") for (int n = 0; n < 2; ++n) _Pragma("unroll") for (int k = 0; k < 2; ++k) dst[n][k] = *(const LAS bf16x8*)(lds + PG8_SB(b, h) + boff + n * 2048 + k * 1024); } while (0)
; #define PG8_MMA(ai, bj, At, Bt) do { __builtin_amdgcn_s_setprio(1); _Pragma("unroll") for (int m = 0; m < 4; ++m) _Pragma("unroll") for (int n = 0; n < 2; ++n) _Pragma("unroll") for (int k = 0; k < 2; ++k) \
;         acc[ai][bj][m][n] = __builtin_amdgcn_mfma_f32_16x16x32_bf16(Bt[n][k], At[m][k], acc[ai][bj][m][n], 0, 0, 0); __builtin_amdgcn_s_setprio(0); } while (0)
; #define PG8_WAIT_V(n) asm volatile("s_waitcnt vmcnt(" #n ")" ::: "memory")
; #define PG8_WAIT_L(n) asm volatile("s_waitcnt lgkmcnt(" #n ")" ::: "memory")
; #define PG8_BAR __builtin_amdgcn_s_barrier()
; #define PG8_SCHED __builtin_amdgcn_sched_barrier(0)
; template <class Epi, class Sched>
; __device__ __forceinline__ void gemm_phase(LAS unsigned char* lds, const Gemm g, const Sched& S, const Epi& E) {
;     ...
;             PG8_BAR; PG8_WAIT_L(0); PG8_MMA(1, 0, At, B0); PG8_BAR; PG8_SCHED;
;             PG8_STAGE(PG8_SB(0, 1), b2 + hstepB, voffB);
;             PG8_WAIT_V(6); PG8_BAR; PG8_MMA(1, 1, At, B1); PG8_BAR;
;             PG8_LDB(B0, 1, 0); PG8_SCHED; PG8_LDA(At, 1, 0); PG8_STAGE(PG8_SA(0, 1), a2 + hstepA, voffA);
;             PG8_WAIT_L(8); PG8_BAR; PG8_WAIT_L(0); PG8_MMA(0, 0, At, B0); PG8_BAR; PG8_SCHED;
;             PG8_LDB(B1, 1, 1); PG8_STAGE(PG8_SB(1, 0), b3, voffB);
;             PG8_BAR; PG8_WAIT_L(0); PG8_MMA(0, 1, At, B1); PG8_BAR;
	v_mfma_f32_16x16x32_bf16 v[64:67], v[132:135], v[148:151], 0
	v_mfma_f32_16x16x32_bf16 v[60:63], v[140:143], v[148:151], 0
	v_mfma_f32_16x16x32_bf16 v[52:55], v[132:135], v[156:159], 0
	v_mfma_f32_16x16x32_bf16 v[44:47], v[140:143], v[156:159], 0
	v_mfma_f32_16x16x32_bf16 v[36:39], v[132:135], v[164:167], 0
	v_mfma_f32_16x16x32_bf16 v[28:31], v[140:143], v[164:167], 0
	v_mfma_f32_16x16x32_bf16 v[20:23], v[132:135], v[172:175], 0
	v_mfma_f32_16x16x32_bf16 v[12:15], v[140:143], v[172:175], 0
	v_mfma_f32_16x16x32_bf16 v[64:67], v[136:139], v[152:155], v[64:67]
	v_mfma_f32_16x16x32_bf16 v[60:63], v[144:147], v[152:155], v[60:63]
	v_mfma_f32_16x16x32_bf16 v[52:55], v[136:139], v[160:163], v[52:55]
	v_mfma_f32_16x16x32_bf16 v[44:47], v[144:147], v[160:163], v[44:47]
	v_mfma_f32_16x16x32_bf16 v[36:39], v[136:139], v[168:171], v[36:39]
	v_mfma_f32_16x16x32_bf16 v[28:31], v[144:147], v[168:171], v[28:31]
	v_mfma_f32_16x16x32_bf16 v[20:23], v[136:139], v[176:179], v[20:23]
	v_mfma_f32_16x16x32_bf16 v[12:15], v[144:147], v[176:179], v[12:15]
	v_mfma_f32_16x16x32_bf16 v[56:59], v[180:183], v[148:151], 0
	v_mfma_f32_16x16x32_bf16 v[48:51], v[188:191], v[148:151], 0
	v_mfma_f32_16x16x32_bf16 v[40:43], v[180:183], v[156:159], 0
	v_mfma_f32_16x16x32_bf16 v[32:35], v[188:191], v[156:159], 0
	v_mfma_f32_16x16x32_bf16 v[24:27], v[180:183], v[164:167], 0
	v_mfma_f32_16x16x32_bf16 v[16:19], v[188:191], v[164:167], 0
	v_mfma_f32_16x16x32_bf16 v[8:11], v[180:183], v[172:175], 0
	v_mfma_f32_16x16x32_bf16 v[4:7], v[188:191], v[172:175], 0
	v_mfma_f32_16x16x32_bf16 v[56:59], v[184:187], v[152:155], v[56:59]
	v_mfma_f32_16x16x32_bf16 v[48:51], v[202:205], v[152:155], v[48:51]
	v_mfma_f32_16x16x32_bf16 v[40:43], v[184:187], v[160:163], v[40:43]
	v_mfma_f32_16x16x32_bf16 v[32:35], v[202:205], v[160:163], v[32:35]
	v_mfma_f32_16x16x32_bf16 v[24:27], v[184:187], v[168:171], v[24:27]
	v_mfma_f32_16x16x32_bf16 v[16:19], v[202:205], v[168:171], v[16:19]
	v_mfma_f32_16x16x32_bf16 v[8:11], v[184:187], v[176:179], v[8:11]
	v_mfma_f32_16x16x32_bf16 v[4:7], v[202:205], v[176:179], v[4:7]
	s_barrier
	s_add_i32 s52, 0, 0x18000
	v_add_u32_e32 v144, s52, v1
	ds_read_b128 v[132:135], v144
	ds_read_b128 v[136:139], v144 offset:1024
	ds_read_b128 v[140:143], v144 offset:2048
	ds_read_b128 v[144:147], v144 offset:3072
	s_add_u32 s24, s24, 0x80000
	s_addc_u32 s25, s25, 0
	ds_read_b128 v[148:151], v224 offset:32768
	ds_read_b128 v[152:155], v224 offset:33792
	ds_read_b128 v[156:159], v224 offset:34816
	ds_read_b128 v[160:163], v224 offset:35840
	ds_read_b128 v[164:167], v224 offset:36864
	ds_read_b128 v[168:171], v224 offset:37888
	ds_read_b128 v[172:175], v224 offset:38912
	ds_read_b128 v[176:179], v224 offset:39936
	s_mov_b32 m0, s36
	s_nop 0
	global_load_lds_dwordx4 v196, s[24:25]
	s_mov_b32 m0, s37
	s_nop 0
	global_load_lds_dwordx4 v194, s[24:25]
	s_add_i32 s24, 0, 0x1c000
	v_add_u32_e32 v202, s24, v1
	ds_read_b128 v[180:183], v202
	ds_read_b128 v[184:187], v202 offset:1024
	ds_read_b128 v[188:191], v202 offset:2048
	ds_read_b128 v[202:205], v202 offset:3072
	s_waitcnt lgkmcnt(0)
	s_barrier
	v_mfma_f32_16x16x32_bf16 v[128:131], v[132:135], v[148:151], v[128:131]
	v_mfma_f32_16x16x32_bf16 v[124:127], v[140:143], v[148:151], v[124:127]
	v_mfma_f32_16x16x32_bf16 v[112:115], v[132:135], v[156:159], v[112:115]
	v_mfma_f32_16x16x32_bf16 v[108:111], v[140:143], v[156:159], v[108:111]
	v_mfma_f32_16x16x32_bf16 v[100:103], v[132:135], v[164:167], v[100:103]
	v_mfma_f32_16x16x32_bf16 v[92:95], v[140:143], v[164:167], v[92:95]
	v_mfma_f32_16x16x32_bf16 v[84:87], v[132:135], v[172:175], v[84:87]
	v_mfma_f32_16x16x32_bf16 v[76:79], v[140:143], v[172:175], v[76:79]
	v_mfma_f32_16x16x32_bf16 v[128:131], v[136:139], v[152:155], v[128:131]
	v_mfma_f32_16x16x32_bf16 v[124:127], v[144:147], v[152:155], v[124:127]
	v_mfma_f32_16x16x32_bf16 v[112:115], v[136:139], v[160:163], v[112:115]
	v_mfma_f32_16x16x32_bf16 v[108:111], v[144:147], v[160:163], v[108:111]
	v_mfma_f32_16x16x32_bf16 v[100:103], v[136:139], v[168:171], v[100:103]
	v_mfma_f32_16x16x32_bf16 v[92:95], v[144:147], v[168:171], v[92:95]
	v_mfma_f32_16x16x32_bf16 v[84:87], v[136:139], v[176:179], v[84:87]
	v_mfma_f32_16x16x32_bf16 v[76:79], v[144:147], v[176:179], v[76:79]
	v_mfma_f32_16x16x32_bf16 v[120:123], v[180:183], v[148:151], v[120:123]
	v_mfma_f32_16x16x32_bf16 v[116:119], v[188:191], v[148:151], v[116:119]
	v_mfma_f32_16x16x32_bf16 v[104:107], v[180:183], v[156:159], v[104:107]
	v_mfma_f32_16x16x32_bf16 v[96:99], v[188:191], v[156:159], v[96:99]
	v_mfma_f32_16x16x32_bf16 v[88:91], v[180:183], v[164:167], v[88:91]
	v_mfma_f32_16x16x32_bf16 v[80:83], v[188:191], v[164:167], v[80:83]
	v_mfma_f32_16x16x32_bf16 v[72:75], v[180:183], v[172:175], v[72:75]
	v_mfma_f32_16x16x32_bf16 v[68:71], v[188:191], v[172:175], v[68:71]
	v_mfma_f32_16x16x32_bf16 v[120:123], v[184:187], v[152:155], v[120:123]
	v_mfma_f32_16x16x32_bf16 v[116:119], v[202:205], v[152:155], v[116:119]
	v_mfma_f32_16x16x32_bf16 v[104:107], v[184:187], v[160:163], v[104:107]
	v_mfma_f32_16x16x32_bf16 v[96:99], v[202:205], v[160:163], v[96:99]
	v_mfma_f32_16x16x32_bf16 v[88:91], v[184:187], v[168:171], v[88:91]
	v_mfma_f32_16x16x32_bf16 v[80:83], v[202:205], v[168:171], v[80:83]
	v_mfma_f32_16x16x32_bf16 v[72:75], v[184:187], v[176:179], v[72:75]
	v_mfma_f32_16x16x32_bf16 v[68:71], v[202:205], v[176:179], v[68:71]
	s_barrier
; #define PG8_STAGE(bufoff, gbase, voff) do { _Pragma("unroll") for (int _i = 0; _i < 2; ++_i) \
;         __builtin_amdgcn_global_load_lds((const unsigned*)((const char*)(gbase) + (voff)[_i]), (LAS unsigned*)(lds + (bufoff) + ldsw + _i * 8192), 16, 0, 0); } while (0)
; #define PG8_LDA(dst, b, h) do { _Pragma("unroll") for (int m = 0; m < 4; ++m) _Pragma("unroll") for (int k = 0; k < 2; ++k) dst[m][k] = *(const LAS bf16x8*)(lds + PG8_SA(b, h) + aoff + m * 2048 + k * 1024); } while (0)
; #define PG8_LDB(dst, b, h) do { _Pragma("unroll") for (int n = 0; n < 2; ++n) _Pragma("unroll") for (int k = 0; k < 2; ++k) dst[n][k] = *(const LAS bf16x8*)(lds + PG8_SB(b, h) + boff + n * 2048 + k * 1024); } while (0)
; #define PG8_MMA(ai, bj, At, Bt) do { __builtin_amdgcn_s_setprio(1); _Pragma("unroll") for (int m = 0; m < 4; ++m) _Pragma("unroll") for (int n = 0; n < 2; ++n) _Pragma("unroll") for (int k = 0; k < 2; ++k) \
;         acc[ai][bj][m][n] = __builtin_amdgcn_mfma_f32_16x16x32_bf16(Bt[n][k], At[m][k], acc[ai][bj][m][n], 0, 0, 0); __builtin_amdgcn_s_setprio(0); } while (0)
; #define PG8_WAIT_V(n) asm volatile("s_waitcnt vmcnt(" #n ")" ::: "memory")
; #define PG8_WAIT_L(n) asm volatile("s_waitcnt lgkmcnt(" #n ")" ::: "memory")
; #define PG8_BAR __builtin_amdgcn_s_barrier()
; #define PG8_SCHED __builtin_amdgcn_sched_barrier(0)
; template <class Epi, class Sched>
; __device__ __forceinline__ void gemm_phase(LAS unsigned char* lds, const Gemm g, const Sched& S, const Epi& E) {
;     ...
;             PG8_LDB(B0, 0, 0); PG8_SCHED; PG8_LDA(At, 0, 0); PG8_STAGE(PG8_SA(1, 1), a1 + hstepA, voffA);
;             PG8_WAIT_L(8); PG8_BAR; PG8_WAIT_L(0); PG8_MMA(0, 0, At, B0); PG8_BAR; PG8_SCHED;
;     ...
;             PG8_LDA(At, 1, 1); PG8_STAGE(PG8_SA(1, 0), a3, voffA);
;             PG8_BAR; PG8_WAIT_L(0); PG8_MMA(1, 0, At, B0); PG8_BAR; PG8_SCHED;
;             PG8_STAGE(PG8_SB(1, 1), b3 + hstepB, voffB);
;             PG8_WAIT_V(6); PG8_BAR; PG8_MMA(1, 1, At, B1); PG8_BAR;
	ds_read_b128 v[148:151], v224 offset:49152
	ds_read_b128 v[152:155], v224 offset:50176
	ds_read_b128 v[156:159], v224 offset:51200
	ds_read_b128 v[160:163], v224 offset:52224
	ds_read_b128 v[164:167], v224 offset:53248
	ds_read_b128 v[168:171], v224 offset:54272
	ds_read_b128 v[172:175], v224 offset:55296
	ds_read_b128 v[176:179], v224 offset:56320
	s_add_i32 s25, s52, s30
	v_lshl_add_u64 v[206:207], v[206:207], 0, s[8:9]
	s_mov_b32 m0, s25
	s_nop 0
	global_load_lds_dwordx4 v[206:207], off
	v_lshl_add_u64 v[206:207], v[208:209], 0, s[8:9]
	s_add_i32 m0, s25, 0x2000
	s_nop 0
	global_load_lds_dwordx4 v[206:207], off
	s_mov_b32 m0, s40
	v_lshl_add_u64 v[206:207], v[210:211], 0, s[8:9]
	global_load_lds_dwordx4 v[206:207], off
	v_lshl_add_u64 v[206:207], v[212:213], 0, s[8:9]
	s_mov_b32 m0, s41
	s_nop 0
	global_load_lds_dwordx4 v[206:207], off
	s_add_u32 s20, s20, 0x80080
	s_addc_u32 s21, s21, 0
	s_add_i32 s24, s24, s30
	s_mov_b32 m0, s24
	s_nop 0
	global_load_lds_dwordx4 v2, s[20:21]
	s_add_i32 m0, s24, 0x2000
	s_nop 0
	global_load_lds_dwordx4 v192, s[20:21]
	s_add_i32 s51, s51, 2
	s_add_u32 s6, s6, 0x100
	s_addc_u32 s7, s7, 0
	s_add_u32 s49, s49, 0x100
	s_addc_u32 s50, s50, 0
	s_cmp_gt_u32 s51, 29
	s_waitcnt lgkmcnt(0)
	s_waitcnt vmcnt(6)
	s_barrier
	v_mfma_f32_16x16x32_bf16 v[64:67], v[132:135], v[148:151], v[64:67]
	v_mfma_f32_16x16x32_bf16 v[60:63], v[140:143], v[148:151], v[60:63]
	v_mfma_f32_16x16x32_bf16 v[52:55], v[132:135], v[156:159], v[52:55]
	v_mfma_f32_16x16x32_bf16 v[44:47], v[140:143], v[156:159], v[44:47]
	v_mfma_f32_16x16x32_bf16 v[36:39], v[132:135], v[164:167], v[36:39]
	v_mfma_f32_16x16x32_bf16 v[28:31], v[140:143], v[164:167], v[28:31]
	v_mfma_f32_16x16x32_bf16 v[20:23], v[132:135], v[172:175], v[20:23]
	v_mfma_f32_16x16x32_bf16 v[12:15], v[140:143], v[172:175], v[12:15]
	v_mfma_f32_16x16x32_bf16 v[64:67], v[136:139], v[152:155], v[64:67]
	v_mfma_f32_16x16x32_bf16 v[60:63], v[144:147], v[152:155], v[60:63]
	v_mfma_f32_16x16x32_bf16 v[52:55], v[136:139], v[160:163], v[52:55]
	v_mfma_f32_16x16x32_bf16 v[44:47], v[144:147], v[160:163], v[44:47]
	v_mfma_f32_16x16x32_bf16 v[36:39], v[136:139], v[168:171], v[36:39]
	v_mfma_f32_16x16x32_bf16 v[28:31], v[144:147], v[168:171], v[28:31]
	v_mfma_f32_16x16x32_bf16 v[20:23], v[136:139], v[176:179], v[20:23]
	v_mfma_f32_16x16x32_bf16 v[12:15], v[144:147], v[176:179], v[12:15]
	v_mfma_f32_16x16x32_bf16 v[56:59], v[180:183], v[148:151], v[56:59]
	v_mfma_f32_16x16x32_bf16 v[48:51], v[188:191], v[148:151], v[48:51]
	v_mfma_f32_16x16x32_bf16 v[40:43], v[180:183], v[156:159], v[40:43]
	v_mfma_f32_16x16x32_bf16 v[32:35], v[188:191], v[156:159], v[32:35]
	v_mfma_f32_16x16x32_bf16 v[24:27], v[180:183], v[164:167], v[24:27]
	v_mfma_f32_16x16x32_bf16 v[16:19], v[188:191], v[164:167], v[16:19]
	v_mfma_f32_16x16x32_bf16 v[8:11], v[180:183], v[172:175], v[8:11]
	v_mfma_f32_16x16x32_bf16 v[4:7], v[188:191], v[172:175], v[4:7]
	v_mfma_f32_16x16x32_bf16 v[56:59], v[184:187], v[152:155], v[56:59]
	v_mfma_f32_16x16x32_bf16 v[48:51], v[202:205], v[152:155], v[48:51]
	v_mfma_f32_16x16x32_bf16 v[40:43], v[184:187], v[160:163], v[40:43]
	v_mfma_f32_16x16x32_bf16 v[32:35], v[202:205], v[160:163], v[32:35]
	v_mfma_f32_16x16x32_bf16 v[24:27], v[184:187], v[168:171], v[24:27]
	v_mfma_f32_16x16x32_bf16 v[16:19], v[202:205], v[168:171], v[16:19]
	v_mfma_f32_16x16x32_bf16 v[8:11], v[184:187], v[176:179], v[8:11]
	v_mfma_f32_16x16x32_bf16 v[4:7], v[202:205], v[176:179], v[4:7]
	s_barrier
	s_setprio 0
.LBB0_966:
	s_setprio 0
	s_add_u32 s20, s6, 0xfff80080
	s_addc_u32 s21, s7, -1
	s_add_i32 s52, 0, 0x10000
	v_add_u32_e32 v144, s52, v1
	ds_read_b128 v[132:135], v144
	ds_read_b128 v[136:139], v144 offset:1024
	ds_read_b128 v[140:143], v144 offset:2048
	ds_read_b128 v[144:147], v144 offset:3072
	s_cmp_eq_u32 s51, 28
	s_cselect_b32 s25, s15, s21
	s_cselect_b32 s24, s47, s20
	s_cselect_b32 s21, s1, s50
	s_cselect_b32 s20, s48, s49
	ds_read_b128 v[148:151], v224
	ds_read_b128 v[152:155], v224 offset:1024
	ds_read_b128 v[156:159], v224 offset:2048
	ds_read_b128 v[160:163], v224 offset:3072
	ds_read_b128 v[164:167], v224 offset:4096
	ds_read_b128 v[168:171], v224 offset:5120
	ds_read_b128 v[172:175], v224 offset:6144
	ds_read_b128 v[176:179], v224 offset:7168
	s_add_i32 s54, 0, 0x14000
	v_add_u32_e32 v202, s54, v1
	ds_read_b128 v[180:183], v202
	ds_read_b128 v[184:187], v202 offset:1024
	ds_read_b128 v[188:191], v202 offset:2048
	ds_read_b128 v[202:205], v202 offset:3072
	s_add_i32 m0, s31, 0xc000
	s_nop 0
	global_load_lds_dwordx4 v198, s[6:7]
	s_add_i32 m0, s31, 0xe000
	s_nop 0
	global_load_lds_dwordx4 v200, s[6:7]
	s_waitcnt lgkmcnt(0)
	s_barrier
; #define PG8_STAGE(bufoff, gbase, voff) do { _Pragma("unroll") for (int _i = 0; _i < 2; ++_i) \
;         __builtin_amdgcn_global_load_lds((const unsigned*)((const char*)(gbase) + (voff)[_i]), (LAS unsigned*)(lds + (bufoff) + ldsw + _i * 8192), 16, 0, 0); } while (0)
; #define PG8_LDA(dst, b, h) do { _Pragma("unroll") for (int m = 0; m < 4; ++m) _Pragma("unroll") for (int k = 0; k < 2; ++k) dst[m][k] = *(const LAS bf16x8*)(lds + PG8_SA(b, h) + aoff + m * 2048 + k * 1024); } while (0)
; #define PG8_LDB(dst, b, h) do { _Pragma("unroll") for (int n = 0; n < 2; ++n) _Pragma("unroll") for (int k = 0; k < 2; ++k) dst[n][k] = *(const LAS bf16x8*)(lds + PG8_SB(b, h) + boff + n * 2048 + k * 1024); } while (0)
; #define PG8_MMA(ai, bj, At, Bt) do { __builtin_amdgcn_s_setprio(1); _Pragma("unroll") for (int m = 0; m < 4; ++m) _Pragma("unroll") for (int n = 0; n < 2; ++n) _Pragma("unroll") for (int k = 0; k < 2; ++k) \
;         acc[ai][bj][m][n] = __builtin_amdgcn_mfma_f32_16x16x32_bf16(Bt[n][k], At[m][k], acc[ai][bj][m][n], 0, 0, 0); __builtin_amdgcn_s_setprio(0); } while (0)
; #define PG8_WAIT_V(n) asm volatile("s_waitcnt vmcnt(" #n ")" ::: "memory")
; #define PG8_WAIT_L(n) asm volatile("s_waitcnt lgkmcnt(" #n ")" ::: "memory")
; #define PG8_BAR __builtin_amdgcn_s_barrier()
; #define PG8_SCHED __builtin_amdgcn_sched_barrier(0)
; template <class Epi, class Sched>
; __device__ __forceinline__ void gemm_phase(LAS unsigned char* lds, const Gemm g, const Sched& S, const Epi& E) {
;     ...
;             PG8_LDB(B0, 0, 0); PG8_SCHED; PG8_LDA(At, 0, 0); PG8_STAGE(PG8_SA(1, 1), a1 + hstepA, voffA);
;             PG8_WAIT_L(8); PG8_BAR; PG8_WAIT_L(0); PG8_MMA(0, 0, At, B0); PG8_BAR; PG8_SCHED;
;             PG8_LDB(B1, 0, 1); PG8_STAGE(PG8_SB(0, 0), b2, voffB);
;             PG8_BAR; PG8_WAIT_L(0); PG8_MMA(0, 1, At, B1); PG8_BAR;
;             PG8_LDA(At, 0, 1); PG8_STAGE(PG8_SA(0, 0), a2, voffA);
;             PG8_BAR; PG8_WAIT_L(0); PG8_MMA(1, 0, At, B0); PG8_BAR; PG8_SCHED;
;             PG8_STAGE(PG8_SB(0, 1), b2 + hstepB, voffB);
;             PG8_WAIT_V(6); PG8_BAR; PG8_MMA(1, 1, At, B1); PG8_BAR;
	v_mfma_f32_16x16x32_bf16 v[128:131], v[132:135], v[148:151], v[128:131]
	v_mfma_f32_16x16x32_bf16 v[124:127], v[140:143], v[148:151], v[124:127]
	v_mfma_f32_16x16x32_bf16 v[112:115], v[132:135], v[156:159], v[112:115]
	v_mfma_f32_16x16x32_bf16 v[108:111], v[140:143], v[156:159], v[108:111]
	v_mfma_f32_16x16x32_bf16 v[100:103], v[132:135], v[164:167], v[100:103]
	v_mfma_f32_16x16x32_bf16 v[92:95], v[140:143], v[164:167], v[92:95]
	v_mfma_f32_16x16x32_bf16 v[84:87], v[132:135], v[172:175], v[84:87]
	v_mfma_f32_16x16x32_bf16 v[76:79], v[140:143], v[172:175], v[76:79]
	v_mfma_f32_16x16x32_bf16 v[128:131], v[136:139], v[152:155], v[128:131]
	v_mfma_f32_16x16x32_bf16 v[124:127], v[144:147], v[152:155], v[124:127]
	v_mfma_f32_16x16x32_bf16 v[112:115], v[136:139], v[160:163], v[112:115]
	v_mfma_f32_16x16x32_bf16 v[108:111], v[144:147], v[160:163], v[108:111]
	v_mfma_f32_16x16x32_bf16 v[100:103], v[136:139], v[168:171], v[100:103]
	v_mfma_f32_16x16x32_bf16 v[92:95], v[144:147], v[168:171], v[92:95]
	v_mfma_f32_16x16x32_bf16 v[84:87], v[136:139], v[176:179], v[84:87]
	v_mfma_f32_16x16x32_bf16 v[76:79], v[144:147], v[176:179], v[76:79]
	v_mfma_f32_16x16x32_bf16 v[120:123], v[180:183], v[148:151], v[120:123]
	v_mfma_f32_16x16x32_bf16 v[116:119], v[188:191], v[148:151], v[116:119]
	v_mfma_f32_16x16x32_bf16 v[104:107], v[180:183], v[156:159], v[104:107]
	v_mfma_f32_16x16x32_bf16 v[96:99], v[188:191], v[156:159], v[96:99]
	v_mfma_f32_16x16x32_bf16 v[88:91], v[180:183], v[164:167], v[88:91]
	v_mfma_f32_16x16x32_bf16 v[80:83], v[188:191], v[164:167], v[80:83]
	v_mfma_f32_16x16x32_bf16 v[72:75], v[180:183], v[172:175], v[72:75]
	v_mfma_f32_16x16x32_bf16 v[68:71], v[188:191], v[172:175], v[68:71]
	v_mfma_f32_16x16x32_bf16 v[120:123], v[184:187], v[152:155], v[120:123]
	v_mfma_f32_16x16x32_bf16 v[116:119], v[202:205], v[152:155], v[116:119]
	v_mfma_f32_16x16x32_bf16 v[104:107], v[184:187], v[160:163], v[104:107]
	v_mfma_f32_16x16x32_bf16 v[96:99], v[202:205], v[160:163], v[96:99]
	v_mfma_f32_16x16x32_bf16 v[88:91], v[184:187], v[168:171], v[88:91]
	v_mfma_f32_16x16x32_bf16 v[80:83], v[202:205], v[168:171], v[80:83]
	v_mfma_f32_16x16x32_bf16 v[72:75], v[184:187], v[176:179], v[72:75]
	v_mfma_f32_16x16x32_bf16 v[68:71], v[202:205], v[176:179], v[68:71]
	s_barrier
	ds_read_b128 v[148:151], v224 offset:16384
	ds_read_b128 v[152:155], v224 offset:17408
	ds_read_b128 v[156:159], v224 offset:18432
	ds_read_b128 v[160:163], v224 offset:19456
	ds_read_b128 v[164:167], v224 offset:20480
	ds_read_b128 v[168:171], v224 offset:21504
	ds_read_b128 v[172:175], v224 offset:22528
	ds_read_b128 v[176:179], v224 offset:23552
	s_add_i32 s52, s52, s30
	v_lshl_add_u64 v[206:207], s[20:21], 0, v[2:3]
	s_mov_b32 m0, s52
	s_nop 0
	global_load_lds_dwordx4 v[206:207], off
	v_lshl_add_u64 v[208:209], s[20:21], 0, v[192:193]
	s_add_i32 m0, s52, 0x2000
	s_nop 0
	global_load_lds_dwordx4 v[208:209], off
	s_mov_b32 m0, s31
	v_lshl_add_u64 v[210:211], s[24:25], 0, v[196:197]
	global_load_lds_dwordx4 v[210:211], off
	v_lshl_add_u64 v[212:213], s[24:25], 0, v[194:195]
	s_mov_b32 m0, s35
	s_nop 0
	global_load_lds_dwordx4 v[212:213], off
	s_add_u32 s52, s20, 0x80000
	s_addc_u32 s53, s21, 0
	s_add_i32 s54, s54, s30
	s_mov_b32 m0, s54
	s_nop 0
	global_load_lds_dwordx4 v2, s[52:53]
	s_add_i32 m0, s54, 0x2000
	s_nop 0
	global_load_lds_dwordx4 v192, s[52:53]
	s_waitcnt lgkmcnt(0)
	s_waitcnt vmcnt(6)
	s_barrier
	v_mfma_f32_16x16x32_bf16 v[64:67], v[132:135], v[148:151], v[64:67]
	v_mfma_f32_16x16x32_bf16 v[60:63], v[140:143], v[148:151], v[60:63]
	v_mfma_f32_16x16x32_bf16 v[52:55], v[132:135], v[156:159], v[52:55]
	v_mfma_f32_16x16x32_bf16 v[44:47], v[140:143], v[156:159], v[44:47]
	v_mfma_f32_16x16x32_bf16 v[36:39], v[132:135], v[164:167], v[36:39]
	v_mfma_f32_16x16x32_bf16 v[28:31], v[140:143], v[164:167], v[28:31]
	v_mfma_f32_16x16x32_bf16 v[20:23], v[132:135], v[172:175], v[20:23]
	v_mfma_f32_16x16x32_bf16 v[12:15], v[140:143], v[172:175], v[12:15]
	v_mfma_f32_16x16x32_bf16 v[64:67], v[136:139], v[152:155], v[64:67]
	v_mfma_f32_16x16x32_bf16 v[60:63], v[144:147], v[152:155], v[60:63]
	v_mfma_f32_16x16x32_bf16 v[52:55], v[136:139], v[160:163], v[52:55]
	v_mfma_f32_16x16x32_bf16 v[44:47], v[144:147], v[160:163], v[44:47]
	v_mfma_f32_16x16x32_bf16 v[36:39], v[136:139], v[168:171], v[36:39]
	v_mfma_f32_16x16x32_bf16 v[28:31], v[144:147], v[168:171], v[28:31]
	v_mfma_f32_16x16x32_bf16 v[20:23], v[136:139], v[176:179], v[20:23]
	v_mfma_f32_16x16x32_bf16 v[12:15], v[144:147], v[176:179], v[12:15]
	v_mfma_f32_16x16x32_bf16 v[56:59], v[180:183], v[148:151], v[56:59]
	v_mfma_f32_16x16x32_bf16 v[48:51], v[188:191], v[148:151], v[48:51]
	v_mfma_f32_16x16x32_bf16 v[40:43], v[180:183], v[156:159], v[40:43]
	v_mfma_f32_16x16x32_bf16 v[32:35], v[188:191], v[156:159], v[32:35]
	v_mfma_f32_16x16x32_bf16 v[24:27], v[180:183], v[164:167], v[24:27]
	v_mfma_f32_16x16x32_bf16 v[16:19], v[188:191], v[164:167], v[16:19]
	v_mfma_f32_16x16x32_bf16 v[8:11], v[180:183], v[172:175], v[8:11]
	v_mfma_f32_16x16x32_bf16 v[4:7], v[188:191], v[172:175], v[4:7]
	v_mfma_f32_16x16x32_bf16 v[56:59], v[184:187], v[152:155], v[56:59]
	v_mfma_f32_16x16x32_bf16 v[48:51], v[202:205], v[152:155], v[48:51]
	v_mfma_f32_16x16x32_bf16 v[40:43], v[184:187], v[160:163], v[40:43]
	v_mfma_f32_16x16x32_bf16 v[32:35], v[202:205], v[160:163], v[32:35]
	v_mfma_f32_16x16x32_bf16 v[24:27], v[184:187], v[168:171], v[24:27]
	v_mfma_f32_16x16x32_bf16 v[16:19], v[202:205], v[168:171], v[16:19]
	v_mfma_f32_16x16x32_bf16 v[8:11], v[184:187], v[176:179], v[8:11]
	v_mfma_f32_16x16x32_bf16 v[4:7], v[202:205], v[176:179], v[4:7]
	s_barrier
; #define PG8_STAGE(bufoff, gbase, voff) do { _Pragma("unroll") for (int _i = 0; _i < 2; ++_i) \
;         __builtin_amdgcn_global_load_lds((const unsigned*)((const char*)(gbase) + (voff)[_i]), (LAS unsigned*)(lds + (bufoff) + ldsw + _i * 8192), 16, 0, 0); } while (0)
; #define PG8_LDA(dst, b, h) do { _Pragma("unroll") for (int m = 0; m < 4; ++m) _Pragma("unroll") for (int k = 0; k < 2; ++k) dst[m][k] = *(const LAS bf16x8*)(lds + PG8_SA(b, h) + aoff + m * 2048 + k * 1024); } while (0)
; #define PG8_LDB(dst, b, h) do { _Pragma("unroll") for (int n = 0; n < 2; ++n) _Pragma("unroll") for (int k = 0; k < 2; ++k) dst[n][k] = *(const LAS bf16x8*)(lds + PG8_SB(b, h) + boff + n * 2048 + k * 1024); } while (0)
; #define PG8_MMA(ai, bj, At, Bt) do { __builtin_amdgcn_s_setprio(1); _Pragma("unroll") for (int m = 0; m < 4; ++m) _Pragma("unroll") for (int n = 0; n < 2; ++n) _Pragma("unroll") for (int k = 0; k < 2; ++k) \
;         acc[ai][bj][m][n] = __builtin_amdgcn_mfma_f32_16x16x32_bf16(Bt[n][k], At[m][k], acc[ai][bj][m][n], 0, 0, 0); __builtin_amdgcn_s_setprio(0); } while (0)
; #define PG8_WAIT_V(n) asm volatile("s_waitcnt vmcnt(" #n ")" ::: "memory")
; #define PG8_WAIT_L(n) asm volatile("s_waitcnt lgkmcnt(" #n ")" ::: "memory")
; #define PG8_BAR __builtin_amdgcn_s_barrier()
; #define PG8_SCHED __builtin_amdgcn_sched_barrier(0)
; template <class Epi, class Sched>
; __device__ __forceinline__ void gemm_phase(LAS unsigned char* lds, const Gemm g, const Sched& S, const Epi& E) {
;     ...
;             PG8_LDB(B0, 1, 0); PG8_SCHED; PG8_LDA(At, 1, 0); PG8_STAGE(PG8_SA(0, 1), a2 + hstepA, voffA);
;             PG8_WAIT_L(8); PG8_BAR; PG8_WAIT_L(0); PG8_MMA(0, 0, At, B0); PG8_BAR; PG8_SCHED;
;             PG8_LDB(B1, 1, 1); PG8_STAGE(PG8_SB(1, 0), b3, voffB);
;             PG8_BAR; PG8_WAIT_L(0); PG8_MMA(0, 1, At, B1); PG8_BAR;
;             PG8_LDA(At, 1, 1); PG8_STAGE(PG8_SA(1, 0), a3, voffA);
;             PG8_BAR; PG8_WAIT_L(0); PG8_MMA(1, 0, At, B0); PG8_BAR; PG8_SCHED;
;             PG8_STAGE(PG8_SB(1, 1), b3 + hstepB, voffB);
;             PG8_WAIT_V(6); PG8_BAR; PG8_MMA(1, 1, At, B1); PG8_BAR;
	s_add_i32 s52, 0, 0x18000
	v_add_u32_e32 v144, s52, v1
	ds_read_b128 v[132:135], v144
	ds_read_b128 v[136:139], v144 offset:1024
	ds_read_b128 v[140:143], v144 offset:2048
	ds_read_b128 v[144:147], v144 offset:3072
	s_add_u32 s24, s24, 0x80000
	s_addc_u32 s25, s25, 0
	ds_read_b128 v[148:151], v224 offset:32768
	ds_read_b128 v[152:155], v224 offset:33792
	ds_read_b128 v[156:159], v224 offset:34816
	ds_read_b128 v[160:163], v224 offset:35840
	ds_read_b128 v[164:167], v224 offset:36864
	ds_read_b128 v[168:171], v224 offset:37888
	ds_read_b128 v[172:175], v224 offset:38912
	ds_read_b128 v[176:179], v224 offset:39936
	s_mov_b32 m0, s36
	s_nop 0
	global_load_lds_dwordx4 v196, s[24:25]
	s_mov_b32 m0, s37
	s_nop 0
	global_load_lds_dwordx4 v194, s[24:25]
	s_add_i32 s24, 0, 0x1c000
	v_add_u32_e32 v202, s24, v1
	ds_read_b128 v[180:183], v202
	ds_read_b128 v[184:187], v202 offset:1024
	ds_read_b128 v[188:191], v202 offset:2048
	ds_read_b128 v[202:205], v202 offset:3072
	s_waitcnt lgkmcnt(0)
	s_barrier
	v_mfma_f32_16x16x32_bf16 v[128:131], v[132:135], v[148:151], v[128:131]
	v_mfma_f32_16x16x32_bf16 v[124:127], v[140:143], v[148:151], v[124:127]
	v_mfma_f32_16x16x32_bf16 v[112:115], v[132:135], v[156:159], v[112:115]
	v_mfma_f32_16x16x32_bf16 v[108:111], v[140:143], v[156:159], v[108:111]
	v_mfma_f32_16x16x32_bf16 v[100:103], v[132:135], v[164:167], v[100:103]
	v_mfma_f32_16x16x32_bf16 v[92:95], v[140:143], v[164:167], v[92:95]
	v_mfma_f32_16x16x32_bf16 v[84:87], v[132:135], v[172:175], v[84:87]
	v_mfma_f32_16x16x32_bf16 v[76:79], v[140:143], v[172:175], v[76:79]
	v_mfma_f32_16x16x32_bf16 v[128:131], v[136:139], v[152:155], v[128:131]
	v_mfma_f32_16x16x32_bf16 v[124:127], v[144:147], v[152:155], v[124:127]
	v_mfma_f32_16x16x32_bf16 v[112:115], v[136:139], v[160:163], v[112:115]
	v_mfma_f32_16x16x32_bf16 v[108:111], v[144:147], v[160:163], v[108:111]
	v_mfma_f32_16x16x32_bf16 v[100:103], v[136:139], v[168:171], v[100:103]
	v_mfma_f32_16x16x32_bf16 v[92:95], v[144:147], v[168:171], v[92:95]
	v_mfma_f32_16x16x32_bf16 v[84:87], v[136:139], v[176:179], v[84:87]
	v_mfma_f32_16x16x32_bf16 v[76:79], v[144:147], v[176:179], v[76:79]
	v_mfma_f32_16x16x32_bf16 v[120:123], v[180:183], v[148:151], v[120:123]
	v_mfma_f32_16x16x32_bf16 v[116:119], v[188:191], v[148:151], v[116:119]
	v_mfma_f32_16x16x32_bf16 v[104:107], v[180:183], v[156:159], v[104:107]
	v_mfma_f32_16x16x32_bf16 v[96:99], v[188:191], v[156:159], v[96:99]
	v_mfma_f32_16x16x32_bf16 v[88:91], v[180:183], v[164:167], v[88:91]
	v_mfma_f32_16x16x32_bf16 v[80:83], v[188:191], v[164:167], v[80:83]
	v_mfma_f32_16x16x32_bf16 v[72:75], v[180:183], v[172:175], v[72:75]
	v_mfma_f32_16x16x32_bf16 v[68:71], v[188:191], v[172:175], v[68:71]
	v_mfma_f32_16x16x32_bf16 v[120:123], v[184:187], v[152:155], v[120:123]
	v_mfma_f32_16x16x32_bf16 v[116:119], v[202:205], v[152:155], v[116:119]
	v_mfma_f32_16x16x32_bf16 v[104:107], v[184:187], v[160:163], v[104:107]
	v_mfma_f32_16x16x32_bf16 v[96:99], v[202:205], v[160:163], v[96:99]
	v_mfma_f32_16x16x32_bf16 v[88:91], v[184:187], v[168:171], v[88:91]
	v_mfma_f32_16x16x32_bf16 v[80:83], v[202:205], v[168:171], v[80:83]
	v_mfma_f32_16x16x32_bf16 v[72:75], v[184:187], v[176:179], v[72:75]
	v_mfma_f32_16x16x32_bf16 v[68:71], v[202:205], v[176:179], v[68:71]
	s_barrier
	ds_read_b128 v[148:151], v224 offset:49152
	ds_read_b128 v[152:155], v224 offset:50176
	ds_read_b128 v[156:159], v224 offset:51200
	ds_read_b128 v[160:163], v224 offset:52224
	ds_read_b128 v[164:167], v224 offset:53248
	ds_read_b128 v[168:171], v224 offset:54272
	ds_read_b128 v[172:175], v224 offset:55296
	ds_read_b128 v[176:179], v224 offset:56320
	s_add_i32 s25, s52, s30
	v_lshl_add_u64 v[206:207], v[206:207], 0, s[8:9]
	s_mov_b32 m0, s25
	s_nop 0
	global_load_lds_dwordx4 v[206:207], off
	v_lshl_add_u64 v[206:207], v[208:209], 0, s[8:9]
	s_add_i32 m0, s25, 0x2000
	s_nop 0
	global_load_lds_dwordx4 v[206:207], off
	s_mov_b32 m0, s40
	v_lshl_add_u64 v[206:207], v[210:211], 0, s[8:9]
	global_load_lds_dwordx4 v[206:207], off
	v_lshl_add_u64 v[206:207], v[212:213], 0, s[8:9]
	s_mov_b32 m0, s41
	s_nop 0
	global_load_lds_dwordx4 v[206:207], off
	s_add_u32 s20, s20, 0x80080
	s_addc_u32 s21, s21, 0
	s_add_i32 s24, s24, s30
	s_mov_b32 m0, s24
	s_nop 0
	global_load_lds_dwordx4 v2, s[20:21]
	s_add_i32 m0, s24, 0x2000
	s_nop 0
	global_load_lds_dwordx4 v192, s[20:21]
	s_add_i32 s51, s51, 2
	s_add_u32 s6, s6, 0x100
	s_addc_u32 s7, s7, 0
	s_add_u32 s49, s49, 0x100
	s_addc_u32 s50, s50, 0
	s_cmp_gt_u32 s51, 29
	s_waitcnt lgkmcnt(0)
	s_waitcnt vmcnt(6)
	s_barrier
	v_mfma_f32_16x16x32_bf16 v[64:67], v[132:135], v[148:151], v[64:67]
	v_mfma_f32_16x16x32_bf16 v[60:63], v[140:143], v[148:151], v[60:63]
	v_mfma_f32_16x16x32_bf16 v[52:55], v[132:135], v[156:159], v[52:55]
	v_mfma_f32_16x16x32_bf16 v[44:47], v[140:143], v[156:159], v[44:47]
	v_mfma_f32_16x16x32_bf16 v[36:39], v[132:135], v[164:167], v[36:39]
	v_mfma_f32_16x16x32_bf16 v[28:31], v[140:143], v[164:167], v[28:31]
	v_mfma_f32_16x16x32_bf16 v[20:23], v[132:135], v[172:175], v[20:23]
	v_mfma_f32_16x16x32_bf16 v[12:15], v[140:143], v[172:175], v[12:15]
	v_mfma_f32_16x16x32_bf16 v[64:67], v[136:139], v[152:155], v[64:67]
	v_mfma_f32_16x16x32_bf16 v[60:63], v[144:147], v[152:155], v[60:63]
	v_mfma_f32_16x16x32_bf16 v[52:55], v[136:139], v[160:163], v[52:55]
	v_mfma_f32_16x16x32_bf16 v[44:47], v[144:147], v[160:163], v[44:47]
	v_mfma_f32_16x16x32_bf16 v[36:39], v[136:139], v[168:171], v[36:39]
	v_mfma_f32_16x16x32_bf16 v[28:31], v[144:147], v[168:171], v[28:31]
	v_mfma_f32_16x16x32_bf16 v[20:23], v[136:139], v[176:179], v[20:23]
	v_mfma_f32_16x16x32_bf16 v[12:15], v[144:147], v[176:179], v[12:15]
	v_mfma_f32_16x16x32_bf16 v[56:59], v[180:183], v[148:151], v[56:59]
	v_mfma_f32_16x16x32_bf16 v[48:51], v[188:191], v[148:151], v[48:51]
	v_mfma_f32_16x16x32_bf16 v[40:43], v[180:183], v[156:159], v[40:43]
	v_mfma_f32_16x16x32_bf16 v[32:35], v[188:191], v[156:159], v[32:35]
	v_mfma_f32_16x16x32_bf16 v[24:27], v[180:183], v[164:167], v[24:27]
	v_mfma_f32_16x16x32_bf16 v[16:19], v[188:191], v[164:167], v[16:19]
	v_mfma_f32_16x16x32_bf16 v[8:11], v[180:183], v[172:175], v[8:11]
	v_mfma_f32_16x16x32_bf16 v[4:7], v[188:191], v[172:175], v[4:7]
	v_mfma_f32_16x16x32_bf16 v[56:59], v[184:187], v[152:155], v[56:59]
	v_mfma_f32_16x16x32_bf16 v[48:51], v[202:205], v[152:155], v[48:51]
	v_mfma_f32_16x16x32_bf16 v[40:43], v[184:187], v[160:163], v[40:43]
	v_mfma_f32_16x16x32_bf16 v[32:35], v[202:205], v[160:163], v[32:35]
	v_mfma_f32_16x16x32_bf16 v[24:27], v[184:187], v[168:171], v[24:27]
	v_mfma_f32_16x16x32_bf16 v[16:19], v[202:205], v[168:171], v[16:19]
	v_mfma_f32_16x16x32_bf16 v[8:11], v[184:187], v[176:179], v[8:11]
	v_mfma_f32_16x16x32_bf16 v[4:7], v[202:205], v[176:179], v[4:7]
	s_barrier
	s_cbranch_scc0 .LBB0_966
	s_setprio 0
	s_cmpk_gt_u32 s2, 0xff
	s_cbranch_scc1 .Lalign_a_966
	s_barrier

; #define PG8_STAGE(bufoff, gbase, voff) do { _Pragma("unroll") for (int _i = 0; _i < 2; ++_i) \
;         __builtin_amdgcn_global_load_lds((const unsigned*)((const char*)(gbase) + (voff)[_i]), (LAS unsigned*)(lds + (bufoff) + ldsw + _i * 8192), 16, 0, 0); } while (0)
; #define PG8_LDA(dst, b, h) do { _Pragma("unroll") for (int m = 0; m < 4; ++m) _Pragma("unroll") for (int k = 0; k < 2; ++k) dst[m][k] = *(const LAS bf16x8*)(lds + PG8_SA(b, h) + aoff + m * 2048 + k * 1024); } while (0)
; #define PG8_LDB(dst, b, h) do { _Pragma("unroll") for (int n = 0; n < 2; ++n) _Pragma("unroll") for (int k = 0; k < 2; ++k) dst[n][k] = *(const LAS bf16x8*)(lds + PG8_SB(b, h) + boff + n * 2048 + k * 1024); } while (0)
; #define PG8_MMA(ai, bj, At, Bt) do { __builtin_amdgcn_s_setprio(1); _Pragma("unroll") for (int m = 0; m < 4; ++m) _Pragma("unroll") for (int n = 0; n < 2; ++n) _Pragma("unroll") for (int k = 0; k < 2; ++k) \
;         acc[ai][bj][m][n] = __builtin_amdgcn_mfma_f32_16x16x32_bf16(Bt[n][k], At[m][k], acc[ai][bj][m][n], 0, 0, 0); __builtin_amdgcn_s_setprio(0); } while (0)
; #define PG8_BAR __builtin_amdgcn_s_barrier()
; template <class Epi, class Sched>
; __device__ __forceinline__ void gemm_phase(LAS unsigned char* lds, const Gemm g, const Sched& S, const Epi& E) {
;     ...
;         const bool has_next = S.next(ui + 1, nxt);
;         const char* nA = has_next ? (const char*)g.A + (size_t)nxt.pm * tstepA : cA; const char* nB = has_next ? (const char*)g.Bt + (size_t)nxt.pn * tstepB : cB;
;         for (int t = 0; t < nt; t += 2) {
;             const bool last = (t == nt - 2);
;             const char* a1 = cA + (size_t)(t + 1) * kstep;
;             const char* a2 = last ? nA : cA + (size_t)(t + 2) * kstep; const char* b2 = last ? nB : cB + (size_t)(t + 2) * kstep;
;             const char* a3 = a2 + kstep; const char* b3 = b2 + kstep;
;             if (last && has_next) S.a_ready(nxt);
;             PG8_LDB(B0, 0, 0); PG8_SCHED; PG8_LDA(At, 0, 0); PG8_STAGE(PG8_SA(1, 1), a1 + hstepA, voffA);
;             PG8_WAIT_L(8); PG8_BAR; PG8_WAIT_L(0); PG8_MMA(0, 0, At, B0); PG8_BAR; PG8_SCHED;
;             PG8_LDB(B1, 0, 1); PG8_STAGE(PG8_SB(0, 0), b2, voffB);
;             PG8_BAR; PG8_WAIT_L(0); PG8_MMA(0, 1, At, B1); PG8_BAR;
;             PG8_LDA(At, 0, 1); PG8_STAGE(PG8_SA(0, 0), a2, voffA);
;             PG8_BAR; PG8_WAIT_L(0); PG8_MMA(1, 0, At, B0); PG8_BAR; PG8_SCHED;
.LBB0_1093:
	v_mov_b64_e32 v[4:5], 0x900
	s_ashr_i32 s5, s4, 31
	v_cmp_lt_i64_e32 vcc, s[6:7], v[4:5]
	s_lshl_b64 s[6:7], s[4:5], 20
	s_add_u32 s6, s88, s6
	s_addc_u32 s7, s89, s7
	s_and_b64 s[14:15], vcc, exec
	s_cselect_b32 s5, s7, s19
	s_cselect_b32 s49, s6, s18
	s_ashr_i32 s1, s0, 31
	s_lshl_b64 s[14:15], s[0:1], 20
	s_add_u32 s14, s28, s14
	s_addc_u32 s15, s29, s15
	s_and_b64 s[24:25], vcc, exec
	s_cselect_b32 s1, s15, s21
	s_cselect_b32 s50, s14, s20
	s_add_u32 s18, s18, 0x80080
	s_addc_u32 s19, s19, 0
	s_add_u32 s51, s20, 0x100
	s_addc_u32 s52, s21, 0
	s_mov_b32 s53, -2
	s_setprio 0
	s_add_u32 s20, s18, 0xfff80080
	s_addc_u32 s21, s19, -1
	s_add_i32 s54, 0, 0x10000
	v_add_u32_e32 v146, s54, v1
	ds_read_b128 v[142:145], v146
	ds_read_b128 v[150:153], v146 offset:1024
	ds_read_b128 v[154:157], v146 offset:2048
	ds_read_b128 v[158:161], v146 offset:3072
	s_cmp_eq_u32 s53, 28
	s_cselect_b32 s25, s5, s21
	s_cselect_b32 s24, s49, s20
	s_cselect_b32 s21, s1, s52
	s_cselect_b32 s20, s50, s51
	ds_read_b128 v[162:165], v148
	ds_read_b128 v[166:169], v148 offset:1024
	ds_read_b128 v[170:173], v148 offset:2048
	ds_read_b128 v[174:177], v148 offset:3072
	ds_read_b128 v[178:181], v148 offset:4096
	ds_read_b128 v[182:185], v148 offset:5120
	ds_read_b128 v[186:189], v148 offset:6144
	ds_read_b128 v[190:193], v148 offset:7168
	s_add_i32 s56, 0, 0x14000
	v_add_u32_e32 v146, s56, v1
	ds_read_b128 v[194:197], v146
	ds_read_b128 v[198:201], v146 offset:1024
	ds_read_b128 v[202:205], v146 offset:2048
	ds_read_b128 v[206:209], v146 offset:3072
	s_add_i32 m0, s31, 0xc000
	s_nop 0
	global_load_lds_dwordx4 v138, s[18:19]
	s_add_i32 m0, s31, 0xe000
	s_nop 0
	global_load_lds_dwordx4 v140, s[18:19]
	s_waitcnt lgkmcnt(0)
	s_barrier
	v_mfma_f32_16x16x32_bf16 v[128:131], v[142:145], v[162:165], 0
	v_mfma_f32_16x16x32_bf16 v[124:127], v[154:157], v[162:165], 0
	v_mfma_f32_16x16x32_bf16 v[120:123], v[142:145], v[170:173], 0
	v_mfma_f32_16x16x32_bf16 v[112:115], v[154:157], v[170:173], 0
	v_mfma_f32_16x16x32_bf16 v[104:107], v[142:145], v[178:181], 0
	v_mfma_f32_16x16x32_bf16 v[96:99], v[154:157], v[178:181], 0
	v_mfma_f32_16x16x32_bf16 v[88:91], v[142:145], v[186:189], 0
	v_mfma_f32_16x16x32_bf16 v[80:83], v[154:157], v[186:189], 0
	v_mfma_f32_16x16x32_bf16 v[128:131], v[150:153], v[166:169], v[128:131]
	v_mfma_f32_16x16x32_bf16 v[124:127], v[158:161], v[166:169], v[124:127]
	v_mfma_f32_16x16x32_bf16 v[120:123], v[150:153], v[174:177], v[120:123]
	v_mfma_f32_16x16x32_bf16 v[112:115], v[158:161], v[174:177], v[112:115]
	v_mfma_f32_16x16x32_bf16 v[104:107], v[150:153], v[182:185], v[104:107]
	v_mfma_f32_16x16x32_bf16 v[96:99], v[158:161], v[182:185], v[96:99]
	v_mfma_f32_16x16x32_bf16 v[88:91], v[150:153], v[190:193], v[88:91]
	v_mfma_f32_16x16x32_bf16 v[80:83], v[158:161], v[190:193], v[80:83]
	v_mfma_f32_16x16x32_bf16 v[116:119], v[194:197], v[162:165], 0
	v_mfma_f32_16x16x32_bf16 v[108:111], v[202:205], v[162:165], 0
	v_mfma_f32_16x16x32_bf16 v[100:103], v[194:197], v[170:173], 0
	v_mfma_f32_16x16x32_bf16 v[92:95], v[202:205], v[170:173], 0
	v_mfma_f32_16x16x32_bf16 v[84:87], v[194:197], v[178:181], 0
	v_mfma_f32_16x16x32_bf16 v[76:79], v[202:205], v[178:181], 0
	v_mfma_f32_16x16x32_bf16 v[72:75], v[194:197], v[186:189], 0
	v_mfma_f32_16x16x32_bf16 v[68:71], v[202:205], v[186:189], 0
	v_mfma_f32_16x16x32_bf16 v[116:119], v[198:201], v[166:169], v[116:119]
	v_mfma_f32_16x16x32_bf16 v[108:111], v[206:209], v[166:169], v[108:111]
	v_mfma_f32_16x16x32_bf16 v[100:103], v[198:201], v[174:177], v[100:103]
	v_mfma_f32_16x16x32_bf16 v[92:95], v[206:209], v[174:177], v[92:95]
	v_mfma_f32_16x16x32_bf16 v[84:87], v[198:201], v[182:185], v[84:87]
	v_mfma_f32_16x16x32_bf16 v[76:79], v[206:209], v[182:185], v[76:79]
	v_mfma_f32_16x16x32_bf16 v[72:75], v[198:201], v[190:193], v[72:75]
	v_mfma_f32_16x16x32_bf16 v[68:71], v[206:209], v[190:193], v[68:71]
	s_barrier
	ds_read_b128 v[162:165], v148 offset:16384
	ds_read_b128 v[166:169], v148 offset:17408
	ds_read_b128 v[170:173], v148 offset:18432
	ds_read_b128 v[174:177], v148 offset:19456
	ds_read_b128 v[178:181], v148 offset:20480
	ds_read_b128 v[182:185], v148 offset:21504
	ds_read_b128 v[186:189], v148 offset:22528
	ds_read_b128 v[190:193], v148 offset:23552
	s_add_i32 s54, s54, s30
	v_lshl_add_u64 v[146:147], s[20:21], 0, v[2:3]
	s_mov_b32 m0, s54
	v_lshl_add_u64 v[210:211], s[20:21], 0, v[132:133]
	global_load_lds_dwordx4 v[146:147], off
	s_add_i32 m0, s54, 0x2000
	s_nop 0
	global_load_lds_dwordx4 v[210:211], off
	s_mov_b32 m0, s31
	v_lshl_add_u64 v[212:213], s[24:25], 0, v[136:137]
	global_load_lds_dwordx4 v[212:213], off
	v_lshl_add_u64 v[216:217], s[24:25], 0, v[134:135]
	s_mov_b32 m0, s35
	s_nop 0
	global_load_lds_dwordx4 v[216:217], off
	s_add_u32 s54, s20, 0x80000
	s_addc_u32 s55, s21, 0
	s_add_i32 s56, s56, s30
	s_mov_b32 m0, s56
	s_nop 0
	global_load_lds_dwordx4 v2, s[54:55]
	s_add_i32 m0, s56, 0x2000
	s_nop 0
	global_load_lds_dwordx4 v132, s[54:55]
	s_waitcnt lgkmcnt(0)
	s_waitcnt vmcnt(6)
	s_barrier
; #define PG8_STAGE(bufoff, gbase, voff) do { _Pragma("unroll") for (int _i = 0; _i < 2; ++_i) \
;         __builtin_amdgcn_global_load_lds((const unsigned*)((const char*)(gbase) + (voff)[_i]), (LAS unsigned*)(lds + (bufoff) + ldsw + _i * 8192), 16, 0, 0); } while (0)
; #define PG8_LDA(dst, b, h) do { _Pragma("unroll") for (int m = 0; m < 4; ++m) _Pragma("unroll") for (int k = 0; k < 2; ++k) dst[m][k] = *(const LAS bf16x8*)(lds + PG8_SA(b, h) + aoff + m * 2048 + k * 1024); } while (0)
; #define PG8_LDB(dst, b, h) do { _Pragma("unroll") for (int n = 0; n < 2; ++n) _Pragma("unroll") for (int k = 0; k < 2; ++k) dst[n][k] = *(const LAS bf16x8*)(lds + PG8_SB(b, h) + boff + n * 2048 + k * 1024); } while (0)
; #define PG8_MMA(ai, bj, At, Bt) do { __builtin_amdgcn_s_setprio(1); _Pragma("unroll") for (int m = 0; m < 4; ++m) _Pragma("unroll") for (int n = 0; n < 2; ++n) _Pragma("unroll") for (int k = 0; k < 2; ++k) \
;         acc[ai][bj][m][n] = __builtin_amdgcn_mfma_f32_16x16x32_bf16(Bt[n][k], At[m][k], acc[ai][bj][m][n], 0, 0, 0); __builtin_amdgcn_s_setprio(0); } while (0)
; #define PG8_WAIT_V(n) asm volatile("s_waitcnt vmcnt(" #n ")" ::: "memory")
; #define PG8_WAIT_L(n) asm volatile("s_waitcnt lgkmcnt(" #n ")" ::: "memory")
; #define PG8_BAR __builtin_amdgcn_s_barrier()
; #define PG8_SCHED __builtin_amdgcn_sched_barrier(0)
; template <class Epi, class Sched>
; __device__ __forceinline__ void gemm_phase(LAS unsigned char* lds, const Gemm g, const Sched& S, const Epi& E) {
;     ...
;             PG8_BAR; PG8_WAIT_L(0); PG8_MMA(1, 0, At, B0); PG8_BAR; PG8_SCHED;
;             PG8_STAGE(PG8_SB(0, 1), b2 + hstepB, voffB);
;             PG8_WAIT_V(6); PG8_BAR; PG8_MMA(1, 1, At, B1); PG8_BAR;
;             PG8_LDB(B0, 1, 0); PG8_SCHED; PG8_LDA(At, 1, 0); PG8_STAGE(PG8_SA(0, 1), a2 + hstepA, voffA);
;             PG8_WAIT_L(8); PG8_BAR; PG8_WAIT_L(0); PG8_MMA(0, 0, At, B0); PG8_BAR; PG8_SCHED;
;             PG8_LDB(B1, 1, 1); PG8_STAGE(PG8_SB(1, 0), b3, voffB);
;             PG8_BAR; PG8_WAIT_L(0); PG8_MMA(0, 1, At, B1); PG8_BAR;
	v_mfma_f32_16x16x32_bf16 v[64:67], v[142:145], v[162:165], 0
	v_mfma_f32_16x16x32_bf16 v[60:63], v[154:157], v[162:165], 0
	v_mfma_f32_16x16x32_bf16 v[56:59], v[142:145], v[170:173], 0
	v_mfma_f32_16x16x32_bf16 v[48:51], v[154:157], v[170:173], 0
	v_mfma_f32_16x16x32_bf16 v[40:43], v[142:145], v[178:181], 0
	v_mfma_f32_16x16x32_bf16 v[32:35], v[154:157], v[178:181], 0
	v_mfma_f32_16x16x32_bf16 v[24:27], v[142:145], v[186:189], 0
	v_mfma_f32_16x16x32_bf16 v[16:19], v[154:157], v[186:189], 0
	v_mfma_f32_16x16x32_bf16 v[64:67], v[150:153], v[166:169], v[64:67]
	v_mfma_f32_16x16x32_bf16 v[60:63], v[158:161], v[166:169], v[60:63]
	v_mfma_f32_16x16x32_bf16 v[56:59], v[150:153], v[174:177], v[56:59]
	v_mfma_f32_16x16x32_bf16 v[48:51], v[158:161], v[174:177], v[48:51]
	v_mfma_f32_16x16x32_bf16 v[40:43], v[150:153], v[182:185], v[40:43]
	v_mfma_f32_16x16x32_bf16 v[32:35], v[158:161], v[182:185], v[32:35]
	v_mfma_f32_16x16x32_bf16 v[24:27], v[150:153], v[190:193], v[24:27]
	v_mfma_f32_16x16x32_bf16 v[16:19], v[158:161], v[190:193], v[16:19]
	v_mfma_f32_16x16x32_bf16 v[52:55], v[194:197], v[162:165], 0
	v_mfma_f32_16x16x32_bf16 v[44:47], v[202:205], v[162:165], 0
	v_mfma_f32_16x16x32_bf16 v[36:39], v[194:197], v[170:173], 0
	v_mfma_f32_16x16x32_bf16 v[28:31], v[202:205], v[170:173], 0
	v_mfma_f32_16x16x32_bf16 v[20:23], v[194:197], v[178:181], 0
	v_mfma_f32_16x16x32_bf16 v[12:15], v[202:205], v[178:181], 0
	v_mfma_f32_16x16x32_bf16 v[8:11], v[194:197], v[186:189], 0
	v_mfma_f32_16x16x32_bf16 v[4:7], v[202:205], v[186:189], 0
	v_mfma_f32_16x16x32_bf16 v[52:55], v[198:201], v[166:169], v[52:55]
	v_mfma_f32_16x16x32_bf16 v[44:47], v[206:209], v[166:169], v[44:47]
	v_mfma_f32_16x16x32_bf16 v[36:39], v[198:201], v[174:177], v[36:39]
	v_mfma_f32_16x16x32_bf16 v[28:31], v[206:209], v[174:177], v[28:31]
	v_mfma_f32_16x16x32_bf16 v[20:23], v[198:201], v[182:185], v[20:23]
	v_mfma_f32_16x16x32_bf16 v[12:15], v[206:209], v[182:185], v[12:15]
	v_mfma_f32_16x16x32_bf16 v[8:11], v[198:201], v[190:193], v[8:11]
	v_mfma_f32_16x16x32_bf16 v[4:7], v[206:209], v[190:193], v[4:7]
	s_barrier
	s_add_i32 s54, 0, 0x18000
	v_add_u32_e32 v149, s54, v1
	ds_read_b128 v[142:145], v149
	ds_read_b128 v[150:153], v149 offset:1024
	ds_read_b128 v[154:157], v149 offset:2048
	ds_read_b128 v[158:161], v149 offset:3072
	s_add_u32 s24, s24, 0x80000
	s_addc_u32 s25, s25, 0
	ds_read_b128 v[162:165], v148 offset:32768
	ds_read_b128 v[166:169], v148 offset:33792
	ds_read_b128 v[170:173], v148 offset:34816
	ds_read_b128 v[174:177], v148 offset:35840
	ds_read_b128 v[178:181], v148 offset:36864
	ds_read_b128 v[182:185], v148 offset:37888
	ds_read_b128 v[186:189], v148 offset:38912
	ds_read_b128 v[190:193], v148 offset:39936
	s_mov_b32 m0, s36
	s_nop 0
	global_load_lds_dwordx4 v136, s[24:25]
	s_mov_b32 m0, s37
	s_nop 0
	global_load_lds_dwordx4 v134, s[24:25]
	s_add_i32 s24, 0, 0x1c000
	v_add_u32_e32 v149, s24, v1
	ds_read_b128 v[194:197], v149
	ds_read_b128 v[198:201], v149 offset:1024
	ds_read_b128 v[202:205], v149 offset:2048
	ds_read_b128 v[206:209], v149 offset:3072
	s_waitcnt lgkmcnt(0)
	s_barrier
	v_mfma_f32_16x16x32_bf16 v[128:131], v[142:145], v[162:165], v[128:131]
	v_mfma_f32_16x16x32_bf16 v[124:127], v[154:157], v[162:165], v[124:127]
	v_mfma_f32_16x16x32_bf16 v[120:123], v[142:145], v[170:173], v[120:123]
	v_mfma_f32_16x16x32_bf16 v[112:115], v[154:157], v[170:173], v[112:115]
	v_mfma_f32_16x16x32_bf16 v[104:107], v[142:145], v[178:181], v[104:107]
	v_mfma_f32_16x16x32_bf16 v[96:99], v[154:157], v[178:181], v[96:99]
	v_mfma_f32_16x16x32_bf16 v[88:91], v[142:145], v[186:189], v[88:91]
	v_mfma_f32_16x16x32_bf16 v[80:83], v[154:157], v[186:189], v[80:83]
	v_mfma_f32_16x16x32_bf16 v[128:131], v[150:153], v[166:169], v[128:131]
	v_mfma_f32_16x16x32_bf16 v[124:127], v[158:161], v[166:169], v[124:127]
	v_mfma_f32_16x16x32_bf16 v[120:123], v[150:153], v[174:177], v[120:123]
	v_mfma_f32_16x16x32_bf16 v[112:115], v[158:161], v[174:177], v[112:115]
	v_mfma_f32_16x16x32_bf16 v[104:107], v[150:153], v[182:185], v[104:107]
	v_mfma_f32_16x16x32_bf16 v[96:99], v[158:161], v[182:185], v[96:99]
	v_mfma_f32_16x16x32_bf16 v[88:91], v[150:153], v[190:193], v[88:91]
	v_mfma_f32_16x16x32_bf16 v[80:83], v[158:161], v[190:193], v[80:83]
	v_mfma_f32_16x16x32_bf16 v[116:119], v[194:197], v[162:165], v[116:119]
	v_mfma_f32_16x16x32_bf16 v[108:111], v[202:205], v[162:165], v[108:111]
	v_mfma_f32_16x16x32_bf16 v[100:103], v[194:197], v[170:173], v[100:103]
	v_mfma_f32_16x16x32_bf16 v[92:95], v[202:205], v[170:173], v[92:95]
	v_mfma_f32_16x16x32_bf16 v[84:87], v[194:197], v[178:181], v[84:87]
	v_mfma_f32_16x16x32_bf16 v[76:79], v[202:205], v[178:181], v[76:79]
	v_mfma_f32_16x16x32_bf16 v[72:75], v[194:197], v[186:189], v[72:75]
	v_mfma_f32_16x16x32_bf16 v[68:71], v[202:205], v[186:189], v[68:71]
	v_mfma_f32_16x16x32_bf16 v[116:119], v[198:201], v[166:169], v[116:119]
	v_mfma_f32_16x16x32_bf16 v[108:111], v[206:209], v[166:169], v[108:111]
	v_mfma_f32_16x16x32_bf16 v[100:103], v[198:201], v[174:177], v[100:103]
	v_mfma_f32_16x16x32_bf16 v[92:95], v[206:209], v[174:177], v[92:95]
	v_mfma_f32_16x16x32_bf16 v[84:87], v[198:201], v[182:185], v[84:87]
	v_mfma_f32_16x16x32_bf16 v[76:79], v[206:209], v[182:185], v[76:79]
	v_mfma_f32_16x16x32_bf16 v[72:75], v[198:201], v[190:193], v[72:75]
	v_mfma_f32_16x16x32_bf16 v[68:71], v[206:209], v[190:193], v[68:71]
	s_barrier
; #define PG8_STAGE(bufoff, gbase, voff) do { _Pragma("unroll") for (int _i = 0; _i < 2; ++_i) \
;         __builtin_amdgcn_global_load_lds((const unsigned*)((const char*)(gbase) + (voff)[_i]), (LAS unsigned*)(lds + (bufoff) + ldsw + _i * 8192), 16, 0, 0); } while (0)
; #define PG8_LDA(dst, b, h) do { _Pragma("unroll") for (int m = 0; m < 4; ++m) _Pragma("unroll") for (int k = 0; k < 2; ++k) dst[m][k] = *(const LAS bf16x8*)(lds + PG8_SA(b, h) + aoff + m * 2048 + k * 1024); } while (0)
; #define PG8_LDB(dst, b, h) do { _Pragma("unroll") for (int n = 0; n < 2; ++n) _Pragma("unroll") for (int k = 0; k < 2; ++k) dst[n][k] = *(const LAS bf16x8*)(lds + PG8_SB(b, h) + boff + n * 2048 + k * 1024); } while (0)
; #define PG8_MMA(ai, bj, At, Bt) do { __builtin_amdgcn_s_setprio(1); _Pragma("unroll") for (int m = 0; m < 4; ++m) _Pragma("unroll") for (int n = 0; n < 2; ++n) _Pragma("unroll") for (int k = 0; k < 2; ++k) \
;         acc[ai][bj][m][n] = __builtin_amdgcn_mfma_f32_16x16x32_bf16(Bt[n][k], At[m][k], acc[ai][bj][m][n], 0, 0, 0); __builtin_amdgcn_s_setprio(0); } while (0)
; #define PG8_WAIT_V(n) asm volatile("s_waitcnt vmcnt(" #n ")" ::: "memory")
; #define PG8_WAIT_L(n) asm volatile("s_waitcnt lgkmcnt(" #n ")" ::: "memory")
; #define PG8_BAR __builtin_amdgcn_s_barrier()
; #define PG8_SCHED __builtin_amdgcn_sched_barrier(0)
; template <class Epi, class Sched>
; __device__ __forceinline__ void gemm_phase(LAS unsigned char* lds, const Gemm g, const Sched& S, const Epi& E) {
;     ...
;             PG8_LDB(B0, 0, 0); PG8_SCHED; PG8_LDA(At, 0, 0); PG8_STAGE(PG8_SA(1, 1), a1 + hstepA, voffA);
;             PG8_WAIT_L(8); PG8_BAR; PG8_WAIT_L(0); PG8_MMA(0, 0, At, B0); PG8_BAR; PG8_SCHED;
;     ...
;             PG8_LDA(At, 1, 1); PG8_STAGE(PG8_SA(1, 0), a3, voffA);
;             PG8_BAR; PG8_WAIT_L(0); PG8_MMA(1, 0, At, B0); PG8_BAR; PG8_SCHED;
;             PG8_STAGE(PG8_SB(1, 1), b3 + hstepB, voffB);
;             PG8_WAIT_V(6); PG8_BAR; PG8_MMA(1, 1, At, B1); PG8_BAR;
	ds_read_b128 v[162:165], v148 offset:49152
	ds_read_b128 v[166:169], v148 offset:50176
	ds_read_b128 v[170:173], v148 offset:51200
	ds_read_b128 v[174:177], v148 offset:52224
	ds_read_b128 v[178:181], v148 offset:53248
	ds_read_b128 v[182:185], v148 offset:54272
	ds_read_b128 v[186:189], v148 offset:55296
	ds_read_b128 v[190:193], v148 offset:56320
	s_add_i32 s25, s54, s30
	v_lshl_add_u64 v[146:147], v[146:147], 0, s[8:9]
	s_mov_b32 m0, s25
	s_nop 0
	global_load_lds_dwordx4 v[146:147], off
	v_lshl_add_u64 v[146:147], v[210:211], 0, s[8:9]
	s_add_i32 m0, s25, 0x2000
	s_nop 0
	global_load_lds_dwordx4 v[146:147], off
	s_mov_b32 m0, s42
	v_lshl_add_u64 v[146:147], v[212:213], 0, s[8:9]
	global_load_lds_dwordx4 v[146:147], off
	v_lshl_add_u64 v[146:147], v[216:217], 0, s[8:9]
	s_mov_b32 m0, s43
	s_nop 0
	global_load_lds_dwordx4 v[146:147], off
	s_add_u32 s20, s20, 0x80080
	s_addc_u32 s21, s21, 0
	s_add_i32 s24, s24, s30
	s_mov_b32 m0, s24
	s_nop 0
	global_load_lds_dwordx4 v2, s[20:21]
	s_add_i32 m0, s24, 0x2000
	s_nop 0
	global_load_lds_dwordx4 v132, s[20:21]
	s_add_i32 s53, s53, 2
	s_add_u32 s18, s18, 0x100
	s_addc_u32 s19, s19, 0
	s_add_u32 s51, s51, 0x100
	s_addc_u32 s52, s52, 0
	s_cmp_gt_u32 s53, 29
	s_waitcnt lgkmcnt(0)
	s_waitcnt vmcnt(6)
	s_barrier
	v_mfma_f32_16x16x32_bf16 v[64:67], v[142:145], v[162:165], v[64:67]
	v_mfma_f32_16x16x32_bf16 v[60:63], v[154:157], v[162:165], v[60:63]
	v_mfma_f32_16x16x32_bf16 v[56:59], v[142:145], v[170:173], v[56:59]
	v_mfma_f32_16x16x32_bf16 v[48:51], v[154:157], v[170:173], v[48:51]
	v_mfma_f32_16x16x32_bf16 v[40:43], v[142:145], v[178:181], v[40:43]
	v_mfma_f32_16x16x32_bf16 v[32:35], v[154:157], v[178:181], v[32:35]
	v_mfma_f32_16x16x32_bf16 v[24:27], v[142:145], v[186:189], v[24:27]
	v_mfma_f32_16x16x32_bf16 v[16:19], v[154:157], v[186:189], v[16:19]
	v_mfma_f32_16x16x32_bf16 v[64:67], v[150:153], v[166:169], v[64:67]
	v_mfma_f32_16x16x32_bf16 v[60:63], v[158:161], v[166:169], v[60:63]
	v_mfma_f32_16x16x32_bf16 v[56:59], v[150:153], v[174:177], v[56:59]
	v_mfma_f32_16x16x32_bf16 v[48:51], v[158:161], v[174:177], v[48:51]
	v_mfma_f32_16x16x32_bf16 v[40:43], v[150:153], v[182:185], v[40:43]
	v_mfma_f32_16x16x32_bf16 v[32:35], v[158:161], v[182:185], v[32:35]
	v_mfma_f32_16x16x32_bf16 v[24:27], v[150:153], v[190:193], v[24:27]
	v_mfma_f32_16x16x32_bf16 v[16:19], v[158:161], v[190:193], v[16:19]
	v_mfma_f32_16x16x32_bf16 v[52:55], v[194:197], v[162:165], v[52:55]
	v_mfma_f32_16x16x32_bf16 v[44:47], v[202:205], v[162:165], v[44:47]
	v_mfma_f32_16x16x32_bf16 v[36:39], v[194:197], v[170:173], v[36:39]
	v_mfma_f32_16x16x32_bf16 v[28:31], v[202:205], v[170:173], v[28:31]
	v_mfma_f32_16x16x32_bf16 v[20:23], v[194:197], v[178:181], v[20:23]
	v_mfma_f32_16x16x32_bf16 v[12:15], v[202:205], v[178:181], v[12:15]
	v_mfma_f32_16x16x32_bf16 v[8:11], v[194:197], v[186:189], v[8:11]
	v_mfma_f32_16x16x32_bf16 v[4:7], v[202:205], v[186:189], v[4:7]
	v_mfma_f32_16x16x32_bf16 v[52:55], v[198:201], v[166:169], v[52:55]
	v_mfma_f32_16x16x32_bf16 v[44:47], v[206:209], v[166:169], v[44:47]
	v_mfma_f32_16x16x32_bf16 v[36:39], v[198:201], v[174:177], v[36:39]
	v_mfma_f32_16x16x32_bf16 v[28:31], v[206:209], v[174:177], v[28:31]
	v_mfma_f32_16x16x32_bf16 v[20:23], v[198:201], v[182:185], v[20:23]
	v_mfma_f32_16x16x32_bf16 v[12:15], v[206:209], v[182:185], v[12:15]
	v_mfma_f32_16x16x32_bf16 v[8:11], v[198:201], v[190:193], v[8:11]
	v_mfma_f32_16x16x32_bf16 v[4:7], v[206:209], v[190:193], v[4:7]
	s_barrier
	s_setprio 0
.LBB0_1094:
	s_setprio 0
	s_add_u32 s20, s18, 0xfff80080
	s_addc_u32 s21, s19, -1
	s_add_i32 s54, 0, 0x10000
	v_add_u32_e32 v146, s54, v1
	ds_read_b128 v[142:145], v146
	ds_read_b128 v[150:153], v146 offset:1024
	ds_read_b128 v[154:157], v146 offset:2048
	ds_read_b128 v[158:161], v146 offset:3072
	s_cmp_eq_u32 s53, 28
	s_cselect_b32 s25, s5, s21
	s_cselect_b32 s24, s49, s20
	s_cselect_b32 s21, s1, s52
	s_cselect_b32 s20, s50, s51
	ds_read_b128 v[162:165], v148
	ds_read_b128 v[166:169], v148 offset:1024
	ds_read_b128 v[170:173], v148 offset:2048
	ds_read_b128 v[174:177], v148 offset:3072
	ds_read_b128 v[178:181], v148 offset:4096
	ds_read_b128 v[182:185], v148 offset:5120
	ds_read_b128 v[186:189], v148 offset:6144
	ds_read_b128 v[190:193], v148 offset:7168
	s_add_i32 s56, 0, 0x14000
	v_add_u32_e32 v146, s56, v1
	ds_read_b128 v[194:197], v146
	ds_read_b128 v[198:201], v146 offset:1024
	ds_read_b128 v[202:205], v146 offset:2048
	ds_read_b128 v[206:209], v146 offset:3072
	s_add_i32 m0, s31, 0xc000
	s_nop 0
	global_load_lds_dwordx4 v138, s[18:19]
	s_add_i32 m0, s31, 0xe000
	s_nop 0
	global_load_lds_dwordx4 v140, s[18:19]
	s_waitcnt lgkmcnt(0)
	s_barrier
; #define PG8_STAGE(bufoff, gbase, voff) do { _Pragma("unroll") for (int _i = 0; _i < 2; ++_i) \
;         __builtin_amdgcn_global_load_lds((const unsigned*)((const char*)(gbase) + (voff)[_i]), (LAS unsigned*)(lds + (bufoff) + ldsw + _i * 8192), 16, 0, 0); } while (0)
; #define PG8_LDA(dst, b, h) do { _Pragma("unroll") for (int m = 0; m < 4; ++m) _Pragma("unroll") for (int k = 0; k < 2; ++k) dst[m][k] = *(const LAS bf16x8*)(lds + PG8_SA(b, h) + aoff + m * 2048 + k * 1024); } while (0)
; #define PG8_LDB(dst, b, h) do { _Pragma("unroll") for (int n = 0; n < 2; ++n) _Pragma("unroll") for (int k = 0; k < 2; ++k) dst[n][k] = *(const LAS bf16x8*)(lds + PG8_SB(b, h) + boff + n * 2048 + k * 1024); } while (0)
; #define PG8_MMA(ai, bj, At, Bt) do { __builtin_amdgcn_s_setprio(1); _Pragma("unroll") for (int m = 0; m < 4; ++m) _Pragma("unroll") for (int n = 0; n < 2; ++n) _Pragma("unroll") for (int k = 0; k < 2; ++k) \
;         acc[ai][bj][m][n] = __builtin_amdgcn_mfma_f32_16x16x32_bf16(Bt[n][k], At[m][k], acc[ai][bj][m][n], 0, 0, 0); __builtin_amdgcn_s_setprio(0); } while (0)
; #define PG8_WAIT_V(n) asm volatile("s_waitcnt vmcnt(" #n ")" ::: "memory")
; #define PG8_WAIT_L(n) asm volatile("s_waitcnt lgkmcnt(" #n ")" ::: "memory")
; #define PG8_BAR __builtin_amdgcn_s_barrier()
; #define PG8_SCHED __builtin_amdgcn_sched_barrier(0)
; template <class Epi, class Sched>
; __device__ __forceinline__ void gemm_phase(LAS unsigned char* lds, const Gemm g, const Sched& S, const Epi& E) {
;     ...
;             PG8_LDB(B0, 0, 0); PG8_SCHED; PG8_LDA(At, 0, 0); PG8_STAGE(PG8_SA(1, 1), a1 + hstepA, voffA);
;             PG8_WAIT_L(8); PG8_BAR; PG8_WAIT_L(0); PG8_MMA(0, 0, At, B0); PG8_BAR; PG8_SCHED;
;             PG8_LDB(B1, 0, 1); PG8_STAGE(PG8_SB(0, 0), b2, voffB);
;             PG8_BAR; PG8_WAIT_L(0); PG8_MMA(0, 1, At, B1); PG8_BAR;
;             PG8_LDA(At, 0, 1); PG8_STAGE(PG8_SA(0, 0), a2, voffA);
;             PG8_BAR; PG8_WAIT_L(0); PG8_MMA(1, 0, At, B0); PG8_BAR; PG8_SCHED;
;             PG8_STAGE(PG8_SB(0, 1), b2 + hstepB, voffB);
;             PG8_WAIT_V(6); PG8_BAR; PG8_MMA(1, 1, At, B1); PG8_BAR;
	v_mfma_f32_16x16x32_bf16 v[128:131], v[142:145], v[162:165], v[128:131]
	v_mfma_f32_16x16x32_bf16 v[124:127], v[154:157], v[162:165], v[124:127]
	v_mfma_f32_16x16x32_bf16 v[120:123], v[142:145], v[170:173], v[120:123]
	v_mfma_f32_16x16x32_bf16 v[112:115], v[154:157], v[170:173], v[112:115]
	v_mfma_f32_16x16x32_bf16 v[104:107], v[142:145], v[178:181], v[104:107]
	v_mfma_f32_16x16x32_bf16 v[96:99], v[154:157], v[178:181], v[96:99]
	v_mfma_f32_16x16x32_bf16 v[88:91], v[142:145], v[186:189], v[88:91]
	v_mfma_f32_16x16x32_bf16 v[80:83], v[154:157], v[186:189], v[80:83]
	v_mfma_f32_16x16x32_bf16 v[128:131], v[150:153], v[166:169], v[128:131]
	v_mfma_f32_16x16x32_bf16 v[124:127], v[158:161], v[166:169], v[124:127]
	v_mfma_f32_16x16x32_bf16 v[120:123], v[150:153], v[174:177], v[120:123]
	v_mfma_f32_16x16x32_bf16 v[112:115], v[158:161], v[174:177], v[112:115]
	v_mfma_f32_16x16x32_bf16 v[104:107], v[150:153], v[182:185], v[104:107]
	v_mfma_f32_16x16x32_bf16 v[96:99], v[158:161], v[182:185], v[96:99]
	v_mfma_f32_16x16x32_bf16 v[88:91], v[150:153], v[190:193], v[88:91]
	v_mfma_f32_16x16x32_bf16 v[80:83], v[158:161], v[190:193], v[80:83]
	v_mfma_f32_16x16x32_bf16 v[116:119], v[194:197], v[162:165], v[116:119]
	v_mfma_f32_16x16x32_bf16 v[108:111], v[202:205], v[162:165], v[108:111]
	v_mfma_f32_16x16x32_bf16 v[100:103], v[194:197], v[170:173], v[100:103]
	v_mfma_f32_16x16x32_bf16 v[92:95], v[202:205], v[170:173], v[92:95]
	v_mfma_f32_16x16x32_bf16 v[84:87], v[194:197], v[178:181], v[84:87]
	v_mfma_f32_16x16x32_bf16 v[76:79], v[202:205], v[178:181], v[76:79]
	v_mfma_f32_16x16x32_bf16 v[72:75], v[194:197], v[186:189], v[72:75]
	v_mfma_f32_16x16x32_bf16 v[68:71], v[202:205], v[186:189], v[68:71]
	v_mfma_f32_16x16x32_bf16 v[116:119], v[198:201], v[166:169], v[116:119]
	v_mfma_f32_16x16x32_bf16 v[108:111], v[206:209], v[166:169], v[108:111]
	v_mfma_f32_16x16x32_bf16 v[100:103], v[198:201], v[174:177], v[100:103]
	v_mfma_f32_16x16x32_bf16 v[92:95], v[206:209], v[174:177], v[92:95]
	v_mfma_f32_16x16x32_bf16 v[84:87], v[198:201], v[182:185], v[84:87]
	v_mfma_f32_16x16x32_bf16 v[76:79], v[206:209], v[182:185], v[76:79]
	v_mfma_f32_16x16x32_bf16 v[72:75], v[198:201], v[190:193], v[72:75]
	v_mfma_f32_16x16x32_bf16 v[68:71], v[206:209], v[190:193], v[68:71]
	s_barrier
	ds_read_b128 v[162:165], v148 offset:16384
	ds_read_b128 v[166:169], v148 offset:17408
	ds_read_b128 v[170:173], v148 offset:18432
	ds_read_b128 v[174:177], v148 offset:19456
	ds_read_b128 v[178:181], v148 offset:20480
	ds_read_b128 v[182:185], v148 offset:21504
	ds_read_b128 v[186:189], v148 offset:22528
	ds_read_b128 v[190:193], v148 offset:23552
	s_add_i32 s54, s54, s30
	v_lshl_add_u64 v[146:147], s[20:21], 0, v[2:3]
	s_mov_b32 m0, s54
	v_lshl_add_u64 v[210:211], s[20:21], 0, v[132:133]
	global_load_lds_dwordx4 v[146:147], off
	s_add_i32 m0, s54, 0x2000
	s_nop 0
	global_load_lds_dwordx4 v[210:211], off
	s_mov_b32 m0, s31
	v_lshl_add_u64 v[212:213], s[24:25], 0, v[136:137]
	global_load_lds_dwordx4 v[212:213], off
	v_lshl_add_u64 v[216:217], s[24:25], 0, v[134:135]
	s_mov_b32 m0, s35
	s_nop 0
	global_load_lds_dwordx4 v[216:217], off
	s_add_u32 s54, s20, 0x80000
	s_addc_u32 s55, s21, 0
	s_add_i32 s56, s56, s30
	s_mov_b32 m0, s56
	s_nop 0
	global_load_lds_dwordx4 v2, s[54:55]
	s_add_i32 m0, s56, 0x2000
	s_nop 0
	global_load_lds_dwordx4 v132, s[54:55]
	s_waitcnt lgkmcnt(0)
	s_waitcnt vmcnt(6)
	s_barrier
	v_mfma_f32_16x16x32_bf16 v[64:67], v[142:145], v[162:165], v[64:67]
	v_mfma_f32_16x16x32_bf16 v[60:63], v[154:157], v[162:165], v[60:63]
	v_mfma_f32_16x16x32_bf16 v[56:59], v[142:145], v[170:173], v[56:59]
	v_mfma_f32_16x16x32_bf16 v[48:51], v[154:157], v[170:173], v[48:51]
	v_mfma_f32_16x16x32_bf16 v[40:43], v[142:145], v[178:181], v[40:43]
	v_mfma_f32_16x16x32_bf16 v[32:35], v[154:157], v[178:181], v[32:35]
	v_mfma_f32_16x16x32_bf16 v[24:27], v[142:145], v[186:189], v[24:27]
	v_mfma_f32_16x16x32_bf16 v[16:19], v[154:157], v[186:189], v[16:19]
	v_mfma_f32_16x16x32_bf16 v[64:67], v[150:153], v[166:169], v[64:67]
	v_mfma_f32_16x16x32_bf16 v[60:63], v[158:161], v[166:169], v[60:63]
	v_mfma_f32_16x16x32_bf16 v[56:59], v[150:153], v[174:177], v[56:59]
	v_mfma_f32_16x16x32_bf16 v[48:51], v[158:161], v[174:177], v[48:51]
	v_mfma_f32_16x16x32_bf16 v[40:43], v[150:153], v[182:185], v[40:43]
	v_mfma_f32_16x16x32_bf16 v[32:35], v[158:161], v[182:185], v[32:35]
	v_mfma_f32_16x16x32_bf16 v[24:27], v[150:153], v[190:193], v[24:27]
	v_mfma_f32_16x16x32_bf16 v[16:19], v[158:161], v[190:193], v[16:19]
	v_mfma_f32_16x16x32_bf16 v[52:55], v[194:197], v[162:165], v[52:55]
	v_mfma_f32_16x16x32_bf16 v[44:47], v[202:205], v[162:165], v[44:47]
	v_mfma_f32_16x16x32_bf16 v[36:39], v[194:197], v[170:173], v[36:39]
	v_mfma_f32_16x16x32_bf16 v[28:31], v[202:205], v[170:173], v[28:31]
	v_mfma_f32_16x16x32_bf16 v[20:23], v[194:197], v[178:181], v[20:23]
	v_mfma_f32_16x16x32_bf16 v[12:15], v[202:205], v[178:181], v[12:15]
	v_mfma_f32_16x16x32_bf16 v[8:11], v[194:197], v[186:189], v[8:11]
	v_mfma_f32_16x16x32_bf16 v[4:7], v[202:205], v[186:189], v[4:7]
	v_mfma_f32_16x16x32_bf16 v[52:55], v[198:201], v[166:169], v[52:55]
	v_mfma_f32_16x16x32_bf16 v[44:47], v[206:209], v[166:169], v[44:47]
	v_mfma_f32_16x16x32_bf16 v[36:39], v[198:201], v[174:177], v[36:39]
	v_mfma_f32_16x16x32_bf16 v[28:31], v[206:209], v[174:177], v[28:31]
	v_mfma_f32_16x16x32_bf16 v[20:23], v[198:201], v[182:185], v[20:23]
	v_mfma_f32_16x16x32_bf16 v[12:15], v[206:209], v[182:185], v[12:15]
	v_mfma_f32_16x16x32_bf16 v[8:11], v[198:201], v[190:193], v[8:11]
	v_mfma_f32_16x16x32_bf16 v[4:7], v[206:209], v[190:193], v[4:7]
	s_barrier
; #define PG8_STAGE(bufoff, gbase, voff) do { _Pragma("unroll") for (int _i = 0; _i < 2; ++_i) \
;         __builtin_amdgcn_global_load_lds((const unsigned*)((const char*)(gbase) + (voff)[_i]), (LAS unsigned*)(lds + (bufoff) + ldsw + _i * 8192), 16, 0, 0); } while (0)
; #define PG8_LDA(dst, b, h) do { _Pragma("unroll") for (int m = 0; m < 4; ++m) _Pragma("unroll") for (int k = 0; k < 2; ++k) dst[m][k] = *(const LAS bf16x8*)(lds + PG8_SA(b, h) + aoff + m * 2048 + k * 1024); } while (0)
; #define PG8_LDB(dst, b, h) do { _Pragma("unroll") for (int n = 0; n < 2; ++n) _Pragma("unroll") for (int k = 0; k < 2; ++k) dst[n][k] = *(const LAS bf16x8*)(lds + PG8_SB(b, h) + boff + n * 2048 + k * 1024); } while (0)
; #define PG8_MMA(ai, bj, At, Bt) do { __builtin_amdgcn_s_setprio(1); _Pragma("unroll") for (int m = 0; m < 4; ++m) _Pragma("unroll") for (int n = 0; n < 2; ++n) _Pragma("unroll") for (int k = 0; k < 2; ++k) \
;         acc[ai][bj][m][n] = __builtin_amdgcn_mfma_f32_16x16x32_bf16(Bt[n][k], At[m][k], acc[ai][bj][m][n], 0, 0, 0); __builtin_amdgcn_s_setprio(0); } while (0)
; #define PG8_WAIT_V(n) asm volatile("s_waitcnt vmcnt(" #n ")" ::: "memory")
; #define PG8_WAIT_L(n) asm volatile("s_waitcnt lgkmcnt(" #n ")" ::: "memory")
; #define PG8_BAR __builtin_amdgcn_s_barrier()
; #define PG8_SCHED __builtin_amdgcn_sched_barrier(0)
; template <class Epi, class Sched>
; __device__ __forceinline__ void gemm_phase(LAS unsigned char* lds, const Gemm g, const Sched& S, const Epi& E) {
;     ...
;             PG8_LDB(B0, 1, 0); PG8_SCHED; PG8_LDA(At, 1, 0); PG8_STAGE(PG8_SA(0, 1), a2 + hstepA, voffA);
;             PG8_WAIT_L(8); PG8_BAR; PG8_WAIT_L(0); PG8_MMA(0, 0, At, B0); PG8_BAR; PG8_SCHED;
;             PG8_LDB(B1, 1, 1); PG8_STAGE(PG8_SB(1, 0), b3, voffB);
;             PG8_BAR; PG8_WAIT_L(0); PG8_MMA(0, 1, At, B1); PG8_BAR;
;             PG8_LDA(At, 1, 1); PG8_STAGE(PG8_SA(1, 0), a3, voffA);
;             PG8_BAR; PG8_WAIT_L(0); PG8_MMA(1, 0, At, B0); PG8_BAR; PG8_SCHED;
;             PG8_STAGE(PG8_SB(1, 1), b3 + hstepB, voffB);
;             PG8_WAIT_V(6); PG8_BAR; PG8_MMA(1, 1, At, B1); PG8_BAR;
	s_add_i32 s54, 0, 0x18000
	v_add_u32_e32 v149, s54, v1
	ds_read_b128 v[142:145], v149
	ds_read_b128 v[150:153], v149 offset:1024
	ds_read_b128 v[154:157], v149 offset:2048
	ds_read_b128 v[158:161], v149 offset:3072
	s_add_u32 s24, s24, 0x80000
	s_addc_u32 s25, s25, 0
	ds_read_b128 v[162:165], v148 offset:32768
	ds_read_b128 v[166:169], v148 offset:33792
	ds_read_b128 v[170:173], v148 offset:34816
	ds_read_b128 v[174:177], v148 offset:35840
	ds_read_b128 v[178:181], v148 offset:36864
	ds_read_b128 v[182:185], v148 offset:37888
	ds_read_b128 v[186:189], v148 offset:38912
	ds_read_b128 v[190:193], v148 offset:39936
	s_mov_b32 m0, s36
	s_nop 0
	global_load_lds_dwordx4 v136, s[24:25]
	s_mov_b32 m0, s37
	s_nop 0
	global_load_lds_dwordx4 v134, s[24:25]
	s_add_i32 s24, 0, 0x1c000
	v_add_u32_e32 v149, s24, v1
	ds_read_b128 v[194:197], v149
	ds_read_b128 v[198:201], v149 offset:1024
	ds_read_b128 v[202:205], v149 offset:2048
	ds_read_b128 v[206:209], v149 offset:3072
	s_waitcnt lgkmcnt(0)
	s_barrier
	v_mfma_f32_16x16x32_bf16 v[128:131], v[142:145], v[162:165], v[128:131]
	v_mfma_f32_16x16x32_bf16 v[124:127], v[154:157], v[162:165], v[124:127]
	v_mfma_f32_16x16x32_bf16 v[120:123], v[142:145], v[170:173], v[120:123]
	v_mfma_f32_16x16x32_bf16 v[112:115], v[154:157], v[170:173], v[112:115]
	v_mfma_f32_16x16x32_bf16 v[104:107], v[142:145], v[178:181], v[104:107]
	v_mfma_f32_16x16x32_bf16 v[96:99], v[154:157], v[178:181], v[96:99]
	v_mfma_f32_16x16x32_bf16 v[88:91], v[142:145], v[186:189], v[88:91]
	v_mfma_f32_16x16x32_bf16 v[80:83], v[154:157], v[186:189], v[80:83]
	v_mfma_f32_16x16x32_bf16 v[128:131], v[150:153], v[166:169], v[128:131]
	v_mfma_f32_16x16x32_bf16 v[124:127], v[158:161], v[166:169], v[124:127]
	v_mfma_f32_16x16x32_bf16 v[120:123], v[150:153], v[174:177], v[120:123]
	v_mfma_f32_16x16x32_bf16 v[112:115], v[158:161], v[174:177], v[112:115]
	v_mfma_f32_16x16x32_bf16 v[104:107], v[150:153], v[182:185], v[104:107]
	v_mfma_f32_16x16x32_bf16 v[96:99], v[158:161], v[182:185], v[96:99]
	v_mfma_f32_16x16x32_bf16 v[88:91], v[150:153], v[190:193], v[88:91]
	v_mfma_f32_16x16x32_bf16 v[80:83], v[158:161], v[190:193], v[80:83]
	v_mfma_f32_16x16x32_bf16 v[116:119], v[194:197], v[162:165], v[116:119]
	v_mfma_f32_16x16x32_bf16 v[108:111], v[202:205], v[162:165], v[108:111]
	v_mfma_f32_16x16x32_bf16 v[100:103], v[194:197], v[170:173], v[100:103]
	v_mfma_f32_16x16x32_bf16 v[92:95], v[202:205], v[170:173], v[92:95]
	v_mfma_f32_16x16x32_bf16 v[84:87], v[194:197], v[178:181], v[84:87]
	v_mfma_f32_16x16x32_bf16 v[76:79], v[202:205], v[178:181], v[76:79]
	v_mfma_f32_16x16x32_bf16 v[72:75], v[194:197], v[186:189], v[72:75]
	v_mfma_f32_16x16x32_bf16 v[68:71], v[202:205], v[186:189], v[68:71]
	v_mfma_f32_16x16x32_bf16 v[116:119], v[198:201], v[166:169], v[116:119]
	v_mfma_f32_16x16x32_bf16 v[108:111], v[206:209], v[166:169], v[108:111]
	v_mfma_f32_16x16x32_bf16 v[100:103], v[198:201], v[174:177], v[100:103]
	v_mfma_f32_16x16x32_bf16 v[92:95], v[206:209], v[174:177], v[92:95]
	v_mfma_f32_16x16x32_bf16 v[84:87], v[198:201], v[182:185], v[84:87]
	v_mfma_f32_16x16x32_bf16 v[76:79], v[206:209], v[182:185], v[76:79]
	v_mfma_f32_16x16x32_bf16 v[72:75], v[198:201], v[190:193], v[72:75]
	v_mfma_f32_16x16x32_bf16 v[68:71], v[206:209], v[190:193], v[68:71]
	s_barrier
	ds_read_b128 v[162:165], v148 offset:49152
	ds_read_b128 v[166:169], v148 offset:50176
	ds_read_b128 v[170:173], v148 offset:51200
	ds_read_b128 v[174:177], v148 offset:52224
	ds_read_b128 v[178:181], v148 offset:53248
	ds_read_b128 v[182:185], v148 offset:54272
	ds_read_b128 v[186:189], v148 offset:55296
	ds_read_b128 v[190:193], v148 offset:56320
	s_add_i32 s25, s54, s30
	v_lshl_add_u64 v[146:147], v[146:147], 0, s[8:9]
	s_mov_b32 m0, s25
	s_nop 0
	global_load_lds_dwordx4 v[146:147], off
	v_lshl_add_u64 v[146:147], v[210:211], 0, s[8:9]
	s_add_i32 m0, s25, 0x2000
	s_nop 0
	global_load_lds_dwordx4 v[146:147], off
	s_mov_b32 m0, s42
	v_lshl_add_u64 v[146:147], v[212:213], 0, s[8:9]
	global_load_lds_dwordx4 v[146:147], off
	v_lshl_add_u64 v[146:147], v[216:217], 0, s[8:9]
	s_mov_b32 m0, s43
	s_nop 0
	global_load_lds_dwordx4 v[146:147], off
	s_add_u32 s20, s20, 0x80080
	s_addc_u32 s21, s21, 0
	s_add_i32 s24, s24, s30
	s_mov_b32 m0, s24
	s_nop 0
	global_load_lds_dwordx4 v2, s[20:21]
	s_add_i32 m0, s24, 0x2000
	s_nop 0
	global_load_lds_dwordx4 v132, s[20:21]
	s_add_i32 s53, s53, 2
	s_add_u32 s18, s18, 0x100
	s_addc_u32 s19, s19, 0
	s_add_u32 s51, s51, 0x100
	s_addc_u32 s52, s52, 0
	s_cmp_gt_u32 s53, 29
	s_waitcnt lgkmcnt(0)
	s_waitcnt vmcnt(6)
	s_barrier
	v_mfma_f32_16x16x32_bf16 v[64:67], v[142:145], v[162:165], v[64:67]
	v_mfma_f32_16x16x32_bf16 v[60:63], v[154:157], v[162:165], v[60:63]
	v_mfma_f32_16x16x32_bf16 v[56:59], v[142:145], v[170:173], v[56:59]
	v_mfma_f32_16x16x32_bf16 v[48:51], v[154:157], v[170:173], v[48:51]
	v_mfma_f32_16x16x32_bf16 v[40:43], v[142:145], v[178:181], v[40:43]
	v_mfma_f32_16x16x32_bf16 v[32:35], v[154:157], v[178:181], v[32:35]
	v_mfma_f32_16x16x32_bf16 v[24:27], v[142:145], v[186:189], v[24:27]
	v_mfma_f32_16x16x32_bf16 v[16:19], v[154:157], v[186:189], v[16:19]
	v_mfma_f32_16x16x32_bf16 v[64:67], v[150:153], v[166:169], v[64:67]
	v_mfma_f32_16x16x32_bf16 v[60:63], v[158:161], v[166:169], v[60:63]
	v_mfma_f32_16x16x32_bf16 v[56:59], v[150:153], v[174:177], v[56:59]
	v_mfma_f32_16x16x32_bf16 v[48:51], v[158:161], v[174:177], v[48:51]
	v_mfma_f32_16x16x32_bf16 v[40:43], v[150:153], v[182:185], v[40:43]
	v_mfma_f32_16x16x32_bf16 v[32:35], v[158:161], v[182:185], v[32:35]
	v_mfma_f32_16x16x32_bf16 v[24:27], v[150:153], v[190:193], v[24:27]
	v_mfma_f32_16x16x32_bf16 v[16:19], v[158:161], v[190:193], v[16:19]
	v_mfma_f32_16x16x32_bf16 v[52:55], v[194:197], v[162:165], v[52:55]
	v_mfma_f32_16x16x32_bf16 v[44:47], v[202:205], v[162:165], v[44:47]
	v_mfma_f32_16x16x32_bf16 v[36:39], v[194:197], v[170:173], v[36:39]
	v_mfma_f32_16x16x32_bf16 v[28:31], v[202:205], v[170:173], v[28:31]
	v_mfma_f32_16x16x32_bf16 v[20:23], v[194:197], v[178:181], v[20:23]
	v_mfma_f32_16x16x32_bf16 v[12:15], v[202:205], v[178:181], v[12:15]
	v_mfma_f32_16x16x32_bf16 v[8:11], v[194:197], v[186:189], v[8:11]
	v_mfma_f32_16x16x32_bf16 v[4:7], v[202:205], v[186:189], v[4:7]
	v_mfma_f32_16x16x32_bf16 v[52:55], v[198:201], v[166:169], v[52:55]
	v_mfma_f32_16x16x32_bf16 v[44:47], v[206:209], v[166:169], v[44:47]
	v_mfma_f32_16x16x32_bf16 v[36:39], v[198:201], v[174:177], v[36:39]
	v_mfma_f32_16x16x32_bf16 v[28:31], v[206:209], v[174:177], v[28:31]
	v_mfma_f32_16x16x32_bf16 v[20:23], v[198:201], v[182:185], v[20:23]
	v_mfma_f32_16x16x32_bf16 v[12:15], v[206:209], v[182:185], v[12:15]
	v_mfma_f32_16x16x32_bf16 v[8:11], v[198:201], v[190:193], v[8:11]
	v_mfma_f32_16x16x32_bf16 v[4:7], v[206:209], v[190:193], v[4:7]
	s_barrier
	s_cbranch_scc0 .LBB0_1094
	s_setprio 0
	s_cmpk_gt_u32 s2, 0xff
	s_cbranch_scc1 .Lalign_a_1094
	s_barrier

; #define PG8_STAGE(bufoff, gbase, voff) do { _Pragma("unroll") for (int _i = 0; _i < 2; ++_i) \
;         __builtin_amdgcn_global_load_lds((const unsigned*)((const char*)(gbase) + (voff)[_i]), (LAS unsigned*)(lds + (bufoff) + ldsw + _i * 8192), 16, 0, 0); } while (0)
; #define PG8_LDA(dst, b, h) do { _Pragma("unroll") for (int m = 0; m < 4; ++m) _Pragma("unroll") for (int k = 0; k < 2; ++k) dst[m][k] = *(const LAS bf16x8*)(lds + PG8_SA(b, h) + aoff + m * 2048 + k * 1024); } while (0)
; #define PG8_LDB(dst, b, h) do { _Pragma("unroll") for (int n = 0; n < 2; ++n) _Pragma("unroll") for (int k = 0; k < 2; ++k) dst[n][k] = *(const LAS bf16x8*)(lds + PG8_SB(b, h) + boff + n * 2048 + k * 1024); } while (0)
; #define PG8_MMA(ai, bj, At, Bt) do { __builtin_amdgcn_s_setprio(1); _Pragma("unroll") for (int m = 0; m < 4; ++m) _Pragma("unroll") for (int n = 0; n < 2; ++n) _Pragma("unroll") for (int k = 0; k < 2; ++k) \
;         acc[ai][bj][m][n] = __builtin_amdgcn_mfma_f32_16x16x32_bf16(Bt[n][k], At[m][k], acc[ai][bj][m][n], 0, 0, 0); __builtin_amdgcn_s_setprio(0); } while (0)
; #define PG8_BAR __builtin_amdgcn_s_barrier()
; template <class Epi, class Sched>
; __device__ __forceinline__ void gemm_phase(LAS unsigned char* lds, const Gemm g, const Sched& S, const Epi& E) {
;     ...
;         const bool has_next = S.next(ui + 1, nxt);
;         const char* nA = has_next ? (const char*)g.A + (size_t)nxt.pm * tstepA : cA; const char* nB = has_next ? (const char*)g.Bt + (size_t)nxt.pn * tstepB : cB;
;         for (int t = 0; t < nt; t += 2) {
;             const bool last = (t == nt - 2);
;             const char* a1 = cA + (size_t)(t + 1) * kstep;
;             const char* a2 = last ? nA : cA + (size_t)(t + 2) * kstep; const char* b2 = last ? nB : cB + (size_t)(t + 2) * kstep;
;             const char* a3 = a2 + kstep; const char* b3 = b2 + kstep;
;             if (last && has_next) S.a_ready(nxt);
;             PG8_LDB(B0, 0, 0); PG8_SCHED; PG8_LDA(At, 0, 0); PG8_STAGE(PG8_SA(1, 1), a1 + hstepA, voffA);
;             PG8_WAIT_L(8); PG8_BAR; PG8_WAIT_L(0); PG8_MMA(0, 0, At, B0); PG8_BAR; PG8_SCHED;
;             PG8_LDB(B1, 0, 1); PG8_STAGE(PG8_SB(0, 0), b2, voffB);
;             PG8_BAR; PG8_WAIT_L(0); PG8_MMA(0, 1, At, B1); PG8_BAR;
;             PG8_LDA(At, 0, 1); PG8_STAGE(PG8_SA(0, 0), a2, voffA);
;             PG8_BAR; PG8_WAIT_L(0); PG8_MMA(1, 0, At, B0); PG8_BAR; PG8_SCHED;
.LBB0_1395:
	v_mov_b64_e32 v[4:5], 0x400
	s_ashr_i32 s15, s14, 31
	v_cmp_lt_i64_e32 vcc, s[4:5], v[4:5]
	s_lshl_b64 s[4:5], s[14:15], 20
	v_readlane_b32 s48, v252, 0
	v_readlane_b32 s49, v252, 1
	s_add_u32 s4, s48, s4
	s_addc_u32 s5, s49, s5
	s_and_b64 s[18:19], vcc, exec
	s_cselect_b32 s15, s5, s7
	s_cselect_b32 s47, s4, s6
	s_ashr_i32 s1, s0, 31
	s_lshl_b64 s[18:19], s[0:1], 20
	s_add_u32 s18, s28, s18
	s_addc_u32 s19, s29, s19
	s_and_b64 s[24:25], vcc, exec
	s_cselect_b32 s1, s19, s21
	s_cselect_b32 s48, s18, s20
	s_add_u32 s6, s6, 0x80080
	s_addc_u32 s7, s7, 0
	v_readlane_b32 s50, v252, 2
	v_readlane_b32 s51, v252, 3
	s_add_u32 s49, s20, 0x100
	s_addc_u32 s50, s21, 0
	s_mov_b32 s51, -2
	s_setprio 0
	s_add_u32 s20, s6, 0xfff80080
	s_addc_u32 s21, s7, -1
	s_add_i32 s52, 0, 0x10000
	v_add_u32_e32 v144, s52, v1
	ds_read_b128 v[132:135], v144
	ds_read_b128 v[136:139], v144 offset:1024
	ds_read_b128 v[140:143], v144 offset:2048
	ds_read_b128 v[144:147], v144 offset:3072
	s_cmp_eq_u32 s51, 28
	s_cselect_b32 s25, s15, s21
	s_cselect_b32 s24, s47, s20
	s_cselect_b32 s21, s1, s50
	s_cselect_b32 s20, s48, s49
	ds_read_b128 v[148:151], v224
	ds_read_b128 v[152:155], v224 offset:1024
	ds_read_b128 v[156:159], v224 offset:2048
	ds_read_b128 v[160:163], v224 offset:3072
	ds_read_b128 v[164:167], v224 offset:4096
	ds_read_b128 v[168:171], v224 offset:5120
	ds_read_b128 v[172:175], v224 offset:6144
	ds_read_b128 v[176:179], v224 offset:7168
	s_add_i32 s54, 0, 0x14000
	v_add_u32_e32 v202, s54, v1
	ds_read_b128 v[180:183], v202
	ds_read_b128 v[184:187], v202 offset:1024
	ds_read_b128 v[188:191], v202 offset:2048
	ds_read_b128 v[202:205], v202 offset:3072
	s_add_i32 m0, s31, 0xc000
	s_nop 0
	global_load_lds_dwordx4 v198, s[6:7]
	s_add_i32 m0, s31, 0xe000
	s_nop 0
	global_load_lds_dwordx4 v200, s[6:7]
	s_waitcnt lgkmcnt(0)
	s_barrier
	v_mfma_f32_16x16x32_bf16 v[128:131], v[132:135], v[148:151], 0
	v_mfma_f32_16x16x32_bf16 v[124:127], v[140:143], v[148:151], 0
	v_mfma_f32_16x16x32_bf16 v[112:115], v[132:135], v[156:159], 0
	v_mfma_f32_16x16x32_bf16 v[108:111], v[140:143], v[156:159], 0
	v_mfma_f32_16x16x32_bf16 v[100:103], v[132:135], v[164:167], 0
	v_mfma_f32_16x16x32_bf16 v[92:95], v[140:143], v[164:167], 0
	v_mfma_f32_16x16x32_bf16 v[84:87], v[132:135], v[172:175], 0
	v_mfma_f32_16x16x32_bf16 v[76:79], v[140:143], v[172:175], 0
	v_mfma_f32_16x16x32_bf16 v[128:131], v[136:139], v[152:155], v[128:131]
	v_mfma_f32_16x16x32_bf16 v[124:127], v[144:147], v[152:155], v[124:127]
	v_mfma_f32_16x16x32_bf16 v[112:115], v[136:139], v[160:163], v[112:115]
	v_mfma_f32_16x16x32_bf16 v[108:111], v[144:147], v[160:163], v[108:111]
	v_mfma_f32_16x16x32_bf16 v[100:103], v[136:139], v[168:171], v[100:103]
	v_mfma_f32_16x16x32_bf16 v[92:95], v[144:147], v[168:171], v[92:95]
	v_mfma_f32_16x16x32_bf16 v[84:87], v[136:139], v[176:179], v[84:87]
	v_mfma_f32_16x16x32_bf16 v[76:79], v[144:147], v[176:179], v[76:79]
	v_mfma_f32_16x16x32_bf16 v[120:123], v[180:183], v[148:151], 0
	v_mfma_f32_16x16x32_bf16 v[116:119], v[188:191], v[148:151], 0
	v_mfma_f32_16x16x32_bf16 v[104:107], v[180:183], v[156:159], 0
	v_mfma_f32_16x16x32_bf16 v[96:99], v[188:191], v[156:159], 0
	v_mfma_f32_16x16x32_bf16 v[88:91], v[180:183], v[164:167], 0
	v_mfma_f32_16x16x32_bf16 v[80:83], v[188:191], v[164:167], 0
	v_mfma_f32_16x16x32_bf16 v[72:75], v[180:183], v[172:175], 0
	v_mfma_f32_16x16x32_bf16 v[68:71], v[188:191], v[172:175], 0
	v_mfma_f32_16x16x32_bf16 v[120:123], v[184:187], v[152:155], v[120:123]
	v_mfma_f32_16x16x32_bf16 v[116:119], v[202:205], v[152:155], v[116:119]
	v_mfma_f32_16x16x32_bf16 v[104:107], v[184:187], v[160:163], v[104:107]
	v_mfma_f32_16x16x32_bf16 v[96:99], v[202:205], v[160:163], v[96:99]
	v_mfma_f32_16x16x32_bf16 v[88:91], v[184:187], v[168:171], v[88:91]
	v_mfma_f32_16x16x32_bf16 v[80:83], v[202:205], v[168:171], v[80:83]
	v_mfma_f32_16x16x32_bf16 v[72:75], v[184:187], v[176:179], v[72:75]
	v_mfma_f32_16x16x32_bf16 v[68:71], v[202:205], v[176:179], v[68:71]
	s_barrier
	ds_read_b128 v[148:151], v224 offset:16384
	ds_read_b128 v[152:155], v224 offset:17408
	ds_read_b128 v[156:159], v224 offset:18432
	ds_read_b128 v[160:163], v224 offset:19456
	ds_read_b128 v[164:167], v224 offset:20480
	ds_read_b128 v[168:171], v224 offset:21504
	ds_read_b128 v[172:175], v224 offset:22528
	ds_read_b128 v[176:179], v224 offset:23552
	s_add_i32 s52, s52, s30
	v_lshl_add_u64 v[206:207], s[20:21], 0, v[2:3]
	s_mov_b32 m0, s52
	s_nop 0
	global_load_lds_dwordx4 v[206:207], off
	v_lshl_add_u64 v[208:209], s[20:21], 0, v[192:193]
	s_add_i32 m0, s52, 0x2000
	s_nop 0
	global_load_lds_dwordx4 v[208:209], off
	s_mov_b32 m0, s31
	v_lshl_add_u64 v[210:211], s[24:25], 0, v[196:197]
	global_load_lds_dwordx4 v[210:211], off
	v_lshl_add_u64 v[212:213], s[24:25], 0, v[194:195]
	s_mov_b32 m0, s35
	s_nop 0
	global_load_lds_dwordx4 v[212:213], off
	s_add_u32 s52, s20, 0x80000
	s_addc_u32 s53, s21, 0
	s_add_i32 s54, s54, s30
	s_mov_b32 m0, s54
	s_nop 0
	global_load_lds_dwordx4 v2, s[52:53]
	s_add_i32 m0, s54, 0x2000
	s_nop 0
	global_load_lds_dwordx4 v192, s[52:53]
	s_waitcnt lgkmcnt(0)
	s_waitcnt vmcnt(6)
	s_barrier
; #define PG8_STAGE(bufoff, gbase, voff) do { _Pragma("unroll") for (int _i = 0; _i < 2; ++_i) \
;         __builtin_amdgcn_global_load_lds((const unsigned*)((const char*)(gbase) + (voff)[_i]), (LAS unsigned*)(lds + (bufoff) + ldsw + _i * 8192), 16, 0, 0); } while (0)
; #define PG8_LDA(dst, b, h) do { _Pragma("unroll") for (int m = 0; m < 4; ++m) _Pragma("unroll") for (int k = 0; k < 2; ++k) dst[m][k] = *(const LAS bf16x8*)(lds + PG8_SA(b, h) + aoff + m * 2048 + k * 1024); } while (0)
; #define PG8_LDB(dst, b, h) do { _Pragma("unroll") for (int n = 0; n < 2; ++n) _Pragma("unroll") for (int k = 0; k < 2; ++k) dst[n][k] = *(const LAS bf16x8*)(lds + PG8_SB(b, h) + boff + n * 2048 + k * 1024); } while (0)
; #define PG8_MMA(ai, bj, At, Bt) do { __builtin_amdgcn_s_setprio(1); _Pragma("unroll") for (int m = 0; m < 4; ++m) _Pragma("unroll") for (int n = 0; n < 2; ++n) _Pragma("unroll") for (int k = 0; k < 2; ++k) \
;         acc[ai][bj][m][n] = __builtin_amdgcn_mfma_f32_16x16x32_bf16(Bt[n][k], At[m][k], acc[ai][bj][m][n], 0, 0, 0); __builtin_amdgcn_s_setprio(0); } while (0)
; #define PG8_WAIT_V(n) asm volatile("s_waitcnt vmcnt(" #n ")" ::: "memory")
; #define PG8_WAIT_L(n) asm volatile("s_waitcnt lgkmcnt(" #n ")" ::: "memory")
; #define PG8_BAR __builtin_amdgcn_s_barrier()
; #define PG8_SCHED __builtin_amdgcn_sched_barrier(0)
; template <class Epi, class Sched>
; __device__ __forceinline__ void gemm_phase(LAS unsigned char* lds, const Gemm g, const Sched& S, const Epi& E) {
;     ...
;             PG8_BAR; PG8_WAIT_L(0); PG8_MMA(1, 0, At, B0); PG8_BAR; PG8_SCHED;
;             PG8_STAGE(PG8_SB(0, 1), b2 + hstepB, voffB);
;             PG8_WAIT_V(6); PG8_BAR; PG8_MMA(1, 1, At, B1); PG8_BAR;
;             PG8_LDB(B0, 1, 0); PG8_SCHED; PG8_LDA(At, 1, 0); PG8_STAGE(PG8_SA(0, 1), a2 + hstepA, voffA);
;             PG8_WAIT_L(8); PG8_BAR; PG8_WAIT_L(0); PG8_MMA(0, 0, At, B0); PG8_BAR; PG8_SCHED;
;             PG8_LDB(B1, 1, 1); PG8_STAGE(PG8_SB(1, 0), b3, voffB);
;             PG8_BAR; PG8_WAIT_L(0); PG8_MMA(0, 1, At, B1); PG8_BAR;
	v_mfma_f32_16x16x32_bf16 v[64:67], v[132:135], v[148:151], 0
	v_mfma_f32_16x16x32_bf16 v[60:63], v[140:143], v[148:151], 0
	v_mfma_f32_16x16x32_bf16 v[52:55], v[132:135], v[156:159], 0
	v_mfma_f32_16x16x32_bf16 v[44:47], v[140:143], v[156:159], 0
	v_mfma_f32_16x16x32_bf16 v[36:39], v[132:135], v[164:167], 0
	v_mfma_f32_16x16x32_bf16 v[28:31], v[140:143], v[164:167], 0
	v_mfma_f32_16x16x32_bf16 v[20:23], v[132:135], v[172:175], 0
	v_mfma_f32_16x16x32_bf16 v[12:15], v[140:143], v[172:175], 0
	v_mfma_f32_16x16x32_bf16 v[64:67], v[136:139], v[152:155], v[64:67]
	v_mfma_f32_16x16x32_bf16 v[60:63], v[144:147], v[152:155], v[60:63]
	v_mfma_f32_16x16x32_bf16 v[52:55], v[136:139], v[160:163], v[52:55]
	v_mfma_f32_16x16x32_bf16 v[44:47], v[144:147], v[160:163], v[44:47]
	v_mfma_f32_16x16x32_bf16 v[36:39], v[136:139], v[168:171], v[36:39]
	v_mfma_f32_16x16x32_bf16 v[28:31], v[144:147], v[168:171], v[28:31]
	v_mfma_f32_16x16x32_bf16 v[20:23], v[136:139], v[176:179], v[20:23]
	v_mfma_f32_16x16x32_bf16 v[12:15], v[144:147], v[176:179], v[12:15]
	v_mfma_f32_16x16x32_bf16 v[56:59], v[180:183], v[148:151], 0
	v_mfma_f32_16x16x32_bf16 v[48:51], v[188:191], v[148:151], 0
	v_mfma_f32_16x16x32_bf16 v[40:43], v[180:183], v[156:159], 0
	v_mfma_f32_16x16x32_bf16 v[32:35], v[188:191], v[156:159], 0
	v_mfma_f32_16x16x32_bf16 v[24:27], v[180:183], v[164:167], 0
	v_mfma_f32_16x16x32_bf16 v[16:19], v[188:191], v[164:167], 0
	v_mfma_f32_16x16x32_bf16 v[8:11], v[180:183], v[172:175], 0
	v_mfma_f32_16x16x32_bf16 v[4:7], v[188:191], v[172:175], 0
	v_mfma_f32_16x16x32_bf16 v[56:59], v[184:187], v[152:155], v[56:59]
	v_mfma_f32_16x16x32_bf16 v[48:51], v[202:205], v[152:155], v[48:51]
	v_mfma_f32_16x16x32_bf16 v[40:43], v[184:187], v[160:163], v[40:43]
	v_mfma_f32_16x16x32_bf16 v[32:35], v[202:205], v[160:163], v[32:35]
	v_mfma_f32_16x16x32_bf16 v[24:27], v[184:187], v[168:171], v[24:27]
	v_mfma_f32_16x16x32_bf16 v[16:19], v[202:205], v[168:171], v[16:19]
	v_mfma_f32_16x16x32_bf16 v[8:11], v[184:187], v[176:179], v[8:11]
	v_mfma_f32_16x16x32_bf16 v[4:7], v[202:205], v[176:179], v[4:7]
	s_barrier
	s_add_i32 s52, 0, 0x18000
	v_add_u32_e32 v144, s52, v1
	ds_read_b128 v[132:135], v144
	ds_read_b128 v[136:139], v144 offset:1024
	ds_read_b128 v[140:143], v144 offset:2048
	ds_read_b128 v[144:147], v144 offset:3072
	s_add_u32 s24, s24, 0x80000
	s_addc_u32 s25, s25, 0
	ds_read_b128 v[148:151], v224 offset:32768
	ds_read_b128 v[152:155], v224 offset:33792
	ds_read_b128 v[156:159], v224 offset:34816
	ds_read_b128 v[160:163], v224 offset:35840
	ds_read_b128 v[164:167], v224 offset:36864
	ds_read_b128 v[168:171], v224 offset:37888
	ds_read_b128 v[172:175], v224 offset:38912
	ds_read_b128 v[176:179], v224 offset:39936
	s_mov_b32 m0, s36
	s_nop 0
	global_load_lds_dwordx4 v196, s[24:25]
	s_mov_b32 m0, s37
	s_nop 0
	global_load_lds_dwordx4 v194, s[24:25]
	s_add_i32 s24, 0, 0x1c000
	v_add_u32_e32 v202, s24, v1
	ds_read_b128 v[180:183], v202
	ds_read_b128 v[184:187], v202 offset:1024
	ds_read_b128 v[188:191], v202 offset:2048
	ds_read_b128 v[202:205], v202 offset:3072
	s_waitcnt lgkmcnt(0)
	s_barrier
	v_mfma_f32_16x16x32_bf16 v[128:131], v[132:135], v[148:151], v[128:131]
	v_mfma_f32_16x16x32_bf16 v[124:127], v[140:143], v[148:151], v[124:127]
	v_mfma_f32_16x16x32_bf16 v[112:115], v[132:135], v[156:159], v[112:115]
	v_mfma_f32_16x16x32_bf16 v[108:111], v[140:143], v[156:159], v[108:111]
	v_mfma_f32_16x16x32_bf16 v[100:103], v[132:135], v[164:167], v[100:103]
	v_mfma_f32_16x16x32_bf16 v[92:95], v[140:143], v[164:167], v[92:95]
	v_mfma_f32_16x16x32_bf16 v[84:87], v[132:135], v[172:175], v[84:87]
	v_mfma_f32_16x16x32_bf16 v[76:79], v[140:143], v[172:175], v[76:79]
	v_mfma_f32_16x16x32_bf16 v[128:131], v[136:139], v[152:155], v[128:131]
	v_mfma_f32_16x16x32_bf16 v[124:127], v[144:147], v[152:155], v[124:127]
	v_mfma_f32_16x16x32_bf16 v[112:115], v[136:139], v[160:163], v[112:115]
	v_mfma_f32_16x16x32_bf16 v[108:111], v[144:147], v[160:163], v[108:111]
	v_mfma_f32_16x16x32_bf16 v[100:103], v[136:139], v[168:171], v[100:103]
	v_mfma_f32_16x16x32_bf16 v[92:95], v[144:147], v[168:171], v[92:95]
	v_mfma_f32_16x16x32_bf16 v[84:87], v[136:139], v[176:179], v[84:87]
	v_mfma_f32_16x16x32_bf16 v[76:79], v[144:147], v[176:179], v[76:79]
	v_mfma_f32_16x16x32_bf16 v[120:123], v[180:183], v[148:151], v[120:123]
	v_mfma_f32_16x16x32_bf16 v[116:119], v[188:191], v[148:151], v[116:119]
	v_mfma_f32_16x16x32_bf16 v[104:107], v[180:183], v[156:159], v[104:107]
	v_mfma_f32_16x16x32_bf16 v[96:99], v[188:191], v[156:159], v[96:99]
	v_mfma_f32_16x16x32_bf16 v[88:91], v[180:183], v[164:167], v[88:91]
	v_mfma_f32_16x16x32_bf16 v[80:83], v[188:191], v[164:167], v[80:83]
	v_mfma_f32_16x16x32_bf16 v[72:75], v[180:183], v[172:175], v[72:75]
	v_mfma_f32_16x16x32_bf16 v[68:71], v[188:191], v[172:175], v[68:71]
	v_mfma_f32_16x16x32_bf16 v[120:123], v[184:187], v[152:155], v[120:123]
	v_mfma_f32_16x16x32_bf16 v[116:119], v[202:205], v[152:155], v[116:119]
	v_mfma_f32_16x16x32_bf16 v[104:107], v[184:187], v[160:163], v[104:107]
	v_mfma_f32_16x16x32_bf16 v[96:99], v[202:205], v[160:163], v[96:99]
	v_mfma_f32_16x16x32_bf16 v[88:91], v[184:187], v[168:171], v[88:91]
	v_mfma_f32_16x16x32_bf16 v[80:83], v[202:205], v[168:171], v[80:83]
	v_mfma_f32_16x16x32_bf16 v[72:75], v[184:187], v[176:179], v[72:75]
	v_mfma_f32_16x16x32_bf16 v[68:71], v[202:205], v[176:179], v[68:71]
	s_barrier
; #define PG8_STAGE(bufoff, gbase, voff) do { _Pragma("unroll") for (int _i = 0; _i < 2; ++_i) \
;         __builtin_amdgcn_global_load_lds((const unsigned*)((const char*)(gbase) + (voff)[_i]), (LAS unsigned*)(lds + (bufoff) + ldsw + _i * 8192), 16, 0, 0); } while (0)
; #define PG8_LDA(dst, b, h) do { _Pragma("unroll") for (int m = 0; m < 4; ++m) _Pragma("unroll") for (int k = 0; k < 2; ++k) dst[m][k] = *(const LAS bf16x8*)(lds + PG8_SA(b, h) + aoff + m * 2048 + k * 1024); } while (0)
; #define PG8_LDB(dst, b, h) do { _Pragma("unroll") for (int n = 0; n < 2; ++n) _Pragma("unroll") for (int k = 0; k < 2; ++k) dst[n][k] = *(const LAS bf16x8*)(lds + PG8_SB(b, h) + boff + n * 2048 + k * 1024); } while (0)
; #define PG8_MMA(ai, bj, At, Bt) do { __builtin_amdgcn_s_setprio(1); _Pragma("unroll") for (int m = 0; m < 4; ++m) _Pragma("unroll") for (int n = 0; n < 2; ++n) _Pragma("unroll") for (int k = 0; k < 2; ++k) \
;         acc[ai][bj][m][n] = __builtin_amdgcn_mfma_f32_16x16x32_bf16(Bt[n][k], At[m][k], acc[ai][bj][m][n], 0, 0, 0); __builtin_amdgcn_s_setprio(0); } while (0)
; #define PG8_WAIT_V(n) asm volatile("s_waitcnt vmcnt(" #n ")" ::: "memory")
; #define PG8_WAIT_L(n) asm volatile("s_waitcnt lgkmcnt(" #n ")" ::: "memory")
; #define PG8_BAR __builtin_amdgcn_s_barrier()
; #define PG8_SCHED __builtin_amdgcn_sched_barrier(0)
; template <class Epi, class Sched>
; __device__ __forceinline__ void gemm_phase(LAS unsigned char* lds, const Gemm g, const Sched& S, const Epi& E) {
;     ...
;             PG8_LDB(B0, 0, 0); PG8_SCHED; PG8_LDA(At, 0, 0); PG8_STAGE(PG8_SA(1, 1), a1 + hstepA, voffA);
;             PG8_WAIT_L(8); PG8_BAR; PG8_WAIT_L(0); PG8_MMA(0, 0, At, B0); PG8_BAR; PG8_SCHED;
;     ...
;             PG8_LDA(At, 1, 1); PG8_STAGE(PG8_SA(1, 0), a3, voffA);
;             PG8_BAR; PG8_WAIT_L(0); PG8_MMA(1, 0, At, B0); PG8_BAR; PG8_SCHED;
;             PG8_STAGE(PG8_SB(1, 1), b3 + hstepB, voffB);
;             PG8_WAIT_V(6); PG8_BAR; PG8_MMA(1, 1, At, B1); PG8_BAR;
	ds_read_b128 v[148:151], v224 offset:49152
	ds_read_b128 v[152:155], v224 offset:50176
	ds_read_b128 v[156:159], v224 offset:51200
	ds_read_b128 v[160:163], v224 offset:52224
	ds_read_b128 v[164:167], v224 offset:53248
	ds_read_b128 v[168:171], v224 offset:54272
	ds_read_b128 v[172:175], v224 offset:55296
	ds_read_b128 v[176:179], v224 offset:56320
	s_add_i32 s25, s52, s30
	v_lshl_add_u64 v[206:207], v[206:207], 0, s[8:9]
	s_mov_b32 m0, s25
	s_nop 0
	global_load_lds_dwordx4 v[206:207], off
	v_lshl_add_u64 v[206:207], v[208:209], 0, s[8:9]
	s_add_i32 m0, s25, 0x2000
	s_nop 0
	global_load_lds_dwordx4 v[206:207], off
	s_mov_b32 m0, s42
	v_lshl_add_u64 v[206:207], v[210:211], 0, s[8:9]
	global_load_lds_dwordx4 v[206:207], off
	v_lshl_add_u64 v[206:207], v[212:213], 0, s[8:9]
	s_mov_b32 m0, s43
	s_nop 0
	global_load_lds_dwordx4 v[206:207], off
	s_add_u32 s20, s20, 0x80080
	s_addc_u32 s21, s21, 0
	s_add_i32 s24, s24, s30
	s_mov_b32 m0, s24
	s_nop 0
	global_load_lds_dwordx4 v2, s[20:21]
	s_add_i32 m0, s24, 0x2000
	s_nop 0
	global_load_lds_dwordx4 v192, s[20:21]
	s_add_i32 s51, s51, 2
	s_add_u32 s6, s6, 0x100
	s_addc_u32 s7, s7, 0
	s_add_u32 s49, s49, 0x100
	s_addc_u32 s50, s50, 0
	s_cmp_gt_u32 s51, 29
	s_waitcnt lgkmcnt(0)
	s_waitcnt vmcnt(6)
	s_barrier
	v_mfma_f32_16x16x32_bf16 v[64:67], v[132:135], v[148:151], v[64:67]
	v_mfma_f32_16x16x32_bf16 v[60:63], v[140:143], v[148:151], v[60:63]
	v_mfma_f32_16x16x32_bf16 v[52:55], v[132:135], v[156:159], v[52:55]
	v_mfma_f32_16x16x32_bf16 v[44:47], v[140:143], v[156:159], v[44:47]
	v_mfma_f32_16x16x32_bf16 v[36:39], v[132:135], v[164:167], v[36:39]
	v_mfma_f32_16x16x32_bf16 v[28:31], v[140:143], v[164:167], v[28:31]
	v_mfma_f32_16x16x32_bf16 v[20:23], v[132:135], v[172:175], v[20:23]
	v_mfma_f32_16x16x32_bf16 v[12:15], v[140:143], v[172:175], v[12:15]
	v_mfma_f32_16x16x32_bf16 v[64:67], v[136:139], v[152:155], v[64:67]
	v_mfma_f32_16x16x32_bf16 v[60:63], v[144:147], v[152:155], v[60:63]
	v_mfma_f32_16x16x32_bf16 v[52:55], v[136:139], v[160:163], v[52:55]
	v_mfma_f32_16x16x32_bf16 v[44:47], v[144:147], v[160:163], v[44:47]
	v_mfma_f32_16x16x32_bf16 v[36:39], v[136:139], v[168:171], v[36:39]
	v_mfma_f32_16x16x32_bf16 v[28:31], v[144:147], v[168:171], v[28:31]
	v_mfma_f32_16x16x32_bf16 v[20:23], v[136:139], v[176:179], v[20:23]
	v_mfma_f32_16x16x32_bf16 v[12:15], v[144:147], v[176:179], v[12:15]
	v_mfma_f32_16x16x32_bf16 v[56:59], v[180:183], v[148:151], v[56:59]
	v_mfma_f32_16x16x32_bf16 v[48:51], v[188:191], v[148:151], v[48:51]
	v_mfma_f32_16x16x32_bf16 v[40:43], v[180:183], v[156:159], v[40:43]
	v_mfma_f32_16x16x32_bf16 v[32:35], v[188:191], v[156:159], v[32:35]
	v_mfma_f32_16x16x32_bf16 v[24:27], v[180:183], v[164:167], v[24:27]
	v_mfma_f32_16x16x32_bf16 v[16:19], v[188:191], v[164:167], v[16:19]
	v_mfma_f32_16x16x32_bf16 v[8:11], v[180:183], v[172:175], v[8:11]
	v_mfma_f32_16x16x32_bf16 v[4:7], v[188:191], v[172:175], v[4:7]
	v_mfma_f32_16x16x32_bf16 v[56:59], v[184:187], v[152:155], v[56:59]
	v_mfma_f32_16x16x32_bf16 v[48:51], v[202:205], v[152:155], v[48:51]
	v_mfma_f32_16x16x32_bf16 v[40:43], v[184:187], v[160:163], v[40:43]
	v_mfma_f32_16x16x32_bf16 v[32:35], v[202:205], v[160:163], v[32:35]
	v_mfma_f32_16x16x32_bf16 v[24:27], v[184:187], v[168:171], v[24:27]
	v_mfma_f32_16x16x32_bf16 v[16:19], v[202:205], v[168:171], v[16:19]
	v_mfma_f32_16x16x32_bf16 v[8:11], v[184:187], v[176:179], v[8:11]
	v_mfma_f32_16x16x32_bf16 v[4:7], v[202:205], v[176:179], v[4:7]
	s_barrier
	s_setprio 0
.LBB0_1396:
	s_setprio 0
	s_add_u32 s20, s6, 0xfff80080
	s_addc_u32 s21, s7, -1
	s_add_i32 s52, 0, 0x10000
	v_add_u32_e32 v144, s52, v1
	ds_read_b128 v[132:135], v144
	ds_read_b128 v[136:139], v144 offset:1024
	ds_read_b128 v[140:143], v144 offset:2048
	ds_read_b128 v[144:147], v144 offset:3072
	s_cmp_eq_u32 s51, 28
	s_cselect_b32 s25, s15, s21
	s_cselect_b32 s24, s47, s20
	s_cselect_b32 s21, s1, s50
	s_cselect_b32 s20, s48, s49
	ds_read_b128 v[148:151], v224
	ds_read_b128 v[152:155], v224 offset:1024
	ds_read_b128 v[156:159], v224 offset:2048
	ds_read_b128 v[160:163], v224 offset:3072
	ds_read_b128 v[164:167], v224 offset:4096
	ds_read_b128 v[168:171], v224 offset:5120
	ds_read_b128 v[172:175], v224 offset:6144
	ds_read_b128 v[176:179], v224 offset:7168
	s_add_i32 s54, 0, 0x14000
	v_add_u32_e32 v202, s54, v1
	ds_read_b128 v[180:183], v202
	ds_read_b128 v[184:187], v202 offset:1024
	ds_read_b128 v[188:191], v202 offset:2048
	ds_read_b128 v[202:205], v202 offset:3072
	s_add_i32 m0, s31, 0xc000
	s_nop 0
	global_load_lds_dwordx4 v198, s[6:7]
	s_add_i32 m0, s31, 0xe000
	s_nop 0
	global_load_lds_dwordx4 v200, s[6:7]
	s_waitcnt lgkmcnt(0)
	s_barrier
; #define PG8_STAGE(bufoff, gbase, voff) do { _Pragma("unroll") for (int _i = 0; _i < 2; ++_i) \
;         __builtin_amdgcn_global_load_lds((const unsigned*)((const char*)(gbase) + (voff)[_i]), (LAS unsigned*)(lds + (bufoff) + ldsw + _i * 8192), 16, 0, 0); } while (0)
; #define PG8_LDA(dst, b, h) do { _Pragma("unroll") for (int m = 0; m < 4; ++m) _Pragma("unroll") for (int k = 0; k < 2; ++k) dst[m][k] = *(const LAS bf16x8*)(lds + PG8_SA(b, h) + aoff + m * 2048 + k * 1024); } while (0)
; #define PG8_LDB(dst, b, h) do { _Pragma("unroll") for (int n = 0; n < 2; ++n) _Pragma("unroll") for (int k = 0; k < 2; ++k) dst[n][k] = *(const LAS bf16x8*)(lds + PG8_SB(b, h) + boff + n * 2048 + k * 1024); } while (0)
; #define PG8_MMA(ai, bj, At, Bt) do { __builtin_amdgcn_s_setprio(1); _Pragma("unroll") for (int m = 0; m < 4; ++m) _Pragma("unroll") for (int n = 0; n < 2; ++n) _Pragma("unroll") for (int k = 0; k < 2; ++k) \
;         acc[ai][bj][m][n] = __builtin_amdgcn_mfma_f32_16x16x32_bf16(Bt[n][k], At[m][k], acc[ai][bj][m][n], 0, 0, 0); __builtin_amdgcn_s_setprio(0); } while (0)
; #define PG8_WAIT_V(n) asm volatile("s_waitcnt vmcnt(" #n ")" ::: "memory")
; #define PG8_WAIT_L(n) asm volatile("s_waitcnt lgkmcnt(" #n ")" ::: "memory")
; #define PG8_BAR __builtin_amdgcn_s_barrier()
; #define PG8_SCHED __builtin_amdgcn_sched_barrier(0)
; template <class Epi, class Sched>
; __device__ __forceinline__ void gemm_phase(LAS unsigned char* lds, const Gemm g, const Sched& S, const Epi& E) {
;     ...
;             PG8_LDB(B0, 0, 0); PG8_SCHED; PG8_LDA(At, 0, 0); PG8_STAGE(PG8_SA(1, 1), a1 + hstepA, voffA);
;             PG8_WAIT_L(8); PG8_BAR; PG8_WAIT_L(0); PG8_MMA(0, 0, At, B0); PG8_BAR; PG8_SCHED;
;             PG8_LDB(B1, 0, 1); PG8_STAGE(PG8_SB(0, 0), b2, voffB);
;             PG8_BAR; PG8_WAIT_L(0); PG8_MMA(0, 1, At, B1); PG8_BAR;
;             PG8_LDA(At, 0, 1); PG8_STAGE(PG8_SA(0, 0), a2, voffA);
;             PG8_BAR; PG8_WAIT_L(0); PG8_MMA(1, 0, At, B0); PG8_BAR; PG8_SCHED;
;             PG8_STAGE(PG8_SB(0, 1), b2 + hstepB, voffB);
;             PG8_WAIT_V(6); PG8_BAR; PG8_MMA(1, 1, At, B1); PG8_BAR;
	v_mfma_f32_16x16x32_bf16 v[128:131], v[132:135], v[148:151], v[128:131]
	v_mfma_f32_16x16x32_bf16 v[124:127], v[140:143], v[148:151], v[124:127]
	v_mfma_f32_16x16x32_bf16 v[112:115], v[132:135], v[156:159], v[112:115]
	v_mfma_f32_16x16x32_bf16 v[108:111], v[140:143], v[156:159], v[108:111]
	v_mfma_f32_16x16x32_bf16 v[100:103], v[132:135], v[164:167], v[100:103]
	v_mfma_f32_16x16x32_bf16 v[92:95], v[140:143], v[164:167], v[92:95]
	v_mfma_f32_16x16x32_bf16 v[84:87], v[132:135], v[172:175], v[84:87]
	v_mfma_f32_16x16x32_bf16 v[76:79], v[140:143], v[172:175], v[76:79]
	v_mfma_f32_16x16x32_bf16 v[128:131], v[136:139], v[152:155], v[128:131]
	v_mfma_f32_16x16x32_bf16 v[124:127], v[144:147], v[152:155], v[124:127]
	v_mfma_f32_16x16x32_bf16 v[112:115], v[136:139], v[160:163], v[112:115]
	v_mfma_f32_16x16x32_bf16 v[108:111], v[144:147], v[160:163], v[108:111]
	v_mfma_f32_16x16x32_bf16 v[100:103], v[136:139], v[168:171], v[100:103]
	v_mfma_f32_16x16x32_bf16 v[92:95], v[144:147], v[168:171], v[92:95]
	v_mfma_f32_16x16x32_bf16 v[84:87], v[136:139], v[176:179], v[84:87]
	v_mfma_f32_16x16x32_bf16 v[76:79], v[144:147], v[176:179], v[76:79]
	v_mfma_f32_16x16x32_bf16 v[120:123], v[180:183], v[148:151], v[120:123]
	v_mfma_f32_16x16x32_bf16 v[116:119], v[188:191], v[148:151], v[116:119]
	v_mfma_f32_16x16x32_bf16 v[104:107], v[180:183], v[156:159], v[104:107]
	v_mfma_f32_16x16x32_bf16 v[96:99], v[188:191], v[156:159], v[96:99]
	v_mfma_f32_16x16x32_bf16 v[88:91], v[180:183], v[164:167], v[88:91]
	v_mfma_f32_16x16x32_bf16 v[80:83], v[188:191], v[164:167], v[80:83]
	v_mfma_f32_16x16x32_bf16 v[72:75], v[180:183], v[172:175], v[72:75]
	v_mfma_f32_16x16x32_bf16 v[68:71], v[188:191], v[172:175], v[68:71]
	v_mfma_f32_16x16x32_bf16 v[120:123], v[184:187], v[152:155], v[120:123]
	v_mfma_f32_16x16x32_bf16 v[116:119], v[202:205], v[152:155], v[116:119]
	v_mfma_f32_16x16x32_bf16 v[104:107], v[184:187], v[160:163], v[104:107]
	v_mfma_f32_16x16x32_bf16 v[96:99], v[202:205], v[160:163], v[96:99]
	v_mfma_f32_16x16x32_bf16 v[88:91], v[184:187], v[168:171], v[88:91]
	v_mfma_f32_16x16x32_bf16 v[80:83], v[202:205], v[168:171], v[80:83]
	v_mfma_f32_16x16x32_bf16 v[72:75], v[184:187], v[176:179], v[72:75]
	v_mfma_f32_16x16x32_bf16 v[68:71], v[202:205], v[176:179], v[68:71]
	s_barrier
	ds_read_b128 v[148:151], v224 offset:16384
	ds_read_b128 v[152:155], v224 offset:17408
	ds_read_b128 v[156:159], v224 offset:18432
	ds_read_b128 v[160:163], v224 offset:19456
	ds_read_b128 v[164:167], v224 offset:20480
	ds_read_b128 v[168:171], v224 offset:21504
	ds_read_b128 v[172:175], v224 offset:22528
	ds_read_b128 v[176:179], v224 offset:23552
	s_add_i32 s52, s52, s30
	v_lshl_add_u64 v[206:207], s[20:21], 0, v[2:3]
	s_mov_b32 m0, s52
	s_nop 0
	global_load_lds_dwordx4 v[206:207], off
	v_lshl_add_u64 v[208:209], s[20:21], 0, v[192:193]
	s_add_i32 m0, s52, 0x2000
	s_nop 0
	global_load_lds_dwordx4 v[208:209], off
	s_mov_b32 m0, s31
	v_lshl_add_u64 v[210:211], s[24:25], 0, v[196:197]
	global_load_lds_dwordx4 v[210:211], off
	v_lshl_add_u64 v[212:213], s[24:25], 0, v[194:195]
	s_mov_b32 m0, s35
	s_nop 0
	global_load_lds_dwordx4 v[212:213], off
	s_add_u32 s52, s20, 0x80000
	s_addc_u32 s53, s21, 0
	s_add_i32 s54, s54, s30
	s_mov_b32 m0, s54
	s_nop 0
	global_load_lds_dwordx4 v2, s[52:53]
	s_add_i32 m0, s54, 0x2000
	s_nop 0
	global_load_lds_dwordx4 v192, s[52:53]
	s_waitcnt lgkmcnt(0)
	s_waitcnt vmcnt(6)
	s_barrier
	v_mfma_f32_16x16x32_bf16 v[64:67], v[132:135], v[148:151], v[64:67]
	v_mfma_f32_16x16x32_bf16 v[60:63], v[140:143], v[148:151], v[60:63]
	v_mfma_f32_16x16x32_bf16 v[52:55], v[132:135], v[156:159], v[52:55]
	v_mfma_f32_16x16x32_bf16 v[44:47], v[140:143], v[156:159], v[44:47]
	v_mfma_f32_16x16x32_bf16 v[36:39], v[132:135], v[164:167], v[36:39]
	v_mfma_f32_16x16x32_bf16 v[28:31], v[140:143], v[164:167], v[28:31]
	v_mfma_f32_16x16x32_bf16 v[20:23], v[132:135], v[172:175], v[20:23]
	v_mfma_f32_16x16x32_bf16 v[12:15], v[140:143], v[172:175], v[12:15]
	v_mfma_f32_16x16x32_bf16 v[64:67], v[136:139], v[152:155], v[64:67]
	v_mfma_f32_16x16x32_bf16 v[60:63], v[144:147], v[152:155], v[60:63]
	v_mfma_f32_16x16x32_bf16 v[52:55], v[136:139], v[160:163], v[52:55]
	v_mfma_f32_16x16x32_bf16 v[44:47], v[144:147], v[160:163], v[44:47]
	v_mfma_f32_16x16x32_bf16 v[36:39], v[136:139], v[168:171], v[36:39]
	v_mfma_f32_16x16x32_bf16 v[28:31], v[144:147], v[168:171], v[28:31]
	v_mfma_f32_16x16x32_bf16 v[20:23], v[136:139], v[176:179], v[20:23]
	v_mfma_f32_16x16x32_bf16 v[12:15], v[144:147], v[176:179], v[12:15]
	v_mfma_f32_16x16x32_bf16 v[56:59], v[180:183], v[148:151], v[56:59]
	v_mfma_f32_16x16x32_bf16 v[48:51], v[188:191], v[148:151], v[48:51]
	v_mfma_f32_16x16x32_bf16 v[40:43], v[180:183], v[156:159], v[40:43]
	v_mfma_f32_16x16x32_bf16 v[32:35], v[188:191], v[156:159], v[32:35]
	v_mfma_f32_16x16x32_bf16 v[24:27], v[180:183], v[164:167], v[24:27]
	v_mfma_f32_16x16x32_bf16 v[16:19], v[188:191], v[164:167], v[16:19]
	v_mfma_f32_16x16x32_bf16 v[8:11], v[180:183], v[172:175], v[8:11]
	v_mfma_f32_16x16x32_bf16 v[4:7], v[188:191], v[172:175], v[4:7]
	v_mfma_f32_16x16x32_bf16 v[56:59], v[184:187], v[152:155], v[56:59]
	v_mfma_f32_16x16x32_bf16 v[48:51], v[202:205], v[152:155], v[48:51]
	v_mfma_f32_16x16x32_bf16 v[40:43], v[184:187], v[160:163], v[40:43]
	v_mfma_f32_16x16x32_bf16 v[32:35], v[202:205], v[160:163], v[32:35]
	v_mfma_f32_16x16x32_bf16 v[24:27], v[184:187], v[168:171], v[24:27]
	v_mfma_f32_16x16x32_bf16 v[16:19], v[202:205], v[168:171], v[16:19]
	v_mfma_f32_16x16x32_bf16 v[8:11], v[184:187], v[176:179], v[8:11]
	v_mfma_f32_16x16x32_bf16 v[4:7], v[202:205], v[176:179], v[4:7]
	s_barrier
; #define PG8_STAGE(bufoff, gbase, voff) do { _Pragma("unroll") for (int _i = 0; _i < 2; ++_i) \
;         __builtin_amdgcn_global_load_lds((const unsigned*)((const char*)(gbase) + (voff)[_i]), (LAS unsigned*)(lds + (bufoff) + ldsw + _i * 8192), 16, 0, 0); } while (0)
; #define PG8_LDA(dst, b, h) do { _Pragma("unroll") for (int m = 0; m < 4; ++m) _Pragma("unroll") for (int k = 0; k < 2; ++k) dst[m][k] = *(const LAS bf16x8*)(lds + PG8_SA(b, h) + aoff + m * 2048 + k * 1024); } while (0)
; #define PG8_LDB(dst, b, h) do { _Pragma("unroll") for (int n = 0; n < 2; ++n) _Pragma("unroll") for (int k = 0; k < 2; ++k) dst[n][k] = *(const LAS bf16x8*)(lds + PG8_SB(b, h) + boff + n * 2048 + k * 1024); } while (0)
; #define PG8_MMA(ai, bj, At, Bt) do { __builtin_amdgcn_s_setprio(1); _Pragma("unroll") for (int m = 0; m < 4; ++m) _Pragma("unroll") for (int n = 0; n < 2; ++n) _Pragma("unroll") for (int k = 0; k < 2; ++k) \
;         acc[ai][bj][m][n] = __builtin_amdgcn_mfma_f32_16x16x32_bf16(Bt[n][k], At[m][k], acc[ai][bj][m][n], 0, 0, 0); __builtin_amdgcn_s_setprio(0); } while (0)
; #define PG8_WAIT_V(n) asm volatile("s_waitcnt vmcnt(" #n ")" ::: "memory")
; #define PG8_WAIT_L(n) asm volatile("s_waitcnt lgkmcnt(" #n ")" ::: "memory")
; #define PG8_BAR __builtin_amdgcn_s_barrier()
; #define PG8_SCHED __builtin_amdgcn_sched_barrier(0)
; template <class Epi, class Sched>
; __device__ __forceinline__ void gemm_phase(LAS unsigned char* lds, const Gemm g, const Sched& S, const Epi& E) {
;     ...
;             PG8_LDB(B0, 1, 0); PG8_SCHED; PG8_LDA(At, 1, 0); PG8_STAGE(PG8_SA(0, 1), a2 + hstepA, voffA);
;             PG8_WAIT_L(8); PG8_BAR; PG8_WAIT_L(0); PG8_MMA(0, 0, At, B0); PG8_BAR; PG8_SCHED;
;             PG8_LDB(B1, 1, 1); PG8_STAGE(PG8_SB(1, 0), b3, voffB);
;             PG8_BAR; PG8_WAIT_L(0); PG8_MMA(0, 1, At, B1); PG8_BAR;
;             PG8_LDA(At, 1, 1); PG8_STAGE(PG8_SA(1, 0), a3, voffA);
;             PG8_BAR; PG8_WAIT_L(0); PG8_MMA(1, 0, At, B0); PG8_BAR; PG8_SCHED;
;             PG8_STAGE(PG8_SB(1, 1), b3 + hstepB, voffB);
;             PG8_WAIT_V(6); PG8_BAR; PG8_MMA(1, 1, At, B1); PG8_BAR;
	s_add_i32 s52, 0, 0x18000
	v_add_u32_e32 v144, s52, v1
	ds_read_b128 v[132:135], v144
	ds_read_b128 v[136:139], v144 offset:1024
	ds_read_b128 v[140:143], v144 offset:2048
	ds_read_b128 v[144:147], v144 offset:3072
	s_add_u32 s24, s24, 0x80000
	s_addc_u32 s25, s25, 0
	ds_read_b128 v[148:151], v224 offset:32768
	ds_read_b128 v[152:155], v224 offset:33792
	ds_read_b128 v[156:159], v224 offset:34816
	ds_read_b128 v[160:163], v224 offset:35840
	ds_read_b128 v[164:167], v224 offset:36864
	ds_read_b128 v[168:171], v224 offset:37888
	ds_read_b128 v[172:175], v224 offset:38912
	ds_read_b128 v[176:179], v224 offset:39936
	s_mov_b32 m0, s36
	s_nop 0
	global_load_lds_dwordx4 v196, s[24:25]
	s_mov_b32 m0, s37
	s_nop 0
	global_load_lds_dwordx4 v194, s[24:25]
	s_add_i32 s24, 0, 0x1c000
	v_add_u32_e32 v202, s24, v1
	ds_read_b128 v[180:183], v202
	ds_read_b128 v[184:187], v202 offset:1024
	ds_read_b128 v[188:191], v202 offset:2048
	ds_read_b128 v[202:205], v202 offset:3072
	s_waitcnt lgkmcnt(0)
	s_barrier
	v_mfma_f32_16x16x32_bf16 v[128:131], v[132:135], v[148:151], v[128:131]
	v_mfma_f32_16x16x32_bf16 v[124:127], v[140:143], v[148:151], v[124:127]
	v_mfma_f32_16x16x32_bf16 v[112:115], v[132:135], v[156:159], v[112:115]
	v_mfma_f32_16x16x32_bf16 v[108:111], v[140:143], v[156:159], v[108:111]
	v_mfma_f32_16x16x32_bf16 v[100:103], v[132:135], v[164:167], v[100:103]
	v_mfma_f32_16x16x32_bf16 v[92:95], v[140:143], v[164:167], v[92:95]
	v_mfma_f32_16x16x32_bf16 v[84:87], v[132:135], v[172:175], v[84:87]
	v_mfma_f32_16x16x32_bf16 v[76:79], v[140:143], v[172:175], v[76:79]
	v_mfma_f32_16x16x32_bf16 v[128:131], v[136:139], v[152:155], v[128:131]
	v_mfma_f32_16x16x32_bf16 v[124:127], v[144:147], v[152:155], v[124:127]
	v_mfma_f32_16x16x32_bf16 v[112:115], v[136:139], v[160:163], v[112:115]
	v_mfma_f32_16x16x32_bf16 v[108:111], v[144:147], v[160:163], v[108:111]
	v_mfma_f32_16x16x32_bf16 v[100:103], v[136:139], v[168:171], v[100:103]
	v_mfma_f32_16x16x32_bf16 v[92:95], v[144:147], v[168:171], v[92:95]
	v_mfma_f32_16x16x32_bf16 v[84:87], v[136:139], v[176:179], v[84:87]
	v_mfma_f32_16x16x32_bf16 v[76:79], v[144:147], v[176:179], v[76:79]
	v_mfma_f32_16x16x32_bf16 v[120:123], v[180:183], v[148:151], v[120:123]
	v_mfma_f32_16x16x32_bf16 v[116:119], v[188:191], v[148:151], v[116:119]
	v_mfma_f32_16x16x32_bf16 v[104:107], v[180:183], v[156:159], v[104:107]
	v_mfma_f32_16x16x32_bf16 v[96:99], v[188:191], v[156:159], v[96:99]
	v_mfma_f32_16x16x32_bf16 v[88:91], v[180:183], v[164:167], v[88:91]
	v_mfma_f32_16x16x32_bf16 v[80:83], v[188:191], v[164:167], v[80:83]
	v_mfma_f32_16x16x32_bf16 v[72:75], v[180:183], v[172:175], v[72:75]
	v_mfma_f32_16x16x32_bf16 v[68:71], v[188:191], v[172:175], v[68:71]
	v_mfma_f32_16x16x32_bf16 v[120:123], v[184:187], v[152:155], v[120:123]
	v_mfma_f32_16x16x32_bf16 v[116:119], v[202:205], v[152:155], v[116:119]
	v_mfma_f32_16x16x32_bf16 v[104:107], v[184:187], v[160:163], v[104:107]
	v_mfma_f32_16x16x32_bf16 v[96:99], v[202:205], v[160:163], v[96:99]
	v_mfma_f32_16x16x32_bf16 v[88:91], v[184:187], v[168:171], v[88:91]
	v_mfma_f32_16x16x32_bf16 v[80:83], v[202:205], v[168:171], v[80:83]
	v_mfma_f32_16x16x32_bf16 v[72:75], v[184:187], v[176:179], v[72:75]
	v_mfma_f32_16x16x32_bf16 v[68:71], v[202:205], v[176:179], v[68:71]
	s_barrier
	ds_read_b128 v[148:151], v224 offset:49152
	ds_read_b128 v[152:155], v224 offset:50176
	ds_read_b128 v[156:159], v224 offset:51200
	ds_read_b128 v[160:163], v224 offset:52224
	ds_read_b128 v[164:167], v224 offset:53248
	ds_read_b128 v[168:171], v224 offset:54272
	ds_read_b128 v[172:175], v224 offset:55296
	ds_read_b128 v[176:179], v224 offset:56320
	s_add_i32 s25, s52, s30
	v_lshl_add_u64 v[206:207], v[206:207], 0, s[8:9]
	s_mov_b32 m0, s25
	s_nop 0
	global_load_lds_dwordx4 v[206:207], off
	v_lshl_add_u64 v[206:207], v[208:209], 0, s[8:9]
	s_add_i32 m0, s25, 0x2000
	s_nop 0
	global_load_lds_dwordx4 v[206:207], off
	s_mov_b32 m0, s42
	v_lshl_add_u64 v[206:207], v[210:211], 0, s[8:9]
	global_load_lds_dwordx4 v[206:207], off
	v_lshl_add_u64 v[206:207], v[212:213], 0, s[8:9]
	s_mov_b32 m0, s43
	s_nop 0
	global_load_lds_dwordx4 v[206:207], off
	s_add_u32 s20, s20, 0x80080
	s_addc_u32 s21, s21, 0
	s_add_i32 s24, s24, s30
	s_mov_b32 m0, s24
	s_nop 0
	global_load_lds_dwordx4 v2, s[20:21]
	s_add_i32 m0, s24, 0x2000
	s_nop 0
	global_load_lds_dwordx4 v192, s[20:21]
	s_add_i32 s51, s51, 2
	s_add_u32 s6, s6, 0x100
	s_addc_u32 s7, s7, 0
	s_add_u32 s49, s49, 0x100
	s_addc_u32 s50, s50, 0
	s_cmp_gt_u32 s51, 29
	s_waitcnt lgkmcnt(0)
	s_waitcnt vmcnt(6)
	s_barrier
	v_mfma_f32_16x16x32_bf16 v[64:67], v[132:135], v[148:151], v[64:67]
	v_mfma_f32_16x16x32_bf16 v[60:63], v[140:143], v[148:151], v[60:63]
	v_mfma_f32_16x16x32_bf16 v[52:55], v[132:135], v[156:159], v[52:55]
	v_mfma_f32_16x16x32_bf16 v[44:47], v[140:143], v[156:159], v[44:47]
	v_mfma_f32_16x16x32_bf16 v[36:39], v[132:135], v[164:167], v[36:39]
	v_mfma_f32_16x16x32_bf16 v[28:31], v[140:143], v[164:167], v[28:31]
	v_mfma_f32_16x16x32_bf16 v[20:23], v[132:135], v[172:175], v[20:23]
	v_mfma_f32_16x16x32_bf16 v[12:15], v[140:143], v[172:175], v[12:15]
	v_mfma_f32_16x16x32_bf16 v[64:67], v[136:139], v[152:155], v[64:67]
	v_mfma_f32_16x16x32_bf16 v[60:63], v[144:147], v[152:155], v[60:63]
	v_mfma_f32_16x16x32_bf16 v[52:55], v[136:139], v[160:163], v[52:55]
	v_mfma_f32_16x16x32_bf16 v[44:47], v[144:147], v[160:163], v[44:47]
	v_mfma_f32_16x16x32_bf16 v[36:39], v[136:139], v[168:171], v[36:39]
	v_mfma_f32_16x16x32_bf16 v[28:31], v[144:147], v[168:171], v[28:31]
	v_mfma_f32_16x16x32_bf16 v[20:23], v[136:139], v[176:179], v[20:23]
	v_mfma_f32_16x16x32_bf16 v[12:15], v[144:147], v[176:179], v[12:15]
	v_mfma_f32_16x16x32_bf16 v[56:59], v[180:183], v[148:151], v[56:59]
	v_mfma_f32_16x16x32_bf16 v[48:51], v[188:191], v[148:151], v[48:51]
	v_mfma_f32_16x16x32_bf16 v[40:43], v[180:183], v[156:159], v[40:43]
	v_mfma_f32_16x16x32_bf16 v[32:35], v[188:191], v[156:159], v[32:35]
	v_mfma_f32_16x16x32_bf16 v[24:27], v[180:183], v[164:167], v[24:27]
	v_mfma_f32_16x16x32_bf16 v[16:19], v[188:191], v[164:167], v[16:19]
	v_mfma_f32_16x16x32_bf16 v[8:11], v[180:183], v[172:175], v[8:11]
	v_mfma_f32_16x16x32_bf16 v[4:7], v[188:191], v[172:175], v[4:7]
	v_mfma_f32_16x16x32_bf16 v[56:59], v[184:187], v[152:155], v[56:59]
	v_mfma_f32_16x16x32_bf16 v[48:51], v[202:205], v[152:155], v[48:51]
	v_mfma_f32_16x16x32_bf16 v[40:43], v[184:187], v[160:163], v[40:43]
	v_mfma_f32_16x16x32_bf16 v[32:35], v[202:205], v[160:163], v[32:35]
	v_mfma_f32_16x16x32_bf16 v[24:27], v[184:187], v[168:171], v[24:27]
	v_mfma_f32_16x16x32_bf16 v[16:19], v[202:205], v[168:171], v[16:19]
	v_mfma_f32_16x16x32_bf16 v[8:11], v[184:187], v[176:179], v[8:11]
	v_mfma_f32_16x16x32_bf16 v[4:7], v[202:205], v[176:179], v[4:7]
	s_barrier
	s_cbranch_scc0 .LBB0_1396
	s_setprio 0
	s_cmpk_gt_u32 s2, 0xff
	s_cbranch_scc1 .Lalign_a_1396
	s_barrier

; #define PG8_STAGE(bufoff, gbase, voff) do { _Pragma("unroll") for (int _i = 0; _i < 2; ++_i) \
;         __builtin_amdgcn_global_load_lds((const unsigned*)((const char*)(gbase) + (voff)[_i]), (LAS unsigned*)(lds + (bufoff) + ldsw + _i * 8192), 16, 0, 0); } while (0)
; #define PG8_LDA(dst, b, h) do { _Pragma("unroll") for (int m = 0; m < 4; ++m) _Pragma("unroll") for (int k = 0; k < 2; ++k) dst[m][k] = *(const LAS bf16x8*)(lds + PG8_SA(b, h) + aoff + m * 2048 + k * 1024); } while (0)
; #define PG8_LDB(dst, b, h) do { _Pragma("unroll") for (int n = 0; n < 2; ++n) _Pragma("unroll") for (int k = 0; k < 2; ++k) dst[n][k] = *(const LAS bf16x8*)(lds + PG8_SB(b, h) + boff + n * 2048 + k * 1024); } while (0)
; #define PG8_MMA(ai, bj, At, Bt) do { __builtin_amdgcn_s_setprio(1); _Pragma("unroll") for (int m = 0; m < 4; ++m) _Pragma("unroll") for (int n = 0; n < 2; ++n) _Pragma("unroll") for (int k = 0; k < 2; ++k) \
;         acc[ai][bj][m][n] = __builtin_amdgcn_mfma_f32_16x16x32_bf16(Bt[n][k], At[m][k], acc[ai][bj][m][n], 0, 0, 0); __builtin_amdgcn_s_setprio(0); } while (0)
; #define PG8_BAR __builtin_amdgcn_s_barrier()
; template <class Epi, class Sched>
; __device__ __forceinline__ void gemm_phase(LAS unsigned char* lds, const Gemm g, const Sched& S, const Epi& E) {
;     ...
;         const bool has_next = S.next(ui + 1, nxt);
;         const char* nA = has_next ? (const char*)g.A + (size_t)nxt.pm * tstepA : cA; const char* nB = has_next ? (const char*)g.Bt + (size_t)nxt.pn * tstepB : cB;
;         for (int t = 0; t < nt; t += 2) {
;             const bool last = (t == nt - 2);
;             const char* a1 = cA + (size_t)(t + 1) * kstep;
;             const char* a2 = last ? nA : cA + (size_t)(t + 2) * kstep; const char* b2 = last ? nB : cB + (size_t)(t + 2) * kstep;
;             const char* a3 = a2 + kstep; const char* b3 = b2 + kstep;
;             if (last && has_next) S.a_ready(nxt);
;             PG8_LDB(B0, 0, 0); PG8_SCHED; PG8_LDA(At, 0, 0); PG8_STAGE(PG8_SA(1, 1), a1 + hstepA, voffA);
;             PG8_WAIT_L(8); PG8_BAR; PG8_WAIT_L(0); PG8_MMA(0, 0, At, B0); PG8_BAR; PG8_SCHED;
;             PG8_LDB(B1, 0, 1); PG8_STAGE(PG8_SB(0, 0), b2, voffB);
;             PG8_BAR; PG8_WAIT_L(0); PG8_MMA(0, 1, At, B1); PG8_BAR;
;             PG8_LDA(At, 0, 1); PG8_STAGE(PG8_SA(0, 0), a2, voffA);
;             PG8_BAR; PG8_WAIT_L(0); PG8_MMA(1, 0, At, B0); PG8_BAR; PG8_SCHED;
.LBB0_1525:
	v_mov_b64_e32 v[4:5], 0x1600
	s_ashr_i32 s57, s56, 31
	v_cmp_lt_i64_e32 vcc, s[14:15], v[4:5]
	s_lshl_b64 s[14:15], s[56:57], 20
	s_add_u32 s58, s88, s14
	s_addc_u32 s59, s89, s15
	s_and_b64 s[14:15], vcc, exec
	s_cselect_b32 s57, s59, s5
	s_cselect_b32 s67, s58, s4
	s_ashr_i32 s55, s54, 31
	s_lshl_b64 s[14:15], s[54:55], 20
	s_add_u32 s60, s2, s14
	s_addc_u32 s61, s18, s15
	s_and_b64 s[14:15], vcc, exec
	s_cselect_b32 s55, s61, s7
	s_cselect_b32 s68, s60, s6
	s_add_u32 s4, s4, 0x80080
	s_addc_u32 s5, s5, 0
	s_add_u32 s69, s6, 0x100
	s_addc_u32 s70, s7, 0
	s_mov_b32 s71, -2
	s_setprio 0
	s_add_u32 s6, s4, 0xfff80080
	s_addc_u32 s7, s5, -1
	s_add_i32 s72, 0, 0x10000
	v_add_u32_e32 v2, s72, v1
	ds_read_b128 v[132:135], v2
	ds_read_b128 v[136:139], v2 offset:1024
	ds_read_b128 v[140:143], v2 offset:2048
	ds_read_b128 v[144:147], v2 offset:3072
	s_cmp_eq_u32 s71, 28
	s_cselect_b32 s15, s57, s7
	s_cselect_b32 s14, s67, s6
	s_cselect_b32 s7, s55, s70
	s_cselect_b32 s6, s68, s69
	ds_read_b128 v[148:151], v207
	ds_read_b128 v[152:155], v207 offset:1024
	ds_read_b128 v[156:159], v207 offset:2048
	ds_read_b128 v[160:163], v207 offset:3072
	ds_read_b128 v[164:167], v207 offset:4096
	ds_read_b128 v[168:171], v207 offset:5120
	ds_read_b128 v[186:189], v207 offset:6144
	ds_read_b128 v[190:193], v207 offset:7168
	s_add_i32 s74, 0, 0x14000
	v_add_u32_e32 v2, s74, v1
	ds_read_b128 v[194:197], v2
	ds_read_b128 v[198:201], v2 offset:1024
	ds_read_b128 v[202:205], v2 offset:2048
	ds_read_b128 v[208:211], v2 offset:3072
	s_add_i32 m0, s20, 0xc000
	s_nop 0
	global_load_lds_dwordx4 v182, s[4:5]
	s_add_i32 m0, s20, 0xe000
	s_nop 0
	global_load_lds_dwordx4 v184, s[4:5]
	s_waitcnt lgkmcnt(0)
	s_barrier
	v_mfma_f32_16x16x32_bf16 v[68:71], v[132:135], v[148:151], 0
	v_mfma_f32_16x16x32_bf16 v[72:75], v[140:143], v[148:151], 0
	v_mfma_f32_16x16x32_bf16 v[120:123], v[132:135], v[156:159], 0
	v_mfma_f32_16x16x32_bf16 v[116:119], v[140:143], v[156:159], 0
	v_mfma_f32_16x16x32_bf16 v[112:115], v[132:135], v[164:167], 0
	v_mfma_f32_16x16x32_bf16 v[108:111], v[140:143], v[164:167], 0
	v_mfma_f32_16x16x32_bf16 v[104:107], v[132:135], v[186:189], 0
	v_mfma_f32_16x16x32_bf16 v[100:103], v[140:143], v[186:189], 0
	v_mfma_f32_16x16x32_bf16 v[68:71], v[136:139], v[152:155], v[68:71]
	v_mfma_f32_16x16x32_bf16 v[72:75], v[144:147], v[152:155], v[72:75]
	v_mfma_f32_16x16x32_bf16 v[120:123], v[136:139], v[160:163], v[120:123]
	v_mfma_f32_16x16x32_bf16 v[116:119], v[144:147], v[160:163], v[116:119]
	v_mfma_f32_16x16x32_bf16 v[112:115], v[136:139], v[168:171], v[112:115]
	v_mfma_f32_16x16x32_bf16 v[108:111], v[144:147], v[168:171], v[108:111]
	v_mfma_f32_16x16x32_bf16 v[104:107], v[136:139], v[190:193], v[104:107]
	v_mfma_f32_16x16x32_bf16 v[100:103], v[144:147], v[190:193], v[100:103]
	v_mfma_f32_16x16x32_bf16 v[76:79], v[194:197], v[148:151], 0
	v_mfma_f32_16x16x32_bf16 v[80:83], v[202:205], v[148:151], 0
	v_mfma_f32_16x16x32_bf16 v[96:99], v[194:197], v[156:159], 0
	v_mfma_f32_16x16x32_bf16 v[92:95], v[202:205], v[156:159], 0
	v_mfma_f32_16x16x32_bf16 v[88:91], v[194:197], v[164:167], 0
	v_mfma_f32_16x16x32_bf16 v[84:87], v[202:205], v[164:167], 0
	v_mfma_f32_16x16x32_bf16 v[128:131], v[194:197], v[186:189], 0
	v_mfma_f32_16x16x32_bf16 v[124:127], v[202:205], v[186:189], 0
	v_mfma_f32_16x16x32_bf16 v[76:79], v[198:201], v[152:155], v[76:79]
	v_mfma_f32_16x16x32_bf16 v[80:83], v[208:211], v[152:155], v[80:83]
	v_mfma_f32_16x16x32_bf16 v[96:99], v[198:201], v[160:163], v[96:99]
	v_mfma_f32_16x16x32_bf16 v[92:95], v[208:211], v[160:163], v[92:95]
	v_mfma_f32_16x16x32_bf16 v[88:91], v[198:201], v[168:171], v[88:91]
	v_mfma_f32_16x16x32_bf16 v[84:87], v[208:211], v[168:171], v[84:87]
	v_mfma_f32_16x16x32_bf16 v[128:131], v[198:201], v[190:193], v[128:131]
	v_mfma_f32_16x16x32_bf16 v[124:127], v[208:211], v[190:193], v[124:127]
	s_barrier
	ds_read_b128 v[148:151], v207 offset:16384
	ds_read_b128 v[152:155], v207 offset:17408
	ds_read_b128 v[156:159], v207 offset:18432
	ds_read_b128 v[160:163], v207 offset:19456
	ds_read_b128 v[164:167], v207 offset:20480
	ds_read_b128 v[168:171], v207 offset:21504
	ds_read_b128 v[186:189], v207 offset:22528
	ds_read_b128 v[190:193], v207 offset:23552
	s_add_i32 s72, s72, s19
	v_lshl_add_u64 v[172:173], s[6:7], 0, v[178:179]
	s_mov_b32 m0, s72
	s_nop 0
	global_load_lds_dwordx4 v[172:173], off
	v_lshl_add_u64 v[212:213], s[6:7], 0, v[174:175]
	s_add_i32 m0, s72, 0x2000
	s_nop 0
	global_load_lds_dwordx4 v[212:213], off
	s_mov_b32 m0, s20
	v_lshl_add_u64 v[216:217], s[14:15], 0, v[180:181]
	global_load_lds_dwordx4 v[216:217], off
	v_lshl_add_u64 v[218:219], s[14:15], 0, v[176:177]
	s_mov_b32 m0, s21
	s_nop 0
	global_load_lds_dwordx4 v[218:219], off
	s_add_u32 s72, s6, 0x80000
	s_addc_u32 s73, s7, 0
	s_add_i32 s74, s74, s19
	s_mov_b32 m0, s74
	s_nop 0
	global_load_lds_dwordx4 v178, s[72:73]
	s_add_i32 m0, s74, 0x2000
	s_nop 0
	global_load_lds_dwordx4 v174, s[72:73]
	s_waitcnt lgkmcnt(0)
	s_waitcnt vmcnt(6)
	s_barrier
; #define PG8_STAGE(bufoff, gbase, voff) do { _Pragma("unroll") for (int _i = 0; _i < 2; ++_i) \
;         __builtin_amdgcn_global_load_lds((const unsigned*)((const char*)(gbase) + (voff)[_i]), (LAS unsigned*)(lds + (bufoff) + ldsw + _i * 8192), 16, 0, 0); } while (0)
; #define PG8_LDA(dst, b, h) do { _Pragma("unroll") for (int m = 0; m < 4; ++m) _Pragma("unroll") for (int k = 0; k < 2; ++k) dst[m][k] = *(const LAS bf16x8*)(lds + PG8_SA(b, h) + aoff + m * 2048 + k * 1024); } while (0)
; #define PG8_LDB(dst, b, h) do { _Pragma("unroll") for (int n = 0; n < 2; ++n) _Pragma("unroll") for (int k = 0; k < 2; ++k) dst[n][k] = *(const LAS bf16x8*)(lds + PG8_SB(b, h) + boff + n * 2048 + k * 1024); } while (0)
; #define PG8_MMA(ai, bj, At, Bt) do { __builtin_amdgcn_s_setprio(1); _Pragma("unroll") for (int m = 0; m < 4; ++m) _Pragma("unroll") for (int n = 0; n < 2; ++n) _Pragma("unroll") for (int k = 0; k < 2; ++k) \
;         acc[ai][bj][m][n] = __builtin_amdgcn_mfma_f32_16x16x32_bf16(Bt[n][k], At[m][k], acc[ai][bj][m][n], 0, 0, 0); __builtin_amdgcn_s_setprio(0); } while (0)
; #define PG8_WAIT_V(n) asm volatile("s_waitcnt vmcnt(" #n ")" ::: "memory")
; #define PG8_WAIT_L(n) asm volatile("s_waitcnt lgkmcnt(" #n ")" ::: "memory")
; #define PG8_BAR __builtin_amdgcn_s_barrier()
; #define PG8_SCHED __builtin_amdgcn_sched_barrier(0)
; template <class Epi, class Sched>
; __device__ __forceinline__ void gemm_phase(LAS unsigned char* lds, const Gemm g, const Sched& S, const Epi& E) {
;     ...
;             PG8_BAR; PG8_WAIT_L(0); PG8_MMA(1, 0, At, B0); PG8_BAR; PG8_SCHED;
;             PG8_STAGE(PG8_SB(0, 1), b2 + hstepB, voffB);
;             PG8_WAIT_V(6); PG8_BAR; PG8_MMA(1, 1, At, B1); PG8_BAR;
;             PG8_LDB(B0, 1, 0); PG8_SCHED; PG8_LDA(At, 1, 0); PG8_STAGE(PG8_SA(0, 1), a2 + hstepA, voffA);
;             PG8_WAIT_L(8); PG8_BAR; PG8_WAIT_L(0); PG8_MMA(0, 0, At, B0); PG8_BAR; PG8_SCHED;
;             PG8_LDB(B1, 1, 1); PG8_STAGE(PG8_SB(1, 0), b3, voffB);
;             PG8_BAR; PG8_WAIT_L(0); PG8_MMA(0, 1, At, B1); PG8_BAR;
	v_mfma_f32_16x16x32_bf16 v[56:59], v[132:135], v[148:151], 0
	v_mfma_f32_16x16x32_bf16 v[52:55], v[140:143], v[148:151], 0
	v_mfma_f32_16x16x32_bf16 v[48:51], v[132:135], v[156:159], 0
	v_mfma_f32_16x16x32_bf16 v[44:47], v[140:143], v[156:159], 0
	v_mfma_f32_16x16x32_bf16 v[40:43], v[132:135], v[164:167], 0
	v_mfma_f32_16x16x32_bf16 v[36:39], v[140:143], v[164:167], 0
	v_mfma_f32_16x16x32_bf16 v[32:35], v[132:135], v[186:189], 0
	v_mfma_f32_16x16x32_bf16 v[28:31], v[140:143], v[186:189], 0
	v_mfma_f32_16x16x32_bf16 v[56:59], v[136:139], v[152:155], v[56:59]
	v_mfma_f32_16x16x32_bf16 v[52:55], v[144:147], v[152:155], v[52:55]
	v_mfma_f32_16x16x32_bf16 v[48:51], v[136:139], v[160:163], v[48:51]
	v_mfma_f32_16x16x32_bf16 v[44:47], v[144:147], v[160:163], v[44:47]
	v_mfma_f32_16x16x32_bf16 v[40:43], v[136:139], v[168:171], v[40:43]
	v_mfma_f32_16x16x32_bf16 v[36:39], v[144:147], v[168:171], v[36:39]
	v_mfma_f32_16x16x32_bf16 v[32:35], v[136:139], v[190:193], v[32:35]
	v_mfma_f32_16x16x32_bf16 v[28:31], v[144:147], v[190:193], v[28:31]
	v_mfma_f32_16x16x32_bf16 v[24:27], v[194:197], v[148:151], 0
	v_mfma_f32_16x16x32_bf16 v[20:23], v[202:205], v[148:151], 0
	v_mfma_f32_16x16x32_bf16 v[16:19], v[194:197], v[156:159], 0
	v_mfma_f32_16x16x32_bf16 v[12:15], v[202:205], v[156:159], 0
	v_mfma_f32_16x16x32_bf16 v[8:11], v[194:197], v[164:167], 0
	v_mfma_f32_16x16x32_bf16 v[4:7], v[202:205], v[164:167], 0
	v_mfma_f32_16x16x32_bf16 v[60:63], v[194:197], v[186:189], 0
	v_mfma_f32_16x16x32_bf16 v[64:67], v[202:205], v[186:189], 0
	v_mfma_f32_16x16x32_bf16 v[24:27], v[198:201], v[152:155], v[24:27]
	v_mfma_f32_16x16x32_bf16 v[20:23], v[208:211], v[152:155], v[20:23]
	v_mfma_f32_16x16x32_bf16 v[16:19], v[198:201], v[160:163], v[16:19]
	v_mfma_f32_16x16x32_bf16 v[12:15], v[208:211], v[160:163], v[12:15]
	v_mfma_f32_16x16x32_bf16 v[8:11], v[198:201], v[168:171], v[8:11]
	v_mfma_f32_16x16x32_bf16 v[4:7], v[208:211], v[168:171], v[4:7]
	v_mfma_f32_16x16x32_bf16 v[60:63], v[198:201], v[190:193], v[60:63]
	v_mfma_f32_16x16x32_bf16 v[64:67], v[208:211], v[190:193], v[64:67]
	s_barrier
	s_add_i32 s72, 0, 0x18000
	v_add_u32_e32 v2, s72, v1
	ds_read_b128 v[132:135], v2
	ds_read_b128 v[136:139], v2 offset:1024
	ds_read_b128 v[140:143], v2 offset:2048
	ds_read_b128 v[144:147], v2 offset:3072
	s_add_u32 s14, s14, 0x80000
	s_addc_u32 s15, s15, 0
	ds_read_b128 v[148:151], v207 offset:32768
	ds_read_b128 v[152:155], v207 offset:33792
	ds_read_b128 v[156:159], v207 offset:34816
	ds_read_b128 v[160:163], v207 offset:35840
	ds_read_b128 v[164:167], v207 offset:36864
	ds_read_b128 v[168:171], v207 offset:37888
	ds_read_b128 v[186:189], v207 offset:38912
	ds_read_b128 v[190:193], v207 offset:39936
	s_mov_b32 m0, s24
	s_nop 0
	global_load_lds_dwordx4 v180, s[14:15]
	s_mov_b32 m0, s25
	s_nop 0
	global_load_lds_dwordx4 v176, s[14:15]
	s_add_i32 s14, 0, 0x1c000
	v_add_u32_e32 v2, s14, v1
	ds_read_b128 v[194:197], v2
	ds_read_b128 v[198:201], v2 offset:1024
	ds_read_b128 v[202:205], v2 offset:2048
	ds_read_b128 v[208:211], v2 offset:3072
	s_waitcnt lgkmcnt(0)
	s_barrier
	v_mfma_f32_16x16x32_bf16 v[68:71], v[132:135], v[148:151], v[68:71]
	v_mfma_f32_16x16x32_bf16 v[72:75], v[140:143], v[148:151], v[72:75]
	v_mfma_f32_16x16x32_bf16 v[120:123], v[132:135], v[156:159], v[120:123]
	v_mfma_f32_16x16x32_bf16 v[116:119], v[140:143], v[156:159], v[116:119]
	v_mfma_f32_16x16x32_bf16 v[112:115], v[132:135], v[164:167], v[112:115]
	v_mfma_f32_16x16x32_bf16 v[108:111], v[140:143], v[164:167], v[108:111]
	v_mfma_f32_16x16x32_bf16 v[104:107], v[132:135], v[186:189], v[104:107]
	v_mfma_f32_16x16x32_bf16 v[100:103], v[140:143], v[186:189], v[100:103]
	v_mfma_f32_16x16x32_bf16 v[68:71], v[136:139], v[152:155], v[68:71]
	v_mfma_f32_16x16x32_bf16 v[72:75], v[144:147], v[152:155], v[72:75]
	v_mfma_f32_16x16x32_bf16 v[120:123], v[136:139], v[160:163], v[120:123]
	v_mfma_f32_16x16x32_bf16 v[116:119], v[144:147], v[160:163], v[116:119]
	v_mfma_f32_16x16x32_bf16 v[112:115], v[136:139], v[168:171], v[112:115]
	v_mfma_f32_16x16x32_bf16 v[108:111], v[144:147], v[168:171], v[108:111]
	v_mfma_f32_16x16x32_bf16 v[104:107], v[136:139], v[190:193], v[104:107]
	v_mfma_f32_16x16x32_bf16 v[100:103], v[144:147], v[190:193], v[100:103]
	v_mfma_f32_16x16x32_bf16 v[76:79], v[194:197], v[148:151], v[76:79]
	v_mfma_f32_16x16x32_bf16 v[80:83], v[202:205], v[148:151], v[80:83]
	v_mfma_f32_16x16x32_bf16 v[96:99], v[194:197], v[156:159], v[96:99]
	v_mfma_f32_16x16x32_bf16 v[92:95], v[202:205], v[156:159], v[92:95]
	v_mfma_f32_16x16x32_bf16 v[88:91], v[194:197], v[164:167], v[88:91]
	v_mfma_f32_16x16x32_bf16 v[84:87], v[202:205], v[164:167], v[84:87]
	v_mfma_f32_16x16x32_bf16 v[128:131], v[194:197], v[186:189], v[128:131]
	v_mfma_f32_16x16x32_bf16 v[124:127], v[202:205], v[186:189], v[124:127]
	v_mfma_f32_16x16x32_bf16 v[76:79], v[198:201], v[152:155], v[76:79]
	v_mfma_f32_16x16x32_bf16 v[80:83], v[208:211], v[152:155], v[80:83]
	v_mfma_f32_16x16x32_bf16 v[96:99], v[198:201], v[160:163], v[96:99]
	v_mfma_f32_16x16x32_bf16 v[92:95], v[208:211], v[160:163], v[92:95]
	v_mfma_f32_16x16x32_bf16 v[88:91], v[198:201], v[168:171], v[88:91]
	v_mfma_f32_16x16x32_bf16 v[84:87], v[208:211], v[168:171], v[84:87]
	v_mfma_f32_16x16x32_bf16 v[128:131], v[198:201], v[190:193], v[128:131]
	v_mfma_f32_16x16x32_bf16 v[124:127], v[208:211], v[190:193], v[124:127]
	s_barrier
; #define PG8_STAGE(bufoff, gbase, voff) do { _Pragma("unroll") for (int _i = 0; _i < 2; ++_i) \
;         __builtin_amdgcn_global_load_lds((const unsigned*)((const char*)(gbase) + (voff)[_i]), (LAS unsigned*)(lds + (bufoff) + ldsw + _i * 8192), 16, 0, 0); } while (0)
; #define PG8_LDA(dst, b, h) do { _Pragma("unroll") for (int m = 0; m < 4; ++m) _Pragma("unroll") for (int k = 0; k < 2; ++k) dst[m][k] = *(const LAS bf16x8*)(lds + PG8_SA(b, h) + aoff + m * 2048 + k * 1024); } while (0)
; #define PG8_LDB(dst, b, h) do { _Pragma("unroll") for (int n = 0; n < 2; ++n) _Pragma("unroll") for (int k = 0; k < 2; ++k) dst[n][k] = *(const LAS bf16x8*)(lds + PG8_SB(b, h) + boff + n * 2048 + k * 1024); } while (0)
; #define PG8_MMA(ai, bj, At, Bt) do { __builtin_amdgcn_s_setprio(1); _Pragma("unroll") for (int m = 0; m < 4; ++m) _Pragma("unroll") for (int n = 0; n < 2; ++n) _Pragma("unroll") for (int k = 0; k < 2; ++k) \
;         acc[ai][bj][m][n] = __builtin_amdgcn_mfma_f32_16x16x32_bf16(Bt[n][k], At[m][k], acc[ai][bj][m][n], 0, 0, 0); __builtin_amdgcn_s_setprio(0); } while (0)
; #define PG8_WAIT_V(n) asm volatile("s_waitcnt vmcnt(" #n ")" ::: "memory")
; #define PG8_WAIT_L(n) asm volatile("s_waitcnt lgkmcnt(" #n ")" ::: "memory")
; #define PG8_BAR __builtin_amdgcn_s_barrier()
; #define PG8_SCHED __builtin_amdgcn_sched_barrier(0)
; template <class Epi, class Sched>
; __device__ __forceinline__ void gemm_phase(LAS unsigned char* lds, const Gemm g, const Sched& S, const Epi& E) {
;     ...
;             PG8_LDB(B0, 0, 0); PG8_SCHED; PG8_LDA(At, 0, 0); PG8_STAGE(PG8_SA(1, 1), a1 + hstepA, voffA);
;             PG8_WAIT_L(8); PG8_BAR; PG8_WAIT_L(0); PG8_MMA(0, 0, At, B0); PG8_BAR; PG8_SCHED;
;     ...
;             PG8_LDA(At, 1, 1); PG8_STAGE(PG8_SA(1, 0), a3, voffA);
;             PG8_BAR; PG8_WAIT_L(0); PG8_MMA(1, 0, At, B0); PG8_BAR; PG8_SCHED;
;             PG8_STAGE(PG8_SB(1, 1), b3 + hstepB, voffB);
;             PG8_WAIT_V(6); PG8_BAR; PG8_MMA(1, 1, At, B1); PG8_BAR;
	ds_read_b128 v[148:151], v207 offset:49152
	ds_read_b128 v[152:155], v207 offset:50176
	ds_read_b128 v[156:159], v207 offset:51200
	ds_read_b128 v[160:163], v207 offset:52224
	ds_read_b128 v[164:167], v207 offset:53248
	ds_read_b128 v[168:171], v207 offset:54272
	ds_read_b128 v[186:189], v207 offset:55296
	ds_read_b128 v[190:193], v207 offset:56320
	s_add_i32 s15, s72, s19
	v_lshl_add_u64 v[172:173], v[172:173], 0, s[8:9]
	s_mov_b32 m0, s15
	s_nop 0
	global_load_lds_dwordx4 v[172:173], off
	v_lshl_add_u64 v[172:173], v[212:213], 0, s[8:9]
	s_add_i32 m0, s15, 0x2000
	s_nop 0
	global_load_lds_dwordx4 v[172:173], off
	s_mov_b32 m0, s30
	v_lshl_add_u64 v[172:173], v[216:217], 0, s[8:9]
	global_load_lds_dwordx4 v[172:173], off
	v_lshl_add_u64 v[172:173], v[218:219], 0, s[8:9]
	s_mov_b32 m0, s31
	s_nop 0
	global_load_lds_dwordx4 v[172:173], off
	s_add_u32 s6, s6, 0x80080
	s_addc_u32 s7, s7, 0
	s_add_i32 s14, s14, s19
	s_mov_b32 m0, s14
	s_nop 0
	global_load_lds_dwordx4 v178, s[6:7]
	s_add_i32 m0, s14, 0x2000
	s_nop 0
	global_load_lds_dwordx4 v174, s[6:7]
	s_add_i32 s71, s71, 2
	s_add_u32 s4, s4, 0x100
	s_addc_u32 s5, s5, 0
	s_add_u32 s69, s69, 0x100
	s_addc_u32 s70, s70, 0
	s_cmp_gt_u32 s71, 29
	s_waitcnt lgkmcnt(0)
	s_waitcnt vmcnt(6)
	s_barrier
	v_mfma_f32_16x16x32_bf16 v[56:59], v[132:135], v[148:151], v[56:59]
	v_mfma_f32_16x16x32_bf16 v[52:55], v[140:143], v[148:151], v[52:55]
	v_mfma_f32_16x16x32_bf16 v[48:51], v[132:135], v[156:159], v[48:51]
	v_mfma_f32_16x16x32_bf16 v[44:47], v[140:143], v[156:159], v[44:47]
	v_mfma_f32_16x16x32_bf16 v[40:43], v[132:135], v[164:167], v[40:43]
	v_mfma_f32_16x16x32_bf16 v[36:39], v[140:143], v[164:167], v[36:39]
	v_mfma_f32_16x16x32_bf16 v[32:35], v[132:135], v[186:189], v[32:35]
	v_mfma_f32_16x16x32_bf16 v[28:31], v[140:143], v[186:189], v[28:31]
	v_mfma_f32_16x16x32_bf16 v[56:59], v[136:139], v[152:155], v[56:59]
	v_mfma_f32_16x16x32_bf16 v[52:55], v[144:147], v[152:155], v[52:55]
	v_mfma_f32_16x16x32_bf16 v[48:51], v[136:139], v[160:163], v[48:51]
	v_mfma_f32_16x16x32_bf16 v[44:47], v[144:147], v[160:163], v[44:47]
	v_mfma_f32_16x16x32_bf16 v[40:43], v[136:139], v[168:171], v[40:43]
	v_mfma_f32_16x16x32_bf16 v[36:39], v[144:147], v[168:171], v[36:39]
	v_mfma_f32_16x16x32_bf16 v[32:35], v[136:139], v[190:193], v[32:35]
	v_mfma_f32_16x16x32_bf16 v[28:31], v[144:147], v[190:193], v[28:31]
	v_mfma_f32_16x16x32_bf16 v[24:27], v[194:197], v[148:151], v[24:27]
	v_mfma_f32_16x16x32_bf16 v[20:23], v[202:205], v[148:151], v[20:23]
	v_mfma_f32_16x16x32_bf16 v[16:19], v[194:197], v[156:159], v[16:19]
	v_mfma_f32_16x16x32_bf16 v[12:15], v[202:205], v[156:159], v[12:15]
	v_mfma_f32_16x16x32_bf16 v[8:11], v[194:197], v[164:167], v[8:11]
	v_mfma_f32_16x16x32_bf16 v[4:7], v[202:205], v[164:167], v[4:7]
	v_mfma_f32_16x16x32_bf16 v[60:63], v[194:197], v[186:189], v[60:63]
	v_mfma_f32_16x16x32_bf16 v[64:67], v[202:205], v[186:189], v[64:67]
	v_mfma_f32_16x16x32_bf16 v[24:27], v[198:201], v[152:155], v[24:27]
	v_mfma_f32_16x16x32_bf16 v[20:23], v[208:211], v[152:155], v[20:23]
	v_mfma_f32_16x16x32_bf16 v[16:19], v[198:201], v[160:163], v[16:19]
	v_mfma_f32_16x16x32_bf16 v[12:15], v[208:211], v[160:163], v[12:15]
	v_mfma_f32_16x16x32_bf16 v[8:11], v[198:201], v[168:171], v[8:11]
	v_mfma_f32_16x16x32_bf16 v[4:7], v[208:211], v[168:171], v[4:7]
	v_mfma_f32_16x16x32_bf16 v[60:63], v[198:201], v[190:193], v[60:63]
	v_mfma_f32_16x16x32_bf16 v[64:67], v[208:211], v[190:193], v[64:67]
	s_barrier
	s_setprio 0
.LBB0_1526:
	s_setprio 0
	s_add_u32 s6, s4, 0xfff80080
	s_addc_u32 s7, s5, -1
	s_add_i32 s72, 0, 0x10000
	v_add_u32_e32 v2, s72, v1
	ds_read_b128 v[132:135], v2
	ds_read_b128 v[136:139], v2 offset:1024
	ds_read_b128 v[140:143], v2 offset:2048
	ds_read_b128 v[144:147], v2 offset:3072
	s_cmp_eq_u32 s71, 28
	s_cselect_b32 s15, s57, s7
	s_cselect_b32 s14, s67, s6
	s_cselect_b32 s7, s55, s70
	s_cselect_b32 s6, s68, s69
	ds_read_b128 v[148:151], v207
	ds_read_b128 v[152:155], v207 offset:1024
	ds_read_b128 v[156:159], v207 offset:2048
	ds_read_b128 v[160:163], v207 offset:3072
	ds_read_b128 v[164:167], v207 offset:4096
	ds_read_b128 v[168:171], v207 offset:5120
	ds_read_b128 v[186:189], v207 offset:6144
	ds_read_b128 v[190:193], v207 offset:7168
	s_add_i32 s74, 0, 0x14000
	v_add_u32_e32 v2, s74, v1
	ds_read_b128 v[194:197], v2
	ds_read_b128 v[198:201], v2 offset:1024
	ds_read_b128 v[202:205], v2 offset:2048
	ds_read_b128 v[208:211], v2 offset:3072
	s_add_i32 m0, s20, 0xc000
	s_nop 0
	global_load_lds_dwordx4 v182, s[4:5]
	s_add_i32 m0, s20, 0xe000
	s_nop 0
	global_load_lds_dwordx4 v184, s[4:5]
	s_waitcnt lgkmcnt(0)
	s_barrier
; #define PG8_STAGE(bufoff, gbase, voff) do { _Pragma("unroll") for (int _i = 0; _i < 2; ++_i) \
;         __builtin_amdgcn_global_load_lds((const unsigned*)((const char*)(gbase) + (voff)[_i]), (LAS unsigned*)(lds + (bufoff) + ldsw + _i * 8192), 16, 0, 0); } while (0)
; #define PG8_LDA(dst, b, h) do { _Pragma("unroll") for (int m = 0; m < 4; ++m) _Pragma("unroll") for (int k = 0; k < 2; ++k) dst[m][k] = *(const LAS bf16x8*)(lds + PG8_SA(b, h) + aoff + m * 2048 + k * 1024); } while (0)
; #define PG8_LDB(dst, b, h) do { _Pragma("unroll") for (int n = 0; n < 2; ++n) _Pragma("unroll") for (int k = 0; k < 2; ++k) dst[n][k] = *(const LAS bf16x8*)(lds + PG8_SB(b, h) + boff + n * 2048 + k * 1024); } while (0)
; #define PG8_MMA(ai, bj, At, Bt) do { __builtin_amdgcn_s_setprio(1); _Pragma("unroll") for (int m = 0; m < 4; ++m) _Pragma("unroll") for (int n = 0; n < 2; ++n) _Pragma("unroll") for (int k = 0; k < 2; ++k) \
;         acc[ai][bj][m][n] = __builtin_amdgcn_mfma_f32_16x16x32_bf16(Bt[n][k], At[m][k], acc[ai][bj][m][n], 0, 0, 0); __builtin_amdgcn_s_setprio(0); } while (0)
; #define PG8_WAIT_V(n) asm volatile("s_waitcnt vmcnt(" #n ")" ::: "memory")
; #define PG8_WAIT_L(n) asm volatile("s_waitcnt lgkmcnt(" #n ")" ::: "memory")
; #define PG8_BAR __builtin_amdgcn_s_barrier()
; #define PG8_SCHED __builtin_amdgcn_sched_barrier(0)
; template <class Epi, class Sched>
; __device__ __forceinline__ void gemm_phase(LAS unsigned char* lds, const Gemm g, const Sched& S, const Epi& E) {
;     ...
;             PG8_LDB(B0, 0, 0); PG8_SCHED; PG8_LDA(At, 0, 0); PG8_STAGE(PG8_SA(1, 1), a1 + hstepA, voffA);
;             PG8_WAIT_L(8); PG8_BAR; PG8_WAIT_L(0); PG8_MMA(0, 0, At, B0); PG8_BAR; PG8_SCHED;
;             PG8_LDB(B1, 0, 1); PG8_STAGE(PG8_SB(0, 0), b2, voffB);
;             PG8_BAR; PG8_WAIT_L(0); PG8_MMA(0, 1, At, B1); PG8_BAR;
;             PG8_LDA(At, 0, 1); PG8_STAGE(PG8_SA(0, 0), a2, voffA);
;             PG8_BAR; PG8_WAIT_L(0); PG8_MMA(1, 0, At, B0); PG8_BAR; PG8_SCHED;
;             PG8_STAGE(PG8_SB(0, 1), b2 + hstepB, voffB);
;             PG8_WAIT_V(6); PG8_BAR; PG8_MMA(1, 1, At, B1); PG8_BAR;
	v_mfma_f32_16x16x32_bf16 v[68:71], v[132:135], v[148:151], v[68:71]
	v_mfma_f32_16x16x32_bf16 v[72:75], v[140:143], v[148:151], v[72:75]
	v_mfma_f32_16x16x32_bf16 v[120:123], v[132:135], v[156:159], v[120:123]
	v_mfma_f32_16x16x32_bf16 v[116:119], v[140:143], v[156:159], v[116:119]
	v_mfma_f32_16x16x32_bf16 v[112:115], v[132:135], v[164:167], v[112:115]
	v_mfma_f32_16x16x32_bf16 v[108:111], v[140:143], v[164:167], v[108:111]
	v_mfma_f32_16x16x32_bf16 v[104:107], v[132:135], v[186:189], v[104:107]
	v_mfma_f32_16x16x32_bf16 v[100:103], v[140:143], v[186:189], v[100:103]
	v_mfma_f32_16x16x32_bf16 v[68:71], v[136:139], v[152:155], v[68:71]
	v_mfma_f32_16x16x32_bf16 v[72:75], v[144:147], v[152:155], v[72:75]
	v_mfma_f32_16x16x32_bf16 v[120:123], v[136:139], v[160:163], v[120:123]
	v_mfma_f32_16x16x32_bf16 v[116:119], v[144:147], v[160:163], v[116:119]
	v_mfma_f32_16x16x32_bf16 v[112:115], v[136:139], v[168:171], v[112:115]
	v_mfma_f32_16x16x32_bf16 v[108:111], v[144:147], v[168:171], v[108:111]
	v_mfma_f32_16x16x32_bf16 v[104:107], v[136:139], v[190:193], v[104:107]
	v_mfma_f32_16x16x32_bf16 v[100:103], v[144:147], v[190:193], v[100:103]
	v_mfma_f32_16x16x32_bf16 v[76:79], v[194:197], v[148:151], v[76:79]
	v_mfma_f32_16x16x32_bf16 v[80:83], v[202:205], v[148:151], v[80:83]
	v_mfma_f32_16x16x32_bf16 v[96:99], v[194:197], v[156:159], v[96:99]
	v_mfma_f32_16x16x32_bf16 v[92:95], v[202:205], v[156:159], v[92:95]
	v_mfma_f32_16x16x32_bf16 v[88:91], v[194:197], v[164:167], v[88:91]
	v_mfma_f32_16x16x32_bf16 v[84:87], v[202:205], v[164:167], v[84:87]
	v_mfma_f32_16x16x32_bf16 v[128:131], v[194:197], v[186:189], v[128:131]
	v_mfma_f32_16x16x32_bf16 v[124:127], v[202:205], v[186:189], v[124:127]
	v_mfma_f32_16x16x32_bf16 v[76:79], v[198:201], v[152:155], v[76:79]
	v_mfma_f32_16x16x32_bf16 v[80:83], v[208:211], v[152:155], v[80:83]
	v_mfma_f32_16x16x32_bf16 v[96:99], v[198:201], v[160:163], v[96:99]
	v_mfma_f32_16x16x32_bf16 v[92:95], v[208:211], v[160:163], v[92:95]
	v_mfma_f32_16x16x32_bf16 v[88:91], v[198:201], v[168:171], v[88:91]
	v_mfma_f32_16x16x32_bf16 v[84:87], v[208:211], v[168:171], v[84:87]
	v_mfma_f32_16x16x32_bf16 v[128:131], v[198:201], v[190:193], v[128:131]
	v_mfma_f32_16x16x32_bf16 v[124:127], v[208:211], v[190:193], v[124:127]
	s_barrier
	ds_read_b128 v[148:151], v207 offset:16384
	ds_read_b128 v[152:155], v207 offset:17408
	ds_read_b128 v[156:159], v207 offset:18432
	ds_read_b128 v[160:163], v207 offset:19456
	ds_read_b128 v[164:167], v207 offset:20480
	ds_read_b128 v[168:171], v207 offset:21504
	ds_read_b128 v[186:189], v207 offset:22528
	ds_read_b128 v[190:193], v207 offset:23552
	s_add_i32 s72, s72, s19
	v_lshl_add_u64 v[172:173], s[6:7], 0, v[178:179]
	s_mov_b32 m0, s72
	s_nop 0
	global_load_lds_dwordx4 v[172:173], off
	v_lshl_add_u64 v[212:213], s[6:7], 0, v[174:175]
	s_add_i32 m0, s72, 0x2000
	s_nop 0
	global_load_lds_dwordx4 v[212:213], off
	s_mov_b32 m0, s20
	v_lshl_add_u64 v[216:217], s[14:15], 0, v[180:181]
	global_load_lds_dwordx4 v[216:217], off
	v_lshl_add_u64 v[218:219], s[14:15], 0, v[176:177]
	s_mov_b32 m0, s21
	s_nop 0
	global_load_lds_dwordx4 v[218:219], off
	s_add_u32 s72, s6, 0x80000
	s_addc_u32 s73, s7, 0
	s_add_i32 s74, s74, s19
	s_mov_b32 m0, s74
	s_nop 0
	global_load_lds_dwordx4 v178, s[72:73]
	s_add_i32 m0, s74, 0x2000
	s_nop 0
	global_load_lds_dwordx4 v174, s[72:73]
	s_waitcnt lgkmcnt(0)
	s_waitcnt vmcnt(6)
	s_barrier
	v_mfma_f32_16x16x32_bf16 v[56:59], v[132:135], v[148:151], v[56:59]
	v_mfma_f32_16x16x32_bf16 v[52:55], v[140:143], v[148:151], v[52:55]
	v_mfma_f32_16x16x32_bf16 v[48:51], v[132:135], v[156:159], v[48:51]
	v_mfma_f32_16x16x32_bf16 v[44:47], v[140:143], v[156:159], v[44:47]
	v_mfma_f32_16x16x32_bf16 v[40:43], v[132:135], v[164:167], v[40:43]
	v_mfma_f32_16x16x32_bf16 v[36:39], v[140:143], v[164:167], v[36:39]
	v_mfma_f32_16x16x32_bf16 v[32:35], v[132:135], v[186:189], v[32:35]
	v_mfma_f32_16x16x32_bf16 v[28:31], v[140:143], v[186:189], v[28:31]
	v_mfma_f32_16x16x32_bf16 v[56:59], v[136:139], v[152:155], v[56:59]
	v_mfma_f32_16x16x32_bf16 v[52:55], v[144:147], v[152:155], v[52:55]
	v_mfma_f32_16x16x32_bf16 v[48:51], v[136:139], v[160:163], v[48:51]
	v_mfma_f32_16x16x32_bf16 v[44:47], v[144:147], v[160:163], v[44:47]
	v_mfma_f32_16x16x32_bf16 v[40:43], v[136:139], v[168:171], v[40:43]
	v_mfma_f32_16x16x32_bf16 v[36:39], v[144:147], v[168:171], v[36:39]
	v_mfma_f32_16x16x32_bf16 v[32:35], v[136:139], v[190:193], v[32:35]
	v_mfma_f32_16x16x32_bf16 v[28:31], v[144:147], v[190:193], v[28:31]
	v_mfma_f32_16x16x32_bf16 v[24:27], v[194:197], v[148:151], v[24:27]
	v_mfma_f32_16x16x32_bf16 v[20:23], v[202:205], v[148:151], v[20:23]
	v_mfma_f32_16x16x32_bf16 v[16:19], v[194:197], v[156:159], v[16:19]
	v_mfma_f32_16x16x32_bf16 v[12:15], v[202:205], v[156:159], v[12:15]
	v_mfma_f32_16x16x32_bf16 v[8:11], v[194:197], v[164:167], v[8:11]
	v_mfma_f32_16x16x32_bf16 v[4:7], v[202:205], v[164:167], v[4:7]
	v_mfma_f32_16x16x32_bf16 v[60:63], v[194:197], v[186:189], v[60:63]
	v_mfma_f32_16x16x32_bf16 v[64:67], v[202:205], v[186:189], v[64:67]
	v_mfma_f32_16x16x32_bf16 v[24:27], v[198:201], v[152:155], v[24:27]
	v_mfma_f32_16x16x32_bf16 v[20:23], v[208:211], v[152:155], v[20:23]
	v_mfma_f32_16x16x32_bf16 v[16:19], v[198:201], v[160:163], v[16:19]
	v_mfma_f32_16x16x32_bf16 v[12:15], v[208:211], v[160:163], v[12:15]
	v_mfma_f32_16x16x32_bf16 v[8:11], v[198:201], v[168:171], v[8:11]
	v_mfma_f32_16x16x32_bf16 v[4:7], v[208:211], v[168:171], v[4:7]
	v_mfma_f32_16x16x32_bf16 v[60:63], v[198:201], v[190:193], v[60:63]
	v_mfma_f32_16x16x32_bf16 v[64:67], v[208:211], v[190:193], v[64:67]
	s_barrier
; #define PG8_STAGE(bufoff, gbase, voff) do { _Pragma("unroll") for (int _i = 0; _i < 2; ++_i) \
;         __builtin_amdgcn_global_load_lds((const unsigned*)((const char*)(gbase) + (voff)[_i]), (LAS unsigned*)(lds + (bufoff) + ldsw + _i * 8192), 16, 0, 0); } while (0)
; #define PG8_LDA(dst, b, h) do { _Pragma("unroll") for (int m = 0; m < 4; ++m) _Pragma("unroll") for (int k = 0; k < 2; ++k) dst[m][k] = *(const LAS bf16x8*)(lds + PG8_SA(b, h) + aoff + m * 2048 + k * 1024); } while (0)
; #define PG8_LDB(dst, b, h) do { _Pragma("unroll") for (int n = 0; n < 2; ++n) _Pragma("unroll") for (int k = 0; k < 2; ++k) dst[n][k] = *(const LAS bf16x8*)(lds + PG8_SB(b, h) + boff + n * 2048 + k * 1024); } while (0)
; #define PG8_MMA(ai, bj, At, Bt) do { __builtin_amdgcn_s_setprio(1); _Pragma("unroll") for (int m = 0; m < 4; ++m) _Pragma("unroll") for (int n = 0; n < 2; ++n) _Pragma("unroll") for (int k = 0; k < 2; ++k) \
;         acc[ai][bj][m][n] = __builtin_amdgcn_mfma_f32_16x16x32_bf16(Bt[n][k], At[m][k], acc[ai][bj][m][n], 0, 0, 0); __builtin_amdgcn_s_setprio(0); } while (0)
; #define PG8_WAIT_V(n) asm volatile("s_waitcnt vmcnt(" #n ")" ::: "memory")
; #define PG8_WAIT_L(n) asm volatile("s_waitcnt lgkmcnt(" #n ")" ::: "memory")
; #define PG8_BAR __builtin_amdgcn_s_barrier()
; #define PG8_SCHED __builtin_amdgcn_sched_barrier(0)
; template <class Epi, class Sched>
; __device__ __forceinline__ void gemm_phase(LAS unsigned char* lds, const Gemm g, const Sched& S, const Epi& E) {
;     ...
;             PG8_LDB(B0, 1, 0); PG8_SCHED; PG8_LDA(At, 1, 0); PG8_STAGE(PG8_SA(0, 1), a2 + hstepA, voffA);
;             PG8_WAIT_L(8); PG8_BAR; PG8_WAIT_L(0); PG8_MMA(0, 0, At, B0); PG8_BAR; PG8_SCHED;
;             PG8_LDB(B1, 1, 1); PG8_STAGE(PG8_SB(1, 0), b3, voffB);
;             PG8_BAR; PG8_WAIT_L(0); PG8_MMA(0, 1, At, B1); PG8_BAR;
;             PG8_LDA(At, 1, 1); PG8_STAGE(PG8_SA(1, 0), a3, voffA);
;             PG8_BAR; PG8_WAIT_L(0); PG8_MMA(1, 0, At, B0); PG8_BAR; PG8_SCHED;
;             PG8_STAGE(PG8_SB(1, 1), b3 + hstepB, voffB);
;             PG8_WAIT_V(6); PG8_BAR; PG8_MMA(1, 1, At, B1); PG8_BAR;
	s_add_i32 s72, 0, 0x18000
	v_add_u32_e32 v2, s72, v1
	ds_read_b128 v[132:135], v2
	ds_read_b128 v[136:139], v2 offset:1024
	ds_read_b128 v[140:143], v2 offset:2048
	ds_read_b128 v[144:147], v2 offset:3072
	s_add_u32 s14, s14, 0x80000
	s_addc_u32 s15, s15, 0
	ds_read_b128 v[148:151], v207 offset:32768
	ds_read_b128 v[152:155], v207 offset:33792
	ds_read_b128 v[156:159], v207 offset:34816
	ds_read_b128 v[160:163], v207 offset:35840
	ds_read_b128 v[164:167], v207 offset:36864
	ds_read_b128 v[168:171], v207 offset:37888
	ds_read_b128 v[186:189], v207 offset:38912
	ds_read_b128 v[190:193], v207 offset:39936
	s_mov_b32 m0, s24
	s_nop 0
	global_load_lds_dwordx4 v180, s[14:15]
	s_mov_b32 m0, s25
	s_nop 0
	global_load_lds_dwordx4 v176, s[14:15]
	s_add_i32 s14, 0, 0x1c000
	v_add_u32_e32 v2, s14, v1
	ds_read_b128 v[194:197], v2
	ds_read_b128 v[198:201], v2 offset:1024
	ds_read_b128 v[202:205], v2 offset:2048
	ds_read_b128 v[208:211], v2 offset:3072
	s_waitcnt lgkmcnt(0)
	s_barrier
	v_mfma_f32_16x16x32_bf16 v[68:71], v[132:135], v[148:151], v[68:71]
	v_mfma_f32_16x16x32_bf16 v[72:75], v[140:143], v[148:151], v[72:75]
	v_mfma_f32_16x16x32_bf16 v[120:123], v[132:135], v[156:159], v[120:123]
	v_mfma_f32_16x16x32_bf16 v[116:119], v[140:143], v[156:159], v[116:119]
	v_mfma_f32_16x16x32_bf16 v[112:115], v[132:135], v[164:167], v[112:115]
	v_mfma_f32_16x16x32_bf16 v[108:111], v[140:143], v[164:167], v[108:111]
	v_mfma_f32_16x16x32_bf16 v[104:107], v[132:135], v[186:189], v[104:107]
	v_mfma_f32_16x16x32_bf16 v[100:103], v[140:143], v[186:189], v[100:103]
	v_mfma_f32_16x16x32_bf16 v[68:71], v[136:139], v[152:155], v[68:71]
	v_mfma_f32_16x16x32_bf16 v[72:75], v[144:147], v[152:155], v[72:75]
	v_mfma_f32_16x16x32_bf16 v[120:123], v[136:139], v[160:163], v[120:123]
	v_mfma_f32_16x16x32_bf16 v[116:119], v[144:147], v[160:163], v[116:119]
	v_mfma_f32_16x16x32_bf16 v[112:115], v[136:139], v[168:171], v[112:115]
	v_mfma_f32_16x16x32_bf16 v[108:111], v[144:147], v[168:171], v[108:111]
	v_mfma_f32_16x16x32_bf16 v[104:107], v[136:139], v[190:193], v[104:107]
	v_mfma_f32_16x16x32_bf16 v[100:103], v[144:147], v[190:193], v[100:103]
	v_mfma_f32_16x16x32_bf16 v[76:79], v[194:197], v[148:151], v[76:79]
	v_mfma_f32_16x16x32_bf16 v[80:83], v[202:205], v[148:151], v[80:83]
	v_mfma_f32_16x16x32_bf16 v[96:99], v[194:197], v[156:159], v[96:99]
	v_mfma_f32_16x16x32_bf16 v[92:95], v[202:205], v[156:159], v[92:95]
	v_mfma_f32_16x16x32_bf16 v[88:91], v[194:197], v[164:167], v[88:91]
	v_mfma_f32_16x16x32_bf16 v[84:87], v[202:205], v[164:167], v[84:87]
	v_mfma_f32_16x16x32_bf16 v[128:131], v[194:197], v[186:189], v[128:131]
	v_mfma_f32_16x16x32_bf16 v[124:127], v[202:205], v[186:189], v[124:127]
	v_mfma_f32_16x16x32_bf16 v[76:79], v[198:201], v[152:155], v[76:79]
	v_mfma_f32_16x16x32_bf16 v[80:83], v[208:211], v[152:155], v[80:83]
	v_mfma_f32_16x16x32_bf16 v[96:99], v[198:201], v[160:163], v[96:99]
	v_mfma_f32_16x16x32_bf16 v[92:95], v[208:211], v[160:163], v[92:95]
	v_mfma_f32_16x16x32_bf16 v[88:91], v[198:201], v[168:171], v[88:91]
	v_mfma_f32_16x16x32_bf16 v[84:87], v[208:211], v[168:171], v[84:87]
	v_mfma_f32_16x16x32_bf16 v[128:131], v[198:201], v[190:193], v[128:131]
	v_mfma_f32_16x16x32_bf16 v[124:127], v[208:211], v[190:193], v[124:127]
	s_barrier
	ds_read_b128 v[148:151], v207 offset:49152
	ds_read_b128 v[152:155], v207 offset:50176
	ds_read_b128 v[156:159], v207 offset:51200
	ds_read_b128 v[160:163], v207 offset:52224
	ds_read_b128 v[164:167], v207 offset:53248
	ds_read_b128 v[168:171], v207 offset:54272
	ds_read_b128 v[186:189], v207 offset:55296
	ds_read_b128 v[190:193], v207 offset:56320
	s_add_i32 s15, s72, s19
	v_lshl_add_u64 v[172:173], v[172:173], 0, s[8:9]
	s_mov_b32 m0, s15
	s_nop 0
	global_load_lds_dwordx4 v[172:173], off
	v_lshl_add_u64 v[172:173], v[212:213], 0, s[8:9]
	s_add_i32 m0, s15, 0x2000
	s_nop 0
	global_load_lds_dwordx4 v[172:173], off
	s_mov_b32 m0, s30
	v_lshl_add_u64 v[172:173], v[216:217], 0, s[8:9]
	global_load_lds_dwordx4 v[172:173], off
	v_lshl_add_u64 v[172:173], v[218:219], 0, s[8:9]
	s_mov_b32 m0, s31
	s_nop 0
	global_load_lds_dwordx4 v[172:173], off
	s_add_u32 s6, s6, 0x80080
	s_addc_u32 s7, s7, 0
	s_add_i32 s14, s14, s19
	s_mov_b32 m0, s14
	s_nop 0
	global_load_lds_dwordx4 v178, s[6:7]
	s_add_i32 m0, s14, 0x2000
	s_nop 0
	global_load_lds_dwordx4 v174, s[6:7]
	s_add_i32 s71, s71, 2
	s_add_u32 s4, s4, 0x100
	s_addc_u32 s5, s5, 0
	s_add_u32 s69, s69, 0x100
	s_addc_u32 s70, s70, 0
	s_cmp_gt_u32 s71, 29
	s_waitcnt lgkmcnt(0)
	s_waitcnt vmcnt(6)
	s_barrier
	v_mfma_f32_16x16x32_bf16 v[56:59], v[132:135], v[148:151], v[56:59]
	v_mfma_f32_16x16x32_bf16 v[52:55], v[140:143], v[148:151], v[52:55]
	v_mfma_f32_16x16x32_bf16 v[48:51], v[132:135], v[156:159], v[48:51]
	v_mfma_f32_16x16x32_bf16 v[44:47], v[140:143], v[156:159], v[44:47]
	v_mfma_f32_16x16x32_bf16 v[40:43], v[132:135], v[164:167], v[40:43]
	v_mfma_f32_16x16x32_bf16 v[36:39], v[140:143], v[164:167], v[36:39]
	v_mfma_f32_16x16x32_bf16 v[32:35], v[132:135], v[186:189], v[32:35]
	v_mfma_f32_16x16x32_bf16 v[28:31], v[140:143], v[186:189], v[28:31]
	v_mfma_f32_16x16x32_bf16 v[56:59], v[136:139], v[152:155], v[56:59]
	v_mfma_f32_16x16x32_bf16 v[52:55], v[144:147], v[152:155], v[52:55]
	v_mfma_f32_16x16x32_bf16 v[48:51], v[136:139], v[160:163], v[48:51]
	v_mfma_f32_16x16x32_bf16 v[44:47], v[144:147], v[160:163], v[44:47]
	v_mfma_f32_16x16x32_bf16 v[40:43], v[136:139], v[168:171], v[40:43]
	v_mfma_f32_16x16x32_bf16 v[36:39], v[144:147], v[168:171], v[36:39]
	v_mfma_f32_16x16x32_bf16 v[32:35], v[136:139], v[190:193], v[32:35]
	v_mfma_f32_16x16x32_bf16 v[28:31], v[144:147], v[190:193], v[28:31]
	v_mfma_f32_16x16x32_bf16 v[24:27], v[194:197], v[148:151], v[24:27]
	v_mfma_f32_16x16x32_bf16 v[20:23], v[202:205], v[148:151], v[20:23]
	v_mfma_f32_16x16x32_bf16 v[16:19], v[194:197], v[156:159], v[16:19]
	v_mfma_f32_16x16x32_bf16 v[12:15], v[202:205], v[156:159], v[12:15]
	v_mfma_f32_16x16x32_bf16 v[8:11], v[194:197], v[164:167], v[8:11]
	v_mfma_f32_16x16x32_bf16 v[4:7], v[202:205], v[164:167], v[4:7]
	v_mfma_f32_16x16x32_bf16 v[60:63], v[194:197], v[186:189], v[60:63]
	v_mfma_f32_16x16x32_bf16 v[64:67], v[202:205], v[186:189], v[64:67]
	v_mfma_f32_16x16x32_bf16 v[24:27], v[198:201], v[152:155], v[24:27]
	v_mfma_f32_16x16x32_bf16 v[20:23], v[208:211], v[152:155], v[20:23]
	v_mfma_f32_16x16x32_bf16 v[16:19], v[198:201], v[160:163], v[16:19]
	v_mfma_f32_16x16x32_bf16 v[12:15], v[208:211], v[160:163], v[12:15]
	v_mfma_f32_16x16x32_bf16 v[8:11], v[198:201], v[168:171], v[8:11]
	v_mfma_f32_16x16x32_bf16 v[4:7], v[208:211], v[168:171], v[4:7]
	v_mfma_f32_16x16x32_bf16 v[60:63], v[198:201], v[190:193], v[60:63]
	v_mfma_f32_16x16x32_bf16 v[64:67], v[208:211], v[190:193], v[64:67]
	s_barrier
	s_cbranch_scc0 .LBB0_1526
	s_setprio 0
	s_andn2_b64 vcc, exec, s[46:47]
	s_cbranch_vccnz .Lalign_a_1526
	s_barrier

; #define PG8_STAGE(bufoff, gbase, voff) do { _Pragma("unroll") for (int _i = 0; _i < 2; ++_i) \
;         __builtin_amdgcn_global_load_lds((const unsigned*)((const char*)(gbase) + (voff)[_i]), (LAS unsigned*)(lds + (bufoff) + ldsw + _i * 8192), 16, 0, 0); } while (0)
; #define PG8_LDA(dst, b, h) do { _Pragma("unroll") for (int m = 0; m < 4; ++m) _Pragma("unroll") for (int k = 0; k < 2; ++k) dst[m][k] = *(const LAS bf16x8*)(lds + PG8_SA(b, h) + aoff + m * 2048 + k * 1024); } while (0)
; #define PG8_LDB(dst, b, h) do { _Pragma("unroll") for (int n = 0; n < 2; ++n) _Pragma("unroll") for (int k = 0; k < 2; ++k) dst[n][k] = *(const LAS bf16x8*)(lds + PG8_SB(b, h) + boff + n * 2048 + k * 1024); } while (0)
; #define PG8_MMA(ai, bj, At, Bt) do { __builtin_amdgcn_s_setprio(1); _Pragma("unroll") for (int m = 0; m < 4; ++m) _Pragma("unroll") for (int n = 0; n < 2; ++n) _Pragma("unroll") for (int k = 0; k < 2; ++k) \
;         acc[ai][bj][m][n] = __builtin_amdgcn_mfma_f32_16x16x32_bf16(Bt[n][k], At[m][k], acc[ai][bj][m][n], 0, 0, 0); __builtin_amdgcn_s_setprio(0); } while (0)
; #define PG8_WAIT_V(n) asm volatile("s_waitcnt vmcnt(" #n ")" ::: "memory")
; #define PG8_BAR __builtin_amdgcn_s_barrier()
; template <class Epi, class Sched>
; __device__ __forceinline__ void gemm_phase(LAS unsigned char* lds, const Gemm g, const Sched& S, const Epi& E) {
;     ...
;         for (int t = 0; t < nt; t += 2) {
;             const bool last = (t == nt - 2);
;             const char* a1 = cA + (size_t)(t + 1) * kstep;
;             const char* a2 = last ? nA : cA + (size_t)(t + 2) * kstep; const char* b2 = last ? nB : cB + (size_t)(t + 2) * kstep;
;             const char* a3 = a2 + kstep; const char* b3 = b2 + kstep;
;             if (last && has_next) S.a_ready(nxt);
;             PG8_LDB(B0, 0, 0); PG8_SCHED; PG8_LDA(At, 0, 0); PG8_STAGE(PG8_SA(1, 1), a1 + hstepA, voffA);
;             PG8_WAIT_L(8); PG8_BAR; PG8_WAIT_L(0); PG8_MMA(0, 0, At, B0); PG8_BAR; PG8_SCHED;
;             PG8_LDB(B1, 0, 1); PG8_STAGE(PG8_SB(0, 0), b2, voffB);
;             PG8_BAR; PG8_WAIT_L(0); PG8_MMA(0, 1, At, B1); PG8_BAR;
;             PG8_LDA(At, 0, 1); PG8_STAGE(PG8_SA(0, 0), a2, voffA);
;             PG8_BAR; PG8_WAIT_L(0); PG8_MMA(1, 0, At, B0); PG8_BAR; PG8_SCHED;
;             PG8_STAGE(PG8_SB(0, 1), b2 + hstepB, voffB);
;             PG8_WAIT_V(6); PG8_BAR; PG8_MMA(1, 1, At, B1); PG8_BAR;
.LBB0_1665:
	s_add_u32 s42, s14, 0x100
	s_addc_u32 s43, s15, 0
	s_mov_b32 s44, -2
	s_setprio 0
	s_add_u32 s14, s6, 0x100
	s_addc_u32 s15, s7, 0
	s_add_i32 s45, 0, 0x10000
	v_add_u32_e32 v144, s45, v1
	ds_read_b128 v[132:135], v144
	ds_read_b128 v[136:139], v144 offset:1024
	ds_read_b128 v[140:143], v144 offset:2048
	ds_read_b128 v[144:147], v144 offset:3072
	s_cmpk_eq_i32 s44, 0x54
	s_cselect_b32 s21, s1, s15
	s_cselect_b32 s20, s0, s14
	s_cselect_b32 s19, s5, s43
	s_cselect_b32 s18, s4, s42
	ds_read_b128 v[148:151], v224
	ds_read_b128 v[152:155], v224 offset:1024
	ds_read_b128 v[156:159], v224 offset:2048
	ds_read_b128 v[160:163], v224 offset:3072
	ds_read_b128 v[164:167], v224 offset:4096
	ds_read_b128 v[168:171], v224 offset:5120
	ds_read_b128 v[172:175], v224 offset:6144
	ds_read_b128 v[176:179], v224 offset:7168
	s_add_i32 s51, 0, 0x14000
	v_add_u32_e32 v202, s51, v1
	ds_read_b128 v[180:183], v202
	ds_read_b128 v[184:187], v202 offset:1024
	ds_read_b128 v[188:191], v202 offset:2048
	ds_read_b128 v[202:205], v202 offset:3072
	s_add_i32 m0, s29, 0xc000
	s_nop 0
	global_load_lds_dwordx4 v198, s[6:7]
	s_add_i32 m0, s29, 0xe000
	s_nop 0
	global_load_lds_dwordx4 v200, s[6:7]
	s_waitcnt lgkmcnt(0)
	s_barrier
	v_mfma_f32_16x16x32_bf16 v[128:131], v[132:135], v[148:151], 0
	v_mfma_f32_16x16x32_bf16 v[124:127], v[140:143], v[148:151], 0
	v_mfma_f32_16x16x32_bf16 v[112:115], v[132:135], v[156:159], 0
	v_mfma_f32_16x16x32_bf16 v[108:111], v[140:143], v[156:159], 0
	v_mfma_f32_16x16x32_bf16 v[100:103], v[132:135], v[164:167], 0
	v_mfma_f32_16x16x32_bf16 v[92:95], v[140:143], v[164:167], 0
	v_mfma_f32_16x16x32_bf16 v[84:87], v[132:135], v[172:175], 0
	v_mfma_f32_16x16x32_bf16 v[76:79], v[140:143], v[172:175], 0
	v_mfma_f32_16x16x32_bf16 v[128:131], v[136:139], v[152:155], v[128:131]
	v_mfma_f32_16x16x32_bf16 v[124:127], v[144:147], v[152:155], v[124:127]
	v_mfma_f32_16x16x32_bf16 v[112:115], v[136:139], v[160:163], v[112:115]
	v_mfma_f32_16x16x32_bf16 v[108:111], v[144:147], v[160:163], v[108:111]
	v_mfma_f32_16x16x32_bf16 v[100:103], v[136:139], v[168:171], v[100:103]
	v_mfma_f32_16x16x32_bf16 v[92:95], v[144:147], v[168:171], v[92:95]
	v_mfma_f32_16x16x32_bf16 v[84:87], v[136:139], v[176:179], v[84:87]
	v_mfma_f32_16x16x32_bf16 v[76:79], v[144:147], v[176:179], v[76:79]
	v_mfma_f32_16x16x32_bf16 v[120:123], v[180:183], v[148:151], 0
	v_mfma_f32_16x16x32_bf16 v[116:119], v[188:191], v[148:151], 0
	v_mfma_f32_16x16x32_bf16 v[104:107], v[180:183], v[156:159], 0
	v_mfma_f32_16x16x32_bf16 v[96:99], v[188:191], v[156:159], 0
	v_mfma_f32_16x16x32_bf16 v[88:91], v[180:183], v[164:167], 0
	v_mfma_f32_16x16x32_bf16 v[80:83], v[188:191], v[164:167], 0
	v_mfma_f32_16x16x32_bf16 v[72:75], v[180:183], v[172:175], 0
	v_mfma_f32_16x16x32_bf16 v[68:71], v[188:191], v[172:175], 0
	v_mfma_f32_16x16x32_bf16 v[120:123], v[184:187], v[152:155], v[120:123]
	v_mfma_f32_16x16x32_bf16 v[116:119], v[202:205], v[152:155], v[116:119]
	v_mfma_f32_16x16x32_bf16 v[104:107], v[184:187], v[160:163], v[104:107]
	v_mfma_f32_16x16x32_bf16 v[96:99], v[202:205], v[160:163], v[96:99]
	v_mfma_f32_16x16x32_bf16 v[88:91], v[184:187], v[168:171], v[88:91]
	v_mfma_f32_16x16x32_bf16 v[80:83], v[202:205], v[168:171], v[80:83]
	v_mfma_f32_16x16x32_bf16 v[72:75], v[184:187], v[176:179], v[72:75]
	v_mfma_f32_16x16x32_bf16 v[68:71], v[202:205], v[176:179], v[68:71]
	s_barrier
	ds_read_b128 v[148:151], v224 offset:16384
	ds_read_b128 v[152:155], v224 offset:17408
	ds_read_b128 v[156:159], v224 offset:18432
	ds_read_b128 v[160:163], v224 offset:19456
	ds_read_b128 v[164:167], v224 offset:20480
	ds_read_b128 v[168:171], v224 offset:21504
	ds_read_b128 v[172:175], v224 offset:22528
	ds_read_b128 v[176:179], v224 offset:23552
	s_add_i32 s6, s45, s28
	v_lshl_add_u64 v[206:207], s[18:19], 0, v[2:3]
	s_mov_b32 m0, s6
	s_nop 0
	global_load_lds_dwordx4 v[206:207], off
	v_lshl_add_u64 v[208:209], s[18:19], 0, v[192:193]
	s_add_i32 m0, s6, 0x2000
	s_nop 0
	global_load_lds_dwordx4 v[208:209], off
	s_mov_b32 m0, s29
	v_lshl_add_u64 v[210:211], s[20:21], 0, v[196:197]
	global_load_lds_dwordx4 v[210:211], off
	v_lshl_add_u64 v[212:213], s[20:21], 0, v[194:195]
	s_mov_b32 m0, s30
	s_nop 0
	global_load_lds_dwordx4 v[212:213], off
	s_add_u32 s6, s18, 0x160000
	s_addc_u32 s7, s19, 0
	s_add_i32 s45, s51, s28
	s_mov_b32 m0, s45
	s_nop 0
	global_load_lds_dwordx4 v2, s[6:7]
	s_add_i32 m0, s45, 0x2000
	s_nop 0
	global_load_lds_dwordx4 v192, s[6:7]
	s_waitcnt lgkmcnt(0)
	s_waitcnt vmcnt(6)
	s_barrier
	v_mfma_f32_16x16x32_bf16 v[64:67], v[132:135], v[148:151], 0
	v_mfma_f32_16x16x32_bf16 v[60:63], v[140:143], v[148:151], 0
	v_mfma_f32_16x16x32_bf16 v[52:55], v[132:135], v[156:159], 0
	v_mfma_f32_16x16x32_bf16 v[44:47], v[140:143], v[156:159], 0
	v_mfma_f32_16x16x32_bf16 v[36:39], v[132:135], v[164:167], 0
	v_mfma_f32_16x16x32_bf16 v[28:31], v[140:143], v[164:167], 0
	v_mfma_f32_16x16x32_bf16 v[20:23], v[132:135], v[172:175], 0
	v_mfma_f32_16x16x32_bf16 v[12:15], v[140:143], v[172:175], 0
	v_mfma_f32_16x16x32_bf16 v[64:67], v[136:139], v[152:155], v[64:67]
	v_mfma_f32_16x16x32_bf16 v[60:63], v[144:147], v[152:155], v[60:63]
	v_mfma_f32_16x16x32_bf16 v[52:55], v[136:139], v[160:163], v[52:55]
	v_mfma_f32_16x16x32_bf16 v[44:47], v[144:147], v[160:163], v[44:47]
	v_mfma_f32_16x16x32_bf16 v[36:39], v[136:139], v[168:171], v[36:39]
	v_mfma_f32_16x16x32_bf16 v[28:31], v[144:147], v[168:171], v[28:31]
	v_mfma_f32_16x16x32_bf16 v[20:23], v[136:139], v[176:179], v[20:23]
	v_mfma_f32_16x16x32_bf16 v[12:15], v[144:147], v[176:179], v[12:15]
	v_mfma_f32_16x16x32_bf16 v[56:59], v[180:183], v[148:151], 0
	v_mfma_f32_16x16x32_bf16 v[48:51], v[188:191], v[148:151], 0
	v_mfma_f32_16x16x32_bf16 v[40:43], v[180:183], v[156:159], 0
	v_mfma_f32_16x16x32_bf16 v[32:35], v[188:191], v[156:159], 0
	v_mfma_f32_16x16x32_bf16 v[24:27], v[180:183], v[164:167], 0
	v_mfma_f32_16x16x32_bf16 v[16:19], v[188:191], v[164:167], 0
	v_mfma_f32_16x16x32_bf16 v[8:11], v[180:183], v[172:175], 0
	v_mfma_f32_16x16x32_bf16 v[4:7], v[188:191], v[172:175], 0
	v_mfma_f32_16x16x32_bf16 v[56:59], v[184:187], v[152:155], v[56:59]
	v_mfma_f32_16x16x32_bf16 v[48:51], v[202:205], v[152:155], v[48:51]
	v_mfma_f32_16x16x32_bf16 v[40:43], v[184:187], v[160:163], v[40:43]
	v_mfma_f32_16x16x32_bf16 v[32:35], v[202:205], v[160:163], v[32:35]
	v_mfma_f32_16x16x32_bf16 v[24:27], v[184:187], v[168:171], v[24:27]
	v_mfma_f32_16x16x32_bf16 v[16:19], v[202:205], v[168:171], v[16:19]
	v_mfma_f32_16x16x32_bf16 v[8:11], v[184:187], v[176:179], v[8:11]
	v_mfma_f32_16x16x32_bf16 v[4:7], v[202:205], v[176:179], v[4:7]
	s_barrier
; #define PG8_STAGE(bufoff, gbase, voff) do { _Pragma("unroll") for (int _i = 0; _i < 2; ++_i) \
;         __builtin_amdgcn_global_load_lds((const unsigned*)((const char*)(gbase) + (voff)[_i]), (LAS unsigned*)(lds + (bufoff) + ldsw + _i * 8192), 16, 0, 0); } while (0)
; #define PG8_LDA(dst, b, h) do { _Pragma("unroll") for (int m = 0; m < 4; ++m) _Pragma("unroll") for (int k = 0; k < 2; ++k) dst[m][k] = *(const LAS bf16x8*)(lds + PG8_SA(b, h) + aoff + m * 2048 + k * 1024); } while (0)
; #define PG8_LDB(dst, b, h) do { _Pragma("unroll") for (int n = 0; n < 2; ++n) _Pragma("unroll") for (int k = 0; k < 2; ++k) dst[n][k] = *(const LAS bf16x8*)(lds + PG8_SB(b, h) + boff + n * 2048 + k * 1024); } while (0)
; #define PG8_MMA(ai, bj, At, Bt) do { __builtin_amdgcn_s_setprio(1); _Pragma("unroll") for (int m = 0; m < 4; ++m) _Pragma("unroll") for (int n = 0; n < 2; ++n) _Pragma("unroll") for (int k = 0; k < 2; ++k) \
;         acc[ai][bj][m][n] = __builtin_amdgcn_mfma_f32_16x16x32_bf16(Bt[n][k], At[m][k], acc[ai][bj][m][n], 0, 0, 0); __builtin_amdgcn_s_setprio(0); } while (0)
; #define PG8_WAIT_V(n) asm volatile("s_waitcnt vmcnt(" #n ")" ::: "memory")
; #define PG8_WAIT_L(n) asm volatile("s_waitcnt lgkmcnt(" #n ")" ::: "memory")
; #define PG8_BAR __builtin_amdgcn_s_barrier()
; #define PG8_SCHED __builtin_amdgcn_sched_barrier(0)
; template <class Epi, class Sched>
; __device__ __forceinline__ void gemm_phase(LAS unsigned char* lds, const Gemm g, const Sched& S, const Epi& E) {
;     ...
;             PG8_LDB(B0, 1, 0); PG8_SCHED; PG8_LDA(At, 1, 0); PG8_STAGE(PG8_SA(0, 1), a2 + hstepA, voffA);
;             PG8_WAIT_L(8); PG8_BAR; PG8_WAIT_L(0); PG8_MMA(0, 0, At, B0); PG8_BAR; PG8_SCHED;
;             PG8_LDB(B1, 1, 1); PG8_STAGE(PG8_SB(1, 0), b3, voffB);
;             PG8_BAR; PG8_WAIT_L(0); PG8_MMA(0, 1, At, B1); PG8_BAR;
;             PG8_LDA(At, 1, 1); PG8_STAGE(PG8_SA(1, 0), a3, voffA);
;             PG8_BAR; PG8_WAIT_L(0); PG8_MMA(1, 0, At, B0); PG8_BAR; PG8_SCHED;
;             PG8_STAGE(PG8_SB(1, 1), b3 + hstepB, voffB);
;             PG8_WAIT_V(6); PG8_BAR; PG8_MMA(1, 1, At, B1); PG8_BAR;
	s_add_i32 s45, 0, 0x18000
	v_add_u32_e32 v144, s45, v1
	ds_read_b128 v[132:135], v144
	ds_read_b128 v[136:139], v144 offset:1024
	ds_read_b128 v[140:143], v144 offset:2048
	ds_read_b128 v[144:147], v144 offset:3072
	s_add_u32 s6, s20, 0x160000
	s_addc_u32 s7, s21, 0
	ds_read_b128 v[148:151], v224 offset:32768
	ds_read_b128 v[152:155], v224 offset:33792
	ds_read_b128 v[156:159], v224 offset:34816
	ds_read_b128 v[160:163], v224 offset:35840
	ds_read_b128 v[164:167], v224 offset:36864
	ds_read_b128 v[168:171], v224 offset:37888
	ds_read_b128 v[172:175], v224 offset:38912
	ds_read_b128 v[176:179], v224 offset:39936
	s_mov_b32 m0, s31
	s_nop 0
	global_load_lds_dwordx4 v196, s[6:7]
	s_mov_b32 m0, s35
	s_nop 0
	global_load_lds_dwordx4 v194, s[6:7]
	s_add_i32 s20, 0, 0x1c000
	v_add_u32_e32 v202, s20, v1
	ds_read_b128 v[180:183], v202
	ds_read_b128 v[184:187], v202 offset:1024
	ds_read_b128 v[188:191], v202 offset:2048
	ds_read_b128 v[202:205], v202 offset:3072
	s_waitcnt lgkmcnt(0)
	s_barrier
	v_mfma_f32_16x16x32_bf16 v[128:131], v[132:135], v[148:151], v[128:131]
	v_mfma_f32_16x16x32_bf16 v[124:127], v[140:143], v[148:151], v[124:127]
	v_mfma_f32_16x16x32_bf16 v[112:115], v[132:135], v[156:159], v[112:115]
	v_mfma_f32_16x16x32_bf16 v[108:111], v[140:143], v[156:159], v[108:111]
	v_mfma_f32_16x16x32_bf16 v[100:103], v[132:135], v[164:167], v[100:103]
	v_mfma_f32_16x16x32_bf16 v[92:95], v[140:143], v[164:167], v[92:95]
	v_mfma_f32_16x16x32_bf16 v[84:87], v[132:135], v[172:175], v[84:87]
	v_mfma_f32_16x16x32_bf16 v[76:79], v[140:143], v[172:175], v[76:79]
	v_mfma_f32_16x16x32_bf16 v[128:131], v[136:139], v[152:155], v[128:131]
	v_mfma_f32_16x16x32_bf16 v[124:127], v[144:147], v[152:155], v[124:127]
	v_mfma_f32_16x16x32_bf16 v[112:115], v[136:139], v[160:163], v[112:115]
	v_mfma_f32_16x16x32_bf16 v[108:111], v[144:147], v[160:163], v[108:111]
	v_mfma_f32_16x16x32_bf16 v[100:103], v[136:139], v[168:171], v[100:103]
	v_mfma_f32_16x16x32_bf16 v[92:95], v[144:147], v[168:171], v[92:95]
	v_mfma_f32_16x16x32_bf16 v[84:87], v[136:139], v[176:179], v[84:87]
	v_mfma_f32_16x16x32_bf16 v[76:79], v[144:147], v[176:179], v[76:79]
	v_mfma_f32_16x16x32_bf16 v[120:123], v[180:183], v[148:151], v[120:123]
	v_mfma_f32_16x16x32_bf16 v[116:119], v[188:191], v[148:151], v[116:119]
	v_mfma_f32_16x16x32_bf16 v[104:107], v[180:183], v[156:159], v[104:107]
	v_mfma_f32_16x16x32_bf16 v[96:99], v[188:191], v[156:159], v[96:99]
	v_mfma_f32_16x16x32_bf16 v[88:91], v[180:183], v[164:167], v[88:91]
	v_mfma_f32_16x16x32_bf16 v[80:83], v[188:191], v[164:167], v[80:83]
	v_mfma_f32_16x16x32_bf16 v[72:75], v[180:183], v[172:175], v[72:75]
	v_mfma_f32_16x16x32_bf16 v[68:71], v[188:191], v[172:175], v[68:71]
	v_mfma_f32_16x16x32_bf16 v[120:123], v[184:187], v[152:155], v[120:123]
	v_mfma_f32_16x16x32_bf16 v[116:119], v[202:205], v[152:155], v[116:119]
	v_mfma_f32_16x16x32_bf16 v[104:107], v[184:187], v[160:163], v[104:107]
	v_mfma_f32_16x16x32_bf16 v[96:99], v[202:205], v[160:163], v[96:99]
	v_mfma_f32_16x16x32_bf16 v[88:91], v[184:187], v[168:171], v[88:91]
	v_mfma_f32_16x16x32_bf16 v[80:83], v[202:205], v[168:171], v[80:83]
	v_mfma_f32_16x16x32_bf16 v[72:75], v[184:187], v[176:179], v[72:75]
	v_mfma_f32_16x16x32_bf16 v[68:71], v[202:205], v[176:179], v[68:71]
	s_barrier
	ds_read_b128 v[148:151], v224 offset:49152
	ds_read_b128 v[152:155], v224 offset:50176
	ds_read_b128 v[156:159], v224 offset:51200
	ds_read_b128 v[160:163], v224 offset:52224
	ds_read_b128 v[164:167], v224 offset:53248
	ds_read_b128 v[168:171], v224 offset:54272
	ds_read_b128 v[172:175], v224 offset:55296
	ds_read_b128 v[176:179], v224 offset:56320
	s_add_i32 s6, s45, s28
	v_lshl_add_u64 v[206:207], v[206:207], 0, s[8:9]
	s_mov_b32 m0, s6
	s_nop 0
	global_load_lds_dwordx4 v[206:207], off
	v_lshl_add_u64 v[206:207], v[208:209], 0, s[8:9]
	s_add_i32 m0, s6, 0x2000
	s_nop 0
	global_load_lds_dwordx4 v[206:207], off
	s_mov_b32 m0, s38
	v_lshl_add_u64 v[206:207], v[210:211], 0, s[8:9]
	global_load_lds_dwordx4 v[206:207], off
	v_lshl_add_u64 v[206:207], v[212:213], 0, s[8:9]
	s_mov_b32 m0, s39
	s_nop 0
	global_load_lds_dwordx4 v[206:207], off
	s_add_u32 s6, s18, 0x160080
	s_addc_u32 s7, s19, 0
	s_add_i32 s18, s20, s28
	s_mov_b32 m0, s18
	s_nop 0
	global_load_lds_dwordx4 v2, s[6:7]
	s_add_i32 m0, s18, 0x2000
	s_nop 0
	global_load_lds_dwordx4 v192, s[6:7]
	s_add_i32 s44, s44, 2
	s_add_u32 s42, s42, 0x100
	s_addc_u32 s43, s43, 0
	s_cmpk_gt_u32 s44, 0x55
	s_mov_b64 s[6:7], s[14:15]
	s_waitcnt lgkmcnt(0)
	s_waitcnt vmcnt(6)
	s_barrier
	v_mfma_f32_16x16x32_bf16 v[64:67], v[132:135], v[148:151], v[64:67]
	v_mfma_f32_16x16x32_bf16 v[60:63], v[140:143], v[148:151], v[60:63]
	v_mfma_f32_16x16x32_bf16 v[52:55], v[132:135], v[156:159], v[52:55]
	v_mfma_f32_16x16x32_bf16 v[44:47], v[140:143], v[156:159], v[44:47]
	v_mfma_f32_16x16x32_bf16 v[36:39], v[132:135], v[164:167], v[36:39]
	v_mfma_f32_16x16x32_bf16 v[28:31], v[140:143], v[164:167], v[28:31]
	v_mfma_f32_16x16x32_bf16 v[20:23], v[132:135], v[172:175], v[20:23]
	v_mfma_f32_16x16x32_bf16 v[12:15], v[140:143], v[172:175], v[12:15]
	v_mfma_f32_16x16x32_bf16 v[64:67], v[136:139], v[152:155], v[64:67]
	v_mfma_f32_16x16x32_bf16 v[60:63], v[144:147], v[152:155], v[60:63]
	v_mfma_f32_16x16x32_bf16 v[52:55], v[136:139], v[160:163], v[52:55]
	v_mfma_f32_16x16x32_bf16 v[44:47], v[144:147], v[160:163], v[44:47]
	v_mfma_f32_16x16x32_bf16 v[36:39], v[136:139], v[168:171], v[36:39]
	v_mfma_f32_16x16x32_bf16 v[28:31], v[144:147], v[168:171], v[28:31]
	v_mfma_f32_16x16x32_bf16 v[20:23], v[136:139], v[176:179], v[20:23]
	v_mfma_f32_16x16x32_bf16 v[12:15], v[144:147], v[176:179], v[12:15]
	v_mfma_f32_16x16x32_bf16 v[56:59], v[180:183], v[148:151], v[56:59]
	v_mfma_f32_16x16x32_bf16 v[48:51], v[188:191], v[148:151], v[48:51]
	v_mfma_f32_16x16x32_bf16 v[40:43], v[180:183], v[156:159], v[40:43]
	v_mfma_f32_16x16x32_bf16 v[32:35], v[188:191], v[156:159], v[32:35]
	v_mfma_f32_16x16x32_bf16 v[24:27], v[180:183], v[164:167], v[24:27]
	v_mfma_f32_16x16x32_bf16 v[16:19], v[188:191], v[164:167], v[16:19]
	v_mfma_f32_16x16x32_bf16 v[8:11], v[180:183], v[172:175], v[8:11]
	v_mfma_f32_16x16x32_bf16 v[4:7], v[188:191], v[172:175], v[4:7]
	v_mfma_f32_16x16x32_bf16 v[56:59], v[184:187], v[152:155], v[56:59]
	v_mfma_f32_16x16x32_bf16 v[48:51], v[202:205], v[152:155], v[48:51]
	v_mfma_f32_16x16x32_bf16 v[40:43], v[184:187], v[160:163], v[40:43]
	v_mfma_f32_16x16x32_bf16 v[32:35], v[202:205], v[160:163], v[32:35]
	v_mfma_f32_16x16x32_bf16 v[24:27], v[184:187], v[168:171], v[24:27]
	v_mfma_f32_16x16x32_bf16 v[16:19], v[202:205], v[168:171], v[16:19]
	v_mfma_f32_16x16x32_bf16 v[8:11], v[184:187], v[176:179], v[8:11]
	v_mfma_f32_16x16x32_bf16 v[4:7], v[202:205], v[176:179], v[4:7]
	s_barrier
	s_setprio 0
; #define PG8_STAGE(bufoff, gbase, voff) do { _Pragma("unroll") for (int _i = 0; _i < 2; ++_i) \
;         __builtin_amdgcn_global_load_lds((const unsigned*)((const char*)(gbase) + (voff)[_i]), (LAS unsigned*)(lds + (bufoff) + ldsw + _i * 8192), 16, 0, 0); } while (0)
; #define PG8_LDA(dst, b, h) do { _Pragma("unroll") for (int m = 0; m < 4; ++m) _Pragma("unroll") for (int k = 0; k < 2; ++k) dst[m][k] = *(const LAS bf16x8*)(lds + PG8_SA(b, h) + aoff + m * 2048 + k * 1024); } while (0)
; #define PG8_LDB(dst, b, h) do { _Pragma("unroll") for (int n = 0; n < 2; ++n) _Pragma("unroll") for (int k = 0; k < 2; ++k) dst[n][k] = *(const LAS bf16x8*)(lds + PG8_SB(b, h) + boff + n * 2048 + k * 1024); } while (0)
; #define PG8_MMA(ai, bj, At, Bt) do { __builtin_amdgcn_s_setprio(1); _Pragma("unroll") for (int m = 0; m < 4; ++m) _Pragma("unroll") for (int n = 0; n < 2; ++n) _Pragma("unroll") for (int k = 0; k < 2; ++k) \
;         acc[ai][bj][m][n] = __builtin_amdgcn_mfma_f32_16x16x32_bf16(Bt[n][k], At[m][k], acc[ai][bj][m][n], 0, 0, 0); __builtin_amdgcn_s_setprio(0); } while (0)
; #define PG8_WAIT_L(n) asm volatile("s_waitcnt lgkmcnt(" #n ")" ::: "memory")
; #define PG8_BAR __builtin_amdgcn_s_barrier()
; #define PG8_SCHED __builtin_amdgcn_sched_barrier(0)
; template <class Epi, class Sched>
; __device__ __forceinline__ void gemm_phase(LAS unsigned char* lds, const Gemm g, const Sched& S, const Epi& E) {
;     ...
;         for (int t = 0; t < nt; t += 2) {
;             const bool last = (t == nt - 2);
;             const char* a1 = cA + (size_t)(t + 1) * kstep;
;             const char* a2 = last ? nA : cA + (size_t)(t + 2) * kstep; const char* b2 = last ? nB : cB + (size_t)(t + 2) * kstep;
;             const char* a3 = a2 + kstep; const char* b3 = b2 + kstep;
;             if (last && has_next) S.a_ready(nxt);
;             PG8_LDB(B0, 0, 0); PG8_SCHED; PG8_LDA(At, 0, 0); PG8_STAGE(PG8_SA(1, 1), a1 + hstepA, voffA);
;             PG8_WAIT_L(8); PG8_BAR; PG8_WAIT_L(0); PG8_MMA(0, 0, At, B0); PG8_BAR; PG8_SCHED;
;             PG8_LDB(B1, 0, 1); PG8_STAGE(PG8_SB(0, 0), b2, voffB);
;             PG8_BAR; PG8_WAIT_L(0); PG8_MMA(0, 1, At, B1); PG8_BAR;
;             PG8_LDA(At, 0, 1); PG8_STAGE(PG8_SA(0, 0), a2, voffA);
;             PG8_BAR; PG8_WAIT_L(0); PG8_MMA(1, 0, At, B0); PG8_BAR; PG8_SCHED;
.LBB0_1666:
	s_setprio 0
	s_add_u32 s14, s6, 0x100
	s_addc_u32 s15, s7, 0
	s_add_i32 s45, 0, 0x10000
	v_add_u32_e32 v144, s45, v1
	ds_read_b128 v[132:135], v144
	ds_read_b128 v[136:139], v144 offset:1024
	ds_read_b128 v[140:143], v144 offset:2048
	ds_read_b128 v[144:147], v144 offset:3072
	s_cmpk_eq_i32 s44, 0x54
	s_cselect_b32 s21, s1, s15
	s_cselect_b32 s20, s0, s14
	s_cselect_b32 s19, s5, s43
	s_cselect_b32 s18, s4, s42
	ds_read_b128 v[148:151], v224
	ds_read_b128 v[152:155], v224 offset:1024
	ds_read_b128 v[156:159], v224 offset:2048
	ds_read_b128 v[160:163], v224 offset:3072
	ds_read_b128 v[164:167], v224 offset:4096
	ds_read_b128 v[168:171], v224 offset:5120
	ds_read_b128 v[172:175], v224 offset:6144
	ds_read_b128 v[176:179], v224 offset:7168
	s_add_i32 s51, 0, 0x14000
	v_add_u32_e32 v202, s51, v1
	ds_read_b128 v[180:183], v202
	ds_read_b128 v[184:187], v202 offset:1024
	ds_read_b128 v[188:191], v202 offset:2048
	ds_read_b128 v[202:205], v202 offset:3072
	s_add_i32 m0, s29, 0xc000
	s_nop 0
	global_load_lds_dwordx4 v198, s[6:7]
	s_add_i32 m0, s29, 0xe000
	s_nop 0
	global_load_lds_dwordx4 v200, s[6:7]
	s_waitcnt lgkmcnt(0)
	s_barrier
	v_mfma_f32_16x16x32_bf16 v[128:131], v[132:135], v[148:151], v[128:131]
	v_mfma_f32_16x16x32_bf16 v[124:127], v[140:143], v[148:151], v[124:127]
	v_mfma_f32_16x16x32_bf16 v[112:115], v[132:135], v[156:159], v[112:115]
	v_mfma_f32_16x16x32_bf16 v[108:111], v[140:143], v[156:159], v[108:111]
	v_mfma_f32_16x16x32_bf16 v[100:103], v[132:135], v[164:167], v[100:103]
	v_mfma_f32_16x16x32_bf16 v[92:95], v[140:143], v[164:167], v[92:95]
	v_mfma_f32_16x16x32_bf16 v[84:87], v[132:135], v[172:175], v[84:87]
	v_mfma_f32_16x16x32_bf16 v[76:79], v[140:143], v[172:175], v[76:79]
	v_mfma_f32_16x16x32_bf16 v[128:131], v[136:139], v[152:155], v[128:131]
	v_mfma_f32_16x16x32_bf16 v[124:127], v[144:147], v[152:155], v[124:127]
	v_mfma_f32_16x16x32_bf16 v[112:115], v[136:139], v[160:163], v[112:115]
	v_mfma_f32_16x16x32_bf16 v[108:111], v[144:147], v[160:163], v[108:111]
	v_mfma_f32_16x16x32_bf16 v[100:103], v[136:139], v[168:171], v[100:103]
	v_mfma_f32_16x16x32_bf16 v[92:95], v[144:147], v[168:171], v[92:95]
	v_mfma_f32_16x16x32_bf16 v[84:87], v[136:139], v[176:179], v[84:87]
	v_mfma_f32_16x16x32_bf16 v[76:79], v[144:147], v[176:179], v[76:79]
	v_mfma_f32_16x16x32_bf16 v[120:123], v[180:183], v[148:151], v[120:123]
	v_mfma_f32_16x16x32_bf16 v[116:119], v[188:191], v[148:151], v[116:119]
	v_mfma_f32_16x16x32_bf16 v[104:107], v[180:183], v[156:159], v[104:107]
	v_mfma_f32_16x16x32_bf16 v[96:99], v[188:191], v[156:159], v[96:99]
	v_mfma_f32_16x16x32_bf16 v[88:91], v[180:183], v[164:167], v[88:91]
	v_mfma_f32_16x16x32_bf16 v[80:83], v[188:191], v[164:167], v[80:83]
	v_mfma_f32_16x16x32_bf16 v[72:75], v[180:183], v[172:175], v[72:75]
	v_mfma_f32_16x16x32_bf16 v[68:71], v[188:191], v[172:175], v[68:71]
	v_mfma_f32_16x16x32_bf16 v[120:123], v[184:187], v[152:155], v[120:123]
	v_mfma_f32_16x16x32_bf16 v[116:119], v[202:205], v[152:155], v[116:119]
	v_mfma_f32_16x16x32_bf16 v[104:107], v[184:187], v[160:163], v[104:107]
	v_mfma_f32_16x16x32_bf16 v[96:99], v[202:205], v[160:163], v[96:99]
	v_mfma_f32_16x16x32_bf16 v[88:91], v[184:187], v[168:171], v[88:91]
	v_mfma_f32_16x16x32_bf16 v[80:83], v[202:205], v[168:171], v[80:83]
	v_mfma_f32_16x16x32_bf16 v[72:75], v[184:187], v[176:179], v[72:75]
	v_mfma_f32_16x16x32_bf16 v[68:71], v[202:205], v[176:179], v[68:71]
	s_barrier
	ds_read_b128 v[148:151], v224 offset:16384
	ds_read_b128 v[152:155], v224 offset:17408
	ds_read_b128 v[156:159], v224 offset:18432
	ds_read_b128 v[160:163], v224 offset:19456
	ds_read_b128 v[164:167], v224 offset:20480
	ds_read_b128 v[168:171], v224 offset:21504
	ds_read_b128 v[172:175], v224 offset:22528
	ds_read_b128 v[176:179], v224 offset:23552
	s_add_i32 s6, s45, s28
	v_lshl_add_u64 v[206:207], s[18:19], 0, v[2:3]
	s_mov_b32 m0, s6
	s_nop 0
	global_load_lds_dwordx4 v[206:207], off
	v_lshl_add_u64 v[208:209], s[18:19], 0, v[192:193]
	s_add_i32 m0, s6, 0x2000
	s_nop 0
	global_load_lds_dwordx4 v[208:209], off
	s_mov_b32 m0, s29
	v_lshl_add_u64 v[210:211], s[20:21], 0, v[196:197]
	global_load_lds_dwordx4 v[210:211], off
	v_lshl_add_u64 v[212:213], s[20:21], 0, v[194:195]
	s_mov_b32 m0, s30
	s_nop 0
	global_load_lds_dwordx4 v[212:213], off
	s_add_u32 s6, s18, 0x160000
	s_addc_u32 s7, s19, 0
	s_add_i32 s45, s51, s28
	s_mov_b32 m0, s45
	s_nop 0
	global_load_lds_dwordx4 v2, s[6:7]
	s_add_i32 m0, s45, 0x2000
	s_nop 0
	global_load_lds_dwordx4 v192, s[6:7]
	s_waitcnt lgkmcnt(0)
	s_waitcnt vmcnt(6)
	s_barrier
; #define PG8_STAGE(bufoff, gbase, voff) do { _Pragma("unroll") for (int _i = 0; _i < 2; ++_i) \
;         __builtin_amdgcn_global_load_lds((const unsigned*)((const char*)(gbase) + (voff)[_i]), (LAS unsigned*)(lds + (bufoff) + ldsw + _i * 8192), 16, 0, 0); } while (0)
; #define PG8_LDA(dst, b, h) do { _Pragma("unroll") for (int m = 0; m < 4; ++m) _Pragma("unroll") for (int k = 0; k < 2; ++k) dst[m][k] = *(const LAS bf16x8*)(lds + PG8_SA(b, h) + aoff + m * 2048 + k * 1024); } while (0)
; #define PG8_LDB(dst, b, h) do { _Pragma("unroll") for (int n = 0; n < 2; ++n) _Pragma("unroll") for (int k = 0; k < 2; ++k) dst[n][k] = *(const LAS bf16x8*)(lds + PG8_SB(b, h) + boff + n * 2048 + k * 1024); } while (0)
; #define PG8_MMA(ai, bj, At, Bt) do { __builtin_amdgcn_s_setprio(1); _Pragma("unroll") for (int m = 0; m < 4; ++m) _Pragma("unroll") for (int n = 0; n < 2; ++n) _Pragma("unroll") for (int k = 0; k < 2; ++k) \
;         acc[ai][bj][m][n] = __builtin_amdgcn_mfma_f32_16x16x32_bf16(Bt[n][k], At[m][k], acc[ai][bj][m][n], 0, 0, 0); __builtin_amdgcn_s_setprio(0); } while (0)
; #define PG8_WAIT_V(n) asm volatile("s_waitcnt vmcnt(" #n ")" ::: "memory")
; #define PG8_WAIT_L(n) asm volatile("s_waitcnt lgkmcnt(" #n ")" ::: "memory")
; #define PG8_BAR __builtin_amdgcn_s_barrier()
; #define PG8_SCHED __builtin_amdgcn_sched_barrier(0)
; template <class Epi, class Sched>
; __device__ __forceinline__ void gemm_phase(LAS unsigned char* lds, const Gemm g, const Sched& S, const Epi& E) {
;     ...
;             PG8_BAR; PG8_WAIT_L(0); PG8_MMA(1, 0, At, B0); PG8_BAR; PG8_SCHED;
;             PG8_STAGE(PG8_SB(0, 1), b2 + hstepB, voffB);
;             PG8_WAIT_V(6); PG8_BAR; PG8_MMA(1, 1, At, B1); PG8_BAR;
;             PG8_LDB(B0, 1, 0); PG8_SCHED; PG8_LDA(At, 1, 0); PG8_STAGE(PG8_SA(0, 1), a2 + hstepA, voffA);
;             PG8_WAIT_L(8); PG8_BAR; PG8_WAIT_L(0); PG8_MMA(0, 0, At, B0); PG8_BAR; PG8_SCHED;
;             PG8_LDB(B1, 1, 1); PG8_STAGE(PG8_SB(1, 0), b3, voffB);
;             PG8_BAR; PG8_WAIT_L(0); PG8_MMA(0, 1, At, B1); PG8_BAR;
;             PG8_LDA(At, 1, 1); PG8_STAGE(PG8_SA(1, 0), a3, voffA);
;             PG8_BAR; PG8_WAIT_L(0); PG8_MMA(1, 0, At, B0); PG8_BAR; PG8_SCHED;
	v_mfma_f32_16x16x32_bf16 v[64:67], v[132:135], v[148:151], v[64:67]
	v_mfma_f32_16x16x32_bf16 v[60:63], v[140:143], v[148:151], v[60:63]
	v_mfma_f32_16x16x32_bf16 v[52:55], v[132:135], v[156:159], v[52:55]
	v_mfma_f32_16x16x32_bf16 v[44:47], v[140:143], v[156:159], v[44:47]
	v_mfma_f32_16x16x32_bf16 v[36:39], v[132:135], v[164:167], v[36:39]
	v_mfma_f32_16x16x32_bf16 v[28:31], v[140:143], v[164:167], v[28:31]
	v_mfma_f32_16x16x32_bf16 v[20:23], v[132:135], v[172:175], v[20:23]
	v_mfma_f32_16x16x32_bf16 v[12:15], v[140:143], v[172:175], v[12:15]
	v_mfma_f32_16x16x32_bf16 v[64:67], v[136:139], v[152:155], v[64:67]
	v_mfma_f32_16x16x32_bf16 v[60:63], v[144:147], v[152:155], v[60:63]
	v_mfma_f32_16x16x32_bf16 v[52:55], v[136:139], v[160:163], v[52:55]
	v_mfma_f32_16x16x32_bf16 v[44:47], v[144:147], v[160:163], v[44:47]
	v_mfma_f32_16x16x32_bf16 v[36:39], v[136:139], v[168:171], v[36:39]
	v_mfma_f32_16x16x32_bf16 v[28:31], v[144:147], v[168:171], v[28:31]
	v_mfma_f32_16x16x32_bf16 v[20:23], v[136:139], v[176:179], v[20:23]
	v_mfma_f32_16x16x32_bf16 v[12:15], v[144:147], v[176:179], v[12:15]
	v_mfma_f32_16x16x32_bf16 v[56:59], v[180:183], v[148:151], v[56:59]
	v_mfma_f32_16x16x32_bf16 v[48:51], v[188:191], v[148:151], v[48:51]
	v_mfma_f32_16x16x32_bf16 v[40:43], v[180:183], v[156:159], v[40:43]
	v_mfma_f32_16x16x32_bf16 v[32:35], v[188:191], v[156:159], v[32:35]
	v_mfma_f32_16x16x32_bf16 v[24:27], v[180:183], v[164:167], v[24:27]
	v_mfma_f32_16x16x32_bf16 v[16:19], v[188:191], v[164:167], v[16:19]
	v_mfma_f32_16x16x32_bf16 v[8:11], v[180:183], v[172:175], v[8:11]
	v_mfma_f32_16x16x32_bf16 v[4:7], v[188:191], v[172:175], v[4:7]
	v_mfma_f32_16x16x32_bf16 v[56:59], v[184:187], v[152:155], v[56:59]
	v_mfma_f32_16x16x32_bf16 v[48:51], v[202:205], v[152:155], v[48:51]
	v_mfma_f32_16x16x32_bf16 v[40:43], v[184:187], v[160:163], v[40:43]
	v_mfma_f32_16x16x32_bf16 v[32:35], v[202:205], v[160:163], v[32:35]
	v_mfma_f32_16x16x32_bf16 v[24:27], v[184:187], v[168:171], v[24:27]
	v_mfma_f32_16x16x32_bf16 v[16:19], v[202:205], v[168:171], v[16:19]
	v_mfma_f32_16x16x32_bf16 v[8:11], v[184:187], v[176:179], v[8:11]
	v_mfma_f32_16x16x32_bf16 v[4:7], v[202:205], v[176:179], v[4:7]
	s_barrier
	s_add_i32 s45, 0, 0x18000
	v_add_u32_e32 v144, s45, v1
	ds_read_b128 v[132:135], v144
	ds_read_b128 v[136:139], v144 offset:1024
	ds_read_b128 v[140:143], v144 offset:2048
	ds_read_b128 v[144:147], v144 offset:3072
	s_add_u32 s6, s20, 0x160000
	s_addc_u32 s7, s21, 0
	ds_read_b128 v[148:151], v224 offset:32768
	ds_read_b128 v[152:155], v224 offset:33792
	ds_read_b128 v[156:159], v224 offset:34816
	ds_read_b128 v[160:163], v224 offset:35840
	ds_read_b128 v[164:167], v224 offset:36864
	ds_read_b128 v[168:171], v224 offset:37888
	ds_read_b128 v[172:175], v224 offset:38912
	ds_read_b128 v[176:179], v224 offset:39936
	s_mov_b32 m0, s31
	s_nop 0
	global_load_lds_dwordx4 v196, s[6:7]
	s_mov_b32 m0, s35
	s_nop 0
	global_load_lds_dwordx4 v194, s[6:7]
	s_add_i32 s20, 0, 0x1c000
	v_add_u32_e32 v202, s20, v1
	ds_read_b128 v[180:183], v202
	ds_read_b128 v[184:187], v202 offset:1024
	ds_read_b128 v[188:191], v202 offset:2048
	ds_read_b128 v[202:205], v202 offset:3072
	s_waitcnt lgkmcnt(0)
	s_barrier
	v_mfma_f32_16x16x32_bf16 v[128:131], v[132:135], v[148:151], v[128:131]
	v_mfma_f32_16x16x32_bf16 v[124:127], v[140:143], v[148:151], v[124:127]
	v_mfma_f32_16x16x32_bf16 v[112:115], v[132:135], v[156:159], v[112:115]
	v_mfma_f32_16x16x32_bf16 v[108:111], v[140:143], v[156:159], v[108:111]
	v_mfma_f32_16x16x32_bf16 v[100:103], v[132:135], v[164:167], v[100:103]
	v_mfma_f32_16x16x32_bf16 v[92:95], v[140:143], v[164:167], v[92:95]
	v_mfma_f32_16x16x32_bf16 v[84:87], v[132:135], v[172:175], v[84:87]
	v_mfma_f32_16x16x32_bf16 v[76:79], v[140:143], v[172:175], v[76:79]
	v_mfma_f32_16x16x32_bf16 v[128:131], v[136:139], v[152:155], v[128:131]
	v_mfma_f32_16x16x32_bf16 v[124:127], v[144:147], v[152:155], v[124:127]
	v_mfma_f32_16x16x32_bf16 v[112:115], v[136:139], v[160:163], v[112:115]
	v_mfma_f32_16x16x32_bf16 v[108:111], v[144:147], v[160:163], v[108:111]
	v_mfma_f32_16x16x32_bf16 v[100:103], v[136:139], v[168:171], v[100:103]
	v_mfma_f32_16x16x32_bf16 v[92:95], v[144:147], v[168:171], v[92:95]
	v_mfma_f32_16x16x32_bf16 v[84:87], v[136:139], v[176:179], v[84:87]
	v_mfma_f32_16x16x32_bf16 v[76:79], v[144:147], v[176:179], v[76:79]
	v_mfma_f32_16x16x32_bf16 v[120:123], v[180:183], v[148:151], v[120:123]
	v_mfma_f32_16x16x32_bf16 v[116:119], v[188:191], v[148:151], v[116:119]
	v_mfma_f32_16x16x32_bf16 v[104:107], v[180:183], v[156:159], v[104:107]
	v_mfma_f32_16x16x32_bf16 v[96:99], v[188:191], v[156:159], v[96:99]
	v_mfma_f32_16x16x32_bf16 v[88:91], v[180:183], v[164:167], v[88:91]
	v_mfma_f32_16x16x32_bf16 v[80:83], v[188:191], v[164:167], v[80:83]
	v_mfma_f32_16x16x32_bf16 v[72:75], v[180:183], v[172:175], v[72:75]
	v_mfma_f32_16x16x32_bf16 v[68:71], v[188:191], v[172:175], v[68:71]
	v_mfma_f32_16x16x32_bf16 v[120:123], v[184:187], v[152:155], v[120:123]
	v_mfma_f32_16x16x32_bf16 v[116:119], v[202:205], v[152:155], v[116:119]
	v_mfma_f32_16x16x32_bf16 v[104:107], v[184:187], v[160:163], v[104:107]
	v_mfma_f32_16x16x32_bf16 v[96:99], v[202:205], v[160:163], v[96:99]
	v_mfma_f32_16x16x32_bf16 v[88:91], v[184:187], v[168:171], v[88:91]
	v_mfma_f32_16x16x32_bf16 v[80:83], v[202:205], v[168:171], v[80:83]
	v_mfma_f32_16x16x32_bf16 v[72:75], v[184:187], v[176:179], v[72:75]
	v_mfma_f32_16x16x32_bf16 v[68:71], v[202:205], v[176:179], v[68:71]
	s_barrier
; #define PG8_STAGE(bufoff, gbase, voff) do { _Pragma("unroll") for (int _i = 0; _i < 2; ++_i) \
;         __builtin_amdgcn_global_load_lds((const unsigned*)((const char*)(gbase) + (voff)[_i]), (LAS unsigned*)(lds + (bufoff) + ldsw + _i * 8192), 16, 0, 0); } while (0)
; #define PG8_LDA(dst, b, h) do { _Pragma("unroll") for (int m = 0; m < 4; ++m) _Pragma("unroll") for (int k = 0; k < 2; ++k) dst[m][k] = *(const LAS bf16x8*)(lds + PG8_SA(b, h) + aoff + m * 2048 + k * 1024); } while (0)
; #define PG8_MMA(ai, bj, At, Bt) do { __builtin_amdgcn_s_setprio(1); _Pragma("unroll") for (int m = 0; m < 4; ++m) _Pragma("unroll") for (int n = 0; n < 2; ++n) _Pragma("unroll") for (int k = 0; k < 2; ++k) \
;         acc[ai][bj][m][n] = __builtin_amdgcn_mfma_f32_16x16x32_bf16(Bt[n][k], At[m][k], acc[ai][bj][m][n], 0, 0, 0); __builtin_amdgcn_s_setprio(0); } while (0)
; #define PG8_WAIT_V(n) asm volatile("s_waitcnt vmcnt(" #n ")" ::: "memory")
; #define PG8_WAIT_L(n) asm volatile("s_waitcnt lgkmcnt(" #n ")" ::: "memory")
; #define PG8_BAR __builtin_amdgcn_s_barrier()
; #define PG8_SCHED __builtin_amdgcn_sched_barrier(0)
; template <class Epi, class Sched>
; __device__ __forceinline__ void gemm_phase(LAS unsigned char* lds, const Gemm g, const Sched& S, const Epi& E) {
;     ...
;             PG8_LDA(At, 1, 1); PG8_STAGE(PG8_SA(1, 0), a3, voffA);
;             PG8_BAR; PG8_WAIT_L(0); PG8_MMA(1, 0, At, B0); PG8_BAR; PG8_SCHED;
;             PG8_STAGE(PG8_SB(1, 1), b3 + hstepB, voffB);
;             PG8_WAIT_V(6); PG8_BAR; PG8_MMA(1, 1, At, B1); PG8_BAR;
;         }
;     ...
;     PG8_WAIT_V(0);
;     if (wr == 0) PG8_BAR;
	ds_read_b128 v[148:151], v224 offset:49152
	ds_read_b128 v[152:155], v224 offset:50176
	ds_read_b128 v[156:159], v224 offset:51200
	ds_read_b128 v[160:163], v224 offset:52224
	ds_read_b128 v[164:167], v224 offset:53248
	ds_read_b128 v[168:171], v224 offset:54272
	ds_read_b128 v[172:175], v224 offset:55296
	ds_read_b128 v[176:179], v224 offset:56320
	s_add_i32 s6, s45, s28
	v_lshl_add_u64 v[206:207], v[206:207], 0, s[8:9]
	s_mov_b32 m0, s6
	s_nop 0
	global_load_lds_dwordx4 v[206:207], off
	v_lshl_add_u64 v[206:207], v[208:209], 0, s[8:9]
	s_add_i32 m0, s6, 0x2000
	s_nop 0
	global_load_lds_dwordx4 v[206:207], off
	s_mov_b32 m0, s38
	v_lshl_add_u64 v[206:207], v[210:211], 0, s[8:9]
	global_load_lds_dwordx4 v[206:207], off
	v_lshl_add_u64 v[206:207], v[212:213], 0, s[8:9]
	s_mov_b32 m0, s39
	s_nop 0
	global_load_lds_dwordx4 v[206:207], off
	s_add_u32 s6, s18, 0x160080
	s_addc_u32 s7, s19, 0
	s_add_i32 s18, s20, s28
	s_mov_b32 m0, s18
	s_nop 0
	global_load_lds_dwordx4 v2, s[6:7]
	s_add_i32 m0, s18, 0x2000
	s_nop 0
	global_load_lds_dwordx4 v192, s[6:7]
	s_add_i32 s44, s44, 2
	s_add_u32 s42, s42, 0x100
	s_addc_u32 s43, s43, 0
	s_cmpk_gt_u32 s44, 0x55
	s_mov_b64 s[6:7], s[14:15]
	s_waitcnt lgkmcnt(0)
	s_waitcnt vmcnt(6)
	s_barrier
	v_mfma_f32_16x16x32_bf16 v[64:67], v[132:135], v[148:151], v[64:67]
	v_mfma_f32_16x16x32_bf16 v[60:63], v[140:143], v[148:151], v[60:63]
	v_mfma_f32_16x16x32_bf16 v[52:55], v[132:135], v[156:159], v[52:55]
	v_mfma_f32_16x16x32_bf16 v[44:47], v[140:143], v[156:159], v[44:47]
	v_mfma_f32_16x16x32_bf16 v[36:39], v[132:135], v[164:167], v[36:39]
	v_mfma_f32_16x16x32_bf16 v[28:31], v[140:143], v[164:167], v[28:31]
	v_mfma_f32_16x16x32_bf16 v[20:23], v[132:135], v[172:175], v[20:23]
	v_mfma_f32_16x16x32_bf16 v[12:15], v[140:143], v[172:175], v[12:15]
	v_mfma_f32_16x16x32_bf16 v[64:67], v[136:139], v[152:155], v[64:67]
	v_mfma_f32_16x16x32_bf16 v[60:63], v[144:147], v[152:155], v[60:63]
	v_mfma_f32_16x16x32_bf16 v[52:55], v[136:139], v[160:163], v[52:55]
	v_mfma_f32_16x16x32_bf16 v[44:47], v[144:147], v[160:163], v[44:47]
	v_mfma_f32_16x16x32_bf16 v[36:39], v[136:139], v[168:171], v[36:39]
	v_mfma_f32_16x16x32_bf16 v[28:31], v[144:147], v[168:171], v[28:31]
	v_mfma_f32_16x16x32_bf16 v[20:23], v[136:139], v[176:179], v[20:23]
	v_mfma_f32_16x16x32_bf16 v[12:15], v[144:147], v[176:179], v[12:15]
	v_mfma_f32_16x16x32_bf16 v[56:59], v[180:183], v[148:151], v[56:59]
	v_mfma_f32_16x16x32_bf16 v[48:51], v[188:191], v[148:151], v[48:51]
	v_mfma_f32_16x16x32_bf16 v[40:43], v[180:183], v[156:159], v[40:43]
	v_mfma_f32_16x16x32_bf16 v[32:35], v[188:191], v[156:159], v[32:35]
	v_mfma_f32_16x16x32_bf16 v[24:27], v[180:183], v[164:167], v[24:27]
	v_mfma_f32_16x16x32_bf16 v[16:19], v[188:191], v[164:167], v[16:19]
	v_mfma_f32_16x16x32_bf16 v[8:11], v[180:183], v[172:175], v[8:11]
	v_mfma_f32_16x16x32_bf16 v[4:7], v[188:191], v[172:175], v[4:7]
	v_mfma_f32_16x16x32_bf16 v[56:59], v[184:187], v[152:155], v[56:59]
	v_mfma_f32_16x16x32_bf16 v[48:51], v[202:205], v[152:155], v[48:51]
	v_mfma_f32_16x16x32_bf16 v[40:43], v[184:187], v[160:163], v[40:43]
	v_mfma_f32_16x16x32_bf16 v[32:35], v[202:205], v[160:163], v[32:35]
	v_mfma_f32_16x16x32_bf16 v[24:27], v[184:187], v[168:171], v[24:27]
	v_mfma_f32_16x16x32_bf16 v[16:19], v[202:205], v[168:171], v[16:19]
	v_mfma_f32_16x16x32_bf16 v[8:11], v[184:187], v[176:179], v[8:11]
	v_mfma_f32_16x16x32_bf16 v[4:7], v[202:205], v[176:179], v[4:7]
	s_barrier
	s_cbranch_scc0 .LBB0_1666
	s_setprio 0
	s_cmpk_gt_u32 s2, 0xff
	s_cbranch_scc1 .Lalign_a_1666
	s_barrier
